# out-GEMM A operand: HY(y) rows below MLAT stored pair-interleaved by the attention, G3, SGU and stage-2 epilogues (byte-offset permutation per store), out-GEMM A-tile DMA reads full 128B lines
# speedup vs baseline: 1.1068x; 1.0004x over previous
; template <int TRANS, class AP, class BP, class Epi>
; DI void mfma_gemm_tile(const AP& aptr, const BP& bptr, int m0, int n0, int K, const Epi& epi, bf16* lds) {
;   const int tid = otid(), lane = tid & 63, wave = __builtin_amdgcn_readfirstlane(tid >> 6);
;   const int wm = (wave >> 1) * 64, wn = (wave & 1) * 64;
;   const int lr = tid >> 3, lc = ((tid & 7) ^ (lr & 7)) * 8;
;   const int l16 = lane & 15, lq = lane >> 4;
;   const bf16* ap[4]; const bf16* bp[4];
; #pragma unroll
;   for (int i = 0; i < 4; ++i) { ap[i] = aptr(m0 + lr + 32 * i) + lc; bp[i] = bptr(n0 + lr + 32 * i) + lc; }
;   f32x4 acc[4][4];
; #pragma unroll
;   for (int i = 0; i < 4; ++i)
; #pragma unroll
;     for (int j = 0; j < 4; ++j) acc[i][j] = f32x4{0.f, 0.f, 0.f, 0.f};
;   const int nk = K >> 6;
;     ...
;   GEMM_STAGE(0, 0);
;   if (nk > 1) GEMM_STAGE(1, 1);
;   const unsigned lbase = (unsigned)(size_t)lds;
;   const unsigned sw0 = (unsigned)(((lq ^ (l16 & 7)) * 8) * 2), sw1 = (unsigned)((((4 + lq) ^ (l16 & 7)) * 8) * 2);
;   const unsigned a_row = (unsigned)((wm + l16) * 128), b_row = (unsigned)((128 * 64 + (wn + l16) * 64) * 2);
;     ...
;   for (int ks = 0; ks < nk; ++ks) {
;     if (ks + 1 < nk) asm volatile("s_waitcnt vmcnt(8)\n\ts_barrier" ::: "memory");
;     else asm volatile("s_waitcnt vmcnt(0)\n\ts_barrier" ::: "memory");
;     const unsigned sb_ = lbase + (unsigned)((ks & 1) * (2 * 128 * 64) * 2);
;     const unsigned a0 = sb_ + a_row + sw0, a1 = sb_ + a_row + sw1, b0 = sb_ + b_row + sw0, b1 = sb_ + b_row + sw1;
;     bf16x8 af[2][4], bfr[2][4];
;     LDSR(af[0][0], a0, 0); LDSR(af[0][1], a0, 2048); LDSR(af[0][2], a0, 4096); LDSR(af[0][3], a0, 6144);
;     LDSR(bfr[0][0], b0, 0); LDSR(bfr[0][1], b0, 2048); LDSR(bfr[0][2], b0, 4096); LDSR(bfr[0][3], b0, 6144);
;     LDSR(af[1][0], a1, 0); LDSR(af[1][1], a1, 2048); LDSR(af[1][2], a1, 4096); LDSR(af[1][3], a1, 6144);
;     LDSR(bfr[1][0], b1, 0); LDSR(bfr[1][1], b1, 2048); LDSR(bfr[1][2], b1, 4096); LDSR(bfr[1][3], b1, 6144);
;     asm volatile("s_waitcnt lgkmcnt(0)" : "+v"(af[0][0]), "+v"(af[0][1]), "+v"(af[0][2]), "+v"(af[0][3]), "+v"(bfr[0][0]), "+v"(bfr[0][1]), "+v"(bfr[0][2]), "+v"(bfr[0][3]),
;                  "+v"(af[1][0]), "+v"(af[1][1]), "+v"(af[1][2]), "+v"(af[1][3]), "+v"(bfr[1][0]), "+v"(bfr[1][1]), "+v"(bfr[1][2]), "+v"(bfr[1][3]) : : "memory");
;     if (ks + 2 < nk) {
;       asm volatile("s_barrier" ::: "memory");
.LBB0_377:
	s_cmp_ge_i32 s13, s6
	s_cbranch_scc0 .LBB0_379
	s_add_i32 s0, s10, s16
	s_add_i32 s0, s0, s12
	v_mov_b32_e32 v14, v172
	s_lshl_b32 s0, s0, 6
	s_and_b32 s0, s0, 0xffffff80
	v_ashrrev_i32_e32 v3, 3, v14
	s_lshl_b32 s1, s13, 7
	v_xor_b32_e32 v0, v3, v14
	s_and_b32 s1, s1, 0x80
	v_readfirstlane_b32 s35, v14
	v_add_u32_e32 v2, s0, v3
	v_lshlrev_b32_e32 v0, 4, v0
	v_readlane_b32 s2, v253, 9
	v_and_b32_e32 v0, 0x70, v0
	v_readlane_b32 s3, v253, 10
	v_add_u32_e32 v6, s1, v3
	v_ashrrev_i32_e32 v3, 31, v2
	s_lshl_b32 s17, s35, 4
	v_lshl_add_u64 v[4:5], s[2:3], 0, v[0:1]
	v_lshlrev_b64 v[2:3], 10, v[2:3]
	v_ashrrev_i32_e32 v7, 31, v6
	s_and_b32 s25, s17, 0xfffffc00
	v_lshl_add_u64 v[8:9], s[94:95], 0, v[0:1]
	v_lshl_add_u64 v[98:99], v[4:5], 0, v[2:3]
	v_lshlrev_b64 v[2:3], 10, v[6:7]
	s_mov_b32 m0, s25
	s_add_i32 s26, s25, 0x4000
	v_lshl_add_u64 v[100:101], v[8:9], 0, v[2:3]
	s_mov_b64 s[2:3], 0x8000
	global_load_lds_dwordx4 v[98:99], off
	s_mov_b32 m0, s26
	s_add_i32 s27, s25, 0x1000
	v_lshl_add_u64 v[2:3], v[98:99], 0, s[2:3]
	global_load_lds_dwordx4 v[100:101], off
	s_mov_b32 m0, s27
	s_add_i32 s28, s25, 0x5000
	v_lshl_add_u64 v[4:5], v[100:101], 0, s[2:3]
	s_mov_b64 s[2:3], 0x10000
	global_load_lds_dwordx4 v[2:3], off
	s_mov_b32 m0, s28
	s_add_i32 s29, s25, 0x2000
	v_lshl_add_u64 v[6:7], v[98:99], 0, s[2:3]
	global_load_lds_dwordx4 v[4:5], off
	s_mov_b32 m0, s29
	s_add_i32 s30, s25, 0x6000
	v_lshl_add_u64 v[8:9], v[100:101], 0, s[2:3]
	s_mov_b64 s[2:3], 0x18000
	global_load_lds_dwordx4 v[6:7], off
	s_mov_b32 m0, s30
	s_add_i32 s31, s25, 0x3000
	v_lshl_add_u64 v[10:11], v[98:99], 0, s[2:3]
	global_load_lds_dwordx4 v[8:9], off
	s_mov_b32 m0, s31
	s_add_i32 s34, s25, 0x7000
	v_lshl_add_u64 v[12:13], v[100:101], 0, s[2:3]
	global_load_lds_dwordx4 v[10:11], off
	s_mov_b32 m0, s34
	s_mov_b64 s[2:3], 0x80
	s_add_i32 s24, s25, 0x8000
	global_load_lds_dwordx4 v[12:13], off
	v_lshl_add_u64 v[2:3], v[98:99], 0, s[2:3]
	s_mov_b32 m0, s24
	s_add_i32 s23, s25, 0xc000
	global_load_lds_dwordx4 v[2:3], off
	v_lshl_add_u64 v[2:3], v[100:101], 0, s[2:3]
	s_mov_b32 m0, s23
	s_mov_b64 s[2:3], 0x8080
	s_add_i32 s22, s25, 0x9000
	global_load_lds_dwordx4 v[2:3], off
	v_lshl_add_u64 v[2:3], v[98:99], 0, s[2:3]
	s_mov_b32 m0, s22
	s_add_i32 s18, s25, 0xd000
	global_load_lds_dwordx4 v[2:3], off
	v_lshl_add_u64 v[2:3], v[100:101], 0, s[2:3]
	s_mov_b32 m0, s18
	s_mov_b64 s[2:3], 0x10080
	s_add_i32 s17, s25, 0xa000
	global_load_lds_dwordx4 v[2:3], off
	v_lshl_add_u64 v[2:3], v[98:99], 0, s[2:3]
	s_mov_b32 m0, s17
	s_add_i32 s19, s25, 0xe000
	global_load_lds_dwordx4 v[2:3], off
	v_lshl_add_u64 v[2:3], v[100:101], 0, s[2:3]
	s_mov_b32 m0, s19
	s_mov_b64 s[2:3], 0x18080
	s_add_i32 s20, s25, 0xb000
	global_load_lds_dwordx4 v[2:3], off
	v_lshl_add_u64 v[2:3], v[98:99], 0, s[2:3]
	s_mov_b32 m0, s20
	s_add_i32 s21, s25, 0xf000
	global_load_lds_dwordx4 v[2:3], off
	v_lshl_add_u64 v[2:3], v[100:101], 0, s[2:3]
	s_mov_b32 m0, s21
	s_ashr_i32 s16, s35, 1
	v_lshrrev_b32_e32 v15, 4, v14
	v_and_b32_e32 v16, 15, v14
	global_load_lds_dwordx4 v[2:3], off
	v_bfe_u32 v0, v14, 4, 2
	v_and_b32_e32 v2, 7, v14
	s_andn2_b32 s16, s16, 63
	v_bitop3_b32 v3, v15, v2, 3 bitop3:0x6c
	v_bitop3_b32 v2, v0, v2, 4 bitop3:0x36
	v_and_or_b32 v102, s35, 64, v16
	v_lshlrev_b32_e32 v140, 4, v2
	v_or_b32_e32 v2, s16, v16
	v_lshlrev_b32_e32 v142, 7, v102
	v_lshlrev_b32_e32 v107, 4, v3
	v_lshlrev_b32_e32 v141, 7, v2
	v_or_b32_e32 v2, 0x4000, v142
	s_waitcnt vmcnt(8)
	s_barrier
	v_or_b32_e32 v106, v141, v107
	v_or_b32_e32 v104, v141, v140
	v_or_b32_e32 v105, v2, v107
	v_or_b32_e32 v103, v2, v140
	ds_read_b128 v[2:5], v106 offset:0
	ds_read_b128 v[6:9], v106 offset:0x800
	ds_read_b128 v[10:13], v106 offset:0x1000
	ds_read_b128 v[14:17], v106 offset:0x1800
	ds_read_b128 v[18:21], v105 offset:0
	ds_read_b128 v[22:25], v105 offset:0x800
	ds_read_b128 v[26:29], v105 offset:0x1000
	ds_read_b128 v[34:37], v105 offset:0x1800
	ds_read_b128 v[46:49], v104 offset:0
	ds_read_b128 v[54:57], v104 offset:0x800
	ds_read_b128 v[66:69], v104 offset:0x1000
	ds_read_b128 v[30:33], v104 offset:0x1800
	ds_read_b128 v[58:61], v103 offset:0
	ds_read_b128 v[50:53], v103 offset:0x800
	ds_read_b128 v[42:45], v103 offset:0x1000
	ds_read_b128 v[38:41], v103 offset:0x1800
	s_mov_b64 s[2:3], 0x100
	s_waitcnt lgkmcnt(0)
	s_barrier
	v_lshl_add_u64 v[62:63], v[98:99], 0, s[2:3]
	s_mov_b32 m0, s25
	v_mfma_f32_16x16x32_bf16 v[74:77], v[2:5], v[26:29], 0
	global_load_lds_dwordx4 v[62:63], off
	v_lshl_add_u64 v[62:63], v[100:101], 0, s[2:3]
	s_mov_b32 m0, s26
	s_mov_b64 s[2:3], 0x8100
	global_load_lds_dwordx4 v[62:63], off
	v_lshl_add_u64 v[62:63], v[98:99], 0, s[2:3]
	s_mov_b32 m0, s27
	v_mfma_f32_16x16x32_bf16 v[78:81], v[2:5], v[34:37], 0
	global_load_lds_dwordx4 v[62:63], off
	v_lshl_add_u64 v[62:63], v[100:101], 0, s[2:3]
	s_mov_b32 m0, s28
	s_mov_b64 s[2:3], 0x10100
	global_load_lds_dwordx4 v[62:63], off
	v_lshl_add_u64 v[62:63], v[98:99], 0, s[2:3]
	s_mov_b32 m0, s29
	v_mfma_f32_16x16x32_bf16 v[82:85], v[6:9], v[18:21], 0
	global_load_lds_dwordx4 v[62:63], off
	v_lshl_add_u64 v[62:63], v[100:101], 0, s[2:3]
	s_mov_b32 m0, s30
	s_mov_b64 s[2:3], 0x18100
	global_load_lds_dwordx4 v[62:63], off
	v_lshl_add_u64 v[62:63], v[98:99], 0, s[2:3]
	s_mov_b32 m0, s31
	v_mfma_f32_16x16x32_bf16 v[86:89], v[6:9], v[22:25], 0
	global_load_lds_dwordx4 v[62:63], off
	v_lshl_add_u64 v[62:63], v[100:101], 0, s[2:3]
	s_mov_b32 m0, s34
	v_mfma_f32_16x16x32_bf16 v[124:127], v[14:17], v[18:21], 0
	global_load_lds_dwordx4 v[62:63], off
	s_waitcnt vmcnt(8)
	s_barrier
; #define LDSR(dst, addr, off) asm volatile("ds_read_b128 %0, %1 offset:%2" : "=&v"(dst) : "v"(addr), "n"(off))
; #define LDSR(dst, addr, off) asm volatile("ds_read_b128 %0, %1 offset:%2" : "=&v"(dst) : "v"(addr), "n"(off))
; template <int TRANS, class AP, class BP, class Epi>
; DI void mfma_gemm_tile(const AP& aptr, const BP& bptr, int m0, int n0, int K, const Epi& epi, bf16* lds) {
;     ...
;   for (int ks = 0; ks < nk; ++ks) {
;     if (ks + 1 < nk) asm volatile("s_waitcnt vmcnt(8)\n\ts_barrier" ::: "memory");
;     else asm volatile("s_waitcnt vmcnt(0)\n\ts_barrier" ::: "memory");
;     const unsigned sb_ = lbase + (unsigned)((ks & 1) * (2 * 128 * 64) * 2);
;     const unsigned a0 = sb_ + a_row + sw0, a1 = sb_ + a_row + sw1, b0 = sb_ + b_row + sw0, b1 = sb_ + b_row + sw1;
;     bf16x8 af[2][4], bfr[2][4];
;     LDSR(af[0][0], a0, 0); LDSR(af[0][1], a0, 2048); LDSR(af[0][2], a0, 4096); LDSR(af[0][3], a0, 6144);
;     LDSR(bfr[0][0], b0, 0); LDSR(bfr[0][1], b0, 2048); LDSR(bfr[0][2], b0, 4096); LDSR(bfr[0][3], b0, 6144);
;     LDSR(af[1][0], a1, 0); LDSR(af[1][1], a1, 2048); LDSR(af[1][2], a1, 4096); LDSR(af[1][3], a1, 6144);
;     LDSR(bfr[1][0], b1, 0); LDSR(bfr[1][1], b1, 2048); LDSR(bfr[1][2], b1, 4096); LDSR(bfr[1][3], b1, 6144);
;     asm volatile("s_waitcnt lgkmcnt(0)" : "+v"(af[0][0]), "+v"(af[0][1]), "+v"(af[0][2]), "+v"(af[0][3]), "+v"(bfr[0][0]), "+v"(bfr[0][1]), "+v"(bfr[0][2]), "+v"(bfr[0][3]),
;                  "+v"(af[1][0]), "+v"(af[1][1]), "+v"(af[1][2]), "+v"(af[1][3]), "+v"(bfr[1][0]), "+v"(bfr[1][1]), "+v"(bfr[1][2]), "+v"(bfr[1][3]) : : "memory");
;     if (ks + 2 < nk) {
;       asm volatile("s_barrier" ::: "memory");
;       GEMM_STAGE(ks & 1, ks + 2);
;     }
; #pragma unroll
;     for (int kk = 0; kk < 2; ++kk)
; #pragma unroll
;       for (int i = 0; i < 4; ++i)
; #pragma unroll
;         for (int j = 0; j < 4; ++j)
;           acc[i][j] = TRANS ? __builtin_amdgcn_mfma_f32_16x16x32_bf16(af[kk][i], bfr[kk][j], acc[i][j], 0, 0, 0)
;                             : __builtin_amdgcn_mfma_f32_16x16x32_bf16(bfr[kk][j], af[kk][i], acc[i][j], 0, 0, 0);
;   }
	v_mfma_f32_16x16x32_bf16 v[128:131], v[14:17], v[22:25], 0
	s_mov_b64 s[2:3], 0x180
	v_lshl_add_u64 v[144:145], v[98:99], 0, s[2:3]
	s_mov_b32 m0, s24
	v_mfma_f32_16x16x32_bf16 v[132:135], v[14:17], v[26:29], 0
	s_add_i32 s16, s16, s0
	s_and_b32 s0, s16, 0x1c0
	s_lshl_b32 s0, s0, 1
	v_mfma_f32_16x16x32_bf16 v[136:139], v[14:17], v[34:37], 0
	v_lshl_or_b32 v0, v0, 3, s0
	v_mfma_f32_16x16x32_bf16 v[62:65], v[2:5], v[18:21], 0
	v_mfma_f32_16x16x32_bf16 v[70:73], v[2:5], v[22:25], 0
	v_mfma_f32_16x16x32_bf16 v[108:111], v[10:13], v[18:21], 0
	v_mfma_f32_16x16x32_bf16 v[90:93], v[6:9], v[26:29], 0
	v_mfma_f32_16x16x32_bf16 v[94:97], v[6:9], v[34:37], 0
	v_mfma_f32_16x16x32_bf16 v[112:115], v[10:13], v[22:25], 0
	v_mfma_f32_16x16x32_bf16 v[116:119], v[10:13], v[26:29], 0
	v_mfma_f32_16x16x32_bf16 v[120:123], v[10:13], v[34:37], 0
	v_mfma_f32_16x16x32_bf16 v[10:13], v[46:49], v[42:45], v[74:77]
	v_mfma_f32_16x16x32_bf16 v[14:17], v[46:49], v[38:41], v[78:81]
	v_mfma_f32_16x16x32_bf16 v[18:21], v[54:57], v[58:61], v[82:85]
	v_mfma_f32_16x16x32_bf16 v[22:25], v[54:57], v[50:53], v[86:89]
	v_mfma_f32_16x16x32_bf16 v[74:77], v[30:33], v[58:61], v[124:127]
	v_mfma_f32_16x16x32_bf16 v[78:81], v[30:33], v[50:53], v[128:131]
	v_mfma_f32_16x16x32_bf16 v[82:85], v[30:33], v[42:45], v[132:135]
	v_mfma_f32_16x16x32_bf16 v[86:89], v[30:33], v[38:41], v[136:139]
	v_add_u32_e32 v30, 0x8000, v141
	v_mfma_f32_16x16x32_bf16 v[2:5], v[46:49], v[58:61], v[62:65]
	v_mfma_f32_16x16x32_bf16 v[6:9], v[46:49], v[50:53], v[70:73]
	v_mfma_f32_16x16x32_bf16 v[46:49], v[66:69], v[58:61], v[108:111]
	s_nop 2
	v_or_b32_e32 v110, v30, v107
	v_or_b32_e32 v108, v30, v140
	v_or_b32_e32 v30, 0xc000, v142
	v_mfma_f32_16x16x32_bf16 v[26:29], v[54:57], v[42:45], v[90:93]
	v_or_b32_e32 v109, v30, v107
	v_or_b32_e32 v107, v30, v140
	ds_read_b128 v[90:93], v110 offset:0
	v_mfma_f32_16x16x32_bf16 v[34:37], v[54:57], v[38:41], v[94:97]
	ds_read_b128 v[94:97], v110 offset:0x800
	v_mfma_f32_16x16x32_bf16 v[54:57], v[66:69], v[50:53], v[112:115]
	ds_read_b128 v[112:115], v110 offset:0x1000
	v_mfma_f32_16x16x32_bf16 v[62:65], v[66:69], v[42:45], v[116:119]
	ds_read_b128 v[116:119], v110 offset:0x1800
	v_mfma_f32_16x16x32_bf16 v[66:69], v[66:69], v[38:41], v[120:123]
	ds_read_b128 v[120:123], v109 offset:0
	ds_read_b128 v[124:127], v109 offset:0x800
	ds_read_b128 v[128:131], v109 offset:0x1000
	ds_read_b128 v[132:135], v109 offset:0x1800
	ds_read_b128 v[136:139], v108 offset:0
	ds_read_b128 v[140:143], v108 offset:0x800
	ds_read_b128 v[70:73], v108 offset:0x1000
	ds_read_b128 v[30:33], v108 offset:0x1800
	ds_read_b128 v[58:61], v107 offset:0
	ds_read_b128 v[50:53], v107 offset:0x800
	ds_read_b128 v[42:45], v107 offset:0x1000
	ds_read_b128 v[38:41], v107 offset:0x1800
	s_nop 0
	s_waitcnt lgkmcnt(0)
	s_barrier
	global_load_lds_dwordx4 v[144:145], off
	v_lshl_add_u64 v[144:145], v[100:101], 0, s[2:3]
	s_mov_b32 m0, s23
	s_mov_b64 s[2:3], 0x8180
	global_load_lds_dwordx4 v[144:145], off
	v_lshl_add_u64 v[144:145], v[98:99], 0, s[2:3]
	s_mov_b32 m0, s22
	v_mfma_f32_16x16x32_bf16 v[2:5], v[90:93], v[120:123], v[2:5]
	global_load_lds_dwordx4 v[144:145], off
	v_lshl_add_u64 v[144:145], v[100:101], 0, s[2:3]
	s_mov_b32 m0, s18
	s_mov_b64 s[2:3], 0x10180
	global_load_lds_dwordx4 v[144:145], off
	v_lshl_add_u64 v[144:145], v[98:99], 0, s[2:3]
	s_mov_b32 m0, s17
	v_mfma_f32_16x16x32_bf16 v[6:9], v[90:93], v[124:127], v[6:9]
	global_load_lds_dwordx4 v[144:145], off
	v_lshl_add_u64 v[144:145], v[100:101], 0, s[2:3]
	s_mov_b32 m0, s19
	s_mov_b64 s[2:3], 0x18180
	v_mfma_f32_16x16x32_bf16 v[10:13], v[90:93], v[128:131], v[10:13]
	global_load_lds_dwordx4 v[144:145], off
	v_lshl_add_u64 v[144:145], v[98:99], 0, s[2:3]
	v_mfma_f32_16x16x32_bf16 v[14:17], v[90:93], v[132:135], v[14:17]
	s_mov_b32 m0, s20
	s_nop 0
	global_load_lds_dwordx4 v[144:145], off
	v_mfma_f32_16x16x32_bf16 v[18:21], v[94:97], v[120:123], v[18:21]
	v_lshl_add_u64 v[144:145], v[100:101], 0, s[2:3]
	s_mov_b32 m0, s21
	s_mov_b64 s[2:3], 0x200
	v_mfma_f32_16x16x32_bf16 v[22:25], v[94:97], v[124:127], v[22:25]
	global_load_lds_dwordx4 v[144:145], off
	s_waitcnt vmcnt(8)
	s_barrier
	v_mfma_f32_16x16x32_bf16 v[26:29], v[94:97], v[128:131], v[26:29]
	v_lshl_add_u64 v[144:145], v[98:99], 0, s[2:3]
	s_mov_b32 m0, s25
	v_mfma_f32_16x16x32_bf16 v[34:37], v[94:97], v[132:135], v[34:37]
	v_mfma_f32_16x16x32_bf16 v[46:49], v[112:115], v[120:123], v[46:49]
	v_mfma_f32_16x16x32_bf16 v[54:57], v[112:115], v[124:127], v[54:57]
	v_mfma_f32_16x16x32_bf16 v[90:93], v[112:115], v[128:131], v[62:65]
	v_mfma_f32_16x16x32_bf16 v[94:97], v[112:115], v[132:135], v[66:69]
	v_mfma_f32_16x16x32_bf16 v[112:115], v[116:119], v[120:123], v[74:77]
	v_mfma_f32_16x16x32_bf16 v[78:81], v[116:119], v[124:127], v[78:81]
	v_mfma_f32_16x16x32_bf16 v[82:85], v[116:119], v[128:131], v[82:85]
	v_mfma_f32_16x16x32_bf16 v[86:89], v[116:119], v[132:135], v[86:89]
	v_mfma_f32_16x16x32_bf16 v[2:5], v[136:139], v[58:61], v[2:5]
	v_mfma_f32_16x16x32_bf16 v[6:9], v[136:139], v[50:53], v[6:9]
	v_mfma_f32_16x16x32_bf16 v[10:13], v[136:139], v[42:45], v[10:13]
	v_mfma_f32_16x16x32_bf16 v[14:17], v[136:139], v[38:41], v[14:17]
	v_mfma_f32_16x16x32_bf16 v[18:21], v[140:143], v[58:61], v[18:21]
	v_mfma_f32_16x16x32_bf16 v[22:25], v[140:143], v[50:53], v[22:25]
	v_mfma_f32_16x16x32_bf16 v[26:29], v[140:143], v[42:45], v[26:29]
	v_mfma_f32_16x16x32_bf16 v[34:37], v[140:143], v[38:41], v[34:37]
	v_mfma_f32_16x16x32_bf16 v[62:65], v[70:73], v[58:61], v[46:49]
	v_mfma_f32_16x16x32_bf16 v[66:69], v[70:73], v[50:53], v[54:57]
	v_mfma_f32_16x16x32_bf16 v[74:77], v[70:73], v[42:45], v[90:93]
	v_mfma_f32_16x16x32_bf16 v[70:73], v[70:73], v[38:41], v[94:97]
	v_mfma_f32_16x16x32_bf16 v[90:93], v[30:33], v[58:61], v[112:115]
	v_mfma_f32_16x16x32_bf16 v[78:81], v[30:33], v[50:53], v[78:81]
	v_mfma_f32_16x16x32_bf16 v[82:85], v[30:33], v[42:45], v[82:85]
	v_mfma_f32_16x16x32_bf16 v[38:41], v[30:33], v[38:41], v[86:89]
	ds_read_b128 v[86:89], v106 offset:0
	ds_read_b128 v[94:97], v106 offset:0x800
	ds_read_b128 v[112:115], v106 offset:0x1000
	ds_read_b128 v[116:119], v106 offset:0x1800
	ds_read_b128 v[120:123], v105 offset:0
	ds_read_b128 v[124:127], v105 offset:0x800
	ds_read_b128 v[128:131], v105 offset:0x1000
	ds_read_b128 v[132:135], v105 offset:0x1800
	ds_read_b128 v[136:139], v104 offset:0
	ds_read_b128 v[140:143], v104 offset:0x800
	ds_read_b128 v[58:61], v104 offset:0x1000
	ds_read_b128 v[30:33], v104 offset:0x1800
	ds_read_b128 v[42:45], v103 offset:0
	ds_read_b128 v[46:49], v103 offset:0x800
	ds_read_b128 v[50:53], v103 offset:0x1000
	ds_read_b128 v[54:57], v103 offset:0x1800
	s_nop 0
	s_waitcnt lgkmcnt(0)
	s_barrier
; #define LDSR(dst, addr, off) asm volatile("ds_read_b128 %0, %1 offset:%2" : "=&v"(dst) : "v"(addr), "n"(off))
; #define LDSR(dst, addr, off) asm volatile("ds_read_b128 %0, %1 offset:%2" : "=&v"(dst) : "v"(addr), "n"(off))
; template <int TRANS, class AP, class BP, class Epi>
; DI void mfma_gemm_tile(const AP& aptr, const BP& bptr, int m0, int n0, int K, const Epi& epi, bf16* lds) {
;     ...
;   for (int ks = 0; ks < nk; ++ks) {
;     if (ks + 1 < nk) asm volatile("s_waitcnt vmcnt(8)\n\ts_barrier" ::: "memory");
;     else asm volatile("s_waitcnt vmcnt(0)\n\ts_barrier" ::: "memory");
;     const unsigned sb_ = lbase + (unsigned)((ks & 1) * (2 * 128 * 64) * 2);
;     const unsigned a0 = sb_ + a_row + sw0, a1 = sb_ + a_row + sw1, b0 = sb_ + b_row + sw0, b1 = sb_ + b_row + sw1;
;     bf16x8 af[2][4], bfr[2][4];
;     LDSR(af[0][0], a0, 0); LDSR(af[0][1], a0, 2048); LDSR(af[0][2], a0, 4096); LDSR(af[0][3], a0, 6144);
;     LDSR(bfr[0][0], b0, 0); LDSR(bfr[0][1], b0, 2048); LDSR(bfr[0][2], b0, 4096); LDSR(bfr[0][3], b0, 6144);
;     LDSR(af[1][0], a1, 0); LDSR(af[1][1], a1, 2048); LDSR(af[1][2], a1, 4096); LDSR(af[1][3], a1, 6144);
;     LDSR(bfr[1][0], b1, 0); LDSR(bfr[1][1], b1, 2048); LDSR(bfr[1][2], b1, 4096); LDSR(bfr[1][3], b1, 6144);
;     asm volatile("s_waitcnt lgkmcnt(0)" : "+v"(af[0][0]), "+v"(af[0][1]), "+v"(af[0][2]), "+v"(af[0][3]), "+v"(bfr[0][0]), "+v"(bfr[0][1]), "+v"(bfr[0][2]), "+v"(bfr[0][3]),
;                  "+v"(af[1][0]), "+v"(af[1][1]), "+v"(af[1][2]), "+v"(af[1][3]), "+v"(bfr[1][0]), "+v"(bfr[1][1]), "+v"(bfr[1][2]), "+v"(bfr[1][3]) : : "memory");
;     if (ks + 2 < nk) {
;       asm volatile("s_barrier" ::: "memory");
;       GEMM_STAGE(ks & 1, ks + 2);
;     }
; #pragma unroll
;     for (int kk = 0; kk < 2; ++kk)
; #pragma unroll
;       for (int i = 0; i < 4; ++i)
; #pragma unroll
;         for (int j = 0; j < 4; ++j)
;           acc[i][j] = TRANS ? __builtin_amdgcn_mfma_f32_16x16x32_bf16(af[kk][i], bfr[kk][j], acc[i][j], 0, 0, 0)
;                             : __builtin_amdgcn_mfma_f32_16x16x32_bf16(bfr[kk][j], af[kk][i], acc[i][j], 0, 0, 0);
;   }
	global_load_lds_dwordx4 v[144:145], off
	v_lshl_add_u64 v[144:145], v[100:101], 0, s[2:3]
	s_mov_b32 m0, s26
	s_mov_b64 s[2:3], 0x8200
	global_load_lds_dwordx4 v[144:145], off
	v_lshl_add_u64 v[144:145], v[98:99], 0, s[2:3]
	s_mov_b32 m0, s27
	v_mfma_f32_16x16x32_bf16 v[2:5], v[86:89], v[120:123], v[2:5]
	global_load_lds_dwordx4 v[144:145], off
	v_lshl_add_u64 v[144:145], v[100:101], 0, s[2:3]
	s_mov_b32 m0, s28
	s_mov_b64 s[2:3], 0x10200
	global_load_lds_dwordx4 v[144:145], off
	v_lshl_add_u64 v[144:145], v[98:99], 0, s[2:3]
	s_mov_b32 m0, s29
	v_mfma_f32_16x16x32_bf16 v[6:9], v[86:89], v[124:127], v[6:9]
	global_load_lds_dwordx4 v[144:145], off
	v_lshl_add_u64 v[144:145], v[100:101], 0, s[2:3]
	s_mov_b32 m0, s30
	s_mov_b64 s[2:3], 0x18200
	v_mfma_f32_16x16x32_bf16 v[10:13], v[86:89], v[128:131], v[10:13]
	global_load_lds_dwordx4 v[144:145], off
	v_lshl_add_u64 v[144:145], v[98:99], 0, s[2:3]
	v_mfma_f32_16x16x32_bf16 v[14:17], v[86:89], v[132:135], v[14:17]
	s_mov_b32 m0, s31
	s_nop 0
	global_load_lds_dwordx4 v[144:145], off
	v_mfma_f32_16x16x32_bf16 v[18:21], v[94:97], v[120:123], v[18:21]
	v_lshl_add_u64 v[144:145], v[100:101], 0, s[2:3]
	s_mov_b32 m0, s34
	s_mov_b64 s[2:3], 0x280
	v_mfma_f32_16x16x32_bf16 v[22:25], v[94:97], v[124:127], v[22:25]
	global_load_lds_dwordx4 v[144:145], off
	s_waitcnt vmcnt(8)
	s_barrier
	v_mfma_f32_16x16x32_bf16 v[26:29], v[94:97], v[128:131], v[26:29]
	v_lshl_add_u64 v[144:145], v[98:99], 0, s[2:3]
	s_mov_b32 m0, s24
	v_mfma_f32_16x16x32_bf16 v[34:37], v[94:97], v[132:135], v[34:37]
	v_mfma_f32_16x16x32_bf16 v[62:65], v[112:115], v[120:123], v[62:65]
	v_mfma_f32_16x16x32_bf16 v[66:69], v[112:115], v[124:127], v[66:69]
	v_mfma_f32_16x16x32_bf16 v[74:77], v[112:115], v[128:131], v[74:77]
	v_mfma_f32_16x16x32_bf16 v[70:73], v[112:115], v[132:135], v[70:73]
	v_mfma_f32_16x16x32_bf16 v[86:89], v[116:119], v[120:123], v[90:93]
	v_mfma_f32_16x16x32_bf16 v[78:81], v[116:119], v[124:127], v[78:81]
	v_mfma_f32_16x16x32_bf16 v[82:85], v[116:119], v[128:131], v[82:85]
	v_mfma_f32_16x16x32_bf16 v[90:93], v[116:119], v[132:135], v[38:41]
	v_mfma_f32_16x16x32_bf16 v[2:5], v[136:139], v[42:45], v[2:5]
	v_mfma_f32_16x16x32_bf16 v[6:9], v[136:139], v[46:49], v[6:9]
	v_mfma_f32_16x16x32_bf16 v[10:13], v[136:139], v[50:53], v[10:13]
	v_mfma_f32_16x16x32_bf16 v[14:17], v[136:139], v[54:57], v[14:17]
	v_mfma_f32_16x16x32_bf16 v[18:21], v[140:143], v[42:45], v[18:21]
	v_mfma_f32_16x16x32_bf16 v[22:25], v[140:143], v[46:49], v[22:25]
	v_mfma_f32_16x16x32_bf16 v[26:29], v[140:143], v[50:53], v[26:29]
	v_mfma_f32_16x16x32_bf16 v[38:41], v[140:143], v[54:57], v[34:37]
	v_mfma_f32_16x16x32_bf16 v[62:65], v[58:61], v[42:45], v[62:65]
	v_mfma_f32_16x16x32_bf16 v[66:69], v[58:61], v[46:49], v[66:69]
	v_mfma_f32_16x16x32_bf16 v[74:77], v[58:61], v[50:53], v[74:77]
	v_mfma_f32_16x16x32_bf16 v[94:97], v[58:61], v[54:57], v[70:73]
	v_mfma_f32_16x16x32_bf16 v[86:89], v[30:33], v[42:45], v[86:89]
	v_mfma_f32_16x16x32_bf16 v[78:81], v[30:33], v[46:49], v[78:81]
	v_mfma_f32_16x16x32_bf16 v[82:85], v[30:33], v[50:53], v[82:85]
	v_mfma_f32_16x16x32_bf16 v[54:57], v[30:33], v[54:57], v[90:93]
	ds_read_b128 v[90:93], v110 offset:0
	ds_read_b128 v[112:115], v110 offset:0x800
	ds_read_b128 v[116:119], v110 offset:0x1000
	ds_read_b128 v[120:123], v110 offset:0x1800
	ds_read_b128 v[124:127], v109 offset:0
	ds_read_b128 v[128:131], v109 offset:0x800
	ds_read_b128 v[132:135], v109 offset:0x1000
	ds_read_b128 v[136:139], v109 offset:0x1800
	ds_read_b128 v[140:143], v108 offset:0
	ds_read_b128 v[70:73], v108 offset:0x800
	ds_read_b128 v[34:37], v108 offset:0x1000
	ds_read_b128 v[30:33], v108 offset:0x1800
	ds_read_b128 v[42:45], v107 offset:0
	ds_read_b128 v[46:49], v107 offset:0x800
	ds_read_b128 v[50:53], v107 offset:0x1000
	ds_read_b128 v[58:61], v107 offset:0x1800
	s_nop 0
	s_waitcnt lgkmcnt(0)
	s_barrier
	global_load_lds_dwordx4 v[144:145], off
	v_lshl_add_u64 v[144:145], v[100:101], 0, s[2:3]
	s_mov_b32 m0, s23
	s_mov_b64 s[2:3], 0x8280
	global_load_lds_dwordx4 v[144:145], off
	v_lshl_add_u64 v[144:145], v[98:99], 0, s[2:3]
	s_mov_b32 m0, s22
	v_mfma_f32_16x16x32_bf16 v[2:5], v[90:93], v[124:127], v[2:5]
	global_load_lds_dwordx4 v[144:145], off
	v_lshl_add_u64 v[144:145], v[100:101], 0, s[2:3]
	s_mov_b32 m0, s18
	s_mov_b64 s[2:3], 0x10280
	global_load_lds_dwordx4 v[144:145], off
	v_lshl_add_u64 v[144:145], v[98:99], 0, s[2:3]
	s_mov_b32 m0, s17
	v_mfma_f32_16x16x32_bf16 v[6:9], v[90:93], v[128:131], v[6:9]
	global_load_lds_dwordx4 v[144:145], off
	v_lshl_add_u64 v[144:145], v[100:101], 0, s[2:3]
	s_mov_b32 m0, s19
	s_mov_b64 s[2:3], 0x18280
	v_mfma_f32_16x16x32_bf16 v[10:13], v[90:93], v[132:135], v[10:13]
	global_load_lds_dwordx4 v[144:145], off
	v_lshl_add_u64 v[144:145], v[98:99], 0, s[2:3]
	v_mfma_f32_16x16x32_bf16 v[14:17], v[90:93], v[136:139], v[14:17]
	s_mov_b32 m0, s20
	s_nop 0
	global_load_lds_dwordx4 v[144:145], off
	v_mfma_f32_16x16x32_bf16 v[18:21], v[112:115], v[124:127], v[18:21]
	v_lshl_add_u64 v[144:145], v[100:101], 0, s[2:3]
	s_mov_b32 m0, s21
	s_mov_b64 s[2:3], 0x300
	v_mfma_f32_16x16x32_bf16 v[22:25], v[112:115], v[128:131], v[22:25]
	global_load_lds_dwordx4 v[144:145], off
	s_waitcnt vmcnt(8)
	s_barrier
; #define LDSR(dst, addr, off) asm volatile("ds_read_b128 %0, %1 offset:%2" : "=&v"(dst) : "v"(addr), "n"(off))
; #define LDSR(dst, addr, off) asm volatile("ds_read_b128 %0, %1 offset:%2" : "=&v"(dst) : "v"(addr), "n"(off))
; template <int TRANS, class AP, class BP, class Epi>
; DI void mfma_gemm_tile(const AP& aptr, const BP& bptr, int m0, int n0, int K, const Epi& epi, bf16* lds) {
;     ...
;   for (int ks = 0; ks < nk; ++ks) {
;     if (ks + 1 < nk) asm volatile("s_waitcnt vmcnt(8)\n\ts_barrier" ::: "memory");
;     else asm volatile("s_waitcnt vmcnt(0)\n\ts_barrier" ::: "memory");
;     const unsigned sb_ = lbase + (unsigned)((ks & 1) * (2 * 128 * 64) * 2);
;     const unsigned a0 = sb_ + a_row + sw0, a1 = sb_ + a_row + sw1, b0 = sb_ + b_row + sw0, b1 = sb_ + b_row + sw1;
;     bf16x8 af[2][4], bfr[2][4];
;     LDSR(af[0][0], a0, 0); LDSR(af[0][1], a0, 2048); LDSR(af[0][2], a0, 4096); LDSR(af[0][3], a0, 6144);
;     LDSR(bfr[0][0], b0, 0); LDSR(bfr[0][1], b0, 2048); LDSR(bfr[0][2], b0, 4096); LDSR(bfr[0][3], b0, 6144);
;     LDSR(af[1][0], a1, 0); LDSR(af[1][1], a1, 2048); LDSR(af[1][2], a1, 4096); LDSR(af[1][3], a1, 6144);
;     LDSR(bfr[1][0], b1, 0); LDSR(bfr[1][1], b1, 2048); LDSR(bfr[1][2], b1, 4096); LDSR(bfr[1][3], b1, 6144);
;     asm volatile("s_waitcnt lgkmcnt(0)" : "+v"(af[0][0]), "+v"(af[0][1]), "+v"(af[0][2]), "+v"(af[0][3]), "+v"(bfr[0][0]), "+v"(bfr[0][1]), "+v"(bfr[0][2]), "+v"(bfr[0][3]),
;                  "+v"(af[1][0]), "+v"(af[1][1]), "+v"(af[1][2]), "+v"(af[1][3]), "+v"(bfr[1][0]), "+v"(bfr[1][1]), "+v"(bfr[1][2]), "+v"(bfr[1][3]) : : "memory");
;     if (ks + 2 < nk) {
;       asm volatile("s_barrier" ::: "memory");
;       GEMM_STAGE(ks & 1, ks + 2);
;     }
; #pragma unroll
;     for (int kk = 0; kk < 2; ++kk)
; #pragma unroll
;       for (int i = 0; i < 4; ++i)
; #pragma unroll
;         for (int j = 0; j < 4; ++j)
;           acc[i][j] = TRANS ? __builtin_amdgcn_mfma_f32_16x16x32_bf16(af[kk][i], bfr[kk][j], acc[i][j], 0, 0, 0)
;                             : __builtin_amdgcn_mfma_f32_16x16x32_bf16(bfr[kk][j], af[kk][i], acc[i][j], 0, 0, 0);
;   }
	v_mfma_f32_16x16x32_bf16 v[26:29], v[112:115], v[132:135], v[26:29]
	v_lshl_add_u64 v[144:145], v[98:99], 0, s[2:3]
	s_mov_b32 m0, s25
	v_mfma_f32_16x16x32_bf16 v[38:41], v[112:115], v[136:139], v[38:41]
	v_mfma_f32_16x16x32_bf16 v[62:65], v[116:119], v[124:127], v[62:65]
	v_mfma_f32_16x16x32_bf16 v[90:93], v[116:119], v[128:131], v[66:69]
	v_mfma_f32_16x16x32_bf16 v[112:115], v[116:119], v[132:135], v[74:77]
	v_mfma_f32_16x16x32_bf16 v[94:97], v[116:119], v[136:139], v[94:97]
	v_mfma_f32_16x16x32_bf16 v[116:119], v[120:123], v[124:127], v[86:89]
	v_mfma_f32_16x16x32_bf16 v[78:81], v[120:123], v[128:131], v[78:81]
	v_mfma_f32_16x16x32_bf16 v[124:127], v[120:123], v[132:135], v[82:85]
	v_mfma_f32_16x16x32_bf16 v[120:123], v[120:123], v[136:139], v[54:57]
	v_mfma_f32_16x16x32_bf16 v[2:5], v[140:143], v[42:45], v[2:5]
	v_mfma_f32_16x16x32_bf16 v[6:9], v[140:143], v[46:49], v[6:9]
	v_mfma_f32_16x16x32_bf16 v[10:13], v[140:143], v[50:53], v[10:13]
	v_mfma_f32_16x16x32_bf16 v[14:17], v[140:143], v[58:61], v[14:17]
	v_mfma_f32_16x16x32_bf16 v[18:21], v[70:73], v[42:45], v[18:21]
	v_mfma_f32_16x16x32_bf16 v[22:25], v[70:73], v[46:49], v[22:25]
	v_mfma_f32_16x16x32_bf16 v[54:57], v[70:73], v[50:53], v[26:29]
	v_mfma_f32_16x16x32_bf16 v[66:69], v[70:73], v[58:61], v[38:41]
	v_mfma_f32_16x16x32_bf16 v[74:77], v[34:37], v[42:45], v[62:65]
	v_mfma_f32_16x16x32_bf16 v[82:85], v[34:37], v[46:49], v[90:93]
	v_mfma_f32_16x16x32_bf16 v[86:89], v[34:37], v[50:53], v[112:115]
	ds_read_b128 v[112:115], v106 offset:0
	v_mfma_f32_16x16x32_bf16 v[90:93], v[34:37], v[58:61], v[94:97]
	v_mfma_f32_16x16x32_bf16 v[94:97], v[30:33], v[42:45], v[116:119]
	ds_read_b128 v[116:119], v106 offset:0x800
	v_mfma_f32_16x16x32_bf16 v[78:81], v[30:33], v[46:49], v[78:81]
	v_mfma_f32_16x16x32_bf16 v[70:73], v[30:33], v[50:53], v[124:127]
	v_mfma_f32_16x16x32_bf16 v[58:61], v[30:33], v[58:61], v[120:123]
	ds_read_b128 v[120:123], v106 offset:0x1000
	ds_read_b128 v[124:127], v106 offset:0x1800
	ds_read_b128 v[128:131], v105 offset:0
	ds_read_b128 v[132:135], v105 offset:0x800
	ds_read_b128 v[136:139], v105 offset:0x1000
	ds_read_b128 v[140:143], v105 offset:0x1800
	ds_read_b128 v[62:65], v104 offset:0
	ds_read_b128 v[30:33], v104 offset:0x800
	ds_read_b128 v[34:37], v104 offset:0x1000
	ds_read_b128 v[26:29], v104 offset:0x1800
	ds_read_b128 v[38:41], v103 offset:0
	ds_read_b128 v[42:45], v103 offset:0x800
	ds_read_b128 v[46:49], v103 offset:0x1000
	ds_read_b128 v[50:53], v103 offset:0x1800
	s_nop 0
	s_waitcnt lgkmcnt(0)
	s_barrier
	global_load_lds_dwordx4 v[144:145], off
	v_lshl_add_u64 v[144:145], v[100:101], 0, s[2:3]
	s_mov_b32 m0, s26
	s_mov_b64 s[2:3], 0x8300
	global_load_lds_dwordx4 v[144:145], off
	v_lshl_add_u64 v[144:145], v[98:99], 0, s[2:3]
	s_mov_b32 m0, s27
	v_mfma_f32_16x16x32_bf16 v[2:5], v[112:115], v[128:131], v[2:5]
	global_load_lds_dwordx4 v[144:145], off
	v_lshl_add_u64 v[144:145], v[100:101], 0, s[2:3]
	s_mov_b32 m0, s28
	s_mov_b64 s[2:3], 0x10300
	global_load_lds_dwordx4 v[144:145], off
	v_lshl_add_u64 v[144:145], v[98:99], 0, s[2:3]
	s_mov_b32 m0, s29
	v_mfma_f32_16x16x32_bf16 v[6:9], v[112:115], v[132:135], v[6:9]
	global_load_lds_dwordx4 v[144:145], off
	v_lshl_add_u64 v[144:145], v[100:101], 0, s[2:3]
	s_mov_b32 m0, s30
	s_mov_b64 s[2:3], 0x18300
	v_mfma_f32_16x16x32_bf16 v[10:13], v[112:115], v[136:139], v[10:13]
	global_load_lds_dwordx4 v[144:145], off
	v_lshl_add_u64 v[144:145], v[98:99], 0, s[2:3]
	v_mfma_f32_16x16x32_bf16 v[14:17], v[112:115], v[140:143], v[14:17]
	s_mov_b32 m0, s31
	s_nop 0
	global_load_lds_dwordx4 v[144:145], off
	v_mfma_f32_16x16x32_bf16 v[18:21], v[116:119], v[128:131], v[18:21]
	v_lshl_add_u64 v[144:145], v[100:101], 0, s[2:3]
	s_mov_b32 m0, s34
	s_mov_b64 s[2:3], 0x380
	v_mfma_f32_16x16x32_bf16 v[22:25], v[116:119], v[132:135], v[22:25]
	global_load_lds_dwordx4 v[144:145], off
	s_waitcnt vmcnt(8)
	s_barrier
	v_mfma_f32_16x16x32_bf16 v[54:57], v[116:119], v[136:139], v[54:57]
	v_lshl_add_u64 v[144:145], v[98:99], 0, s[2:3]
	s_mov_b32 m0, s24
	v_readlane_b32 s34, v254, 25
	v_mfma_f32_16x16x32_bf16 v[66:69], v[116:119], v[140:143], v[66:69]
	v_readlane_b32 s35, v254, 26
	v_mfma_f32_16x16x32_bf16 v[74:77], v[120:123], v[128:131], v[74:77]
	v_mfma_f32_16x16x32_bf16 v[82:85], v[120:123], v[132:135], v[82:85]
	v_mfma_f32_16x16x32_bf16 v[86:89], v[120:123], v[136:139], v[86:89]
	v_mfma_f32_16x16x32_bf16 v[90:93], v[120:123], v[140:143], v[90:93]
	v_mfma_f32_16x16x32_bf16 v[94:97], v[124:127], v[128:131], v[94:97]
	v_mfma_f32_16x16x32_bf16 v[78:81], v[124:127], v[132:135], v[78:81]
	v_mfma_f32_16x16x32_bf16 v[70:73], v[124:127], v[136:139], v[70:73]
	v_mfma_f32_16x16x32_bf16 v[112:115], v[124:127], v[140:143], v[58:61]
	v_mfma_f32_16x16x32_bf16 v[2:5], v[62:65], v[38:41], v[2:5]
	v_mfma_f32_16x16x32_bf16 v[6:9], v[62:65], v[42:45], v[6:9]
	v_mfma_f32_16x16x32_bf16 v[10:13], v[62:65], v[46:49], v[10:13]
	v_mfma_f32_16x16x32_bf16 v[14:17], v[62:65], v[50:53], v[14:17]
	v_mfma_f32_16x16x32_bf16 v[18:21], v[30:33], v[38:41], v[18:21]
	v_mfma_f32_16x16x32_bf16 v[22:25], v[30:33], v[42:45], v[22:25]
	v_mfma_f32_16x16x32_bf16 v[54:57], v[30:33], v[46:49], v[54:57]
	v_mfma_f32_16x16x32_bf16 v[30:33], v[30:33], v[50:53], v[66:69]
	v_mfma_f32_16x16x32_bf16 v[58:61], v[34:37], v[38:41], v[74:77]
	v_mfma_f32_16x16x32_bf16 v[62:65], v[34:37], v[42:45], v[82:85]
	v_mfma_f32_16x16x32_bf16 v[66:69], v[34:37], v[46:49], v[86:89]
	v_mfma_f32_16x16x32_bf16 v[34:37], v[34:37], v[50:53], v[90:93]
	v_mfma_f32_16x16x32_bf16 v[38:41], v[26:29], v[38:41], v[94:97]
	v_mfma_f32_16x16x32_bf16 v[42:45], v[26:29], v[42:45], v[78:81]
	v_mfma_f32_16x16x32_bf16 v[46:49], v[26:29], v[46:49], v[70:73]
	v_mfma_f32_16x16x32_bf16 v[26:29], v[26:29], v[50:53], v[112:115]
	ds_read_b128 v[50:53], v110 offset:0
	ds_read_b128 v[70:73], v110 offset:0x800
	ds_read_b128 v[74:77], v110 offset:0x1000
	ds_read_b128 v[78:81], v110 offset:0x1800
	ds_read_b128 v[82:85], v109 offset:0
	ds_read_b128 v[86:89], v109 offset:0x800
	ds_read_b128 v[90:93], v109 offset:0x1000
	ds_read_b128 v[94:97], v109 offset:0x1800
	ds_read_b128 v[112:115], v108 offset:0
	ds_read_b128 v[116:119], v108 offset:0x800
	ds_read_b128 v[120:123], v108 offset:0x1000
	ds_read_b128 v[124:127], v108 offset:0x1800
	ds_read_b128 v[128:131], v107 offset:0
	ds_read_b128 v[132:135], v107 offset:0x800
	ds_read_b128 v[136:139], v107 offset:0x1000
	ds_read_b128 v[140:143], v107 offset:0x1800
	s_nop 0
	s_waitcnt lgkmcnt(0)
	s_barrier
; #define LDSR(dst, addr, off) asm volatile("ds_read_b128 %0, %1 offset:%2" : "=&v"(dst) : "v"(addr), "n"(off))
; #define LDSR(dst, addr, off) asm volatile("ds_read_b128 %0, %1 offset:%2" : "=&v"(dst) : "v"(addr), "n"(off))
; template <int TRANS, class AP, class BP, class Epi>
; DI void mfma_gemm_tile(const AP& aptr, const BP& bptr, int m0, int n0, int K, const Epi& epi, bf16* lds) {
;     ...
;   for (int ks = 0; ks < nk; ++ks) {
;     if (ks + 1 < nk) asm volatile("s_waitcnt vmcnt(8)\n\ts_barrier" ::: "memory");
;     else asm volatile("s_waitcnt vmcnt(0)\n\ts_barrier" ::: "memory");
;     const unsigned sb_ = lbase + (unsigned)((ks & 1) * (2 * 128 * 64) * 2);
;     const unsigned a0 = sb_ + a_row + sw0, a1 = sb_ + a_row + sw1, b0 = sb_ + b_row + sw0, b1 = sb_ + b_row + sw1;
;     bf16x8 af[2][4], bfr[2][4];
;     LDSR(af[0][0], a0, 0); LDSR(af[0][1], a0, 2048); LDSR(af[0][2], a0, 4096); LDSR(af[0][3], a0, 6144);
;     LDSR(bfr[0][0], b0, 0); LDSR(bfr[0][1], b0, 2048); LDSR(bfr[0][2], b0, 4096); LDSR(bfr[0][3], b0, 6144);
;     LDSR(af[1][0], a1, 0); LDSR(af[1][1], a1, 2048); LDSR(af[1][2], a1, 4096); LDSR(af[1][3], a1, 6144);
;     LDSR(bfr[1][0], b1, 0); LDSR(bfr[1][1], b1, 2048); LDSR(bfr[1][2], b1, 4096); LDSR(bfr[1][3], b1, 6144);
;     asm volatile("s_waitcnt lgkmcnt(0)" : "+v"(af[0][0]), "+v"(af[0][1]), "+v"(af[0][2]), "+v"(af[0][3]), "+v"(bfr[0][0]), "+v"(bfr[0][1]), "+v"(bfr[0][2]), "+v"(bfr[0][3]),
;                  "+v"(af[1][0]), "+v"(af[1][1]), "+v"(af[1][2]), "+v"(af[1][3]), "+v"(bfr[1][0]), "+v"(bfr[1][1]), "+v"(bfr[1][2]), "+v"(bfr[1][3]) : : "memory");
;     if (ks + 2 < nk) {
;       asm volatile("s_barrier" ::: "memory");
;       GEMM_STAGE(ks & 1, ks + 2);
;     }
; #pragma unroll
;     for (int kk = 0; kk < 2; ++kk)
; #pragma unroll
;       for (int i = 0; i < 4; ++i)
; #pragma unroll
;         for (int j = 0; j < 4; ++j)
;           acc[i][j] = TRANS ? __builtin_amdgcn_mfma_f32_16x16x32_bf16(af[kk][i], bfr[kk][j], acc[i][j], 0, 0, 0)
;                             : __builtin_amdgcn_mfma_f32_16x16x32_bf16(bfr[kk][j], af[kk][i], acc[i][j], 0, 0, 0);
;   }
	global_load_lds_dwordx4 v[144:145], off
	v_lshl_add_u64 v[144:145], v[100:101], 0, s[2:3]
	s_mov_b32 m0, s23
	s_mov_b64 s[2:3], 0x8380
	global_load_lds_dwordx4 v[144:145], off
	v_lshl_add_u64 v[144:145], v[98:99], 0, s[2:3]
	s_mov_b32 m0, s22
	v_mfma_f32_16x16x32_bf16 v[2:5], v[50:53], v[82:85], v[2:5]
	global_load_lds_dwordx4 v[144:145], off
	v_lshl_add_u64 v[144:145], v[100:101], 0, s[2:3]
	v_mfma_f32_16x16x32_bf16 v[6:9], v[50:53], v[86:89], v[6:9]
	s_mov_b32 m0, s18
	s_mov_b64 s[2:3], 0x10380
	global_load_lds_dwordx4 v[144:145], off
	v_mfma_f32_16x16x32_bf16 v[10:13], v[50:53], v[90:93], v[10:13]
	v_lshl_add_u64 v[144:145], v[98:99], 0, s[2:3]
	s_mov_b32 m0, s17
	v_mfma_f32_16x16x32_bf16 v[14:17], v[50:53], v[94:97], v[14:17]
	global_load_lds_dwordx4 v[144:145], off
	v_lshl_add_u64 v[144:145], v[100:101], 0, s[2:3]
	v_mfma_f32_16x16x32_bf16 v[50:53], v[70:73], v[90:93], v[54:57]
	s_mov_b32 m0, s19
	s_mov_b64 s[2:3], 0x18380
	global_load_lds_dwordx4 v[144:145], off
	v_mfma_f32_16x16x32_bf16 v[54:57], v[74:77], v[82:85], v[58:61]
	v_lshl_add_u64 v[98:99], v[98:99], 0, s[2:3]
	s_mov_b32 m0, s20
	v_mfma_f32_16x16x32_bf16 v[58:61], v[74:77], v[86:89], v[62:65]
	global_load_lds_dwordx4 v[98:99], off
	v_lshl_add_u64 v[98:99], v[100:101], 0, s[2:3]
	v_mfma_f32_16x16x32_bf16 v[18:21], v[70:73], v[82:85], v[18:21]
	s_mov_b32 m0, s21
	s_mov_b32 s2, 0x3bb504f3
	global_load_lds_dwordx4 v[98:99], off
	v_mfma_f32_16x16x32_bf16 v[22:25], v[70:73], v[86:89], v[22:25]
	s_waitcnt vmcnt(8)
	s_barrier
	v_mfma_f32_16x16x32_bf16 v[30:33], v[70:73], v[94:97], v[30:33]
	v_mfma_f32_16x16x32_bf16 v[62:65], v[74:77], v[90:93], v[66:69]
	ds_read_b128 v[66:69], v106 offset:0
	ds_read_b128 v[70:73], v106 offset:0x800
	v_mfma_f32_16x16x32_bf16 v[38:41], v[78:81], v[82:85], v[38:41]
	v_mfma_f32_16x16x32_bf16 v[42:45], v[78:81], v[86:89], v[42:45]
	v_mfma_f32_16x16x32_bf16 v[46:49], v[78:81], v[90:93], v[46:49]
	v_mfma_f32_16x16x32_bf16 v[26:29], v[78:81], v[94:97], v[26:29]
	v_mfma_f32_16x16x32_bf16 v[34:37], v[74:77], v[94:97], v[34:37]
	ds_read_b128 v[74:77], v106 offset:0x1000
	ds_read_b128 v[78:81], v106 offset:0x1800
	ds_read_b128 v[82:85], v105 offset:0
	v_mfma_f32_16x16x32_bf16 v[58:61], v[120:123], v[132:135], v[58:61]
	ds_read_b128 v[86:89], v105 offset:0x800
	ds_read_b128 v[90:93], v105 offset:0x1000
	ds_read_b128 v[94:97], v105 offset:0x1800
	v_mfma_f32_16x16x32_bf16 v[2:5], v[112:115], v[128:131], v[2:5]
	ds_read_b128 v[98:101], v104 offset:0
	v_mfma_f32_16x16x32_bf16 v[6:9], v[112:115], v[132:135], v[6:9]
	v_mfma_f32_16x16x32_bf16 v[10:13], v[112:115], v[136:139], v[10:13]
	v_mfma_f32_16x16x32_bf16 v[14:17], v[112:115], v[140:143], v[14:17]
	ds_read_b128 v[112:115], v104 offset:0x800
	v_mfma_f32_16x16x32_bf16 v[18:21], v[116:119], v[128:131], v[18:21]
	v_mfma_f32_16x16x32_bf16 v[22:25], v[116:119], v[132:135], v[22:25]
	v_mfma_f32_16x16x32_bf16 v[50:53], v[116:119], v[136:139], v[50:53]
	v_mfma_f32_16x16x32_bf16 v[30:33], v[116:119], v[140:143], v[30:33]
	ds_read_b128 v[116:119], v104 offset:0x1000
	v_mfma_f32_16x16x32_bf16 v[54:57], v[120:123], v[128:131], v[54:57]
	v_mfma_f32_16x16x32_bf16 v[62:65], v[120:123], v[136:139], v[62:65]
	v_mfma_f32_16x16x32_bf16 v[38:41], v[124:127], v[128:131], v[38:41]
	v_mfma_f32_16x16x32_bf16 v[42:45], v[124:127], v[132:135], v[42:45]
	v_mfma_f32_16x16x32_bf16 v[46:49], v[124:127], v[136:139], v[46:49]
	v_mfma_f32_16x16x32_bf16 v[26:29], v[124:127], v[140:143], v[26:29]
	v_mfma_f32_16x16x32_bf16 v[34:37], v[120:123], v[140:143], v[34:37]
	ds_read_b128 v[120:123], v104 offset:0x1800
	ds_read_b128 v[124:127], v103 offset:0
	ds_read_b128 v[128:131], v103 offset:0x800
	ds_read_b128 v[132:135], v103 offset:0x1000
	ds_read_b128 v[136:139], v103 offset:0x1800
	s_nop 0
	s_waitcnt lgkmcnt(0)
	s_waitcnt vmcnt(0)
	s_barrier
	s_nop 0
	v_mfma_f32_16x16x32_bf16 v[58:61], v[74:77], v[86:89], v[58:61]
	v_mfma_f32_16x16x32_bf16 v[2:5], v[66:69], v[82:85], v[2:5]
	v_mfma_f32_16x16x32_bf16 v[6:9], v[66:69], v[86:89], v[6:9]
	v_mfma_f32_16x16x32_bf16 v[10:13], v[66:69], v[90:93], v[10:13]
	v_mfma_f32_16x16x32_bf16 v[14:17], v[66:69], v[94:97], v[14:17]
	ds_read_b128 v[66:69], v110 offset:0
	v_mfma_f32_16x16x32_bf16 v[18:21], v[70:73], v[82:85], v[18:21]
	v_mfma_f32_16x16x32_bf16 v[22:25], v[70:73], v[86:89], v[22:25]
	v_mfma_f32_16x16x32_bf16 v[50:53], v[70:73], v[90:93], v[50:53]
	v_mfma_f32_16x16x32_bf16 v[30:33], v[70:73], v[94:97], v[30:33]
	ds_read_b128 v[70:73], v110 offset:0x800
	v_mfma_f32_16x16x32_bf16 v[54:57], v[74:77], v[82:85], v[54:57]
	v_mfma_f32_16x16x32_bf16 v[62:65], v[74:77], v[90:93], v[62:65]
	v_mfma_f32_16x16x32_bf16 v[38:41], v[78:81], v[82:85], v[38:41]
	v_mfma_f32_16x16x32_bf16 v[42:45], v[78:81], v[86:89], v[42:45]
	v_mfma_f32_16x16x32_bf16 v[46:49], v[78:81], v[90:93], v[46:49]
	v_mfma_f32_16x16x32_bf16 v[26:29], v[78:81], v[94:97], v[26:29]
	v_mfma_f32_16x16x32_bf16 v[34:37], v[74:77], v[94:97], v[34:37]
	ds_read_b128 v[74:77], v110 offset:0x1000
	ds_read_b128 v[78:81], v110 offset:0x1800
	ds_read_b128 v[82:85], v109 offset:0
	v_mfma_f32_16x16x32_bf16 v[58:61], v[116:119], v[128:131], v[58:61]
	ds_read_b128 v[86:89], v109 offset:0x800
	ds_read_b128 v[90:93], v109 offset:0x1000
	ds_read_b128 v[94:97], v109 offset:0x1800
	v_mfma_f32_16x16x32_bf16 v[2:5], v[98:101], v[124:127], v[2:5]
	v_mfma_f32_16x16x32_bf16 v[6:9], v[98:101], v[128:131], v[6:9]
	v_mfma_f32_16x16x32_bf16 v[10:13], v[98:101], v[132:135], v[10:13]
	v_mfma_f32_16x16x32_bf16 v[14:17], v[98:101], v[136:139], v[14:17]
	ds_read_b128 v[98:101], v108 offset:0
	v_mfma_f32_16x16x32_bf16 v[18:21], v[112:115], v[124:127], v[18:21]
	v_mfma_f32_16x16x32_bf16 v[22:25], v[112:115], v[128:131], v[22:25]
	v_mfma_f32_16x16x32_bf16 v[50:53], v[112:115], v[132:135], v[50:53]
	v_mfma_f32_16x16x32_bf16 v[30:33], v[112:115], v[136:139], v[30:33]
	ds_read_b128 v[110:113], v108 offset:0x800
	v_mfma_f32_16x16x32_bf16 v[54:57], v[116:119], v[124:127], v[54:57]
	v_mfma_f32_16x16x32_bf16 v[62:65], v[116:119], v[132:135], v[62:65]
	v_mfma_f32_16x16x32_bf16 v[38:41], v[120:123], v[124:127], v[38:41]
	v_mfma_f32_16x16x32_bf16 v[42:45], v[120:123], v[128:131], v[42:45]
	v_mfma_f32_16x16x32_bf16 v[46:49], v[120:123], v[132:135], v[46:49]
	v_mfma_f32_16x16x32_bf16 v[26:29], v[120:123], v[136:139], v[26:29]
	v_mfma_f32_16x16x32_bf16 v[34:37], v[116:119], v[136:139], v[34:37]
	ds_read_b128 v[114:117], v108 offset:0x1000
	ds_read_b128 v[118:121], v108 offset:0x1800
	ds_read_b128 v[122:125], v107 offset:0
	ds_read_b128 v[126:129], v107 offset:0x800
	ds_read_b128 v[130:133], v107 offset:0x1000
	ds_read_b128 v[134:137], v107 offset:0x1800
	s_nop 0
	s_waitcnt lgkmcnt(0)
; template <int TRANS, class AP, class BP, class Epi>
; DI void mfma_gemm_tile(const AP& aptr, const BP& bptr, int m0, int n0, int K, const Epi& epi, bf16* lds) {
;     ...
; #pragma unroll
;   for (int i = 0; i < 4; ++i)
; #pragma unroll
;     for (int j = 0; j < 4; ++j) {
;       if (TRANS) epi(m0 + wm + 16 * i + 4 * lq, n0 + wn + 16 * j + l16, acc[i][j]);
;       else epi(m0 + wm + 16 * i + l16, n0 + wn + 16 * j + 4 * lq, acc[i][j]);
;     }
	s_nop 0
	v_mfma_f32_16x16x32_bf16 v[58:61], v[74:77], v[86:89], v[58:61]
	v_mfma_f32_16x16x32_bf16 v[2:5], v[66:69], v[82:85], v[2:5]
	v_mfma_f32_16x16x32_bf16 v[6:9], v[66:69], v[86:89], v[6:9]
	v_mfma_f32_16x16x32_bf16 v[10:13], v[66:69], v[90:93], v[10:13]
	v_mfma_f32_16x16x32_bf16 v[14:17], v[66:69], v[94:97], v[14:17]
	v_mfma_f32_16x16x32_bf16 v[18:21], v[70:73], v[82:85], v[18:21]
	v_mfma_f32_16x16x32_bf16 v[22:25], v[70:73], v[86:89], v[22:25]
	v_mfma_f32_16x16x32_bf16 v[66:69], v[70:73], v[90:93], v[50:53]
	v_mfma_f32_16x16x32_bf16 v[30:33], v[70:73], v[94:97], v[30:33]
	v_mfma_f32_16x16x32_bf16 v[70:73], v[74:77], v[82:85], v[54:57]
	v_mfma_f32_16x16x32_bf16 v[62:65], v[74:77], v[90:93], v[62:65]
	v_mfma_f32_16x16x32_bf16 v[82:85], v[78:81], v[82:85], v[38:41]
	v_mfma_f32_16x16x32_bf16 v[86:89], v[78:81], v[86:89], v[42:45]
	v_mfma_f32_16x16x32_bf16 v[90:93], v[78:81], v[90:93], v[46:49]
	v_mfma_f32_16x16x32_bf16 v[78:81], v[78:81], v[94:97], v[26:29]
	v_mfma_f32_16x16x32_bf16 v[26:29], v[114:117], v[126:129], v[58:61]
	s_nop 2
	v_or_b32_e32 v58, s1, v102
	s_ashr_i32 s1, s16, 1
	s_and_b32 s1, s1, 0xffffff00
	v_mfma_f32_16x16x32_bf16 v[74:77], v[74:77], v[94:97], v[34:37]
	s_nop 0
	v_mul_f32_e64 v26, v26, s2
	v_mul_f32_e64 v27, v27, s2
	v_pk_mul_f32 v[28:29], v[28:29], s[2:3] op_sel_hi:[1,0]
	v_mfma_f32_16x16x32_bf16 v[94:97], v[98:101], v[122:125], v[2:5]
	v_mfma_f32_16x16x32_bf16 v[2:5], v[118:121], v[134:137], v[78:81]
	s_nop 2
	v_or_b32_e32 v80, s1, v58
	v_mfma_f32_16x16x32_bf16 v[34:37], v[110:113], v[134:137], v[30:33]
	v_add_u32_e32 v58, 0x4000, v80
	v_ashrrev_i32_e32 v59, 31, v58
	s_nop 0
	v_pk_mul_f32 v[2:3], v[2:3], s[2:3] op_sel_hi:[1,0]
	v_mfma_f32_16x16x32_bf16 v[30:33], v[114:117], v[122:125], v[70:73]
	v_mul_f32_e64 v4, v4, s2
	v_mul_f32_e64 v5, v5, s2
	s_nop 0
	v_pk_mul_f32 v[34:35], v[34:35], s[2:3] op_sel_hi:[1,0]
	v_pk_mul_f32 v[36:37], v[36:37], s[2:3] op_sel_hi:[1,0]
	v_mov_b64_e32 v[70:71], s[62:63]
	v_mad_i64_i32 v[60:61], s[0:1], v58, s78, v[70:71]
	v_mfma_f32_16x16x32_bf16 v[42:45], v[110:113], v[126:129], v[22:25]
	v_mul_f32_e64 v72, v94, s2
	v_mul_f32_e64 v73, v95, s2
	v_pk_mul_f32 v[30:31], v[30:31], s[2:3] op_sel_hi:[1,0]
	v_pk_mul_f32 v[32:33], v[32:33], s[2:3] op_sel_hi:[1,0]
	v_mfma_f32_16x16x32_bf16 v[22:25], v[114:117], v[130:133], v[62:65]
	s_nop 2
	v_lshl_add_u64 v[62:63], v[60:61], 0, v[0:1]
	global_load_dwordx2 v[60:61], v[62:63], off offset:1024
	v_mfma_f32_16x16x32_bf16 v[38:41], v[110:113], v[130:133], v[66:69]
	v_mul_f32_e64 v42, v42, s2
	v_mul_f32_e64 v43, v43, s2
	v_pk_mul_f32 v[44:45], v[44:45], s[2:3] op_sel_hi:[1,0]
	v_pk_mul_f32 v[22:23], v[22:23], s[2:3] op_sel_hi:[1,0]
	v_lshl_add_u64 v[68:69], s[60:61], 0, v[0:1]
	v_mfma_f32_16x16x32_bf16 v[46:49], v[110:113], v[122:125], v[18:21]
	s_nop 1
	v_mul_f32_e64 v38, v38, s2
	v_mul_f32_e64 v39, v39, s2
	v_pk_mul_f32 v[40:41], v[40:41], s[2:3] op_sel_hi:[1,0]
	v_pk_mul_f32 v[24:25], v[24:25], s[2:3] op_sel_hi:[1,0]
	v_mfma_f32_16x16x32_bf16 v[18:21], v[114:117], v[134:137], v[74:77]
	s_waitcnt vmcnt(0)
	v_lshlrev_b32_e32 v64, 16, v60
	v_and_b32_e32 v65, 0xffff0000, v60
	v_mul_f32_e32 v60, 0xbfb8aa3b, v64
	v_exp_f32_e32 v60, v60
	v_mfma_f32_16x16x32_bf16 v[104:107], v[98:101], v[126:129], v[6:9]
	v_mul_f32_e64 v46, v46, s2
	v_mul_f32_e64 v47, v47, s2
	v_pk_mul_f32 v[48:49], v[48:49], s[2:3] op_sel_hi:[1,0]
	v_add_f32_e32 v60, 1.0, v60
	v_rcp_f32_e32 v66, v60
	v_mul_f32_e32 v60, 0xbfb8aa3b, v65
	v_exp_f32_e32 v60, v60
	s_nop 0
	v_pk_mul_f32 v[76:77], v[104:105], s[2:3] op_sel_hi:[1,0]
	v_mfma_f32_16x16x32_bf16 v[54:57], v[98:101], v[130:133], v[10:13]
	v_mul_f32_e64 v18, v18, s2
	v_mul_f32_e64 v19, v19, s2
	v_add_f32_e32 v60, 1.0, v60
	v_rcp_f32_e32 v67, v60
	v_mfma_f32_16x16x32_bf16 v[50:53], v[98:101], v[134:137], v[14:17]
	v_mul_f32_e64 v20, v20, s2
	v_mul_f32_e64 v21, v21, s2
	s_nop 0
	v_pk_mul_f32 v[54:55], v[54:55], s[2:3] op_sel_hi:[1,0]
	v_pk_mul_f32 v[64:65], v[66:67], v[64:65]
	v_pk_mul_f32 v[56:57], v[56:57], s[2:3] op_sel_hi:[1,0]
	v_pk_mul_f32 v[64:65], v[72:73], v[64:65]
	v_pk_mul_f32 v[72:73], v[96:97], s[2:3] op_sel_hi:[1,0]
	v_cvt_pk_bf16_f32 v60, v64, v65
	v_lshlrev_b32_e32 v64, 16, v61
	v_and_b32_e32 v65, 0xffff0000, v61
	v_mul_f32_e32 v61, 0xbfb8aa3b, v64
	v_exp_f32_e32 v61, v61
	v_pk_mul_f32 v[50:51], v[50:51], s[2:3] op_sel_hi:[1,0]
	v_pk_mul_f32 v[52:53], v[52:53], s[2:3] op_sel_hi:[1,0]
	v_mfma_f32_16x16x32_bf16 v[14:17], v[118:121], v[122:125], v[82:85]
	v_add_f32_e32 v61, 1.0, v61
	v_rcp_f32_e32 v66, v61
	v_mul_f32_e32 v61, 0xbfb8aa3b, v65
	v_exp_f32_e32 v61, v61
	v_mfma_f32_16x16x32_bf16 v[10:13], v[118:121], v[126:129], v[86:89]
	s_nop 2
	v_mul_f32_e64 v14, v14, s2
	v_mul_f32_e64 v15, v15, s2
	v_pk_mul_f32 v[16:17], v[16:17], s[2:3] op_sel_hi:[1,0]
	v_add_f32_e32 v61, 1.0, v61
	v_rcp_f32_e32 v67, v61
	v_mfma_f32_16x16x32_bf16 v[6:9], v[118:121], v[130:133], v[90:93]
	v_mul_f32_e64 v10, v10, s2
	v_mul_f32_e64 v11, v11, s2
	v_pk_mul_f32 v[12:13], v[12:13], s[2:3] op_sel_hi:[1,0]
	v_pk_mul_f32 v[64:65], v[66:67], v[64:65]
	s_nop 0
	v_pk_mul_f32 v[64:65], v[72:73], v[64:65]
	s_nop 1
	v_pk_mul_f32 v[6:7], v[6:7], s[2:3] op_sel_hi:[1,0]
	v_cvt_pk_bf16_f32 v61, v64, v65
	v_lshlrev_b64 v[64:65], 11, v[58:59]
	v_lshl_add_u64 v[58:59], v[68:69], 0, v[64:65]
	v_readlane_b32 s16, v254, 31
	v_readlane_b32 s17, v254, 32
	v_subrev_u32_e32 v146, s16, v58
	v_and_b32_e32 v147, 0x7c0, v146
	v_and_b32_e32 v148, 0xfffff7ff, v146
	v_add_u32_e32 v148, v148, v147
	v_bfe_u32 v147, v146, 11, 1
	v_lshl_or_b32 v148, v147, 6, v148
	v_bfe_i32 v147, v146, 25, 1
	v_bfi_b32 v148, v147, v146, v148
	global_store_dwordx2 v148, v[60:61], s[16:17]
	v_add_u32_e32 v58, 0x4010, v80
	v_mad_i64_i32 v[60:61], s[0:1], v58, s78, v[70:71]
	v_lshl_add_u64 v[60:61], v[60:61], 0, v[0:1]
	global_load_dwordx2 v[66:67], v[60:61], off offset:1024
	v_ashrrev_i32_e32 v59, 31, v58
	v_pk_mul_f32 v[8:9], v[8:9], s[2:3] op_sel_hi:[1,0]
	s_waitcnt vmcnt(0)
	v_lshlrev_b32_e32 v72, 16, v66
	v_and_b32_e32 v73, 0xffff0000, v66
	v_mul_f32_e32 v66, 0xbfb8aa3b, v72
	v_exp_f32_e32 v66, v66
	s_nop 0
	v_add_f32_e32 v66, 1.0, v66
	v_rcp_f32_e32 v74, v66
	v_mul_f32_e32 v66, 0xbfb8aa3b, v73
	v_exp_f32_e32 v66, v66
	s_nop 0
	v_add_f32_e32 v66, 1.0, v66
	v_rcp_f32_e32 v75, v66
	v_lshlrev_b32_e32 v66, 16, v67
	v_and_b32_e32 v67, 0xffff0000, v67
	v_pk_mul_f32 v[72:73], v[74:75], v[72:73]
	s_nop 0
	v_pk_mul_f32 v[72:73], v[76:77], v[72:73]
	v_pk_mul_f32 v[76:77], v[106:107], s[2:3] op_sel_hi:[1,0]
	v_cvt_pk_bf16_f32 v72, v72, v73
	v_mul_f32_e32 v73, 0xbfb8aa3b, v66
	v_exp_f32_e32 v73, v73
	s_nop 0
	v_add_f32_e32 v73, 1.0, v73
	v_rcp_f32_e32 v74, v73
	v_mul_f32_e32 v73, 0xbfb8aa3b, v67
	v_exp_f32_e32 v73, v73
	s_nop 0
	v_add_f32_e32 v73, 1.0, v73
	v_rcp_f32_e32 v75, v73
	s_nop 0
	v_pk_mul_f32 v[66:67], v[74:75], v[66:67]
	s_nop 0
	v_pk_mul_f32 v[66:67], v[76:77], v[66:67]
	s_nop 0
	v_cvt_pk_bf16_f32 v73, v66, v67
	v_lshlrev_b64 v[66:67], 11, v[58:59]
	v_lshl_add_u64 v[58:59], v[68:69], 0, v[66:67]
	v_readlane_b32 s2, v254, 31
	v_readlane_b32 s3, v254, 32
	v_subrev_u32_e32 v146, s2, v58
	v_and_b32_e32 v147, 0x7c0, v146
	v_and_b32_e32 v148, 0xfffff7ff, v146
	v_add_u32_e32 v148, v148, v147
	v_bfe_u32 v147, v146, 11, 1
	v_lshl_or_b32 v148, v147, 6, v148
	v_bfe_i32 v147, v146, 25, 1
	v_bfi_b32 v148, v147, v146, v148
	global_store_dwordx2 v148, v[72:73], s[2:3]
	v_add_u32_e32 v72, 0x4020, v80
	v_mad_i64_i32 v[58:59], s[0:1], v72, s78, v[70:71]
	v_lshl_add_u64 v[58:59], v[58:59], 0, v[0:1]
	global_load_dwordx2 v[74:75], v[58:59], off offset:1024
	v_ashrrev_i32_e32 v73, 31, v72
	s_waitcnt vmcnt(0)
	v_lshlrev_b32_e32 v76, 16, v74
	v_and_b32_e32 v77, 0xffff0000, v74
	v_mul_f32_e32 v74, 0xbfb8aa3b, v76
	v_exp_f32_e32 v74, v74
	s_nop 0
	v_add_f32_e32 v74, 1.0, v74
	v_rcp_f32_e32 v78, v74
	v_mul_f32_e32 v74, 0xbfb8aa3b, v77
	v_exp_f32_e32 v74, v74
	s_nop 0
	v_add_f32_e32 v74, 1.0, v74
	v_rcp_f32_e32 v79, v74
	v_lshlrev_b32_e32 v74, 16, v75
	v_and_b32_e32 v75, 0xffff0000, v75
	v_pk_mul_f32 v[76:77], v[78:79], v[76:77]
	s_nop 0
	v_pk_mul_f32 v[54:55], v[54:55], v[76:77]
	s_nop 0
	v_cvt_pk_bf16_f32 v54, v54, v55
	v_mul_f32_e32 v55, 0xbfb8aa3b, v74
	v_exp_f32_e32 v55, v55
	s_nop 0
	v_add_f32_e32 v55, 1.0, v55
	v_rcp_f32_e32 v76, v55
	v_mul_f32_e32 v55, 0xbfb8aa3b, v75
	v_exp_f32_e32 v55, v55
	s_nop 0
	v_add_f32_e32 v55, 1.0, v55
	v_rcp_f32_e32 v77, v55
	s_nop 0
	v_pk_mul_f32 v[74:75], v[76:77], v[74:75]
	s_nop 0
	v_pk_mul_f32 v[56:57], v[56:57], v[74:75]
	s_nop 0
	v_cvt_pk_bf16_f32 v55, v56, v57
	v_lshlrev_b64 v[56:57], 11, v[72:73]
	v_lshl_add_u64 v[72:73], v[68:69], 0, v[56:57]
	v_readlane_b32 s2, v254, 31
	v_readlane_b32 s3, v254, 32
	v_subrev_u32_e32 v146, s2, v72
	v_and_b32_e32 v147, 0x7c0, v146
	v_and_b32_e32 v148, 0xfffff7ff, v146
	v_add_u32_e32 v148, v148, v147
	v_bfe_u32 v147, v146, 11, 1
	v_lshl_or_b32 v148, v147, 6, v148
	v_bfe_i32 v147, v146, 25, 1
	v_bfi_b32 v148, v147, v146, v148
	global_store_dwordx2 v148, v[54:55], s[2:3]
	v_add_u32_e32 v72, 0x4030, v80
	v_mad_i64_i32 v[54:55], s[0:1], v72, s78, v[70:71]
	v_lshl_add_u64 v[54:55], v[54:55], 0, v[0:1]
	global_load_dwordx2 v[70:71], v[54:55], off offset:1024
	v_ashrrev_i32_e32 v73, 31, v72
	s_mov_b64 s[0:1], 0
	s_waitcnt vmcnt(0)
	v_lshlrev_b32_e32 v74, 16, v70
	v_and_b32_e32 v75, 0xffff0000, v70
	v_mul_f32_e32 v70, 0xbfb8aa3b, v74
	v_exp_f32_e32 v70, v70
	s_nop 0
	v_add_f32_e32 v70, 1.0, v70
	v_rcp_f32_e32 v76, v70
	v_mul_f32_e32 v70, 0xbfb8aa3b, v75
	v_exp_f32_e32 v70, v70
	s_nop 0
	v_add_f32_e32 v70, 1.0, v70
	v_rcp_f32_e32 v77, v70
	s_nop 0
	v_pk_mul_f32 v[74:75], v[76:77], v[74:75]
	s_nop 0
	v_pk_mul_f32 v[50:51], v[50:51], v[74:75]
	s_nop 0
	v_cvt_pk_bf16_f32 v70, v50, v51
	v_lshlrev_b32_e32 v50, 16, v71
	v_and_b32_e32 v51, 0xffff0000, v71
	v_mul_f32_e32 v71, 0xbfb8aa3b, v50
	v_exp_f32_e32 v71, v71
	s_nop 0
	v_add_f32_e32 v71, 1.0, v71
	v_rcp_f32_e32 v74, v71
	v_mul_f32_e32 v71, 0xbfb8aa3b, v51
	v_exp_f32_e32 v71, v71
	s_nop 0
	v_add_f32_e32 v71, 1.0, v71
	v_rcp_f32_e32 v75, v71
	s_nop 0
	v_pk_mul_f32 v[50:51], v[74:75], v[50:51]
	s_nop 0
	v_pk_mul_f32 v[50:51], v[52:53], v[50:51]
	s_nop 0
	v_cvt_pk_bf16_f32 v71, v50, v51
	v_lshlrev_b64 v[50:51], 11, v[72:73]
	v_lshl_add_u64 v[52:53], v[68:69], 0, v[50:51]
	v_readlane_b32 s2, v254, 31
	v_readlane_b32 s3, v254, 32
	v_subrev_u32_e32 v146, s2, v52
	v_and_b32_e32 v147, 0x7c0, v146
	v_and_b32_e32 v148, 0xfffff7ff, v146
	v_add_u32_e32 v148, v148, v147
	v_bfe_u32 v147, v146, 11, 1
	v_lshl_or_b32 v148, v147, 6, v148
	v_bfe_i32 v147, v146, 25, 1
	v_bfi_b32 v148, v147, v146, v148
	global_store_dwordx2 v148, v[70:71], s[2:3]
	global_load_dwordx2 v[52:53], v[62:63], off offset:1056
	s_waitcnt vmcnt(0)
	v_lshlrev_b32_e32 v68, 16, v52
	v_and_b32_e32 v69, 0xffff0000, v52
	v_mul_f32_e32 v52, 0xbfb8aa3b, v68
	v_exp_f32_e32 v52, v52
	s_nop 0
	v_add_f32_e32 v52, 1.0, v52
	v_rcp_f32_e32 v70, v52
	v_mul_f32_e32 v52, 0xbfb8aa3b, v69
	v_exp_f32_e32 v52, v52
	s_nop 0
	v_add_f32_e32 v52, 1.0, v52
	v_rcp_f32_e32 v71, v52
	s_nop 0
	v_pk_mul_f32 v[68:69], v[70:71], v[68:69]
	s_nop 0
	v_pk_mul_f32 v[46:47], v[46:47], v[68:69]
	s_nop 0
	v_cvt_pk_bf16_f32 v52, v46, v47
	v_lshlrev_b32_e32 v46, 16, v53
	v_and_b32_e32 v47, 0xffff0000, v53
	v_mul_f32_e32 v53, 0xbfb8aa3b, v46
	v_exp_f32_e32 v53, v53
	s_nop 0
	v_add_f32_e32 v53, 1.0, v53
	v_rcp_f32_e32 v68, v53
	v_mul_f32_e32 v53, 0xbfb8aa3b, v47
	v_exp_f32_e32 v53, v53
	s_nop 0
	v_add_f32_e32 v53, 1.0, v53
	v_rcp_f32_e32 v69, v53
	s_nop 0
	v_pk_mul_f32 v[46:47], v[68:69], v[46:47]
	s_nop 0
	v_pk_mul_f32 v[46:47], v[48:49], v[46:47]
	v_or_b32_e32 v48, 32, v0
	v_cvt_pk_bf16_f32 v53, v46, v47
	v_lshl_add_u64 v[46:47], s[60:61], 0, v[64:65]
	v_mov_b32_e32 v49, v1
	v_lshl_add_u64 v[64:65], v[46:47], 0, v[48:49]
	v_readlane_b32 s2, v254, 31
	v_readlane_b32 s3, v254, 32
	v_subrev_u32_e32 v146, s2, v64
	v_and_b32_e32 v147, 0x7c0, v146
	v_and_b32_e32 v148, 0xfffff7ff, v146
	v_add_u32_e32 v148, v148, v147
	v_bfe_u32 v147, v146, 11, 1
	v_lshl_or_b32 v148, v147, 6, v148
	v_bfe_i32 v147, v146, 25, 1
	v_bfi_b32 v148, v147, v146, v148
	global_store_dwordx2 v148, v[52:53], s[2:3]
	global_load_dwordx2 v[52:53], v[60:61], off offset:1056
	s_waitcnt vmcnt(0)
	v_lshlrev_b32_e32 v64, 16, v52
	v_and_b32_e32 v65, 0xffff0000, v52
	v_mul_f32_e32 v52, 0xbfb8aa3b, v64
	v_exp_f32_e32 v52, v52
	s_nop 0
	v_add_f32_e32 v52, 1.0, v52
	v_rcp_f32_e32 v68, v52
	v_mul_f32_e32 v52, 0xbfb8aa3b, v65
	v_exp_f32_e32 v52, v52
	s_nop 0
	v_add_f32_e32 v52, 1.0, v52
	v_rcp_f32_e32 v69, v52
	s_nop 0
	v_pk_mul_f32 v[64:65], v[68:69], v[64:65]
	s_nop 0
	v_pk_mul_f32 v[42:43], v[42:43], v[64:65]
	s_nop 0
	v_cvt_pk_bf16_f32 v52, v42, v43
	v_lshlrev_b32_e32 v42, 16, v53
	v_and_b32_e32 v43, 0xffff0000, v53
	v_mul_f32_e32 v53, 0xbfb8aa3b, v42
	v_exp_f32_e32 v53, v53
	s_nop 0
	v_add_f32_e32 v53, 1.0, v53
	v_rcp_f32_e32 v64, v53
	v_mul_f32_e32 v53, 0xbfb8aa3b, v43
	v_exp_f32_e32 v53, v53
	s_nop 0
	v_add_f32_e32 v53, 1.0, v53
	v_rcp_f32_e32 v65, v53
	s_nop 0
	v_pk_mul_f32 v[42:43], v[64:65], v[42:43]
	s_nop 0
	v_pk_mul_f32 v[42:43], v[44:45], v[42:43]
	s_nop 0
	v_cvt_pk_bf16_f32 v53, v42, v43
	v_lshl_add_u64 v[42:43], s[60:61], 0, v[66:67]
	v_lshl_add_u64 v[44:45], v[42:43], 0, v[48:49]
	v_readlane_b32 s2, v254, 31
	v_readlane_b32 s3, v254, 32
	v_subrev_u32_e32 v146, s2, v44
	v_and_b32_e32 v147, 0x7c0, v146
	v_and_b32_e32 v148, 0xfffff7ff, v146
	v_add_u32_e32 v148, v148, v147
	v_bfe_u32 v147, v146, 11, 1
	v_lshl_or_b32 v148, v147, 6, v148
	v_bfe_i32 v147, v146, 25, 1
	v_bfi_b32 v148, v147, v146, v148
	global_store_dwordx2 v148, v[52:53], s[2:3]
	global_load_dwordx2 v[44:45], v[58:59], off offset:1056
	s_waitcnt vmcnt(0)
	v_lshlrev_b32_e32 v52, 16, v44
	v_and_b32_e32 v53, 0xffff0000, v44
	v_mul_f32_e32 v44, 0xbfb8aa3b, v52
	v_exp_f32_e32 v44, v44
	s_nop 0
	v_add_f32_e32 v44, 1.0, v44
	v_rcp_f32_e32 v64, v44
	v_mul_f32_e32 v44, 0xbfb8aa3b, v53
	v_exp_f32_e32 v44, v44
	s_nop 0
	v_add_f32_e32 v44, 1.0, v44
	v_rcp_f32_e32 v65, v44
	s_nop 0
	v_pk_mul_f32 v[52:53], v[64:65], v[52:53]
	s_nop 0
	v_pk_mul_f32 v[38:39], v[38:39], v[52:53]
	s_nop 0
	v_cvt_pk_bf16_f32 v44, v38, v39
	v_lshlrev_b32_e32 v38, 16, v45
	v_and_b32_e32 v39, 0xffff0000, v45
	v_mul_f32_e32 v45, 0xbfb8aa3b, v38
	v_exp_f32_e32 v45, v45
	s_nop 0
	v_add_f32_e32 v45, 1.0, v45
	v_rcp_f32_e32 v52, v45
	v_mul_f32_e32 v45, 0xbfb8aa3b, v39
	v_exp_f32_e32 v45, v45
	s_nop 0
	v_add_f32_e32 v45, 1.0, v45
	v_rcp_f32_e32 v53, v45
	s_nop 0
	v_pk_mul_f32 v[38:39], v[52:53], v[38:39]
	s_nop 0
	v_pk_mul_f32 v[38:39], v[40:41], v[38:39]
	s_nop 0
	v_cvt_pk_bf16_f32 v45, v38, v39
	v_lshl_add_u64 v[38:39], s[60:61], 0, v[56:57]
	v_lshl_add_u64 v[40:41], v[38:39], 0, v[48:49]
	v_readlane_b32 s2, v254, 31
	v_readlane_b32 s3, v254, 32
	v_subrev_u32_e32 v146, s2, v40
	v_and_b32_e32 v147, 0x7c0, v146
	v_and_b32_e32 v148, 0xfffff7ff, v146
	v_add_u32_e32 v148, v148, v147
	v_bfe_u32 v147, v146, 11, 1
	v_lshl_or_b32 v148, v147, 6, v148
	v_bfe_i32 v147, v146, 25, 1
	v_bfi_b32 v148, v147, v146, v148
	global_store_dwordx2 v148, v[44:45], s[2:3]
	global_load_dwordx2 v[40:41], v[54:55], off offset:1056
	s_waitcnt vmcnt(0)
	v_lshlrev_b32_e32 v44, 16, v40
	v_and_b32_e32 v45, 0xffff0000, v40
	v_mul_f32_e32 v40, 0xbfb8aa3b, v44
	v_exp_f32_e32 v40, v40
	s_nop 0
	v_add_f32_e32 v40, 1.0, v40
	v_rcp_f32_e32 v52, v40
	v_mul_f32_e32 v40, 0xbfb8aa3b, v45
	v_exp_f32_e32 v40, v40
	s_nop 0
	v_add_f32_e32 v40, 1.0, v40
	v_rcp_f32_e32 v53, v40
	s_nop 0
	v_pk_mul_f32 v[44:45], v[52:53], v[44:45]
	s_nop 0
	v_pk_mul_f32 v[34:35], v[34:35], v[44:45]
	s_nop 0
	v_cvt_pk_bf16_f32 v40, v34, v35
	v_lshlrev_b32_e32 v34, 16, v41
	v_and_b32_e32 v35, 0xffff0000, v41
	v_mul_f32_e32 v41, 0xbfb8aa3b, v34
	v_exp_f32_e32 v41, v41
	s_nop 0
	v_add_f32_e32 v41, 1.0, v41
	v_rcp_f32_e32 v44, v41
	v_mul_f32_e32 v41, 0xbfb8aa3b, v35
	v_exp_f32_e32 v41, v41
	s_nop 0
	v_add_f32_e32 v41, 1.0, v41
	v_rcp_f32_e32 v45, v41
	s_nop 0
	v_pk_mul_f32 v[34:35], v[44:45], v[34:35]
	s_nop 0
	v_pk_mul_f32 v[34:35], v[36:37], v[34:35]
	s_nop 0
	v_cvt_pk_bf16_f32 v41, v34, v35
	v_lshl_add_u64 v[34:35], s[60:61], 0, v[50:51]
	v_lshl_add_u64 v[36:37], v[34:35], 0, v[48:49]
	v_readlane_b32 s2, v254, 31
	v_readlane_b32 s3, v254, 32
	v_subrev_u32_e32 v146, s2, v36
	v_and_b32_e32 v147, 0x7c0, v146
	v_and_b32_e32 v148, 0xfffff7ff, v146
	v_add_u32_e32 v148, v148, v147
	v_bfe_u32 v147, v146, 11, 1
	v_lshl_or_b32 v148, v147, 6, v148
	v_bfe_i32 v147, v146, 25, 1
	v_bfi_b32 v148, v147, v146, v148
	global_store_dwordx2 v148, v[40:41], s[2:3]
	global_load_dwordx2 v[36:37], v[62:63], off offset:1088
	s_waitcnt vmcnt(0)
	v_lshlrev_b32_e32 v40, 16, v36
	v_and_b32_e32 v41, 0xffff0000, v36
	v_mul_f32_e32 v36, 0xbfb8aa3b, v40
	v_exp_f32_e32 v36, v36
	s_nop 0
	v_add_f32_e32 v36, 1.0, v36
	v_rcp_f32_e32 v44, v36
	v_mul_f32_e32 v36, 0xbfb8aa3b, v41
	v_exp_f32_e32 v36, v36
	s_nop 0
	v_add_f32_e32 v36, 1.0, v36
	v_rcp_f32_e32 v45, v36
	v_lshlrev_b32_e32 v36, 16, v37
	v_and_b32_e32 v37, 0xffff0000, v37
	v_pk_mul_f32 v[40:41], v[44:45], v[40:41]
	s_nop 0
	v_pk_mul_f32 v[30:31], v[30:31], v[40:41]
	s_nop 0
	v_cvt_pk_bf16_f32 v30, v30, v31
	v_mul_f32_e32 v31, 0xbfb8aa3b, v36
	v_exp_f32_e32 v31, v31
	s_nop 0
	v_add_f32_e32 v31, 1.0, v31
	v_rcp_f32_e32 v40, v31
	v_mul_f32_e32 v31, 0xbfb8aa3b, v37
	v_exp_f32_e32 v31, v31
	s_nop 0
	v_add_f32_e32 v31, 1.0, v31
	v_rcp_f32_e32 v41, v31
	s_nop 0
	v_pk_mul_f32 v[36:37], v[40:41], v[36:37]
	s_nop 0
	v_pk_mul_f32 v[32:33], v[32:33], v[36:37]
	s_nop 0
	v_cvt_pk_bf16_f32 v31, v32, v33
	v_or_b32_e32 v32, 64, v0
	v_mov_b32_e32 v33, v1
	v_lshl_add_u64 v[36:37], v[46:47], 0, v[32:33]
	v_readlane_b32 s2, v254, 31
	v_readlane_b32 s3, v254, 32
	v_subrev_u32_e32 v146, s2, v36
	v_and_b32_e32 v147, 0x7c0, v146
	v_and_b32_e32 v148, 0xfffff7ff, v146
	v_add_u32_e32 v148, v148, v147
	v_bfe_u32 v147, v146, 11, 1
	v_lshl_or_b32 v148, v147, 6, v148
	v_bfe_i32 v147, v146, 25, 1
	v_bfi_b32 v148, v147, v146, v148
	global_store_dwordx2 v148, v[30:31], s[2:3]
	global_load_dwordx2 v[30:31], v[60:61], off offset:1088
	v_or_b32_e32 v0, 0x60, v0
	s_waitcnt vmcnt(0)
	v_lshlrev_b32_e32 v36, 16, v30
	v_and_b32_e32 v37, 0xffff0000, v30
	v_mul_f32_e32 v30, 0xbfb8aa3b, v36
	v_exp_f32_e32 v30, v30
	s_nop 0
	v_add_f32_e32 v30, 1.0, v30
	v_rcp_f32_e32 v40, v30
	v_mul_f32_e32 v30, 0xbfb8aa3b, v37
	v_exp_f32_e32 v30, v30
	s_nop 0
	v_add_f32_e32 v30, 1.0, v30
	v_rcp_f32_e32 v41, v30
	v_lshlrev_b32_e32 v30, 16, v31
	v_and_b32_e32 v31, 0xffff0000, v31
	v_pk_mul_f32 v[36:37], v[40:41], v[36:37]
	s_nop 0
	v_pk_mul_f32 v[26:27], v[26:27], v[36:37]
	s_nop 0
	v_cvt_pk_bf16_f32 v26, v26, v27
	v_mul_f32_e32 v27, 0xbfb8aa3b, v30
	v_exp_f32_e32 v27, v27
	s_nop 0
	v_add_f32_e32 v27, 1.0, v27
	v_rcp_f32_e32 v36, v27
	v_mul_f32_e32 v27, 0xbfb8aa3b, v31
	v_exp_f32_e32 v27, v27
	s_nop 0
	v_add_f32_e32 v27, 1.0, v27
	v_rcp_f32_e32 v37, v27
	s_nop 0
	v_pk_mul_f32 v[30:31], v[36:37], v[30:31]
	s_nop 0
	v_pk_mul_f32 v[28:29], v[28:29], v[30:31]
	s_nop 0
	v_cvt_pk_bf16_f32 v27, v28, v29
	v_lshl_add_u64 v[28:29], v[42:43], 0, v[32:33]
	v_readlane_b32 s2, v254, 31
	v_readlane_b32 s3, v254, 32
	v_subrev_u32_e32 v146, s2, v28
	v_and_b32_e32 v147, 0x7c0, v146
	v_and_b32_e32 v148, 0xfffff7ff, v146
	v_add_u32_e32 v148, v148, v147
	v_bfe_u32 v147, v146, 11, 1
	v_lshl_or_b32 v148, v147, 6, v148
	v_bfe_i32 v147, v146, 25, 1
	v_bfi_b32 v148, v147, v146, v148
	global_store_dwordx2 v148, v[26:27], s[2:3]
	global_load_dwordx2 v[26:27], v[58:59], off offset:1088
	s_waitcnt vmcnt(0)
	v_lshlrev_b32_e32 v28, 16, v26
	v_and_b32_e32 v29, 0xffff0000, v26
	v_mul_f32_e32 v26, 0xbfb8aa3b, v28
	v_exp_f32_e32 v26, v26
	s_nop 0
	v_add_f32_e32 v26, 1.0, v26
	v_rcp_f32_e32 v30, v26
	v_mul_f32_e32 v26, 0xbfb8aa3b, v29
	v_exp_f32_e32 v26, v26
	s_nop 0
	v_add_f32_e32 v26, 1.0, v26
	v_rcp_f32_e32 v31, v26
	v_lshlrev_b32_e32 v26, 16, v27
	v_and_b32_e32 v27, 0xffff0000, v27
	v_pk_mul_f32 v[28:29], v[30:31], v[28:29]
	s_nop 0
	v_pk_mul_f32 v[22:23], v[22:23], v[28:29]
	s_nop 0
	v_cvt_pk_bf16_f32 v22, v22, v23
	v_mul_f32_e32 v23, 0xbfb8aa3b, v26
	v_exp_f32_e32 v23, v23
	s_nop 0
	v_add_f32_e32 v23, 1.0, v23
	v_rcp_f32_e32 v28, v23
	v_mul_f32_e32 v23, 0xbfb8aa3b, v27
	v_exp_f32_e32 v23, v23
	s_nop 0
	v_add_f32_e32 v23, 1.0, v23
	v_rcp_f32_e32 v29, v23
	s_nop 0
	v_pk_mul_f32 v[26:27], v[28:29], v[26:27]
	s_nop 0
	v_pk_mul_f32 v[24:25], v[24:25], v[26:27]
	s_nop 0
	v_cvt_pk_bf16_f32 v23, v24, v25
	v_lshl_add_u64 v[24:25], v[38:39], 0, v[32:33]
	v_readlane_b32 s2, v254, 31
	v_readlane_b32 s3, v254, 32
	v_subrev_u32_e32 v146, s2, v24
	v_and_b32_e32 v147, 0x7c0, v146
	v_and_b32_e32 v148, 0xfffff7ff, v146
	v_add_u32_e32 v148, v148, v147
	v_bfe_u32 v147, v146, 11, 1
	v_lshl_or_b32 v148, v147, 6, v148
	v_bfe_i32 v147, v146, 25, 1
	v_bfi_b32 v148, v147, v146, v148
	global_store_dwordx2 v148, v[22:23], s[2:3]
	global_load_dwordx2 v[22:23], v[54:55], off offset:1088
	s_waitcnt vmcnt(0)
	v_lshlrev_b32_e32 v24, 16, v22
	v_and_b32_e32 v25, 0xffff0000, v22
	v_mul_f32_e32 v22, 0xbfb8aa3b, v24
	v_exp_f32_e32 v22, v22
	s_nop 0
	v_add_f32_e32 v22, 1.0, v22
	v_rcp_f32_e32 v26, v22
	v_mul_f32_e32 v22, 0xbfb8aa3b, v25
	v_exp_f32_e32 v22, v22
	s_nop 0
	v_add_f32_e32 v22, 1.0, v22
	v_rcp_f32_e32 v27, v22
	v_lshlrev_b32_e32 v22, 16, v23
	v_and_b32_e32 v23, 0xffff0000, v23
	v_pk_mul_f32 v[24:25], v[26:27], v[24:25]
	s_nop 0
	v_pk_mul_f32 v[18:19], v[18:19], v[24:25]
	s_nop 0
	v_cvt_pk_bf16_f32 v18, v18, v19
	v_mul_f32_e32 v19, 0xbfb8aa3b, v22
	v_exp_f32_e32 v19, v19
	s_nop 0
	v_add_f32_e32 v19, 1.0, v19
	v_rcp_f32_e32 v24, v19
	v_mul_f32_e32 v19, 0xbfb8aa3b, v23
	v_exp_f32_e32 v19, v19
	s_nop 0
	v_add_f32_e32 v19, 1.0, v19
	v_rcp_f32_e32 v25, v19
	s_nop 0
	v_pk_mul_f32 v[22:23], v[24:25], v[22:23]
	s_nop 0
	v_pk_mul_f32 v[20:21], v[20:21], v[22:23]
	s_nop 0
	v_cvt_pk_bf16_f32 v19, v20, v21
	v_lshl_add_u64 v[20:21], v[34:35], 0, v[32:33]
	v_readlane_b32 s2, v254, 31
	v_readlane_b32 s3, v254, 32
	v_subrev_u32_e32 v146, s2, v20
	v_and_b32_e32 v147, 0x7c0, v146
	v_and_b32_e32 v148, 0xfffff7ff, v146
	v_add_u32_e32 v148, v148, v147
	v_bfe_u32 v147, v146, 11, 1
	v_lshl_or_b32 v148, v147, 6, v148
	v_bfe_i32 v147, v146, 25, 1
	v_bfi_b32 v148, v147, v146, v148
	global_store_dwordx2 v148, v[18:19], s[2:3]
	global_load_dwordx2 v[18:19], v[62:63], off offset:1120
	s_waitcnt vmcnt(0)
	v_lshlrev_b32_e32 v20, 16, v18
	v_and_b32_e32 v21, 0xffff0000, v18
	v_mul_f32_e32 v18, 0xbfb8aa3b, v20
	v_exp_f32_e32 v18, v18
	s_nop 0
	v_add_f32_e32 v18, 1.0, v18
	v_rcp_f32_e32 v22, v18
	v_mul_f32_e32 v18, 0xbfb8aa3b, v21
	v_exp_f32_e32 v18, v18
	s_nop 0
	v_add_f32_e32 v18, 1.0, v18
	v_rcp_f32_e32 v23, v18
	v_lshlrev_b32_e32 v18, 16, v19
	v_and_b32_e32 v19, 0xffff0000, v19
	v_pk_mul_f32 v[20:21], v[22:23], v[20:21]
	s_nop 0
	v_pk_mul_f32 v[14:15], v[14:15], v[20:21]
	s_nop 0
	v_cvt_pk_bf16_f32 v14, v14, v15
	v_mul_f32_e32 v15, 0xbfb8aa3b, v18
	v_exp_f32_e32 v15, v15
	s_nop 0
	v_add_f32_e32 v15, 1.0, v15
	v_rcp_f32_e32 v20, v15
	v_mul_f32_e32 v15, 0xbfb8aa3b, v19
	v_exp_f32_e32 v15, v15
	s_nop 0
	v_add_f32_e32 v15, 1.0, v15
	v_rcp_f32_e32 v21, v15
	s_nop 0
	v_pk_mul_f32 v[18:19], v[20:21], v[18:19]
	s_nop 0
	v_pk_mul_f32 v[16:17], v[16:17], v[18:19]
	s_nop 0
	v_cvt_pk_bf16_f32 v15, v16, v17
	v_lshl_add_u64 v[16:17], v[46:47], 0, v[0:1]
	v_readlane_b32 s2, v254, 31
	v_readlane_b32 s3, v254, 32
	v_subrev_u32_e32 v146, s2, v16
	v_and_b32_e32 v147, 0x7c0, v146
	v_and_b32_e32 v148, 0xfffff7ff, v146
	v_add_u32_e32 v148, v148, v147
	v_bfe_u32 v147, v146, 11, 1
	v_lshl_or_b32 v148, v147, 6, v148
	v_bfe_i32 v147, v146, 25, 1
	v_bfi_b32 v148, v147, v146, v148
	global_store_dwordx2 v148, v[14:15], s[2:3]
	global_load_dwordx2 v[14:15], v[60:61], off offset:1120
	s_waitcnt vmcnt(0)
; DI int otid() { int t = threadIdx.x; asm volatile("" : "+v"(t)); return t; }
;   DI bf16* K() const { return (bf16*)(p.ws + WS_K); }
; template <int TRANS, class AP, class BP, class Epi>
; DI void mfma_gemm_tile(const AP& aptr, const BP& bptr, int m0, int n0, int K, const Epi& epi, bf16* lds) {
;   const int tid = otid(), lane = tid & 63, wave = __builtin_amdgcn_readfirstlane(tid >> 6);
;   const int wm = (wave >> 1) * 64, wn = (wave & 1) * 64;
;   const int lr = tid >> 3, lc = ((tid & 7) ^ (lr & 7)) * 8;
;   const int l16 = lane & 15, lq = lane >> 4;
;   const bf16* ap[4]; const bf16* bp[4];
; #pragma unroll
;   for (int i = 0; i < 4; ++i) { ap[i] = aptr(m0 + lr + 32 * i) + lc; bp[i] = bptr(n0 + lr + 32 * i) + lc; }
;   f32x4 acc[4][4];
; #pragma unroll
;   for (int i = 0; i < 4; ++i)
; #pragma unroll
;     for (int j = 0; j < 4; ++j) acc[i][j] = f32x4{0.f, 0.f, 0.f, 0.f};
;   const int nk = K >> 6;
;     ...
;   GEMM_STAGE(0, 0);
	v_lshlrev_b32_e32 v16, 16, v14
	v_and_b32_e32 v17, 0xffff0000, v14
	v_mul_f32_e32 v14, 0xbfb8aa3b, v16
	v_exp_f32_e32 v14, v14
	s_nop 0
	v_add_f32_e32 v14, 1.0, v14
	v_rcp_f32_e32 v18, v14
	v_mul_f32_e32 v14, 0xbfb8aa3b, v17
	v_exp_f32_e32 v14, v14
	s_nop 0
	v_add_f32_e32 v14, 1.0, v14
	v_rcp_f32_e32 v19, v14
	v_lshlrev_b32_e32 v14, 16, v15
	v_and_b32_e32 v15, 0xffff0000, v15
	v_pk_mul_f32 v[16:17], v[18:19], v[16:17]
	s_nop 0
	v_pk_mul_f32 v[10:11], v[10:11], v[16:17]
	s_nop 0
	v_cvt_pk_bf16_f32 v10, v10, v11
	v_mul_f32_e32 v11, 0xbfb8aa3b, v14
	v_exp_f32_e32 v11, v11
	s_nop 0
	v_add_f32_e32 v11, 1.0, v11
	v_rcp_f32_e32 v16, v11
	v_mul_f32_e32 v11, 0xbfb8aa3b, v15
	v_exp_f32_e32 v11, v11
	s_nop 0
	v_add_f32_e32 v11, 1.0, v11
	v_rcp_f32_e32 v17, v11
	s_nop 0
	v_pk_mul_f32 v[14:15], v[16:17], v[14:15]
	s_nop 0
	v_pk_mul_f32 v[12:13], v[12:13], v[14:15]
	s_nop 0
	v_cvt_pk_bf16_f32 v11, v12, v13
	v_lshl_add_u64 v[12:13], v[42:43], 0, v[0:1]
	v_readlane_b32 s2, v254, 31
	v_readlane_b32 s3, v254, 32
	v_subrev_u32_e32 v146, s2, v12
	v_and_b32_e32 v147, 0x7c0, v146
	v_and_b32_e32 v148, 0xfffff7ff, v146
	v_add_u32_e32 v148, v148, v147
	v_bfe_u32 v147, v146, 11, 1
	v_lshl_or_b32 v148, v147, 6, v148
	v_bfe_i32 v147, v146, 25, 1
	v_bfi_b32 v148, v147, v146, v148
	global_store_dwordx2 v148, v[10:11], s[2:3]
	global_load_dwordx2 v[10:11], v[58:59], off offset:1120
	s_waitcnt vmcnt(0)
	v_lshlrev_b32_e32 v12, 16, v10
	v_and_b32_e32 v13, 0xffff0000, v10
	v_mul_f32_e32 v10, 0xbfb8aa3b, v12
	v_exp_f32_e32 v10, v10
	s_nop 0
	v_add_f32_e32 v10, 1.0, v10
	v_rcp_f32_e32 v14, v10
	v_mul_f32_e32 v10, 0xbfb8aa3b, v13
	v_exp_f32_e32 v10, v10
	s_nop 0
	v_add_f32_e32 v10, 1.0, v10
	v_rcp_f32_e32 v15, v10
	v_lshlrev_b32_e32 v10, 16, v11
	v_and_b32_e32 v11, 0xffff0000, v11
	v_pk_mul_f32 v[12:13], v[14:15], v[12:13]
	s_nop 0
	v_pk_mul_f32 v[6:7], v[6:7], v[12:13]
	s_nop 0
	v_cvt_pk_bf16_f32 v6, v6, v7
	v_mul_f32_e32 v7, 0xbfb8aa3b, v10
	v_exp_f32_e32 v7, v7
	s_nop 0
	v_add_f32_e32 v7, 1.0, v7
	v_rcp_f32_e32 v12, v7
	v_mul_f32_e32 v7, 0xbfb8aa3b, v11
	v_exp_f32_e32 v7, v7
	s_nop 0
	v_add_f32_e32 v7, 1.0, v7
	v_rcp_f32_e32 v13, v7
	s_nop 0
	v_pk_mul_f32 v[10:11], v[12:13], v[10:11]
	s_nop 0
	v_pk_mul_f32 v[8:9], v[8:9], v[10:11]
	s_nop 0
	v_cvt_pk_bf16_f32 v7, v8, v9
	v_lshl_add_u64 v[8:9], v[38:39], 0, v[0:1]
	v_readlane_b32 s2, v254, 31
	v_readlane_b32 s3, v254, 32
	v_subrev_u32_e32 v146, s2, v8
	v_and_b32_e32 v147, 0x7c0, v146
	v_and_b32_e32 v148, 0xfffff7ff, v146
	v_add_u32_e32 v148, v148, v147
	v_bfe_u32 v147, v146, 11, 1
	v_lshl_or_b32 v148, v147, 6, v148
	v_bfe_i32 v147, v146, 25, 1
	v_bfi_b32 v148, v147, v146, v148
	global_store_dwordx2 v148, v[6:7], s[2:3]
	global_load_dwordx2 v[6:7], v[54:55], off offset:1120
	s_waitcnt vmcnt(0)
	v_lshlrev_b32_e32 v8, 16, v6
	v_and_b32_e32 v9, 0xffff0000, v6
	v_mul_f32_e32 v6, 0xbfb8aa3b, v8
	v_exp_f32_e32 v6, v6
	s_nop 0
	v_add_f32_e32 v6, 1.0, v6
	v_rcp_f32_e32 v10, v6
	v_mul_f32_e32 v6, 0xbfb8aa3b, v9
	v_exp_f32_e32 v6, v6
	s_nop 0
	v_add_f32_e32 v6, 1.0, v6
	v_rcp_f32_e32 v11, v6
	v_lshlrev_b32_e32 v6, 16, v7
	v_and_b32_e32 v7, 0xffff0000, v7
	v_pk_mul_f32 v[8:9], v[10:11], v[8:9]
	s_nop 0
	v_pk_mul_f32 v[2:3], v[2:3], v[8:9]
	s_nop 0
	v_cvt_pk_bf16_f32 v2, v2, v3
	v_mul_f32_e32 v3, 0xbfb8aa3b, v6
	v_exp_f32_e32 v3, v3
	s_nop 0
	v_add_f32_e32 v3, 1.0, v3
	v_rcp_f32_e32 v8, v3
	v_mul_f32_e32 v3, 0xbfb8aa3b, v7
	v_exp_f32_e32 v3, v3
	s_nop 0
	v_add_f32_e32 v3, 1.0, v3
	v_rcp_f32_e32 v9, v3
	s_nop 0
	v_pk_mul_f32 v[6:7], v[8:9], v[6:7]
	s_nop 0
	v_pk_mul_f32 v[4:5], v[4:5], v[6:7]
	s_nop 0
	v_cvt_pk_bf16_f32 v3, v4, v5
	v_lshl_add_u64 v[4:5], v[34:35], 0, v[0:1]
	v_readlane_b32 s2, v254, 31
	v_readlane_b32 s3, v254, 32
	v_subrev_u32_e32 v146, s2, v4
	v_and_b32_e32 v147, 0x7c0, v146
	v_and_b32_e32 v148, 0xfffff7ff, v146
	v_add_u32_e32 v148, v148, v147
	v_bfe_u32 v147, v146, 11, 1
	v_lshl_or_b32 v148, v147, 6, v148
	v_bfe_i32 v147, v146, 25, 1
	v_bfi_b32 v148, v147, v146, v148
	global_store_dwordx2 v148, v[2:3], s[2:3]
	s_waitcnt vmcnt(0)
	s_waitcnt lgkmcnt(0)
	s_barrier
.LBB0_379:
	s_andn2_b64 vcc, exec, s[0:1]
	s_cbranch_vccnz .LBB0_381
	s_add_i32 s34, s13, 0xfffffc00
	s_and_b32 s16, s12, 3
	s_lshl_b32 s0, s34, 5
	s_and_b32 s17, s0, 0x7fffff80
	s_lshl_b32 s0, s16, 15
	v_readlane_b32 s2, v253, 15
	s_mov_b32 s35, s85
	v_readlane_b32 s3, v253, 16
	s_add_u32 s18, s2, s0
	s_addc_u32 s19, s3, 0
	s_lshl_b64 s[0:1], s[34:35], 15
	v_readlane_b32 s2, v253, 13
	v_mov_b32_e32 v20, v172
	s_add_u32 s20, s2, s0
	v_readlane_b32 s0, v253, 14
	s_addc_u32 s21, s0, s1
	v_ashrrev_i32_e32 v2, 3, v20
	s_or_b32 s0, s16, s11
	v_readlane_b32 s24, v252, 4
	v_xor_b32_e32 v0, v2, v20
	s_lshl_b32 s0, s0, 9
	v_readlane_b32 s30, v252, 10
	v_lshlrev_b32_e32 v0, 4, v0
	v_readlane_b32 s31, v252, 11
	s_add_u32 s0, s30, s0
	v_readfirstlane_b32 s22, v20
	v_and_b32_e32 v0, 0x70, v0
	s_addc_u32 s1, s31, 0
	v_lshl_add_u64 v[4:5], s[18:19], 0, v[0:1]
	v_ashrrev_i32_e32 v3, 31, v2
	s_lshl_b32 s19, s22, 4
	v_lshlrev_b64 v[2:3], 8, v[2:3]
	s_and_b32 s19, s19, 0xfffffc00
	v_lshl_add_u64 v[6:7], s[20:21], 0, v[0:1]
	v_lshl_add_u64 v[8:9], v[4:5], 0, v[2:3]
	s_mov_b64 s[2:3], 0x2000
	s_mov_b32 m0, s19
	v_lshl_add_u64 v[10:11], v[6:7], 0, v[2:3]
	v_lshl_add_u64 v[12:13], v[2:3], 0, s[2:3]
	global_load_lds_dwordx4 v[8:9], off
	s_add_i32 m0, s19, 0x4000
	v_lshl_add_u64 v[14:15], v[4:5], 0, v[12:13]
	s_mov_b64 s[2:3], 0x4000
	global_load_lds_dwordx4 v[10:11], off
	s_add_i32 m0, s19, 0x1000
	v_lshl_add_u64 v[12:13], v[6:7], 0, v[12:13]
	v_lshl_add_u64 v[16:17], v[2:3], 0, s[2:3]
	global_load_lds_dwordx4 v[14:15], off
	s_add_i32 m0, s19, 0x5000
	v_lshl_add_u64 v[18:19], v[4:5], 0, v[16:17]
; #define LDSR(dst, addr, off) asm volatile("ds_read_b128 %0, %1 offset:%2" : "=&v"(dst) : "v"(addr), "n"(off))
; template <int TRANS, class AP, class BP, class Epi>
; DI void mfma_gemm_tile(const AP& aptr, const BP& bptr, int m0, int n0, int K, const Epi& epi, bf16* lds) {
;     ...
;   GEMM_STAGE(0, 0);
;   if (nk > 1) GEMM_STAGE(1, 1);
;   const unsigned lbase = (unsigned)(size_t)lds;
;   const unsigned sw0 = (unsigned)(((lq ^ (l16 & 7)) * 8) * 2), sw1 = (unsigned)((((4 + lq) ^ (l16 & 7)) * 8) * 2);
;   const unsigned a_row = (unsigned)((wm + l16) * 128), b_row = (unsigned)((128 * 64 + (wn + l16) * 64) * 2);
;     ...
;   for (int ks = 0; ks < nk; ++ks) {
;     if (ks + 1 < nk) asm volatile("s_waitcnt vmcnt(8)\n\ts_barrier" ::: "memory");
;     else asm volatile("s_waitcnt vmcnt(0)\n\ts_barrier" ::: "memory");
;     const unsigned sb_ = lbase + (unsigned)((ks & 1) * (2 * 128 * 64) * 2);
;     const unsigned a0 = sb_ + a_row + sw0, a1 = sb_ + a_row + sw1, b0 = sb_ + b_row + sw0, b1 = sb_ + b_row + sw1;
;     bf16x8 af[2][4], bfr[2][4];
;     LDSR(af[0][0], a0, 0); LDSR(af[0][1], a0, 2048); LDSR(af[0][2], a0, 4096); LDSR(af[0][3], a0, 6144);
;     LDSR(bfr[0][0], b0, 0); LDSR(bfr[0][1], b0, 2048); LDSR(bfr[0][2], b0, 4096); LDSR(bfr[0][3], b0, 6144);
;     LDSR(af[1][0], a1, 0); LDSR(af[1][1], a1, 2048); LDSR(af[1][2], a1, 4096); LDSR(af[1][3], a1, 6144);
;     LDSR(bfr[1][0], b1, 0); LDSR(bfr[1][1], b1, 2048); LDSR(bfr[1][2], b1, 4096); LDSR(bfr[1][3], b1, 6144);
;     asm volatile("s_waitcnt lgkmcnt(0)" : "+v"(af[0][0]), "+v"(af[0][1]), "+v"(af[0][2]), "+v"(af[0][3]), "+v"(bfr[0][0]), "+v"(bfr[0][1]), "+v"(bfr[0][2]), "+v"(bfr[0][3]),
;                  "+v"(af[1][0]), "+v"(af[1][1]), "+v"(af[1][2]), "+v"(af[1][3]), "+v"(bfr[1][0]), "+v"(bfr[1][1]), "+v"(bfr[1][2]), "+v"(bfr[1][3]) : : "memory");
;     if (ks + 2 < nk) {
;       asm volatile("s_barrier" ::: "memory");
;       GEMM_STAGE(ks & 1, ks + 2);
;     }
; #pragma unroll
;     for (int kk = 0; kk < 2; ++kk)
; #pragma unroll
;       for (int i = 0; i < 4; ++i)
; #pragma unroll
;         for (int j = 0; j < 4; ++j)
;           acc[i][j] = TRANS ? __builtin_amdgcn_mfma_f32_16x16x32_bf16(af[kk][i], bfr[kk][j], acc[i][j], 0, 0, 0)
;                             : __builtin_amdgcn_mfma_f32_16x16x32_bf16(bfr[kk][j], af[kk][i], acc[i][j], 0, 0, 0);
;   }
	s_mov_b64 s[2:3], 0x6000
	global_load_lds_dwordx4 v[12:13], off
	s_add_i32 m0, s19, 0x2000
	v_lshl_add_u64 v[16:17], v[6:7], 0, v[16:17]
	v_lshl_add_u64 v[2:3], v[2:3], 0, s[2:3]
	global_load_lds_dwordx4 v[18:19], off
	s_add_i32 m0, s19, 0x6000
	v_lshl_add_u64 v[4:5], v[4:5], 0, v[2:3]
	global_load_lds_dwordx4 v[16:17], off
	s_add_i32 m0, s19, 0x3000
	v_lshl_add_u64 v[2:3], v[6:7], 0, v[2:3]
	global_load_lds_dwordx4 v[4:5], off
	s_add_i32 m0, s19, 0x7000
	s_mov_b64 s[2:3], 0x80
	global_load_lds_dwordx4 v[2:3], off
	v_lshl_add_u64 v[6:7], v[8:9], 0, s[2:3]
	s_add_i32 m0, s19, 0x8000
	s_ashr_i32 s23, s22, 1
	global_load_lds_dwordx4 v[6:7], off
	v_lshl_add_u64 v[6:7], v[10:11], 0, s[2:3]
	s_add_i32 m0, s19, 0xc000
	v_lshl_add_u64 v[4:5], v[4:5], 0, s[2:3]
	global_load_lds_dwordx4 v[6:7], off
	v_lshl_add_u64 v[6:7], v[14:15], 0, s[2:3]
	s_add_i32 m0, s19, 0x9000
	s_andn2_b32 s23, s23, 63
	global_load_lds_dwordx4 v[6:7], off
	v_lshl_add_u64 v[6:7], v[12:13], 0, s[2:3]
	s_add_i32 m0, s19, 0xd000
	v_and_b32_e32 v0, 15, v20
	global_load_lds_dwordx4 v[6:7], off
	v_lshl_add_u64 v[6:7], v[18:19], 0, s[2:3]
	s_add_i32 m0, s19, 0xa000
	s_and_b32 s18, s22, 64
	global_load_lds_dwordx4 v[6:7], off
	v_lshl_add_u64 v[6:7], v[16:17], 0, s[2:3]
	s_add_i32 m0, s19, 0xe000
	v_lshl_add_u64 v[2:3], v[2:3], 0, s[2:3]
	global_load_lds_dwordx4 v[6:7], off
	s_add_i32 m0, s19, 0xb000
	v_lshrrev_b32_e32 v21, 4, v20
	global_load_lds_dwordx4 v[4:5], off
	s_add_i32 m0, s19, 0xf000
	v_bfe_u32 v140, v20, 4, 2
	global_load_lds_dwordx4 v[2:3], off
	v_and_b32_e32 v2, 7, v20
	v_or_b32_e32 v62, s23, v0
	v_or_b32_e32 v0, s18, v0
	v_bitop3_b32 v3, v21, v2, 3 bitop3:0x6c
	v_bitop3_b32 v2, v140, v2, 4 bitop3:0x36
	v_lshlrev_b32_e32 v0, 7, v0
	v_lshlrev_b32_e32 v63, 4, v3
	v_lshlrev_b32_e32 v104, 4, v2
	v_lshlrev_b32_e32 v105, 7, v62
	v_or_b32_e32 v2, 0x4000, v0
	v_or_b32_e32 v18, v105, v63
	v_or_b32_e32 v50, v105, v104
	v_or_b32_e32 v34, v2, v63
	s_waitcnt vmcnt(8)
	s_barrier
	v_or_b32_e32 v68, v2, v104
	ds_read_b128 v[2:5], v18 offset:0
	ds_read_b128 v[6:9], v18 offset:0x800
	ds_read_b128 v[10:13], v18 offset:0x1000
	ds_read_b128 v[14:17], v18 offset:0x1800
	ds_read_b128 v[18:21], v34 offset:0
	ds_read_b128 v[22:25], v34 offset:0x800
	ds_read_b128 v[26:29], v34 offset:0x1000
	ds_read_b128 v[30:33], v34 offset:0x1800
	ds_read_b128 v[34:37], v50 offset:0
	ds_read_b128 v[38:41], v50 offset:0x800
	ds_read_b128 v[42:45], v50 offset:0x1000
	ds_read_b128 v[46:49], v50 offset:0x1800
	ds_read_b128 v[50:53], v68 offset:0
	ds_read_b128 v[54:57], v68 offset:0x800
	ds_read_b128 v[58:61], v68 offset:0x1000
	ds_read_b128 v[64:67], v68 offset:0x1800
	v_or_b32_e32 v0, 0xc000, v0
	s_waitcnt lgkmcnt(0)
	s_waitcnt vmcnt(0)
	s_barrier
	s_lshl_b32 s34, s16, 8
	v_mfma_f32_16x16x32_bf16 v[68:71], v[18:21], v[2:5], 0
	s_movk_i32 s2, 0x1000
	s_mov_b32 s3, 0x3ea7ba05
	s_mov_b32 s16, 0xbfb8aa3b
	v_mfma_f32_16x16x32_bf16 v[72:75], v[22:25], v[2:5], 0
	s_mov_b32 s20, 0x3f87dc22
	s_mov_b32 s22, 0x3fb5f0e3
	v_readlane_b32 s25, v252, 5
	v_mfma_f32_16x16x32_bf16 v[76:79], v[26:29], v[2:5], 0
	v_readlane_b32 s26, v252, 6
	s_mov_b32 s24, 0xbe91a98e
	v_readlane_b32 s27, v252, 7
	v_mfma_f32_16x16x32_bf16 v[2:5], v[30:33], v[2:5], 0
	s_mov_b32 s26, 0x3e827906
	v_readlane_b32 s28, v252, 8
	v_readlane_b32 s29, v252, 9
	v_mfma_f32_16x16x32_bf16 v[80:83], v[18:21], v[6:9], 0
	v_mfma_f32_16x16x32_bf16 v[84:87], v[22:25], v[6:9], 0
	v_mfma_f32_16x16x32_bf16 v[88:91], v[26:29], v[6:9], 0
	v_mfma_f32_16x16x32_bf16 v[6:9], v[30:33], v[6:9], 0
	v_mfma_f32_16x16x32_bf16 v[92:95], v[18:21], v[10:13], 0
	v_mfma_f32_16x16x32_bf16 v[96:99], v[22:25], v[10:13], 0
	v_mfma_f32_16x16x32_bf16 v[100:103], v[26:29], v[10:13], 0
	v_mfma_f32_16x16x32_bf16 v[10:13], v[30:33], v[10:13], 0
	v_mfma_f32_16x16x32_bf16 v[22:25], v[22:25], v[14:17], 0
	v_mfma_f32_16x16x32_bf16 v[26:29], v[26:29], v[14:17], 0
	v_mfma_f32_16x16x32_bf16 v[18:21], v[18:21], v[14:17], 0
	v_mfma_f32_16x16x32_bf16 v[14:17], v[30:33], v[14:17], 0
	v_mfma_f32_16x16x32_bf16 v[30:33], v[50:53], v[34:37], v[68:71]
	v_mfma_f32_16x16x32_bf16 v[68:71], v[54:57], v[34:37], v[72:75]
	v_mfma_f32_16x16x32_bf16 v[72:75], v[58:61], v[34:37], v[76:79]
	v_mfma_f32_16x16x32_bf16 v[2:5], v[64:67], v[34:37], v[2:5]
	v_mfma_f32_16x16x32_bf16 v[34:37], v[50:53], v[38:41], v[80:83]
	v_mfma_f32_16x16x32_bf16 v[76:79], v[54:57], v[38:41], v[84:87]
	v_mfma_f32_16x16x32_bf16 v[80:83], v[58:61], v[38:41], v[88:91]
	v_mfma_f32_16x16x32_bf16 v[6:9], v[64:67], v[38:41], v[6:9]
	v_mfma_f32_16x16x32_bf16 v[38:41], v[50:53], v[42:45], v[92:95]
	v_mfma_f32_16x16x32_bf16 v[84:87], v[54:57], v[42:45], v[96:99]
	v_mfma_f32_16x16x32_bf16 v[88:91], v[58:61], v[42:45], v[100:103]
	v_mfma_f32_16x16x32_bf16 v[10:13], v[64:67], v[42:45], v[10:13]
	v_add_u32_e32 v42, 0x8000, v105
	v_or_b32_e32 v116, v42, v104
	v_mfma_f32_16x16x32_bf16 v[22:25], v[54:57], v[46:49], v[22:25]
	v_mfma_f32_16x16x32_bf16 v[26:29], v[58:61], v[46:49], v[26:29]
	v_or_b32_e32 v58, v42, v63
	v_or_b32_e32 v63, v0, v63
	v_or_b32_e32 v0, v0, v104
	v_mfma_f32_16x16x32_bf16 v[18:21], v[50:53], v[46:49], v[18:21]
	ds_read_b128 v[42:45], v58 offset:0
	v_mfma_f32_16x16x32_bf16 v[14:17], v[64:67], v[46:49], v[14:17]
	ds_read_b128 v[46:49], v58 offset:0x800
	ds_read_b128 v[50:53], v58 offset:0x1000
	ds_read_b128 v[54:57], v58 offset:0x1800
	ds_read_b128 v[58:61], v63 offset:0
	ds_read_b128 v[64:67], v63 offset:0x800
	ds_read_b128 v[92:95], v63 offset:0x1000
	ds_read_b128 v[96:99], v63 offset:0x1800
	ds_read_b128 v[100:103], v116 offset:0
	ds_read_b128 v[104:107], v116 offset:0x800
	ds_read_b128 v[108:111], v116 offset:0x1000
	ds_read_b128 v[112:115], v116 offset:0x1800
	ds_read_b128 v[116:119], v0 offset:0
	ds_read_b128 v[120:123], v0 offset:0x800
	ds_read_b128 v[124:127], v0 offset:0x1000
	ds_read_b128 v[128:131], v0 offset:0x1800
	v_ashrrev_i32_e32 v63, 31, v62
	s_waitcnt lgkmcnt(0)
; template <int TRANS, class AP, class BP, class Epi>
; DI void mfma_gemm_tile(const AP& aptr, const BP& bptr, int m0, int n0, int K, const Epi& epi, bf16* lds) {
;     ...
; #pragma unroll
;     for (int kk = 0; kk < 2; ++kk)
; #pragma unroll
;       for (int i = 0; i < 4; ++i)
; #pragma unroll
;         for (int j = 0; j < 4; ++j)
;           acc[i][j] = TRANS ? __builtin_amdgcn_mfma_f32_16x16x32_bf16(af[kk][i], bfr[kk][j], acc[i][j], 0, 0, 0)
;                             : __builtin_amdgcn_mfma_f32_16x16x32_bf16(bfr[kk][j], af[kk][i], acc[i][j], 0, 0, 0);
;   }
;     ...
; #pragma unroll
;   for (int i = 0; i < 4; ++i)
; #pragma unroll
;     for (int j = 0; j < 4; ++j) {
;       if (TRANS) epi(m0 + wm + 16 * i + 4 * lq, n0 + wn + 16 * j + l16, acc[i][j]);
;       else epi(m0 + wm + 16 * i + l16, n0 + wn + 16 * j + 4 * lq, acc[i][j]);
	s_nop 0
	v_mfma_f32_16x16x32_bf16 v[30:33], v[58:61], v[42:45], v[30:33]
	v_mfma_f32_16x16x32_bf16 v[68:71], v[64:67], v[42:45], v[68:71]
	v_mfma_f32_16x16x32_bf16 v[72:75], v[92:95], v[42:45], v[72:75]
	v_mfma_f32_16x16x32_bf16 v[2:5], v[96:99], v[42:45], v[2:5]
	v_mfma_f32_16x16x32_bf16 v[42:45], v[64:67], v[46:49], v[76:79]
	v_mfma_f32_16x16x32_bf16 v[84:87], v[64:67], v[50:53], v[84:87]
	v_mfma_f32_16x16x32_bf16 v[10:13], v[96:99], v[50:53], v[10:13]
	v_mfma_f32_16x16x32_bf16 v[64:67], v[64:67], v[54:57], v[22:25]
	v_mfma_f32_16x16x32_bf16 v[34:37], v[58:61], v[46:49], v[34:37]
	v_mfma_f32_16x16x32_bf16 v[76:79], v[92:95], v[46:49], v[80:83]
	v_mfma_f32_16x16x32_bf16 v[80:83], v[58:61], v[50:53], v[38:41]
	v_mfma_f32_16x16x32_bf16 v[132:135], v[58:61], v[54:57], v[18:21]
	v_mfma_f32_16x16x32_bf16 v[58:61], v[120:123], v[100:103], v[68:71]
	v_mfma_f32_16x16x32_bf16 v[18:21], v[128:131], v[108:111], v[10:13]
	s_nop 1
	v_mov_b64_e32 v[68:69], s[62:63]
	v_mfma_f32_16x16x32_bf16 v[10:13], v[120:123], v[112:115], v[64:67]
	s_nop 2
	v_add_u32_e32 v66, s17, v62
	v_lshl_add_u64 v[64:65], v[62:63], 2, s[0:1]
	v_mad_i64_i32 v[62:63], s[0:1], v66, s78, v[68:69]
	s_lshl_b32 s0, s18, 1
	v_lshl_add_u64 v[62:63], v[62:63], 0, s[34:35]
	v_lshl_or_b32 v0, v140, 3, s0
	v_mfma_f32_16x16x32_bf16 v[6:9], v[96:99], v[46:49], v[6:9]
	global_load_dword v70, v[64:65], off
	s_mov_b32 s18, 0x3f3504f3
	s_mov_b32 s0, 0xbfba00e3
	v_mfma_f32_16x16x32_bf16 v[88:91], v[92:95], v[50:53], v[88:91]
	s_brev_b32 s17, -2
	v_ashrrev_i32_e32 v67, 31, v66
	v_mfma_f32_16x16x32_bf16 v[92:95], v[92:95], v[54:57], v[26:29]
	v_mfma_f32_16x16x32_bf16 v[96:99], v[96:99], v[54:57], v[14:17]
	v_mfma_f32_16x16x32_bf16 v[54:57], v[124:127], v[100:103], v[72:75]
	s_nop 2
	v_lshl_add_u64 v[74:75], v[62:63], 0, v[0:1]
	v_mfma_f32_16x16x32_bf16 v[38:41], v[124:127], v[104:107], v[76:79]
	v_add_co_u32_e32 v72, vcc, s2, v74
	s_nop 1
	global_load_dwordx2 v[76:77], v[74:75], off offset:2048
	v_addc_co_u32_e32 v73, vcc, 0, v75, vcc
	global_load_dwordx2 v[192:193], v[72:73], off
	global_load_dword v194, v[64:65], off
	global_load_dwordx2 v[196:197], v[74:75], off offset:2080
	global_load_dwordx2 v[198:199], v[72:73], off offset:32
	global_load_dword v200, v[64:65], off
	global_load_dwordx2 v[202:203], v[74:75], off offset:2112
	global_load_dwordx2 v[204:205], v[72:73], off offset:64
	global_load_dword v206, v[64:65], off
	global_load_dwordx2 v[208:209], v[74:75], off offset:2144
	global_load_dwordx2 v[210:211], v[72:73], off offset:96
	v_mfma_f32_16x16x32_bf16 v[136:139], v[116:119], v[100:103], v[30:33]
	s_waitcnt vmcnt(9)
	v_lshlrev_b32_e32 v62, 16, v76
	v_and_b32_e32 v63, 0xffff0000, v76
	v_mfma_f32_16x16x32_bf16 v[30:33], v[116:119], v[108:111], v[80:83]
	s_nop 2
	v_mul_f32_e64 v82, v62, s18
	v_mul_f32_e64 v83, v63, s18
	v_mfma_f32_16x16x32_bf16 v[26:29], v[120:123], v[108:111], v[84:87]
	v_fma_f32 v71, |v82|, s3, 1.0
	v_lshlrev_b32_e32 v80, 16, v192
	v_and_b32_e32 v81, 0xffff0000, v192
	v_rcp_f32_e32 v84, v71
	v_mul_f32_e64 v71, |v82|, s16
	v_mul_f32_e64 v71, |v82|, v71
	v_exp_f32_e32 v86, v71
	v_mul_f32_e32 v71, 0xbfb8aa3b, v80
	v_exp_f32_e32 v71, v71
	v_mfma_f32_16x16x32_bf16 v[22:25], v[124:127], v[108:111], v[88:91]
	v_lshlrev_b32_e32 v78, 16, v193
	v_and_b32_e32 v79, 0xffff0000, v193
	v_add_f32_e32 v71, 1.0, v71
	v_pk_mul_f32 v[90:91], v[62:63], 0.5 op_sel_hi:[1,0]
	v_fma_f32 v62, |v83|, s3, 1.0
	v_rcp_f32_e32 v85, v62
	v_rcp_f32_e32 v88, v71
	v_mov_b64_e32 v[62:63], s[0:1]
	v_mul_f32_e64 v71, |v83|, s16
	v_mfma_f32_16x16x32_bf16 v[46:49], v[116:119], v[104:107], v[34:37]
	v_mul_f32_e64 v71, |v83|, v71
	v_exp_f32_e32 v87, v71
	v_mfma_f32_16x16x32_bf16 v[34:37], v[128:131], v[104:107], v[6:9]
	v_mfma_f32_16x16x32_bf16 v[6:9], v[124:127], v[112:115], v[92:95]
	s_nop 2
	v_fma_f32 v92, v84, s20, v62
	v_fma_f32 v93, v85, s20, v62
	v_mfma_f32_16x16x32_bf16 v[50:53], v[128:131], v[100:103], v[2:5]
	v_fma_f32 v92, v84, v92, s22
	v_fma_f32 v93, v85, v93, s22
	v_pk_fma_f32 v[92:93], v[84:85], v[92:93], s[24:25] op_sel_hi:[1,1,0]
	v_mfma_f32_16x16x32_bf16 v[42:45], v[120:123], v[104:107], v[42:45]
	v_fma_f32 v92, v84, v92, s26
	v_fma_f32 v93, v85, v93, s26
	v_pk_mul_f32 v[84:85], v[84:85], v[92:93]
	v_mfma_f32_16x16x32_bf16 v[14:17], v[116:119], v[112:115], v[132:135]
	v_fma_f32 v84, -v86, v84, 1.0
	v_fma_f32 v85, -v87, v85, 1.0
	v_bfi_b32 v83, s17, v85, v83
	v_bfi_b32 v82, s17, v84, v82
	v_pk_add_f32 v[84:85], v[136:137], v[70:71] op_sel_hi:[1,0]
	v_mul_f32_e32 v71, 0xbfb8aa3b, v81
	v_exp_f32_e32 v71, v71
	v_pk_add_f32 v[82:83], v[82:83], 1.0 op_sel_hi:[1,0]
	v_mfma_f32_16x16x32_bf16 v[2:5], v[128:131], v[112:115], v[96:99]
	v_mul_f32_e64 v82, v90, v82
	v_mul_f32_e64 v83, v91, v83
	v_add_f32_e32 v71, 1.0, v71
	v_rcp_f32_e32 v89, v71
	v_pk_mul_f32 v[82:83], v[84:85], v[82:83]
	v_pk_mul_f32 v[80:81], v[88:89], v[80:81]
	s_nop 0
	v_pk_mul_f32 v[80:81], v[80:81], v[82:83]
	s_nop 0
	v_cvt_pk_bf16_f32 v76, v80, v81
	v_lshlrev_b32_e32 v80, 16, v77
	v_and_b32_e32 v81, 0xffff0000, v77
	v_pk_mul_f32 v[82:83], v[80:81], s[18:19] op_sel_hi:[1,0]
	v_mul_f32_e32 v77, 0xbfb8aa3b, v79
	v_fma_f32 v71, |v82|, s3, 1.0
	v_rcp_f32_e32 v84, v71
	v_mul_f32_e64 v71, |v82|, s16
	v_mul_f32_e64 v71, |v82|, v71
	v_exp_f32_e32 v86, v71
	v_mul_f32_e32 v71, 0xbfb8aa3b, v78
	v_exp_f32_e32 v71, v71
	v_exp_f32_e32 v77, v77
	v_pk_mul_f32 v[80:81], v[80:81], 0.5 op_sel_hi:[1,0]
	v_add_f32_e32 v71, 1.0, v71
	v_rcp_f32_e32 v88, v71
	v_fma_f32 v71, |v83|, s3, 1.0
	v_rcp_f32_e32 v85, v71
	v_mul_f32_e64 v71, |v83|, s16
	v_mul_f32_e64 v71, |v83|, v71
	v_exp_f32_e32 v87, v71
	v_pk_fma_f32 v[90:91], v[84:85], s[20:21], v[62:63] op_sel_hi:[1,0,0]
; DI float erf_as(float x) {
;   const float ax = fabsf(x);
;   const float t = __builtin_amdgcn_rcpf(1.f + 0.3275911f * ax);
;   const float poly = t * (0.254829592f + t * (-0.284496736f + t * (1.421413741f + t * (-1.453152027f + t * 1.061405429f))));
;   const float y = 1.f - poly * __builtin_amdgcn_exp2f(-1.4426950408889634f * ax * ax);
;   return copysignf(y, x);
; }
; DI float gelu(float x) { return 0.5f * x * (1.f + erf_as(x * 0.70710678118654752f)); }
	v_add_f32_e32 v77, 1.0, v77
	v_pk_fma_f32 v[90:91], v[84:85], v[90:91], s[22:23] op_sel_hi:[1,1,0]
	v_rcp_f32_e32 v89, v77
	v_pk_fma_f32 v[90:91], v[84:85], v[90:91], s[24:25] op_sel_hi:[1,1,0]
	v_pk_add_f32 v[70:71], v[138:139], v[70:71] op_sel_hi:[1,0]
	v_pk_fma_f32 v[90:91], v[84:85], v[90:91], s[26:27] op_sel_hi:[1,1,0]
	v_pk_mul_f32 v[78:79], v[88:89], v[78:79]
	v_pk_mul_f32 v[84:85], v[84:85], v[90:91]
	s_nop 0
	v_pk_fma_f32 v[84:85], v[86:87], v[84:85], 1.0 op_sel_hi:[1,1,0] neg_lo:[1,0,0] neg_hi:[1,0,0]
	s_nop 0
	v_bfi_b32 v83, s17, v85, v83
	v_bfi_b32 v82, s17, v84, v82
	v_pk_add_f32 v[82:83], v[82:83], 1.0 op_sel_hi:[1,0]
	s_nop 0
	v_pk_mul_f32 v[80:81], v[80:81], v[82:83]
	s_nop 0
	v_pk_mul_f32 v[70:71], v[70:71], v[80:81]
	s_nop 0
	v_pk_mul_f32 v[70:71], v[78:79], v[70:71]
	s_nop 0
	v_cvt_pk_bf16_f32 v77, v70, v71
	v_lshlrev_b64 v[70:71], 11, v[66:67]
	v_lshl_add_u64 v[70:71], s[60:61], 0, v[70:71]
	v_lshl_add_u64 v[70:71], v[70:71], 0, s[34:35]
	v_lshl_add_u64 v[70:71], v[70:71], 0, v[0:1]
	v_readlane_b32 s28, v254, 31
	v_readlane_b32 s29, v254, 32
	v_subrev_u32_e32 v141, s28, v70
	v_add_u32_e32 v141, 0x400, v141
	v_and_b32_e32 v142, 0x7c0, v141
	v_and_b32_e32 v143, 0xfffff7ff, v141
	v_add_u32_e32 v143, v143, v142
	v_bfe_u32 v142, v141, 11, 1
	v_lshl_or_b32 v143, v142, 6, v143
	v_bfe_i32 v142, v141, 25, 1
	v_bfi_b32 v143, v142, v141, v143
	global_store_dwordx2 v143, v[76:77], s[28:29]
	s_nop 0
	s_waitcnt vmcnt(7)
	v_pk_add_f32 v[58:59], v[58:59], v[194:195] op_sel_hi:[1,0]
	v_lshlrev_b32_e32 v82, 16, v196
	v_and_b32_e32 v83, 0xffff0000, v196
	v_pk_mul_f32 v[86:87], v[82:83], s[18:19] op_sel_hi:[1,0]
	v_lshlrev_b32_e32 v84, 16, v198
	v_fma_f32 v67, |v86|, s3, 1.0
	v_rcp_f32_e32 v88, v67
	v_mul_f32_e64 v67, |v86|, s16
	v_mul_f32_e64 v67, |v86|, v67
	v_exp_f32_e32 v90, v67
	v_mul_f32_e32 v67, 0xbfb8aa3b, v84
	v_exp_f32_e32 v67, v67
	v_and_b32_e32 v85, 0xffff0000, v198
	v_pk_mul_f32 v[82:83], v[82:83], 0.5 op_sel_hi:[1,0]
	v_lshlrev_b32_e32 v78, 16, v197
	v_add_f32_e32 v67, 1.0, v67
	v_rcp_f32_e32 v92, v67
	v_fma_f32 v67, |v87|, s3, 1.0
	v_rcp_f32_e32 v89, v67
	v_mul_f32_e64 v67, |v87|, s16
	v_mul_f32_e64 v67, |v87|, v67
	v_exp_f32_e32 v91, v67
	v_mul_f32_e32 v67, 0xbfb8aa3b, v85
	v_pk_fma_f32 v[94:95], v[88:89], s[20:21], v[62:63] op_sel_hi:[1,0,0]
	v_exp_f32_e32 v67, v67
	v_pk_fma_f32 v[94:95], v[88:89], v[94:95], s[22:23] op_sel_hi:[1,1,0]
	v_and_b32_e32 v79, 0xffff0000, v197
	v_pk_fma_f32 v[94:95], v[88:89], v[94:95], s[24:25] op_sel_hi:[1,1,0]
	v_add_f32_e32 v67, 1.0, v67
	v_pk_fma_f32 v[94:95], v[88:89], v[94:95], s[26:27] op_sel_hi:[1,1,0]
	v_rcp_f32_e32 v93, v67
	v_pk_mul_f32 v[88:89], v[88:89], v[94:95]
	v_lshlrev_b32_e32 v80, 16, v199
	v_pk_fma_f32 v[88:89], v[90:91], v[88:89], 1.0 op_sel_hi:[1,1,0] neg_lo:[1,0,0] neg_hi:[1,0,0]
	v_and_b32_e32 v81, 0xffff0000, v199
	v_bfi_b32 v87, s17, v89, v87
	v_bfi_b32 v86, s17, v88, v86
	v_pk_add_f32 v[86:87], v[86:87], 1.0 op_sel_hi:[1,0]
	v_pk_add_f32 v[60:61], v[60:61], v[194:195] op_sel_hi:[1,0]
	v_pk_mul_f32 v[82:83], v[82:83], v[86:87]
	s_nop 0
	v_pk_mul_f32 v[58:59], v[58:59], v[82:83]
	v_pk_mul_f32 v[82:83], v[92:93], v[84:85]
	s_nop 0
	v_pk_mul_f32 v[58:59], v[82:83], v[58:59]
	v_pk_mul_f32 v[82:83], v[78:79], s[18:19] op_sel_hi:[1,0]
	v_cvt_pk_bf16_f32 v58, v58, v59
	v_fma_f32 v59, |v82|, s3, 1.0
	v_rcp_f32_e32 v84, v59
	v_mul_f32_e64 v59, |v82|, s16
	v_mul_f32_e64 v59, |v82|, v59
	v_exp_f32_e32 v86, v59
	v_mul_f32_e32 v59, 0xbfb8aa3b, v80
	v_exp_f32_e32 v59, v59
	v_pk_mul_f32 v[78:79], v[78:79], 0.5 op_sel_hi:[1,0]
	v_add_f32_e32 v59, 1.0, v59
	v_rcp_f32_e32 v88, v59
	v_fma_f32 v59, |v83|, s3, 1.0
	v_rcp_f32_e32 v85, v59
	v_mul_f32_e64 v59, |v83|, s16
	v_mul_f32_e64 v59, |v83|, v59
	v_exp_f32_e32 v87, v59
	v_mul_f32_e32 v59, 0xbfb8aa3b, v81
	v_pk_fma_f32 v[90:91], v[84:85], s[20:21], v[62:63] op_sel_hi:[1,0,0]
	v_exp_f32_e32 v59, v59
	v_pk_fma_f32 v[90:91], v[84:85], v[90:91], s[22:23] op_sel_hi:[1,1,0]
	v_add_f32_e32 v59, 1.0, v59
	v_pk_fma_f32 v[90:91], v[84:85], v[90:91], s[24:25] op_sel_hi:[1,1,0]
	v_rcp_f32_e32 v89, v59
	v_pk_fma_f32 v[90:91], v[84:85], v[90:91], s[26:27] op_sel_hi:[1,1,0]
	v_pk_mul_f32 v[76:77], v[88:89], v[80:81]
	v_pk_mul_f32 v[84:85], v[84:85], v[90:91]
	s_nop 0
	v_pk_fma_f32 v[84:85], v[86:87], v[84:85], 1.0 op_sel_hi:[1,1,0] neg_lo:[1,0,0] neg_hi:[1,0,0]
	s_nop 0
	v_bfi_b32 v83, s17, v85, v83
	v_bfi_b32 v82, s17, v84, v82
	v_pk_add_f32 v[82:83], v[82:83], 1.0 op_sel_hi:[1,0]
	s_nop 0
	v_pk_mul_f32 v[78:79], v[78:79], v[82:83]
	s_nop 0
	v_pk_mul_f32 v[60:61], v[60:61], v[78:79]
	s_nop 0
	v_pk_mul_f32 v[60:61], v[76:77], v[60:61]
	s_nop 0
	v_cvt_pk_bf16_f32 v59, v60, v61
	v_readlane_b32 s28, v254, 31
	v_readlane_b32 s29, v254, 32
	v_subrev_u32_e32 v141, s28, v70
	v_add_u32_e32 v141, 0x420, v141
	v_and_b32_e32 v142, 0x7c0, v141
	v_and_b32_e32 v143, 0xfffff7ff, v141
	v_add_u32_e32 v143, v143, v142
	v_bfe_u32 v142, v141, 11, 1
	v_lshl_or_b32 v143, v142, 6, v143
	v_bfe_i32 v142, v141, 25, 1
	v_bfi_b32 v143, v142, v141, v143
	global_store_dwordx2 v143, v[58:59], s[28:29]
	s_nop 0
	s_waitcnt vmcnt(5)
; DI float erf_as(float x) {
;   const float ax = fabsf(x);
;   const float t = __builtin_amdgcn_rcpf(1.f + 0.3275911f * ax);
;   const float poly = t * (0.254829592f + t * (-0.284496736f + t * (1.421413741f + t * (-1.453152027f + t * 1.061405429f))));
;   const float y = 1.f - poly * __builtin_amdgcn_exp2f(-1.4426950408889634f * ax * ax);
;   return copysignf(y, x);
; }
; DI float gelu(float x) { return 0.5f * x * (1.f + erf_as(x * 0.70710678118654752f)); }
	v_lshlrev_b32_e32 v78, 16, v202
	v_and_b32_e32 v79, 0xffff0000, v202
	v_pk_mul_f32 v[82:83], v[78:79], s[18:19] op_sel_hi:[1,0]
	v_lshlrev_b32_e32 v80, 16, v204
	v_fma_f32 v59, |v82|, s3, 1.0
	v_rcp_f32_e32 v84, v59
	v_mul_f32_e64 v59, |v82|, s16
	v_mul_f32_e64 v59, |v82|, v59
	v_exp_f32_e32 v86, v59
	v_mul_f32_e32 v59, 0xbfb8aa3b, v80
	v_exp_f32_e32 v59, v59
	v_and_b32_e32 v81, 0xffff0000, v204
	v_pk_mul_f32 v[78:79], v[78:79], 0.5 op_sel_hi:[1,0]
	v_lshlrev_b32_e32 v60, 16, v203
	v_add_f32_e32 v59, 1.0, v59
	v_rcp_f32_e32 v88, v59
	v_fma_f32 v59, |v83|, s3, 1.0
	v_rcp_f32_e32 v85, v59
	v_mul_f32_e64 v59, |v83|, s16
	v_mul_f32_e64 v59, |v83|, v59
	v_exp_f32_e32 v87, v59
	v_pk_add_f32 v[54:55], v[54:55], v[200:201] op_sel_hi:[1,0]
	v_mul_f32_e32 v59, 0xbfb8aa3b, v81
	v_pk_fma_f32 v[90:91], v[84:85], s[20:21], v[62:63] op_sel_hi:[1,0,0]
	v_exp_f32_e32 v59, v59
	v_pk_fma_f32 v[90:91], v[84:85], v[90:91], s[22:23] op_sel_hi:[1,1,0]
	v_and_b32_e32 v61, 0xffff0000, v203
	v_pk_fma_f32 v[90:91], v[84:85], v[90:91], s[24:25] op_sel_hi:[1,1,0]
	v_add_f32_e32 v59, 1.0, v59
	v_pk_fma_f32 v[90:91], v[84:85], v[90:91], s[26:27] op_sel_hi:[1,1,0]
	v_rcp_f32_e32 v89, v59
	v_pk_mul_f32 v[84:85], v[84:85], v[90:91]
	v_lshlrev_b32_e32 v76, 16, v205
	v_pk_fma_f32 v[84:85], v[86:87], v[84:85], 1.0 op_sel_hi:[1,1,0] neg_lo:[1,0,0] neg_hi:[1,0,0]
	v_and_b32_e32 v77, 0xffff0000, v205
	v_bfi_b32 v83, s17, v85, v83
	v_bfi_b32 v82, s17, v84, v82
	v_pk_add_f32 v[82:83], v[82:83], 1.0 op_sel_hi:[1,0]
	v_pk_add_f32 v[56:57], v[56:57], v[200:201] op_sel_hi:[1,0]
	v_pk_mul_f32 v[78:79], v[78:79], v[82:83]
	s_nop 0
	v_pk_mul_f32 v[54:55], v[54:55], v[78:79]
	v_pk_mul_f32 v[78:79], v[88:89], v[80:81]
	s_nop 0
	v_pk_mul_f32 v[54:55], v[78:79], v[54:55]
	v_pk_mul_f32 v[78:79], v[60:61], s[18:19] op_sel_hi:[1,0]
	v_cvt_pk_bf16_f32 v54, v54, v55
	v_fma_f32 v55, |v78|, s3, 1.0
	v_rcp_f32_e32 v80, v55
	v_mul_f32_e64 v55, |v78|, s16
	v_mul_f32_e64 v55, |v78|, v55
	v_exp_f32_e32 v82, v55
	v_mul_f32_e32 v55, 0xbfb8aa3b, v76
	v_exp_f32_e32 v55, v55
	v_pk_mul_f32 v[60:61], v[60:61], 0.5 op_sel_hi:[1,0]
	v_add_f32_e32 v55, 1.0, v55
	v_rcp_f32_e32 v84, v55
	v_fma_f32 v55, |v79|, s3, 1.0
	v_rcp_f32_e32 v81, v55
	v_mul_f32_e64 v55, |v79|, s16
	v_mul_f32_e64 v55, |v79|, v55
	v_exp_f32_e32 v83, v55
	v_mul_f32_e32 v55, 0xbfb8aa3b, v77
	v_pk_fma_f32 v[86:87], v[80:81], s[20:21], v[62:63] op_sel_hi:[1,0,0]
	v_exp_f32_e32 v55, v55
	v_pk_fma_f32 v[86:87], v[80:81], v[86:87], s[22:23] op_sel_hi:[1,1,0]
	v_add_f32_e32 v55, 1.0, v55
	v_pk_fma_f32 v[86:87], v[80:81], v[86:87], s[24:25] op_sel_hi:[1,1,0]
	v_rcp_f32_e32 v85, v55
	v_pk_fma_f32 v[86:87], v[80:81], v[86:87], s[26:27] op_sel_hi:[1,1,0]
	v_pk_mul_f32 v[58:59], v[84:85], v[76:77]
	v_pk_mul_f32 v[80:81], v[80:81], v[86:87]
	s_nop 0
	v_pk_fma_f32 v[80:81], v[82:83], v[80:81], 1.0 op_sel_hi:[1,1,0] neg_lo:[1,0,0] neg_hi:[1,0,0]
	s_nop 0
	v_bfi_b32 v79, s17, v81, v79
	v_bfi_b32 v78, s17, v80, v78
	v_pk_add_f32 v[78:79], v[78:79], 1.0 op_sel_hi:[1,0]
	s_nop 0
	v_pk_mul_f32 v[60:61], v[60:61], v[78:79]
	s_nop 0
	v_pk_mul_f32 v[56:57], v[56:57], v[60:61]
	s_nop 0
	v_pk_mul_f32 v[56:57], v[58:59], v[56:57]
	s_nop 0
	v_cvt_pk_bf16_f32 v55, v56, v57
	v_readlane_b32 s28, v254, 31
	v_readlane_b32 s29, v254, 32
	v_subrev_u32_e32 v141, s28, v70
	v_add_u32_e32 v141, 0x440, v141
	v_and_b32_e32 v142, 0x7c0, v141
	v_and_b32_e32 v143, 0xfffff7ff, v141
	v_add_u32_e32 v143, v143, v142
	v_bfe_u32 v142, v141, 11, 1
	v_lshl_or_b32 v143, v142, 6, v143
	v_bfe_i32 v142, v141, 25, 1
	v_bfi_b32 v143, v142, v141, v143
	global_store_dwordx2 v143, v[54:55], s[28:29]
	s_nop 0
	s_waitcnt vmcnt(3)
	v_lshlrev_b32_e32 v60, 16, v208
	v_and_b32_e32 v61, 0xffff0000, v208
	v_pk_mul_f32 v[74:75], v[60:61], s[18:19] op_sel_hi:[1,0]
	v_lshlrev_b32_e32 v72, 16, v210
	v_fma_f32 v55, |v74|, s3, 1.0
	v_rcp_f32_e32 v76, v55
	v_mul_f32_e64 v55, |v74|, s16
	v_mul_f32_e64 v55, |v74|, v55
	v_exp_f32_e32 v78, v55
	v_mul_f32_e32 v55, 0xbfb8aa3b, v72
	v_exp_f32_e32 v55, v55
	v_and_b32_e32 v73, 0xffff0000, v210
	v_pk_mul_f32 v[60:61], v[60:61], 0.5 op_sel_hi:[1,0]
	v_lshlrev_b32_e32 v56, 16, v209
	v_add_f32_e32 v55, 1.0, v55
	v_rcp_f32_e32 v80, v55
	v_fma_f32 v55, |v75|, s3, 1.0
	v_rcp_f32_e32 v77, v55
	v_mul_f32_e64 v55, |v75|, s16
	v_mul_f32_e64 v55, |v75|, v55
	v_exp_f32_e32 v79, v55
	v_pk_add_f32 v[50:51], v[50:51], v[206:207] op_sel_hi:[1,0]
	v_mul_f32_e32 v55, 0xbfb8aa3b, v73
	v_pk_fma_f32 v[82:83], v[76:77], s[20:21], v[62:63] op_sel_hi:[1,0,0]
	v_exp_f32_e32 v55, v55
	v_pk_fma_f32 v[82:83], v[76:77], v[82:83], s[22:23] op_sel_hi:[1,1,0]
	v_and_b32_e32 v57, 0xffff0000, v209
	v_pk_fma_f32 v[82:83], v[76:77], v[82:83], s[24:25] op_sel_hi:[1,1,0]
	v_add_f32_e32 v55, 1.0, v55
	v_pk_fma_f32 v[82:83], v[76:77], v[82:83], s[26:27] op_sel_hi:[1,1,0]
	v_rcp_f32_e32 v81, v55
	v_pk_mul_f32 v[76:77], v[76:77], v[82:83]
	v_lshlrev_b32_e32 v58, 16, v211
	v_pk_fma_f32 v[76:77], v[78:79], v[76:77], 1.0 op_sel_hi:[1,1,0] neg_lo:[1,0,0] neg_hi:[1,0,0]
	v_and_b32_e32 v59, 0xffff0000, v211
	v_bfi_b32 v75, s17, v77, v75
	v_bfi_b32 v74, s17, v76, v74
	v_pk_add_f32 v[74:75], v[74:75], 1.0 op_sel_hi:[1,0]
	v_pk_add_f32 v[52:53], v[52:53], v[206:207] op_sel_hi:[1,0]
	v_pk_mul_f32 v[60:61], v[60:61], v[74:75]
	s_nop 0
	v_pk_mul_f32 v[50:51], v[50:51], v[60:61]
	v_pk_mul_f32 v[60:61], v[80:81], v[72:73]
	s_nop 0
	v_pk_mul_f32 v[50:51], v[60:61], v[50:51]
	v_pk_mul_f32 v[60:61], v[56:57], s[18:19] op_sel_hi:[1,0]
	v_cvt_pk_bf16_f32 v50, v50, v51
	v_fma_f32 v51, |v60|, s3, 1.0
	v_rcp_f32_e32 v72, v51
	v_mul_f32_e64 v51, |v60|, s16
	v_mul_f32_e64 v51, |v60|, v51
	v_exp_f32_e32 v74, v51
	v_mul_f32_e32 v51, 0xbfb8aa3b, v58
; DI float erf_as(float x) {
;   const float ax = fabsf(x);
;   const float t = __builtin_amdgcn_rcpf(1.f + 0.3275911f * ax);
;   const float poly = t * (0.254829592f + t * (-0.284496736f + t * (1.421413741f + t * (-1.453152027f + t * 1.061405429f))));
;   const float y = 1.f - poly * __builtin_amdgcn_exp2f(-1.4426950408889634f * ax * ax);
;   return copysignf(y, x);
; }
; DI float gelu(float x) { return 0.5f * x * (1.f + erf_as(x * 0.70710678118654752f)); }
	v_exp_f32_e32 v51, v51
	v_pk_mul_f32 v[56:57], v[56:57], 0.5 op_sel_hi:[1,0]
	v_add_f32_e32 v51, 1.0, v51
	v_rcp_f32_e32 v76, v51
	v_fma_f32 v51, |v61|, s3, 1.0
	v_rcp_f32_e32 v73, v51
	v_mul_f32_e64 v51, |v61|, s16
	v_mul_f32_e64 v51, |v61|, v51
	v_exp_f32_e32 v75, v51
	v_mul_f32_e32 v51, 0xbfb8aa3b, v59
	v_pk_fma_f32 v[78:79], v[72:73], s[20:21], v[62:63] op_sel_hi:[1,0,0]
	v_exp_f32_e32 v51, v51
	v_pk_fma_f32 v[78:79], v[72:73], v[78:79], s[22:23] op_sel_hi:[1,1,0]
	v_add_f32_e32 v51, 1.0, v51
	v_pk_fma_f32 v[78:79], v[72:73], v[78:79], s[24:25] op_sel_hi:[1,1,0]
	v_rcp_f32_e32 v77, v51
	v_pk_fma_f32 v[78:79], v[72:73], v[78:79], s[26:27] op_sel_hi:[1,1,0]
	v_pk_mul_f32 v[54:55], v[76:77], v[58:59]
	v_pk_mul_f32 v[72:73], v[72:73], v[78:79]
	s_nop 0
	v_pk_fma_f32 v[72:73], v[74:75], v[72:73], 1.0 op_sel_hi:[1,1,0] neg_lo:[1,0,0] neg_hi:[1,0,0]
	s_nop 0
	v_bfi_b32 v61, s17, v73, v61
	v_bfi_b32 v60, s17, v72, v60
	v_pk_add_f32 v[60:61], v[60:61], 1.0 op_sel_hi:[1,0]
	s_nop 0
	v_pk_mul_f32 v[56:57], v[56:57], v[60:61]
	s_nop 0
	v_pk_mul_f32 v[52:53], v[52:53], v[56:57]
	s_nop 0
	v_pk_mul_f32 v[52:53], v[54:55], v[52:53]
	v_or_b32_e32 v54, 16, v66
	v_cvt_pk_bf16_f32 v51, v52, v53
	v_readlane_b32 s28, v254, 31
	v_readlane_b32 s29, v254, 32
	v_subrev_u32_e32 v141, s28, v70
	v_add_u32_e32 v141, 0x460, v141
	v_and_b32_e32 v142, 0x7c0, v141
	v_and_b32_e32 v143, 0xfffff7ff, v141
	v_add_u32_e32 v143, v143, v142
	v_bfe_u32 v142, v141, 11, 1
	v_lshl_or_b32 v143, v142, 6, v143
	v_bfe_i32 v142, v141, 25, 1
	v_bfi_b32 v143, v142, v141, v143
	global_store_dwordx2 v143, v[50:51], s[28:29]
	v_mad_i64_i32 v[50:51], s[0:1], v54, s78, v[68:69]
	v_lshl_add_u64 v[50:51], v[50:51], 0, s[34:35]
	v_lshl_add_u64 v[52:53], v[50:51], 0, v[0:1]
	global_load_dwordx2 v[58:59], v[52:53], off offset:2048
	v_add_co_u32_e32 v50, vcc, s2, v52
	global_load_dword v56, v[64:65], off offset:64
	s_nop 0
	v_addc_co_u32_e32 v51, vcc, 0, v53, vcc
	global_load_dwordx2 v[212:213], v[50:51], off
	global_load_dword v214, v[64:65], off offset:64
	global_load_dwordx2 v[216:217], v[52:53], off offset:2080
	global_load_dwordx2 v[218:219], v[50:51], off offset:32
	global_load_dword v220, v[64:65], off offset:64
	global_load_dwordx2 v[222:223], v[52:53], off offset:2112
	global_load_dwordx2 v[224:225], v[50:51], off offset:64
	global_load_dword v226, v[64:65], off offset:64
	global_load_dwordx2 v[228:229], v[52:53], off offset:2144
	global_load_dwordx2 v[230:231], v[50:51], off offset:96
	v_ashrrev_i32_e32 v55, 31, v54
	s_waitcnt vmcnt(9)
	v_lshlrev_b32_e32 v70, 16, v58
	v_and_b32_e32 v71, 0xffff0000, v58
	v_pk_mul_f32 v[74:75], v[70:71], s[18:19] op_sel_hi:[1,0]
	v_pk_mul_f32 v[70:71], v[70:71], 0.5 op_sel_hi:[1,0]
	v_fma_f32 v57, |v74|, s3, 1.0
	v_rcp_f32_e32 v76, v57
	v_mul_f32_e64 v57, |v74|, s16
	v_lshlrev_b32_e32 v72, 16, v212
	v_mul_f32_e64 v57, |v74|, v57
	v_exp_f32_e32 v78, v57
	v_mul_f32_e32 v57, 0xbfb8aa3b, v72
	v_exp_f32_e32 v57, v57
	v_and_b32_e32 v73, 0xffff0000, v212
	v_lshlrev_b32_e32 v60, 16, v213
	v_and_b32_e32 v61, 0xffff0000, v213
	v_add_f32_e32 v57, 1.0, v57
	v_rcp_f32_e32 v80, v57
	v_fma_f32 v57, |v75|, s3, 1.0
	v_rcp_f32_e32 v77, v57
	v_mul_f32_e64 v57, |v75|, s16
	v_mul_f32_e64 v57, |v75|, v57
	v_exp_f32_e32 v79, v57
	v_pk_add_f32 v[46:47], v[46:47], v[56:57] op_sel_hi:[1,0]
	v_mul_f32_e32 v57, 0xbfb8aa3b, v73
	v_pk_fma_f32 v[82:83], v[76:77], s[20:21], v[62:63] op_sel_hi:[1,0,0]
	v_exp_f32_e32 v57, v57
	v_pk_fma_f32 v[82:83], v[76:77], v[82:83], s[22:23] op_sel_hi:[1,1,0]
	v_add_f32_e32 v57, 1.0, v57
	v_pk_fma_f32 v[82:83], v[76:77], v[82:83], s[24:25] op_sel_hi:[1,1,0]
	v_rcp_f32_e32 v81, v57
	v_pk_fma_f32 v[82:83], v[76:77], v[82:83], s[26:27] op_sel_hi:[1,1,0]
	s_nop 0
	v_pk_mul_f32 v[76:77], v[76:77], v[82:83]
	s_nop 0
	v_pk_fma_f32 v[76:77], v[78:79], v[76:77], 1.0 op_sel_hi:[1,1,0] neg_lo:[1,0,0] neg_hi:[1,0,0]
	s_nop 0
	v_bfi_b32 v75, s17, v77, v75
	v_bfi_b32 v74, s17, v76, v74
	v_pk_add_f32 v[74:75], v[74:75], 1.0 op_sel_hi:[1,0]
	s_nop 0
	v_pk_mul_f32 v[70:71], v[70:71], v[74:75]
	s_nop 0
	v_pk_mul_f32 v[46:47], v[46:47], v[70:71]
	v_pk_mul_f32 v[70:71], v[80:81], v[72:73]
	s_nop 0
	v_pk_mul_f32 v[46:47], v[70:71], v[46:47]
	s_nop 0
	v_cvt_pk_bf16_f32 v58, v46, v47
	v_lshlrev_b32_e32 v46, 16, v59
	v_and_b32_e32 v47, 0xffff0000, v59
	v_pk_mul_f32 v[70:71], v[46:47], s[18:19] op_sel_hi:[1,0]
	v_pk_mul_f32 v[46:47], v[46:47], 0.5 op_sel_hi:[1,0]
	v_fma_f32 v57, |v70|, s3, 1.0
	v_rcp_f32_e32 v72, v57
	v_mul_f32_e64 v57, |v70|, s16
	v_mul_f32_e64 v57, |v70|, v57
	v_exp_f32_e32 v74, v57
	v_mul_f32_e32 v57, 0xbfb8aa3b, v60
	v_exp_f32_e32 v57, v57
	s_nop 0
	v_add_f32_e32 v57, 1.0, v57
	v_rcp_f32_e32 v76, v57
	v_fma_f32 v57, |v71|, s3, 1.0
	v_rcp_f32_e32 v73, v57
	v_mul_f32_e64 v57, |v71|, s16
	v_mul_f32_e64 v57, |v71|, v57
	v_exp_f32_e32 v75, v57
	v_pk_fma_f32 v[78:79], v[72:73], s[20:21], v[62:63] op_sel_hi:[1,0,0]
	v_pk_add_f32 v[48:49], v[48:49], v[56:57] op_sel_hi:[1,0]
	v_pk_fma_f32 v[78:79], v[72:73], v[78:79], s[22:23] op_sel_hi:[1,1,0]
	s_nop 0
	v_pk_fma_f32 v[78:79], v[72:73], v[78:79], s[24:25] op_sel_hi:[1,1,0]
	s_nop 0
	v_pk_fma_f32 v[78:79], v[72:73], v[78:79], s[26:27] op_sel_hi:[1,1,0]
	s_nop 0
	v_pk_mul_f32 v[72:73], v[72:73], v[78:79]
	s_nop 0
	v_pk_fma_f32 v[72:73], v[74:75], v[72:73], 1.0 op_sel_hi:[1,1,0] neg_lo:[1,0,0] neg_hi:[1,0,0]
	s_nop 0
	v_bfi_b32 v71, s17, v73, v71
	v_bfi_b32 v70, s17, v72, v70
	v_pk_add_f32 v[70:71], v[70:71], 1.0 op_sel_hi:[1,0]
	s_nop 0
	v_pk_mul_f32 v[46:47], v[46:47], v[70:71]
	s_nop 0
	v_pk_mul_f32 v[46:47], v[48:49], v[46:47]
	v_mul_f32_e32 v48, 0xbfb8aa3b, v61
	v_exp_f32_e32 v48, v48
	s_nop 0
	v_add_f32_e32 v48, 1.0, v48
	v_rcp_f32_e32 v77, v48
	s_nop 0
	v_pk_mul_f32 v[48:49], v[76:77], v[60:61]
	s_nop 0
	v_pk_mul_f32 v[46:47], v[48:49], v[46:47]
	s_nop 0
	v_cvt_pk_bf16_f32 v59, v46, v47
	v_lshlrev_b64 v[46:47], 11, v[54:55]
	v_lshl_add_u64 v[46:47], s[60:61], 0, v[46:47]
	v_lshl_add_u64 v[46:47], v[46:47], 0, s[34:35]
	v_lshl_add_u64 v[46:47], v[46:47], 0, v[0:1]
	v_readlane_b32 s28, v254, 31
	v_readlane_b32 s29, v254, 32
	v_subrev_u32_e32 v141, s28, v46
	v_add_u32_e32 v141, 0x400, v141
	v_and_b32_e32 v142, 0x7c0, v141
	v_and_b32_e32 v143, 0xfffff7ff, v141
	v_add_u32_e32 v143, v143, v142
	v_bfe_u32 v142, v141, 11, 1
	v_lshl_or_b32 v143, v142, 6, v143
	v_bfe_i32 v142, v141, 25, 1
	v_bfi_b32 v143, v142, v141, v143
	global_store_dwordx2 v143, v[58:59], s[28:29]
	s_waitcnt vmcnt(7)
; DI float erf_as(float x) {
;   const float ax = fabsf(x);
;   const float t = __builtin_amdgcn_rcpf(1.f + 0.3275911f * ax);
;   const float poly = t * (0.254829592f + t * (-0.284496736f + t * (1.421413741f + t * (-1.453152027f + t * 1.061405429f))));
;   const float y = 1.f - poly * __builtin_amdgcn_exp2f(-1.4426950408889634f * ax * ax);
;   return copysignf(y, x);
; }
; DI float gelu(float x) { return 0.5f * x * (1.f + erf_as(x * 0.70710678118654752f)); }
	v_lshlrev_b32_e32 v58, 16, v216
	v_and_b32_e32 v59, 0xffff0000, v216
	v_pk_mul_f32 v[70:71], v[58:59], s[18:19] op_sel_hi:[1,0]
	v_lshlrev_b32_e32 v60, 16, v218
	v_fma_f32 v49, |v70|, s3, 1.0
	v_rcp_f32_e32 v72, v49
	v_mul_f32_e64 v49, |v70|, s16
	v_mul_f32_e64 v49, |v70|, v49
	v_exp_f32_e32 v74, v49
	v_mul_f32_e32 v49, 0xbfb8aa3b, v60
	v_exp_f32_e32 v49, v49
	v_and_b32_e32 v61, 0xffff0000, v218
	v_pk_mul_f32 v[58:59], v[58:59], 0.5 op_sel_hi:[1,0]
	v_lshlrev_b32_e32 v54, 16, v217
	v_add_f32_e32 v49, 1.0, v49
	v_rcp_f32_e32 v76, v49
	v_fma_f32 v49, |v71|, s3, 1.0
	v_rcp_f32_e32 v73, v49
	v_mul_f32_e64 v49, |v71|, s16
	v_mul_f32_e64 v49, |v71|, v49
	v_exp_f32_e32 v75, v49
	v_pk_add_f32 v[42:43], v[42:43], v[214:215] op_sel_hi:[1,0]
	v_mul_f32_e32 v49, 0xbfb8aa3b, v61
	v_pk_fma_f32 v[78:79], v[72:73], s[20:21], v[62:63] op_sel_hi:[1,0,0]
	v_exp_f32_e32 v49, v49
	v_pk_fma_f32 v[78:79], v[72:73], v[78:79], s[22:23] op_sel_hi:[1,1,0]
	v_and_b32_e32 v55, 0xffff0000, v217
	v_pk_fma_f32 v[78:79], v[72:73], v[78:79], s[24:25] op_sel_hi:[1,1,0]
	v_add_f32_e32 v49, 1.0, v49
	v_pk_fma_f32 v[78:79], v[72:73], v[78:79], s[26:27] op_sel_hi:[1,1,0]
	v_rcp_f32_e32 v77, v49
	v_pk_mul_f32 v[72:73], v[72:73], v[78:79]
	v_lshlrev_b32_e32 v56, 16, v219
	v_pk_fma_f32 v[72:73], v[74:75], v[72:73], 1.0 op_sel_hi:[1,1,0] neg_lo:[1,0,0] neg_hi:[1,0,0]
	v_and_b32_e32 v57, 0xffff0000, v219
	v_bfi_b32 v71, s17, v73, v71
	v_bfi_b32 v70, s17, v72, v70
	v_pk_add_f32 v[70:71], v[70:71], 1.0 op_sel_hi:[1,0]
	v_pk_add_f32 v[44:45], v[44:45], v[214:215] op_sel_hi:[1,0]
	v_pk_mul_f32 v[58:59], v[58:59], v[70:71]
	s_nop 0
	v_pk_mul_f32 v[42:43], v[42:43], v[58:59]
	v_pk_mul_f32 v[58:59], v[76:77], v[60:61]
	s_nop 0
	v_pk_mul_f32 v[42:43], v[58:59], v[42:43]
	v_pk_mul_f32 v[58:59], v[54:55], s[18:19] op_sel_hi:[1,0]
	v_cvt_pk_bf16_f32 v42, v42, v43
	v_fma_f32 v43, |v58|, s3, 1.0
	v_rcp_f32_e32 v60, v43
	v_mul_f32_e64 v43, |v58|, s16
	v_mul_f32_e64 v43, |v58|, v43
	v_exp_f32_e32 v70, v43
	v_mul_f32_e32 v43, 0xbfb8aa3b, v56
	v_exp_f32_e32 v43, v43
	v_pk_mul_f32 v[54:55], v[54:55], 0.5 op_sel_hi:[1,0]
	v_add_f32_e32 v43, 1.0, v43
	v_rcp_f32_e32 v72, v43
	v_fma_f32 v43, |v59|, s3, 1.0
	v_rcp_f32_e32 v61, v43
	v_mul_f32_e64 v43, |v59|, s16
	v_mul_f32_e64 v43, |v59|, v43
	v_exp_f32_e32 v71, v43
	v_mul_f32_e32 v43, 0xbfb8aa3b, v57
	v_pk_fma_f32 v[74:75], v[60:61], s[20:21], v[62:63] op_sel_hi:[1,0,0]
	v_exp_f32_e32 v43, v43
	v_pk_fma_f32 v[74:75], v[60:61], v[74:75], s[22:23] op_sel_hi:[1,1,0]
	v_add_f32_e32 v43, 1.0, v43
	v_pk_fma_f32 v[74:75], v[60:61], v[74:75], s[24:25] op_sel_hi:[1,1,0]
	v_rcp_f32_e32 v73, v43
	v_pk_fma_f32 v[74:75], v[60:61], v[74:75], s[26:27] op_sel_hi:[1,1,0]
	v_pk_mul_f32 v[48:49], v[72:73], v[56:57]
	v_pk_mul_f32 v[60:61], v[60:61], v[74:75]
	s_nop 0
	v_pk_fma_f32 v[60:61], v[70:71], v[60:61], 1.0 op_sel_hi:[1,1,0] neg_lo:[1,0,0] neg_hi:[1,0,0]
	s_nop 0
	v_bfi_b32 v59, s17, v61, v59
	v_bfi_b32 v58, s17, v60, v58
	v_pk_add_f32 v[58:59], v[58:59], 1.0 op_sel_hi:[1,0]
	s_nop 0
	v_pk_mul_f32 v[54:55], v[54:55], v[58:59]
	s_nop 0
	v_pk_mul_f32 v[44:45], v[44:45], v[54:55]
	s_nop 0
	v_pk_mul_f32 v[44:45], v[48:49], v[44:45]
	s_nop 0
	v_cvt_pk_bf16_f32 v43, v44, v45
	v_readlane_b32 s28, v254, 31
	v_readlane_b32 s29, v254, 32
	v_subrev_u32_e32 v141, s28, v46
	v_add_u32_e32 v141, 0x420, v141
	v_and_b32_e32 v142, 0x7c0, v141
	v_and_b32_e32 v143, 0xfffff7ff, v141
	v_add_u32_e32 v143, v143, v142
	v_bfe_u32 v142, v141, 11, 1
	v_lshl_or_b32 v143, v142, 6, v143
	v_bfe_i32 v142, v141, 25, 1
	v_bfi_b32 v143, v142, v141, v143
	global_store_dwordx2 v143, v[42:43], s[28:29]
	s_nop 0
	s_waitcnt vmcnt(5)
	v_lshlrev_b32_e32 v54, 16, v222
	v_and_b32_e32 v55, 0xffff0000, v222
	v_pk_mul_f32 v[58:59], v[54:55], s[18:19] op_sel_hi:[1,0]
	v_lshlrev_b32_e32 v56, 16, v224
	v_fma_f32 v43, |v58|, s3, 1.0
	v_rcp_f32_e32 v60, v43
	v_mul_f32_e64 v43, |v58|, s16
	v_mul_f32_e64 v43, |v58|, v43
	v_exp_f32_e32 v70, v43
	v_mul_f32_e32 v43, 0xbfb8aa3b, v56
	v_exp_f32_e32 v43, v43
	v_and_b32_e32 v57, 0xffff0000, v224
	v_pk_mul_f32 v[54:55], v[54:55], 0.5 op_sel_hi:[1,0]
	v_lshlrev_b32_e32 v44, 16, v223
	v_add_f32_e32 v43, 1.0, v43
	v_rcp_f32_e32 v72, v43
	v_fma_f32 v43, |v59|, s3, 1.0
	v_rcp_f32_e32 v61, v43
	v_mul_f32_e64 v43, |v59|, s16
	v_mul_f32_e64 v43, |v59|, v43
	v_exp_f32_e32 v71, v43
	v_pk_add_f32 v[38:39], v[38:39], v[220:221] op_sel_hi:[1,0]
	v_mul_f32_e32 v43, 0xbfb8aa3b, v57
	v_pk_fma_f32 v[74:75], v[60:61], s[20:21], v[62:63] op_sel_hi:[1,0,0]
	v_exp_f32_e32 v43, v43
	v_pk_fma_f32 v[74:75], v[60:61], v[74:75], s[22:23] op_sel_hi:[1,1,0]
	v_and_b32_e32 v45, 0xffff0000, v223
	v_pk_fma_f32 v[74:75], v[60:61], v[74:75], s[24:25] op_sel_hi:[1,1,0]
	v_add_f32_e32 v43, 1.0, v43
	v_pk_fma_f32 v[74:75], v[60:61], v[74:75], s[26:27] op_sel_hi:[1,1,0]
	v_rcp_f32_e32 v73, v43
	v_pk_mul_f32 v[60:61], v[60:61], v[74:75]
	v_lshlrev_b32_e32 v48, 16, v225
	v_pk_fma_f32 v[60:61], v[70:71], v[60:61], 1.0 op_sel_hi:[1,1,0] neg_lo:[1,0,0] neg_hi:[1,0,0]
	v_and_b32_e32 v49, 0xffff0000, v225
	v_bfi_b32 v59, s17, v61, v59
	v_bfi_b32 v58, s17, v60, v58
	v_pk_add_f32 v[58:59], v[58:59], 1.0 op_sel_hi:[1,0]
	v_pk_add_f32 v[40:41], v[40:41], v[220:221] op_sel_hi:[1,0]
	v_pk_mul_f32 v[54:55], v[54:55], v[58:59]
	s_nop 0
	v_pk_mul_f32 v[38:39], v[38:39], v[54:55]
	v_pk_mul_f32 v[54:55], v[72:73], v[56:57]
	s_nop 0
	v_pk_mul_f32 v[38:39], v[54:55], v[38:39]
	v_pk_mul_f32 v[54:55], v[44:45], s[18:19] op_sel_hi:[1,0]
	v_cvt_pk_bf16_f32 v38, v38, v39
	v_fma_f32 v39, |v54|, s3, 1.0
	v_rcp_f32_e32 v56, v39
	v_mul_f32_e64 v39, |v54|, s16
	v_mul_f32_e64 v39, |v54|, v39
	v_exp_f32_e32 v58, v39
	v_mul_f32_e32 v39, 0xbfb8aa3b, v48
; DI float erf_as(float x) {
;   const float ax = fabsf(x);
;   const float t = __builtin_amdgcn_rcpf(1.f + 0.3275911f * ax);
;   const float poly = t * (0.254829592f + t * (-0.284496736f + t * (1.421413741f + t * (-1.453152027f + t * 1.061405429f))));
;   const float y = 1.f - poly * __builtin_amdgcn_exp2f(-1.4426950408889634f * ax * ax);
;   return copysignf(y, x);
; }
; DI float gelu(float x) { return 0.5f * x * (1.f + erf_as(x * 0.70710678118654752f)); }
	v_exp_f32_e32 v39, v39
	v_pk_mul_f32 v[44:45], v[44:45], 0.5 op_sel_hi:[1,0]
	v_add_f32_e32 v39, 1.0, v39
	v_rcp_f32_e32 v60, v39
	v_fma_f32 v39, |v55|, s3, 1.0
	v_rcp_f32_e32 v57, v39
	v_mul_f32_e64 v39, |v55|, s16
	v_mul_f32_e64 v39, |v55|, v39
	v_exp_f32_e32 v59, v39
	v_mul_f32_e32 v39, 0xbfb8aa3b, v49
	v_pk_fma_f32 v[70:71], v[56:57], s[20:21], v[62:63] op_sel_hi:[1,0,0]
	v_exp_f32_e32 v39, v39
	v_pk_fma_f32 v[70:71], v[56:57], v[70:71], s[22:23] op_sel_hi:[1,1,0]
	v_add_f32_e32 v39, 1.0, v39
	v_pk_fma_f32 v[70:71], v[56:57], v[70:71], s[24:25] op_sel_hi:[1,1,0]
	v_rcp_f32_e32 v61, v39
	v_pk_fma_f32 v[70:71], v[56:57], v[70:71], s[26:27] op_sel_hi:[1,1,0]
	v_pk_mul_f32 v[42:43], v[60:61], v[48:49]
	v_pk_mul_f32 v[56:57], v[56:57], v[70:71]
	s_nop 0
	v_pk_fma_f32 v[56:57], v[58:59], v[56:57], 1.0 op_sel_hi:[1,1,0] neg_lo:[1,0,0] neg_hi:[1,0,0]
	s_nop 0
	v_bfi_b32 v55, s17, v57, v55
	v_bfi_b32 v54, s17, v56, v54
	v_pk_add_f32 v[54:55], v[54:55], 1.0 op_sel_hi:[1,0]
	s_nop 0
	v_pk_mul_f32 v[44:45], v[44:45], v[54:55]
	s_nop 0
	v_pk_mul_f32 v[40:41], v[40:41], v[44:45]
	s_nop 0
	v_pk_mul_f32 v[40:41], v[42:43], v[40:41]
	s_nop 0
	v_cvt_pk_bf16_f32 v39, v40, v41
	v_readlane_b32 s28, v254, 31
	v_readlane_b32 s29, v254, 32
	v_subrev_u32_e32 v141, s28, v46
	v_add_u32_e32 v141, 0x440, v141
	v_and_b32_e32 v142, 0x7c0, v141
	v_and_b32_e32 v143, 0xfffff7ff, v141
	v_add_u32_e32 v143, v143, v142
	v_bfe_u32 v142, v141, 11, 1
	v_lshl_or_b32 v143, v142, 6, v143
	v_bfe_i32 v142, v141, 25, 1
	v_bfi_b32 v143, v142, v141, v143
	global_store_dwordx2 v143, v[38:39], s[28:29]
	s_nop 0
	s_waitcnt vmcnt(3)
	v_lshlrev_b32_e32 v44, 16, v228
	v_and_b32_e32 v45, 0xffff0000, v228
	v_pk_mul_f32 v[50:51], v[44:45], s[18:19] op_sel_hi:[1,0]
	v_lshlrev_b32_e32 v48, 16, v230
	v_fma_f32 v39, |v50|, s3, 1.0
	v_rcp_f32_e32 v52, v39
	v_mul_f32_e64 v39, |v50|, s16
	v_mul_f32_e64 v39, |v50|, v39
	v_exp_f32_e32 v54, v39
	v_mul_f32_e32 v39, 0xbfb8aa3b, v48
	v_exp_f32_e32 v39, v39
	v_and_b32_e32 v49, 0xffff0000, v230
	v_pk_mul_f32 v[44:45], v[44:45], 0.5 op_sel_hi:[1,0]
	v_lshlrev_b32_e32 v40, 16, v229
	v_add_f32_e32 v39, 1.0, v39
	v_rcp_f32_e32 v56, v39
	v_fma_f32 v39, |v51|, s3, 1.0
	v_rcp_f32_e32 v53, v39
	v_mul_f32_e64 v39, |v51|, s16
	v_mul_f32_e64 v39, |v51|, v39
	v_exp_f32_e32 v55, v39
	v_pk_add_f32 v[34:35], v[34:35], v[226:227] op_sel_hi:[1,0]
	v_mul_f32_e32 v39, 0xbfb8aa3b, v49
	v_pk_fma_f32 v[58:59], v[52:53], s[20:21], v[62:63] op_sel_hi:[1,0,0]
	v_exp_f32_e32 v39, v39
	v_pk_fma_f32 v[58:59], v[52:53], v[58:59], s[22:23] op_sel_hi:[1,1,0]
	v_and_b32_e32 v41, 0xffff0000, v229
	v_pk_fma_f32 v[58:59], v[52:53], v[58:59], s[24:25] op_sel_hi:[1,1,0]
	v_add_f32_e32 v39, 1.0, v39
	v_pk_fma_f32 v[58:59], v[52:53], v[58:59], s[26:27] op_sel_hi:[1,1,0]
	v_rcp_f32_e32 v57, v39
	v_pk_mul_f32 v[52:53], v[52:53], v[58:59]
	v_lshlrev_b32_e32 v42, 16, v231
	v_pk_fma_f32 v[52:53], v[54:55], v[52:53], 1.0 op_sel_hi:[1,1,0] neg_lo:[1,0,0] neg_hi:[1,0,0]
	v_and_b32_e32 v43, 0xffff0000, v231
	v_bfi_b32 v51, s17, v53, v51
	v_bfi_b32 v50, s17, v52, v50
	v_pk_add_f32 v[50:51], v[50:51], 1.0 op_sel_hi:[1,0]
	v_pk_add_f32 v[36:37], v[36:37], v[226:227] op_sel_hi:[1,0]
	v_pk_mul_f32 v[44:45], v[44:45], v[50:51]
	s_nop 0
	v_pk_mul_f32 v[34:35], v[34:35], v[44:45]
	v_pk_mul_f32 v[44:45], v[56:57], v[48:49]
	s_nop 0
	v_pk_mul_f32 v[34:35], v[44:45], v[34:35]
	v_pk_mul_f32 v[44:45], v[40:41], s[18:19] op_sel_hi:[1,0]
	v_cvt_pk_bf16_f32 v34, v34, v35
	v_fma_f32 v35, |v44|, s3, 1.0
	v_rcp_f32_e32 v48, v35
	v_mul_f32_e64 v35, |v44|, s16
	v_mul_f32_e64 v35, |v44|, v35
	v_exp_f32_e32 v50, v35
	v_mul_f32_e32 v35, 0xbfb8aa3b, v42
	v_exp_f32_e32 v35, v35
	v_pk_mul_f32 v[40:41], v[40:41], 0.5 op_sel_hi:[1,0]
	v_add_f32_e32 v35, 1.0, v35
	v_rcp_f32_e32 v52, v35
	v_fma_f32 v35, |v45|, s3, 1.0
	v_rcp_f32_e32 v49, v35
	v_mul_f32_e64 v35, |v45|, s16
	v_mul_f32_e64 v35, |v45|, v35
	v_exp_f32_e32 v51, v35
	v_mul_f32_e32 v35, 0xbfb8aa3b, v43
	v_pk_fma_f32 v[54:55], v[48:49], s[20:21], v[62:63] op_sel_hi:[1,0,0]
	v_exp_f32_e32 v35, v35
	v_pk_fma_f32 v[54:55], v[48:49], v[54:55], s[22:23] op_sel_hi:[1,1,0]
	v_add_f32_e32 v35, 1.0, v35
	v_pk_fma_f32 v[54:55], v[48:49], v[54:55], s[24:25] op_sel_hi:[1,1,0]
	v_rcp_f32_e32 v53, v35
	v_pk_fma_f32 v[54:55], v[48:49], v[54:55], s[26:27] op_sel_hi:[1,1,0]
	v_pk_mul_f32 v[38:39], v[52:53], v[42:43]
	v_pk_mul_f32 v[48:49], v[48:49], v[54:55]
	s_nop 0
	v_pk_fma_f32 v[48:49], v[50:51], v[48:49], 1.0 op_sel_hi:[1,1,0] neg_lo:[1,0,0] neg_hi:[1,0,0]
	s_nop 0
	v_bfi_b32 v45, s17, v49, v45
	v_bfi_b32 v44, s17, v48, v44
	v_pk_add_f32 v[44:45], v[44:45], 1.0 op_sel_hi:[1,0]
	s_nop 0
	v_pk_mul_f32 v[40:41], v[40:41], v[44:45]
	s_nop 0
	v_pk_mul_f32 v[36:37], v[36:37], v[40:41]
	s_nop 0
	v_pk_mul_f32 v[36:37], v[38:39], v[36:37]
	v_or_b32_e32 v38, 32, v66
	v_cvt_pk_bf16_f32 v35, v36, v37
	v_readlane_b32 s28, v254, 31
	v_readlane_b32 s29, v254, 32
	v_subrev_u32_e32 v141, s28, v46
	v_add_u32_e32 v141, 0x460, v141
	v_and_b32_e32 v142, 0x7c0, v141
	v_and_b32_e32 v143, 0xfffff7ff, v141
	v_add_u32_e32 v143, v143, v142
	v_bfe_u32 v142, v141, 11, 1
	v_lshl_or_b32 v143, v142, 6, v143
	v_bfe_i32 v142, v141, 25, 1
	v_bfi_b32 v143, v142, v141, v143
	global_store_dwordx2 v143, v[34:35], s[28:29]
	v_mad_i64_i32 v[34:35], s[0:1], v38, s78, v[68:69]
	v_lshl_add_u64 v[34:35], v[34:35], 0, s[34:35]
	v_lshl_add_u64 v[36:37], v[34:35], 0, v[0:1]
	global_load_dwordx2 v[42:43], v[36:37], off offset:2048
	v_add_co_u32_e32 v34, vcc, s2, v36
	global_load_dword v40, v[64:65], off offset:128
	s_nop 0
	v_addc_co_u32_e32 v35, vcc, 0, v37, vcc
	global_load_dwordx2 v[232:233], v[34:35], off
	global_load_dword v234, v[64:65], off offset:128
	global_load_dwordx2 v[236:237], v[36:37], off offset:2080
	global_load_dwordx2 v[238:239], v[34:35], off offset:32
	global_load_dword v240, v[64:65], off offset:128
	global_load_dwordx2 v[242:243], v[36:37], off offset:2112
	global_load_dwordx2 v[244:245], v[34:35], off offset:64
	global_load_dword v246, v[64:65], off offset:128
	global_load_dwordx2 v[248:249], v[36:37], off offset:2144
	global_load_dwordx2 v[250:251], v[34:35], off offset:96
	v_ashrrev_i32_e32 v39, 31, v38
	s_waitcnt vmcnt(9)
; DI float erf_as(float x) {
;   const float ax = fabsf(x);
;   const float t = __builtin_amdgcn_rcpf(1.f + 0.3275911f * ax);
;   const float poly = t * (0.254829592f + t * (-0.284496736f + t * (1.421413741f + t * (-1.453152027f + t * 1.061405429f))));
;   const float y = 1.f - poly * __builtin_amdgcn_exp2f(-1.4426950408889634f * ax * ax);
;   return copysignf(y, x);
; }
; DI float gelu(float x) { return 0.5f * x * (1.f + erf_as(x * 0.70710678118654752f)); }
	v_lshlrev_b32_e32 v46, 16, v42
	v_and_b32_e32 v47, 0xffff0000, v42
	v_pk_mul_f32 v[50:51], v[46:47], s[18:19] op_sel_hi:[1,0]
	v_pk_mul_f32 v[46:47], v[46:47], 0.5 op_sel_hi:[1,0]
	v_fma_f32 v41, |v50|, s3, 1.0
	v_rcp_f32_e32 v52, v41
	v_mul_f32_e64 v41, |v50|, s16
	v_lshlrev_b32_e32 v48, 16, v232
	v_mul_f32_e64 v41, |v50|, v41
	v_exp_f32_e32 v54, v41
	v_mul_f32_e32 v41, 0xbfb8aa3b, v48
	v_exp_f32_e32 v41, v41
	v_and_b32_e32 v49, 0xffff0000, v232
	v_lshlrev_b32_e32 v44, 16, v233
	v_and_b32_e32 v45, 0xffff0000, v233
	v_add_f32_e32 v41, 1.0, v41
	v_rcp_f32_e32 v56, v41
	v_fma_f32 v41, |v51|, s3, 1.0
	v_rcp_f32_e32 v53, v41
	v_mul_f32_e64 v41, |v51|, s16
	v_mul_f32_e64 v41, |v51|, v41
	v_exp_f32_e32 v55, v41
	v_pk_add_f32 v[30:31], v[30:31], v[40:41] op_sel_hi:[1,0]
	v_mul_f32_e32 v41, 0xbfb8aa3b, v49
	v_pk_fma_f32 v[58:59], v[52:53], s[20:21], v[62:63] op_sel_hi:[1,0,0]
	v_exp_f32_e32 v41, v41
	v_pk_fma_f32 v[58:59], v[52:53], v[58:59], s[22:23] op_sel_hi:[1,1,0]
	v_add_f32_e32 v41, 1.0, v41
	v_pk_fma_f32 v[58:59], v[52:53], v[58:59], s[24:25] op_sel_hi:[1,1,0]
	v_rcp_f32_e32 v57, v41
	v_pk_fma_f32 v[58:59], v[52:53], v[58:59], s[26:27] op_sel_hi:[1,1,0]
	s_nop 0
	v_pk_mul_f32 v[52:53], v[52:53], v[58:59]
	s_nop 0
	v_pk_fma_f32 v[52:53], v[54:55], v[52:53], 1.0 op_sel_hi:[1,1,0] neg_lo:[1,0,0] neg_hi:[1,0,0]
	s_nop 0
	v_bfi_b32 v51, s17, v53, v51
	v_bfi_b32 v50, s17, v52, v50
	v_pk_add_f32 v[50:51], v[50:51], 1.0 op_sel_hi:[1,0]
	s_nop 0
	v_pk_mul_f32 v[46:47], v[46:47], v[50:51]
	s_nop 0
	v_pk_mul_f32 v[30:31], v[30:31], v[46:47]
	v_pk_mul_f32 v[46:47], v[56:57], v[48:49]
	s_nop 0
	v_pk_mul_f32 v[30:31], v[46:47], v[30:31]
	s_nop 0
	v_cvt_pk_bf16_f32 v42, v30, v31
	v_lshlrev_b32_e32 v30, 16, v43
	v_and_b32_e32 v31, 0xffff0000, v43
	v_pk_mul_f32 v[46:47], v[30:31], s[18:19] op_sel_hi:[1,0]
	v_pk_mul_f32 v[30:31], v[30:31], 0.5 op_sel_hi:[1,0]
	v_fma_f32 v41, |v46|, s3, 1.0
	v_rcp_f32_e32 v48, v41
	v_mul_f32_e64 v41, |v46|, s16
	v_mul_f32_e64 v41, |v46|, v41
	v_exp_f32_e32 v50, v41
	v_mul_f32_e32 v41, 0xbfb8aa3b, v44
	v_exp_f32_e32 v41, v41
	s_nop 0
	v_add_f32_e32 v41, 1.0, v41
	v_rcp_f32_e32 v52, v41
	v_fma_f32 v41, |v47|, s3, 1.0
	v_rcp_f32_e32 v49, v41
	v_mul_f32_e64 v41, |v47|, s16
	v_mul_f32_e64 v41, |v47|, v41
	v_exp_f32_e32 v51, v41
	v_pk_fma_f32 v[54:55], v[48:49], s[20:21], v[62:63] op_sel_hi:[1,0,0]
	v_pk_add_f32 v[32:33], v[32:33], v[40:41] op_sel_hi:[1,0]
	v_pk_fma_f32 v[54:55], v[48:49], v[54:55], s[22:23] op_sel_hi:[1,1,0]
	s_nop 0
	v_pk_fma_f32 v[54:55], v[48:49], v[54:55], s[24:25] op_sel_hi:[1,1,0]
	s_nop 0
	v_pk_fma_f32 v[54:55], v[48:49], v[54:55], s[26:27] op_sel_hi:[1,1,0]
	s_nop 0
	v_pk_mul_f32 v[48:49], v[48:49], v[54:55]
	s_nop 0
	v_pk_fma_f32 v[48:49], v[50:51], v[48:49], 1.0 op_sel_hi:[1,1,0] neg_lo:[1,0,0] neg_hi:[1,0,0]
	s_nop 0
	v_bfi_b32 v47, s17, v49, v47
	v_bfi_b32 v46, s17, v48, v46
	v_pk_add_f32 v[46:47], v[46:47], 1.0 op_sel_hi:[1,0]
	s_nop 0
	v_pk_mul_f32 v[30:31], v[30:31], v[46:47]
	s_nop 0
	v_pk_mul_f32 v[30:31], v[32:33], v[30:31]
	v_mul_f32_e32 v32, 0xbfb8aa3b, v45
	v_exp_f32_e32 v32, v32
	s_nop 0
	v_add_f32_e32 v32, 1.0, v32
	v_rcp_f32_e32 v53, v32
	s_nop 0
	v_pk_mul_f32 v[32:33], v[52:53], v[44:45]
	s_nop 0
	v_pk_mul_f32 v[30:31], v[32:33], v[30:31]
	s_nop 0
	v_cvt_pk_bf16_f32 v43, v30, v31
	v_lshlrev_b64 v[30:31], 11, v[38:39]
	v_lshl_add_u64 v[30:31], s[60:61], 0, v[30:31]
	v_lshl_add_u64 v[30:31], v[30:31], 0, s[34:35]
	v_lshl_add_u64 v[30:31], v[30:31], 0, v[0:1]
	v_readlane_b32 s28, v254, 31
	v_readlane_b32 s29, v254, 32
	v_subrev_u32_e32 v141, s28, v30
	v_add_u32_e32 v141, 0x400, v141
	v_and_b32_e32 v142, 0x7c0, v141
	v_and_b32_e32 v143, 0xfffff7ff, v141
	v_add_u32_e32 v143, v143, v142
	v_bfe_u32 v142, v141, 11, 1
	v_lshl_or_b32 v143, v142, 6, v143
	v_bfe_i32 v142, v141, 25, 1
	v_bfi_b32 v143, v142, v141, v143
	global_store_dwordx2 v143, v[42:43], s[28:29]
	s_waitcnt vmcnt(7)
	v_lshlrev_b32_e32 v42, 16, v236
	v_and_b32_e32 v43, 0xffff0000, v236
	v_pk_mul_f32 v[46:47], v[42:43], s[18:19] op_sel_hi:[1,0]
	v_lshlrev_b32_e32 v44, 16, v238
	v_fma_f32 v33, |v46|, s3, 1.0
	v_rcp_f32_e32 v48, v33
	v_mul_f32_e64 v33, |v46|, s16
	v_mul_f32_e64 v33, |v46|, v33
	v_exp_f32_e32 v50, v33
	v_mul_f32_e32 v33, 0xbfb8aa3b, v44
	v_exp_f32_e32 v33, v33
	v_and_b32_e32 v45, 0xffff0000, v238
	v_pk_mul_f32 v[42:43], v[42:43], 0.5 op_sel_hi:[1,0]
	v_lshlrev_b32_e32 v38, 16, v237
	v_add_f32_e32 v33, 1.0, v33
	v_rcp_f32_e32 v52, v33
	v_fma_f32 v33, |v47|, s3, 1.0
	v_rcp_f32_e32 v49, v33
	v_mul_f32_e64 v33, |v47|, s16
	v_mul_f32_e64 v33, |v47|, v33
	v_exp_f32_e32 v51, v33
	v_pk_add_f32 v[26:27], v[26:27], v[234:235] op_sel_hi:[1,0]
	v_mul_f32_e32 v33, 0xbfb8aa3b, v45
	v_pk_fma_f32 v[54:55], v[48:49], s[20:21], v[62:63] op_sel_hi:[1,0,0]
	v_exp_f32_e32 v33, v33
	v_pk_fma_f32 v[54:55], v[48:49], v[54:55], s[22:23] op_sel_hi:[1,1,0]
	v_and_b32_e32 v39, 0xffff0000, v237
	v_pk_fma_f32 v[54:55], v[48:49], v[54:55], s[24:25] op_sel_hi:[1,1,0]
	v_add_f32_e32 v33, 1.0, v33
	v_pk_fma_f32 v[54:55], v[48:49], v[54:55], s[26:27] op_sel_hi:[1,1,0]
	v_rcp_f32_e32 v53, v33
	v_pk_mul_f32 v[48:49], v[48:49], v[54:55]
	v_lshlrev_b32_e32 v40, 16, v239
	v_pk_fma_f32 v[48:49], v[50:51], v[48:49], 1.0 op_sel_hi:[1,1,0] neg_lo:[1,0,0] neg_hi:[1,0,0]
	v_and_b32_e32 v41, 0xffff0000, v239
	v_bfi_b32 v47, s17, v49, v47
	v_bfi_b32 v46, s17, v48, v46
	v_pk_add_f32 v[46:47], v[46:47], 1.0 op_sel_hi:[1,0]
	v_pk_add_f32 v[28:29], v[28:29], v[234:235] op_sel_hi:[1,0]
	v_pk_mul_f32 v[42:43], v[42:43], v[46:47]
	s_nop 0
	v_pk_mul_f32 v[26:27], v[26:27], v[42:43]
	v_pk_mul_f32 v[42:43], v[52:53], v[44:45]
	s_nop 0
	v_pk_mul_f32 v[26:27], v[42:43], v[26:27]
; DI float erf_as(float x) {
;   const float ax = fabsf(x);
;   const float t = __builtin_amdgcn_rcpf(1.f + 0.3275911f * ax);
;   const float poly = t * (0.254829592f + t * (-0.284496736f + t * (1.421413741f + t * (-1.453152027f + t * 1.061405429f))));
;   const float y = 1.f - poly * __builtin_amdgcn_exp2f(-1.4426950408889634f * ax * ax);
;   return copysignf(y, x);
; }
; DI float gelu(float x) { return 0.5f * x * (1.f + erf_as(x * 0.70710678118654752f)); }
	v_pk_mul_f32 v[42:43], v[38:39], s[18:19] op_sel_hi:[1,0]
	v_cvt_pk_bf16_f32 v26, v26, v27
	v_fma_f32 v27, |v42|, s3, 1.0
	v_rcp_f32_e32 v44, v27
	v_mul_f32_e64 v27, |v42|, s16
	v_mul_f32_e64 v27, |v42|, v27
	v_exp_f32_e32 v46, v27
	v_mul_f32_e32 v27, 0xbfb8aa3b, v40
	v_exp_f32_e32 v27, v27
	v_pk_mul_f32 v[38:39], v[38:39], 0.5 op_sel_hi:[1,0]
	v_add_f32_e32 v27, 1.0, v27
	v_rcp_f32_e32 v48, v27
	v_fma_f32 v27, |v43|, s3, 1.0
	v_rcp_f32_e32 v45, v27
	v_mul_f32_e64 v27, |v43|, s16
	v_mul_f32_e64 v27, |v43|, v27
	v_exp_f32_e32 v47, v27
	v_mul_f32_e32 v27, 0xbfb8aa3b, v41
	v_pk_fma_f32 v[50:51], v[44:45], s[20:21], v[62:63] op_sel_hi:[1,0,0]
	v_exp_f32_e32 v27, v27
	v_pk_fma_f32 v[50:51], v[44:45], v[50:51], s[22:23] op_sel_hi:[1,1,0]
	v_add_f32_e32 v27, 1.0, v27
	v_pk_fma_f32 v[50:51], v[44:45], v[50:51], s[24:25] op_sel_hi:[1,1,0]
	v_rcp_f32_e32 v49, v27
	v_pk_fma_f32 v[50:51], v[44:45], v[50:51], s[26:27] op_sel_hi:[1,1,0]
	v_pk_mul_f32 v[32:33], v[48:49], v[40:41]
	v_pk_mul_f32 v[44:45], v[44:45], v[50:51]
	s_nop 0
	v_pk_fma_f32 v[44:45], v[46:47], v[44:45], 1.0 op_sel_hi:[1,1,0] neg_lo:[1,0,0] neg_hi:[1,0,0]
	s_nop 0
	v_bfi_b32 v43, s17, v45, v43
	v_bfi_b32 v42, s17, v44, v42
	v_pk_add_f32 v[42:43], v[42:43], 1.0 op_sel_hi:[1,0]
	s_nop 0
	v_pk_mul_f32 v[38:39], v[38:39], v[42:43]
	s_nop 0
	v_pk_mul_f32 v[28:29], v[28:29], v[38:39]
	s_nop 0
	v_pk_mul_f32 v[28:29], v[32:33], v[28:29]
	s_nop 0
	v_cvt_pk_bf16_f32 v27, v28, v29
	v_readlane_b32 s28, v254, 31
	v_readlane_b32 s29, v254, 32
	v_subrev_u32_e32 v141, s28, v30
	v_add_u32_e32 v141, 0x420, v141
	v_and_b32_e32 v142, 0x7c0, v141
	v_and_b32_e32 v143, 0xfffff7ff, v141
	v_add_u32_e32 v143, v143, v142
	v_bfe_u32 v142, v141, 11, 1
	v_lshl_or_b32 v143, v142, 6, v143
	v_bfe_i32 v142, v141, 25, 1
	v_bfi_b32 v143, v142, v141, v143
	global_store_dwordx2 v143, v[26:27], s[28:29]
	s_nop 0
	s_waitcnt vmcnt(5)
	v_lshlrev_b32_e32 v38, 16, v242
	v_and_b32_e32 v39, 0xffff0000, v242
	v_pk_mul_f32 v[42:43], v[38:39], s[18:19] op_sel_hi:[1,0]
	v_lshlrev_b32_e32 v40, 16, v244
	v_fma_f32 v27, |v42|, s3, 1.0
	v_rcp_f32_e32 v44, v27
	v_mul_f32_e64 v27, |v42|, s16
	v_mul_f32_e64 v27, |v42|, v27
	v_exp_f32_e32 v46, v27
	v_mul_f32_e32 v27, 0xbfb8aa3b, v40
	v_exp_f32_e32 v27, v27
	v_and_b32_e32 v41, 0xffff0000, v244
	v_pk_mul_f32 v[38:39], v[38:39], 0.5 op_sel_hi:[1,0]
	v_lshlrev_b32_e32 v28, 16, v243
	v_add_f32_e32 v27, 1.0, v27
	v_rcp_f32_e32 v48, v27
	v_fma_f32 v27, |v43|, s3, 1.0
	v_rcp_f32_e32 v45, v27
	v_mul_f32_e64 v27, |v43|, s16
	v_mul_f32_e64 v27, |v43|, v27
	v_exp_f32_e32 v47, v27
	v_pk_add_f32 v[22:23], v[22:23], v[240:241] op_sel_hi:[1,0]
	v_mul_f32_e32 v27, 0xbfb8aa3b, v41
	v_pk_fma_f32 v[50:51], v[44:45], s[20:21], v[62:63] op_sel_hi:[1,0,0]
	v_exp_f32_e32 v27, v27
	v_pk_fma_f32 v[50:51], v[44:45], v[50:51], s[22:23] op_sel_hi:[1,1,0]
	v_and_b32_e32 v29, 0xffff0000, v243
	v_pk_fma_f32 v[50:51], v[44:45], v[50:51], s[24:25] op_sel_hi:[1,1,0]
	v_add_f32_e32 v27, 1.0, v27
	v_pk_fma_f32 v[50:51], v[44:45], v[50:51], s[26:27] op_sel_hi:[1,1,0]
	v_rcp_f32_e32 v49, v27
	v_pk_mul_f32 v[44:45], v[44:45], v[50:51]
	v_lshlrev_b32_e32 v32, 16, v245
	v_pk_fma_f32 v[44:45], v[46:47], v[44:45], 1.0 op_sel_hi:[1,1,0] neg_lo:[1,0,0] neg_hi:[1,0,0]
	v_and_b32_e32 v33, 0xffff0000, v245
	v_bfi_b32 v43, s17, v45, v43
	v_bfi_b32 v42, s17, v44, v42
	v_pk_add_f32 v[42:43], v[42:43], 1.0 op_sel_hi:[1,0]
	v_pk_add_f32 v[24:25], v[24:25], v[240:241] op_sel_hi:[1,0]
	v_pk_mul_f32 v[38:39], v[38:39], v[42:43]
	s_nop 0
	v_pk_mul_f32 v[22:23], v[22:23], v[38:39]
	v_pk_mul_f32 v[38:39], v[48:49], v[40:41]
	s_nop 0
	v_pk_mul_f32 v[22:23], v[38:39], v[22:23]
	v_pk_mul_f32 v[38:39], v[28:29], s[18:19] op_sel_hi:[1,0]
	v_cvt_pk_bf16_f32 v22, v22, v23
	v_fma_f32 v23, |v38|, s3, 1.0
	v_rcp_f32_e32 v40, v23
	v_mul_f32_e64 v23, |v38|, s16
	v_mul_f32_e64 v23, |v38|, v23
	v_exp_f32_e32 v42, v23
	v_mul_f32_e32 v23, 0xbfb8aa3b, v32
	v_exp_f32_e32 v23, v23
	v_pk_mul_f32 v[28:29], v[28:29], 0.5 op_sel_hi:[1,0]
	v_add_f32_e32 v23, 1.0, v23
	v_rcp_f32_e32 v44, v23
	v_fma_f32 v23, |v39|, s3, 1.0
	v_rcp_f32_e32 v41, v23
	v_mul_f32_e64 v23, |v39|, s16
	v_mul_f32_e64 v23, |v39|, v23
	v_exp_f32_e32 v43, v23
	v_mul_f32_e32 v23, 0xbfb8aa3b, v33
	v_pk_fma_f32 v[46:47], v[40:41], s[20:21], v[62:63] op_sel_hi:[1,0,0]
	v_exp_f32_e32 v23, v23
	v_pk_fma_f32 v[46:47], v[40:41], v[46:47], s[22:23] op_sel_hi:[1,1,0]
	v_add_f32_e32 v23, 1.0, v23
	v_pk_fma_f32 v[46:47], v[40:41], v[46:47], s[24:25] op_sel_hi:[1,1,0]
	v_rcp_f32_e32 v45, v23
	v_pk_fma_f32 v[46:47], v[40:41], v[46:47], s[26:27] op_sel_hi:[1,1,0]
	v_pk_mul_f32 v[26:27], v[44:45], v[32:33]
	v_pk_mul_f32 v[40:41], v[40:41], v[46:47]
	s_nop 0
	v_pk_fma_f32 v[40:41], v[42:43], v[40:41], 1.0 op_sel_hi:[1,1,0] neg_lo:[1,0,0] neg_hi:[1,0,0]
	s_nop 0
	v_bfi_b32 v39, s17, v41, v39
	v_bfi_b32 v38, s17, v40, v38
	v_pk_add_f32 v[38:39], v[38:39], 1.0 op_sel_hi:[1,0]
	s_nop 0
	v_pk_mul_f32 v[28:29], v[28:29], v[38:39]
	s_nop 0
	v_pk_mul_f32 v[24:25], v[24:25], v[28:29]
	s_nop 0
	v_pk_mul_f32 v[24:25], v[26:27], v[24:25]
	s_nop 0
	v_cvt_pk_bf16_f32 v23, v24, v25
	v_readlane_b32 s28, v254, 31
	v_readlane_b32 s29, v254, 32
	v_subrev_u32_e32 v141, s28, v30
	v_add_u32_e32 v141, 0x440, v141
	v_and_b32_e32 v142, 0x7c0, v141
	v_and_b32_e32 v143, 0xfffff7ff, v141
	v_add_u32_e32 v143, v143, v142
	v_bfe_u32 v142, v141, 11, 1
	v_lshl_or_b32 v143, v142, 6, v143
	v_bfe_i32 v142, v141, 25, 1
	v_bfi_b32 v143, v142, v141, v143
	global_store_dwordx2 v143, v[22:23], s[28:29]
	s_nop 0
	s_waitcnt vmcnt(3)
; DI float erf_as(float x) {
;   const float ax = fabsf(x);
;   const float t = __builtin_amdgcn_rcpf(1.f + 0.3275911f * ax);
;   const float poly = t * (0.254829592f + t * (-0.284496736f + t * (1.421413741f + t * (-1.453152027f + t * 1.061405429f))));
;   const float y = 1.f - poly * __builtin_amdgcn_exp2f(-1.4426950408889634f * ax * ax);
;   return copysignf(y, x);
; }
; DI float gelu(float x) { return 0.5f * x * (1.f + erf_as(x * 0.70710678118654752f)); }
	v_lshlrev_b32_e32 v28, 16, v248
	v_and_b32_e32 v29, 0xffff0000, v248
	v_pk_mul_f32 v[34:35], v[28:29], s[18:19] op_sel_hi:[1,0]
	v_lshlrev_b32_e32 v32, 16, v250
	v_fma_f32 v23, |v34|, s3, 1.0
	v_rcp_f32_e32 v36, v23
	v_mul_f32_e64 v23, |v34|, s16
	v_mul_f32_e64 v23, |v34|, v23
	v_exp_f32_e32 v38, v23
	v_mul_f32_e32 v23, 0xbfb8aa3b, v32
	v_exp_f32_e32 v23, v23
	v_and_b32_e32 v33, 0xffff0000, v250
	v_pk_mul_f32 v[28:29], v[28:29], 0.5 op_sel_hi:[1,0]
	v_lshlrev_b32_e32 v24, 16, v249
	v_add_f32_e32 v23, 1.0, v23
	v_rcp_f32_e32 v40, v23
	v_fma_f32 v23, |v35|, s3, 1.0
	v_rcp_f32_e32 v37, v23
	v_mul_f32_e64 v23, |v35|, s16
	v_mul_f32_e64 v23, |v35|, v23
	v_exp_f32_e32 v39, v23
	v_pk_add_f32 v[18:19], v[18:19], v[246:247] op_sel_hi:[1,0]
	v_mul_f32_e32 v23, 0xbfb8aa3b, v33
	v_pk_fma_f32 v[42:43], v[36:37], s[20:21], v[62:63] op_sel_hi:[1,0,0]
	v_exp_f32_e32 v23, v23
	v_pk_fma_f32 v[42:43], v[36:37], v[42:43], s[22:23] op_sel_hi:[1,1,0]
	v_and_b32_e32 v25, 0xffff0000, v249
	v_pk_fma_f32 v[42:43], v[36:37], v[42:43], s[24:25] op_sel_hi:[1,1,0]
	v_add_f32_e32 v23, 1.0, v23
	v_pk_fma_f32 v[42:43], v[36:37], v[42:43], s[26:27] op_sel_hi:[1,1,0]
	v_rcp_f32_e32 v41, v23
	v_pk_mul_f32 v[36:37], v[36:37], v[42:43]
	v_lshlrev_b32_e32 v26, 16, v251
	v_pk_fma_f32 v[36:37], v[38:39], v[36:37], 1.0 op_sel_hi:[1,1,0] neg_lo:[1,0,0] neg_hi:[1,0,0]
	v_and_b32_e32 v27, 0xffff0000, v251
	v_bfi_b32 v35, s17, v37, v35
	v_bfi_b32 v34, s17, v36, v34
	v_pk_add_f32 v[34:35], v[34:35], 1.0 op_sel_hi:[1,0]
	v_pk_add_f32 v[20:21], v[20:21], v[246:247] op_sel_hi:[1,0]
	v_pk_mul_f32 v[28:29], v[28:29], v[34:35]
	s_nop 0
	v_pk_mul_f32 v[18:19], v[18:19], v[28:29]
	v_pk_mul_f32 v[28:29], v[40:41], v[32:33]
	s_nop 0
	v_pk_mul_f32 v[18:19], v[28:29], v[18:19]
	v_pk_mul_f32 v[28:29], v[24:25], s[18:19] op_sel_hi:[1,0]
	v_cvt_pk_bf16_f32 v18, v18, v19
	v_fma_f32 v19, |v28|, s3, 1.0
	v_rcp_f32_e32 v32, v19
	v_mul_f32_e64 v19, |v28|, s16
	v_mul_f32_e64 v19, |v28|, v19
	v_exp_f32_e32 v34, v19
	v_mul_f32_e32 v19, 0xbfb8aa3b, v26
	v_exp_f32_e32 v19, v19
	v_pk_mul_f32 v[24:25], v[24:25], 0.5 op_sel_hi:[1,0]
	v_add_f32_e32 v19, 1.0, v19
	v_rcp_f32_e32 v36, v19
	v_fma_f32 v19, |v29|, s3, 1.0
	v_rcp_f32_e32 v33, v19
	v_mul_f32_e64 v19, |v29|, s16
	v_mul_f32_e64 v19, |v29|, v19
	v_exp_f32_e32 v35, v19
	v_mul_f32_e32 v19, 0xbfb8aa3b, v27
	v_pk_fma_f32 v[38:39], v[32:33], s[20:21], v[62:63] op_sel_hi:[1,0,0]
	v_exp_f32_e32 v19, v19
	v_pk_fma_f32 v[38:39], v[32:33], v[38:39], s[22:23] op_sel_hi:[1,1,0]
	v_add_f32_e32 v19, 1.0, v19
	v_pk_fma_f32 v[38:39], v[32:33], v[38:39], s[24:25] op_sel_hi:[1,1,0]
	v_rcp_f32_e32 v37, v19
	v_pk_fma_f32 v[38:39], v[32:33], v[38:39], s[26:27] op_sel_hi:[1,1,0]
	v_pk_mul_f32 v[22:23], v[36:37], v[26:27]
	v_pk_mul_f32 v[32:33], v[32:33], v[38:39]
	s_nop 0
	v_pk_fma_f32 v[32:33], v[34:35], v[32:33], 1.0 op_sel_hi:[1,1,0] neg_lo:[1,0,0] neg_hi:[1,0,0]
	s_nop 0
	v_bfi_b32 v29, s17, v33, v29
	v_bfi_b32 v28, s17, v32, v28
	v_pk_add_f32 v[28:29], v[28:29], 1.0 op_sel_hi:[1,0]
	s_nop 0
	v_pk_mul_f32 v[24:25], v[24:25], v[28:29]
	s_nop 0
	v_pk_mul_f32 v[20:21], v[20:21], v[24:25]
	s_nop 0
	v_pk_mul_f32 v[20:21], v[22:23], v[20:21]
	v_or_b32_e32 v22, 48, v66
	v_cvt_pk_bf16_f32 v19, v20, v21
	v_readlane_b32 s28, v254, 31
	v_readlane_b32 s29, v254, 32
	v_subrev_u32_e32 v141, s28, v30
	v_add_u32_e32 v141, 0x460, v141
	v_and_b32_e32 v142, 0x7c0, v141
	v_and_b32_e32 v143, 0xfffff7ff, v141
	v_add_u32_e32 v143, v143, v142
	v_bfe_u32 v142, v141, 11, 1
	v_lshl_or_b32 v143, v142, 6, v143
	v_bfe_i32 v142, v141, 25, 1
	v_bfi_b32 v143, v142, v141, v143
	global_store_dwordx2 v143, v[18:19], s[28:29]
	v_mad_i64_i32 v[18:19], s[0:1], v22, s78, v[68:69]
	v_lshl_add_u64 v[18:19], v[18:19], 0, s[34:35]
	v_lshl_add_u64 v[20:21], v[18:19], 0, v[0:1]
	global_load_dwordx2 v[26:27], v[20:21], off offset:2048
	v_add_co_u32_e32 v18, vcc, s2, v20
	global_load_dword v24, v[64:65], off offset:192
	s_nop 0
	v_addc_co_u32_e32 v19, vcc, 0, v21, vcc
	global_load_dwordx2 v[192:193], v[18:19], off
	global_load_dword v194, v[64:65], off offset:192
	global_load_dwordx2 v[196:197], v[20:21], off offset:2080
	global_load_dwordx2 v[198:199], v[18:19], off offset:32
	global_load_dword v200, v[64:65], off offset:192
	global_load_dwordx2 v[202:203], v[20:21], off offset:2112
	global_load_dwordx2 v[204:205], v[18:19], off offset:64
	global_load_dword v206, v[64:65], off offset:192
	global_load_dwordx2 v[208:209], v[20:21], off offset:2144
	global_load_dwordx2 v[210:211], v[18:19], off offset:96
	v_ashrrev_i32_e32 v23, 31, v22
	s_waitcnt vmcnt(9)
; DI float erf_as(float x) {
;   const float ax = fabsf(x);
;   const float t = __builtin_amdgcn_rcpf(1.f + 0.3275911f * ax);
;   const float poly = t * (0.254829592f + t * (-0.284496736f + t * (1.421413741f + t * (-1.453152027f + t * 1.061405429f))));
;   const float y = 1.f - poly * __builtin_amdgcn_exp2f(-1.4426950408889634f * ax * ax);
;   return copysignf(y, x);
; }
; DI float gelu(float x) { return 0.5f * x * (1.f + erf_as(x * 0.70710678118654752f)); }
	v_lshlrev_b32_e32 v30, 16, v26
	v_and_b32_e32 v31, 0xffff0000, v26
	v_pk_mul_f32 v[34:35], v[30:31], s[18:19] op_sel_hi:[1,0]
	v_pk_mul_f32 v[30:31], v[30:31], 0.5 op_sel_hi:[1,0]
	v_fma_f32 v25, |v34|, s3, 1.0
	v_rcp_f32_e32 v36, v25
	v_mul_f32_e64 v25, |v34|, s16
	v_lshlrev_b32_e32 v32, 16, v192
	v_mul_f32_e64 v25, |v34|, v25
	v_exp_f32_e32 v38, v25
	v_mul_f32_e32 v25, 0xbfb8aa3b, v32
	v_exp_f32_e32 v25, v25
	v_and_b32_e32 v33, 0xffff0000, v192
	v_lshlrev_b32_e32 v28, 16, v193
	v_and_b32_e32 v29, 0xffff0000, v193
	v_add_f32_e32 v25, 1.0, v25
	v_rcp_f32_e32 v40, v25
	v_fma_f32 v25, |v35|, s3, 1.0
	v_rcp_f32_e32 v37, v25
	v_mul_f32_e64 v25, |v35|, s16
	v_mul_f32_e64 v25, |v35|, v25
	v_exp_f32_e32 v39, v25
	v_pk_add_f32 v[14:15], v[14:15], v[24:25] op_sel_hi:[1,0]
	v_mul_f32_e32 v25, 0xbfb8aa3b, v33
	v_pk_fma_f32 v[42:43], v[36:37], s[20:21], v[62:63] op_sel_hi:[1,0,0]
	v_exp_f32_e32 v25, v25
	v_pk_fma_f32 v[42:43], v[36:37], v[42:43], s[22:23] op_sel_hi:[1,1,0]
	v_add_f32_e32 v25, 1.0, v25
	v_pk_fma_f32 v[42:43], v[36:37], v[42:43], s[24:25] op_sel_hi:[1,1,0]
	v_rcp_f32_e32 v41, v25
	v_pk_fma_f32 v[42:43], v[36:37], v[42:43], s[26:27] op_sel_hi:[1,1,0]
	s_nop 0
	v_pk_mul_f32 v[36:37], v[36:37], v[42:43]
	s_nop 0
	v_pk_fma_f32 v[36:37], v[38:39], v[36:37], 1.0 op_sel_hi:[1,1,0] neg_lo:[1,0,0] neg_hi:[1,0,0]
	s_nop 0
	v_bfi_b32 v35, s17, v37, v35
	v_bfi_b32 v34, s17, v36, v34
	v_pk_add_f32 v[34:35], v[34:35], 1.0 op_sel_hi:[1,0]
	s_nop 0
	v_pk_mul_f32 v[30:31], v[30:31], v[34:35]
	s_nop 0
	v_pk_mul_f32 v[14:15], v[14:15], v[30:31]
	v_pk_mul_f32 v[30:31], v[40:41], v[32:33]
	s_nop 0
	v_pk_mul_f32 v[14:15], v[30:31], v[14:15]
	s_nop 0
	v_cvt_pk_bf16_f32 v26, v14, v15
	v_lshlrev_b32_e32 v14, 16, v27
	v_and_b32_e32 v15, 0xffff0000, v27
	v_pk_mul_f32 v[30:31], v[14:15], s[18:19] op_sel_hi:[1,0]
	v_pk_mul_f32 v[14:15], v[14:15], 0.5 op_sel_hi:[1,0]
	v_fma_f32 v25, |v30|, s3, 1.0
	v_rcp_f32_e32 v32, v25
	v_mul_f32_e64 v25, |v30|, s16
	v_mul_f32_e64 v25, |v30|, v25
	v_exp_f32_e32 v34, v25
	v_mul_f32_e32 v25, 0xbfb8aa3b, v28
	v_exp_f32_e32 v25, v25
	s_nop 0
	v_add_f32_e32 v25, 1.0, v25
	v_rcp_f32_e32 v36, v25
	v_fma_f32 v25, |v31|, s3, 1.0
	v_rcp_f32_e32 v33, v25
	v_mul_f32_e64 v25, |v31|, s16
	v_mul_f32_e64 v25, |v31|, v25
	v_exp_f32_e32 v35, v25
	v_pk_fma_f32 v[38:39], v[32:33], s[20:21], v[62:63] op_sel_hi:[1,0,0]
	v_pk_add_f32 v[16:17], v[16:17], v[24:25] op_sel_hi:[1,0]
	v_pk_fma_f32 v[38:39], v[32:33], v[38:39], s[22:23] op_sel_hi:[1,1,0]
	s_nop 0
	v_pk_fma_f32 v[38:39], v[32:33], v[38:39], s[24:25] op_sel_hi:[1,1,0]
	s_nop 0
	v_pk_fma_f32 v[38:39], v[32:33], v[38:39], s[26:27] op_sel_hi:[1,1,0]
	s_nop 0
	v_pk_mul_f32 v[32:33], v[32:33], v[38:39]
	s_nop 0
	v_pk_fma_f32 v[32:33], v[34:35], v[32:33], 1.0 op_sel_hi:[1,1,0] neg_lo:[1,0,0] neg_hi:[1,0,0]
	s_nop 0
	v_bfi_b32 v31, s17, v33, v31
	v_bfi_b32 v30, s17, v32, v30
	v_pk_add_f32 v[30:31], v[30:31], 1.0 op_sel_hi:[1,0]
	s_nop 0
	v_pk_mul_f32 v[14:15], v[14:15], v[30:31]
	s_nop 0
	v_pk_mul_f32 v[14:15], v[16:17], v[14:15]
	v_mul_f32_e32 v16, 0xbfb8aa3b, v29
	v_exp_f32_e32 v16, v16
	s_nop 0
	v_add_f32_e32 v16, 1.0, v16
	v_rcp_f32_e32 v37, v16
	s_nop 0
	v_pk_mul_f32 v[16:17], v[36:37], v[28:29]
	s_nop 0
	v_pk_mul_f32 v[14:15], v[16:17], v[14:15]
	s_nop 0
	v_cvt_pk_bf16_f32 v27, v14, v15
	v_lshlrev_b64 v[14:15], 11, v[22:23]
	v_lshl_add_u64 v[14:15], s[60:61], 0, v[14:15]
	v_lshl_add_u64 v[14:15], v[14:15], 0, s[34:35]
	v_lshl_add_u64 v[14:15], v[14:15], 0, v[0:1]
	v_readlane_b32 s28, v254, 31
	v_readlane_b32 s29, v254, 32
	v_subrev_u32_e32 v141, s28, v14
	v_add_u32_e32 v141, 0x400, v141
	v_and_b32_e32 v142, 0x7c0, v141
	v_and_b32_e32 v143, 0xfffff7ff, v141
	v_add_u32_e32 v143, v143, v142
	v_bfe_u32 v142, v141, 11, 1
	v_lshl_or_b32 v143, v142, 6, v143
	v_bfe_i32 v142, v141, 25, 1
	v_bfi_b32 v143, v142, v141, v143
	global_store_dwordx2 v143, v[26:27], s[28:29]
	v_readlane_b32 s34, v254, 25
	v_readlane_b32 s35, v254, 26
	s_waitcnt vmcnt(7)
	v_pk_add_f32 v[10:11], v[10:11], v[194:195] op_sel_hi:[1,0]
	v_lshlrev_b32_e32 v24, 16, v196
	v_and_b32_e32 v25, 0xffff0000, v196
	v_pk_mul_f32 v[28:29], v[24:25], s[18:19] op_sel_hi:[1,0]
	v_lshlrev_b32_e32 v26, 16, v198
	v_fma_f32 v16, |v28|, s3, 1.0
	v_rcp_f32_e32 v30, v16
	v_mul_f32_e64 v16, |v28|, s16
	v_mul_f32_e64 v16, |v28|, v16
	v_exp_f32_e32 v32, v16
	v_mul_f32_e32 v16, 0xbfb8aa3b, v26
	v_exp_f32_e32 v16, v16
	v_and_b32_e32 v27, 0xffff0000, v198
	v_pk_mul_f32 v[24:25], v[24:25], 0.5 op_sel_hi:[1,0]
	v_lshlrev_b32_e32 v22, 16, v199
	v_add_f32_e32 v16, 1.0, v16
	v_rcp_f32_e32 v34, v16
	v_fma_f32 v16, |v29|, s3, 1.0
	v_rcp_f32_e32 v31, v16
	v_mul_f32_e64 v16, |v29|, s16
	v_mul_f32_e64 v16, |v29|, v16
	v_exp_f32_e32 v33, v16
	v_mul_f32_e32 v16, 0xbfb8aa3b, v27
	v_pk_fma_f32 v[36:37], v[30:31], s[20:21], v[62:63] op_sel_hi:[1,0,0]
	v_exp_f32_e32 v16, v16
	v_pk_fma_f32 v[36:37], v[30:31], v[36:37], s[22:23] op_sel_hi:[1,1,0]
	v_and_b32_e32 v23, 0xffff0000, v199
	v_pk_fma_f32 v[36:37], v[30:31], v[36:37], s[24:25] op_sel_hi:[1,1,0]
	v_add_f32_e32 v16, 1.0, v16
	v_pk_fma_f32 v[36:37], v[30:31], v[36:37], s[26:27] op_sel_hi:[1,1,0]
	v_rcp_f32_e32 v35, v16
	v_pk_mul_f32 v[30:31], v[30:31], v[36:37]
	v_lshlrev_b32_e32 v16, 16, v197
	v_pk_fma_f32 v[30:31], v[32:33], v[30:31], 1.0 op_sel_hi:[1,1,0] neg_lo:[1,0,0] neg_hi:[1,0,0]
	v_and_b32_e32 v17, 0xffff0000, v197
	v_bfi_b32 v29, s17, v31, v29
	v_bfi_b32 v28, s17, v30, v28
	v_pk_add_f32 v[28:29], v[28:29], 1.0 op_sel_hi:[1,0]
	v_pk_add_f32 v[12:13], v[12:13], v[194:195] op_sel_hi:[1,0]
	v_pk_mul_f32 v[24:25], v[24:25], v[28:29]
	v_mul_f32_e32 v0, 0xbfb8aa3b, v23
	v_pk_mul_f32 v[10:11], v[10:11], v[24:25]
; DI float erf_as(float x) {
;   const float ax = fabsf(x);
;   const float t = __builtin_amdgcn_rcpf(1.f + 0.3275911f * ax);
;   const float poly = t * (0.254829592f + t * (-0.284496736f + t * (1.421413741f + t * (-1.453152027f + t * 1.061405429f))));
;   const float y = 1.f - poly * __builtin_amdgcn_exp2f(-1.4426950408889634f * ax * ax);
;   return copysignf(y, x);
; }
; DI float gelu(float x) { return 0.5f * x * (1.f + erf_as(x * 0.70710678118654752f)); }
	v_pk_mul_f32 v[24:25], v[34:35], v[26:27]
	v_exp_f32_e32 v0, v0
	v_pk_mul_f32 v[10:11], v[24:25], v[10:11]
	v_pk_mul_f32 v[24:25], v[16:17], s[18:19] op_sel_hi:[1,0]
	v_cvt_pk_bf16_f32 v10, v10, v11
	v_fma_f32 v11, |v24|, s3, 1.0
	v_rcp_f32_e32 v26, v11
	v_mul_f32_e64 v11, |v24|, s16
	v_mul_f32_e64 v11, |v24|, v11
	v_exp_f32_e32 v28, v11
	v_mul_f32_e32 v11, 0xbfb8aa3b, v22
	v_exp_f32_e32 v11, v11
	v_add_f32_e32 v0, 1.0, v0
	v_rcp_f32_e32 v31, v0
	v_pk_mul_f32 v[16:17], v[16:17], 0.5 op_sel_hi:[1,0]
	v_add_f32_e32 v11, 1.0, v11
	v_rcp_f32_e32 v30, v11
	v_fma_f32 v11, |v25|, s3, 1.0
	v_rcp_f32_e32 v27, v11
	v_mul_f32_e64 v11, |v25|, s16
	v_mul_f32_e64 v11, |v25|, v11
	v_exp_f32_e32 v29, v11
	v_pk_fma_f32 v[32:33], v[26:27], s[20:21], v[62:63] op_sel_hi:[1,0,0]
	s_nop 0
	v_pk_fma_f32 v[32:33], v[26:27], v[32:33], s[22:23] op_sel_hi:[1,1,0]
	s_nop 0
	v_pk_fma_f32 v[32:33], v[26:27], v[32:33], s[24:25] op_sel_hi:[1,1,0]
	s_nop 0
	v_pk_fma_f32 v[32:33], v[26:27], v[32:33], s[26:27] op_sel_hi:[1,1,0]
	s_nop 0
	v_pk_mul_f32 v[26:27], v[26:27], v[32:33]
	s_nop 0
	v_pk_fma_f32 v[26:27], v[28:29], v[26:27], 1.0 op_sel_hi:[1,1,0] neg_lo:[1,0,0] neg_hi:[1,0,0]
	s_nop 0
	v_bfi_b32 v25, s17, v27, v25
	v_bfi_b32 v24, s17, v26, v24
	v_pk_add_f32 v[24:25], v[24:25], 1.0 op_sel_hi:[1,0]
	s_nop 0
	v_pk_mul_f32 v[16:17], v[16:17], v[24:25]
	s_nop 0
	v_pk_mul_f32 v[12:13], v[12:13], v[16:17]
	v_pk_mul_f32 v[16:17], v[30:31], v[22:23]
	s_nop 0
	v_pk_mul_f32 v[12:13], v[16:17], v[12:13]
	s_nop 0
	v_cvt_pk_bf16_f32 v11, v12, v13
	v_readlane_b32 s28, v254, 31
	v_readlane_b32 s29, v254, 32
	v_subrev_u32_e32 v141, s28, v14
	v_add_u32_e32 v141, 0x420, v141
	v_and_b32_e32 v142, 0x7c0, v141
	v_and_b32_e32 v143, 0xfffff7ff, v141
	v_add_u32_e32 v143, v143, v142
	v_bfe_u32 v142, v141, 11, 1
	v_lshl_or_b32 v143, v142, 6, v143
	v_bfe_i32 v142, v141, 25, 1
	v_bfi_b32 v143, v142, v141, v143
	global_store_dwordx2 v143, v[10:11], s[28:29]
	s_nop 0
	s_waitcnt vmcnt(5)
	v_pk_add_f32 v[6:7], v[6:7], v[200:201] op_sel_hi:[1,0]
	v_lshlrev_b32_e32 v16, 16, v202
	v_and_b32_e32 v17, 0xffff0000, v202
	v_pk_mul_f32 v[24:25], v[16:17], s[18:19] op_sel_hi:[1,0]
	v_lshlrev_b32_e32 v22, 16, v204
	v_fma_f32 v10, |v24|, s3, 1.0
	v_rcp_f32_e32 v26, v10
	v_mul_f32_e64 v10, |v24|, s16
	v_mul_f32_e64 v10, |v24|, v10
	v_exp_f32_e32 v28, v10
	v_mul_f32_e32 v10, 0xbfb8aa3b, v22
	v_exp_f32_e32 v10, v10
	v_and_b32_e32 v23, 0xffff0000, v204
	v_pk_mul_f32 v[16:17], v[16:17], 0.5 op_sel_hi:[1,0]
	v_lshlrev_b32_e32 v12, 16, v205
	v_add_f32_e32 v10, 1.0, v10
	v_rcp_f32_e32 v30, v10
	v_fma_f32 v10, |v25|, s3, 1.0
	v_rcp_f32_e32 v27, v10
	v_mul_f32_e64 v10, |v25|, s16
	v_mul_f32_e64 v10, |v25|, v10
	v_exp_f32_e32 v29, v10
	v_mul_f32_e32 v10, 0xbfb8aa3b, v23
	v_pk_fma_f32 v[32:33], v[26:27], s[20:21], v[62:63] op_sel_hi:[1,0,0]
	v_exp_f32_e32 v10, v10
	v_pk_fma_f32 v[32:33], v[26:27], v[32:33], s[22:23] op_sel_hi:[1,1,0]
	v_and_b32_e32 v13, 0xffff0000, v205
	v_pk_fma_f32 v[32:33], v[26:27], v[32:33], s[24:25] op_sel_hi:[1,1,0]
	v_add_f32_e32 v10, 1.0, v10
	v_pk_fma_f32 v[32:33], v[26:27], v[32:33], s[26:27] op_sel_hi:[1,1,0]
	v_rcp_f32_e32 v31, v10
	v_pk_mul_f32 v[26:27], v[26:27], v[32:33]
	v_lshlrev_b32_e32 v10, 16, v203
	v_pk_fma_f32 v[26:27], v[28:29], v[26:27], 1.0 op_sel_hi:[1,1,0] neg_lo:[1,0,0] neg_hi:[1,0,0]
	v_and_b32_e32 v11, 0xffff0000, v203
	v_bfi_b32 v25, s17, v27, v25
	v_bfi_b32 v24, s17, v26, v24
	v_pk_add_f32 v[24:25], v[24:25], 1.0 op_sel_hi:[1,0]
	v_pk_add_f32 v[8:9], v[8:9], v[200:201] op_sel_hi:[1,0]
	v_pk_mul_f32 v[16:17], v[16:17], v[24:25]
	v_mul_f32_e32 v0, 0xbfb8aa3b, v13
	v_pk_mul_f32 v[6:7], v[6:7], v[16:17]
	v_pk_mul_f32 v[16:17], v[30:31], v[22:23]
	v_exp_f32_e32 v0, v0
	v_pk_mul_f32 v[6:7], v[16:17], v[6:7]
	v_pk_mul_f32 v[16:17], v[10:11], s[18:19] op_sel_hi:[1,0]
	v_cvt_pk_bf16_f32 v6, v6, v7
	v_fma_f32 v7, |v16|, s3, 1.0
	v_rcp_f32_e32 v22, v7
	v_mul_f32_e64 v7, |v16|, s16
	v_mul_f32_e64 v7, |v16|, v7
	v_exp_f32_e32 v24, v7
	v_mul_f32_e32 v7, 0xbfb8aa3b, v12
	v_exp_f32_e32 v7, v7
	v_add_f32_e32 v0, 1.0, v0
	v_rcp_f32_e32 v27, v0
	v_pk_mul_f32 v[10:11], v[10:11], 0.5 op_sel_hi:[1,0]
	v_add_f32_e32 v7, 1.0, v7
	v_rcp_f32_e32 v26, v7
	v_fma_f32 v7, |v17|, s3, 1.0
	v_rcp_f32_e32 v23, v7
	v_mul_f32_e64 v7, |v17|, s16
	v_mul_f32_e64 v7, |v17|, v7
	v_exp_f32_e32 v25, v7
	v_pk_fma_f32 v[28:29], v[22:23], s[20:21], v[62:63] op_sel_hi:[1,0,0]
	s_nop 0
	v_pk_fma_f32 v[28:29], v[22:23], v[28:29], s[22:23] op_sel_hi:[1,1,0]
	s_nop 0
	v_pk_fma_f32 v[28:29], v[22:23], v[28:29], s[24:25] op_sel_hi:[1,1,0]
	s_nop 0
	v_pk_fma_f32 v[28:29], v[22:23], v[28:29], s[26:27] op_sel_hi:[1,1,0]
	s_nop 0
	v_pk_mul_f32 v[22:23], v[22:23], v[28:29]
	s_nop 0
	v_pk_fma_f32 v[22:23], v[24:25], v[22:23], 1.0 op_sel_hi:[1,1,0] neg_lo:[1,0,0] neg_hi:[1,0,0]
	s_nop 0
	v_bfi_b32 v17, s17, v23, v17
	v_bfi_b32 v16, s17, v22, v16
	v_pk_add_f32 v[16:17], v[16:17], 1.0 op_sel_hi:[1,0]
	s_nop 0
	v_pk_mul_f32 v[10:11], v[10:11], v[16:17]
	s_nop 0
	v_pk_mul_f32 v[8:9], v[8:9], v[10:11]
	v_pk_mul_f32 v[10:11], v[26:27], v[12:13]
	s_nop 0
	v_pk_mul_f32 v[8:9], v[10:11], v[8:9]
	s_nop 0
	v_cvt_pk_bf16_f32 v7, v8, v9
	v_readlane_b32 s28, v254, 31
	v_readlane_b32 s29, v254, 32
	v_subrev_u32_e32 v141, s28, v14
	v_add_u32_e32 v141, 0x440, v141
	v_and_b32_e32 v142, 0x7c0, v141
	v_and_b32_e32 v143, 0xfffff7ff, v141
	v_add_u32_e32 v143, v143, v142
	v_bfe_u32 v142, v141, 11, 1
	v_lshl_or_b32 v143, v142, 6, v143
	v_bfe_i32 v142, v141, 25, 1
	v_bfi_b32 v143, v142, v141, v143
	global_store_dwordx2 v143, v[6:7], s[28:29]
	s_nop 0
	s_waitcnt vmcnt(3)
; DI float erf_as(float x) {
;   const float ax = fabsf(x);
;   const float t = __builtin_amdgcn_rcpf(1.f + 0.3275911f * ax);
;   const float poly = t * (0.254829592f + t * (-0.284496736f + t * (1.421413741f + t * (-1.453152027f + t * 1.061405429f))));
;   const float y = 1.f - poly * __builtin_amdgcn_exp2f(-1.4426950408889634f * ax * ax);
;   return copysignf(y, x);
; }
; DI float gelu(float x) { return 0.5f * x * (1.f + erf_as(x * 0.70710678118654752f)); }
	v_pk_add_f32 v[2:3], v[2:3], v[206:207] op_sel_hi:[1,0]
	v_lshlrev_b32_e32 v10, 16, v208
	v_and_b32_e32 v11, 0xffff0000, v208
	v_pk_mul_f32 v[16:17], v[10:11], s[18:19] op_sel_hi:[1,0]
	v_lshlrev_b32_e32 v12, 16, v210
	v_fma_f32 v6, |v16|, s3, 1.0
	v_rcp_f32_e32 v18, v6
	v_mul_f32_e64 v6, |v16|, s16
	v_mul_f32_e64 v6, |v16|, v6
	v_exp_f32_e32 v20, v6
	v_mul_f32_e32 v6, 0xbfb8aa3b, v12
	v_exp_f32_e32 v6, v6
	v_and_b32_e32 v13, 0xffff0000, v210
	v_pk_mul_f32 v[10:11], v[10:11], 0.5 op_sel_hi:[1,0]
	v_lshlrev_b32_e32 v8, 16, v211
	v_add_f32_e32 v6, 1.0, v6
	v_rcp_f32_e32 v22, v6
	v_fma_f32 v6, |v17|, s3, 1.0
	v_rcp_f32_e32 v19, v6
	v_mul_f32_e64 v6, |v17|, s16
	v_mul_f32_e64 v6, |v17|, v6
	v_exp_f32_e32 v21, v6
	v_mul_f32_e32 v6, 0xbfb8aa3b, v13
	v_pk_fma_f32 v[24:25], v[18:19], s[20:21], v[62:63] op_sel_hi:[1,0,0]
	v_exp_f32_e32 v6, v6
	v_pk_fma_f32 v[24:25], v[18:19], v[24:25], s[22:23] op_sel_hi:[1,1,0]
	v_and_b32_e32 v9, 0xffff0000, v211
	v_pk_fma_f32 v[24:25], v[18:19], v[24:25], s[24:25] op_sel_hi:[1,1,0]
	v_add_f32_e32 v6, 1.0, v6
	v_pk_fma_f32 v[24:25], v[18:19], v[24:25], s[26:27] op_sel_hi:[1,1,0]
	v_rcp_f32_e32 v23, v6
	v_pk_mul_f32 v[18:19], v[18:19], v[24:25]
	v_lshlrev_b32_e32 v6, 16, v209
	v_pk_fma_f32 v[18:19], v[20:21], v[18:19], 1.0 op_sel_hi:[1,1,0] neg_lo:[1,0,0] neg_hi:[1,0,0]
	v_and_b32_e32 v7, 0xffff0000, v209
	v_bfi_b32 v17, s17, v19, v17
	v_bfi_b32 v16, s17, v18, v16
	v_pk_add_f32 v[16:17], v[16:17], 1.0 op_sel_hi:[1,0]
	v_pk_add_f32 v[4:5], v[4:5], v[206:207] op_sel_hi:[1,0]
	v_pk_mul_f32 v[10:11], v[10:11], v[16:17]
	v_mul_f32_e32 v0, 0xbfb8aa3b, v9
	v_pk_mul_f32 v[2:3], v[2:3], v[10:11]
	v_pk_mul_f32 v[10:11], v[22:23], v[12:13]
	v_exp_f32_e32 v0, v0
	v_pk_mul_f32 v[2:3], v[10:11], v[2:3]
	v_pk_mul_f32 v[10:11], v[6:7], s[18:19] op_sel_hi:[1,0]
	v_cvt_pk_bf16_f32 v2, v2, v3
	v_fma_f32 v3, |v10|, s3, 1.0
	v_rcp_f32_e32 v12, v3
	v_mul_f32_e64 v3, |v10|, s16
	v_mul_f32_e64 v3, |v10|, v3
	v_exp_f32_e32 v16, v3
	v_mul_f32_e32 v3, 0xbfb8aa3b, v8
	v_exp_f32_e32 v3, v3
	v_add_f32_e32 v0, 1.0, v0
	v_rcp_f32_e32 v19, v0
	v_pk_mul_f32 v[6:7], v[6:7], 0.5 op_sel_hi:[1,0]
	v_add_f32_e32 v3, 1.0, v3
	v_rcp_f32_e32 v18, v3
	v_fma_f32 v3, |v11|, s3, 1.0
	v_rcp_f32_e32 v13, v3
	v_mul_f32_e64 v3, |v11|, s16
	v_mul_f32_e64 v3, |v11|, v3
	v_exp_f32_e32 v17, v3
	v_pk_fma_f32 v[20:21], v[12:13], s[20:21], v[62:63] op_sel_hi:[1,0,0]
	s_nop 0
	v_pk_fma_f32 v[20:21], v[12:13], v[20:21], s[22:23] op_sel_hi:[1,1,0]
	s_nop 0
	v_pk_fma_f32 v[20:21], v[12:13], v[20:21], s[24:25] op_sel_hi:[1,1,0]
	s_nop 0
	v_pk_fma_f32 v[20:21], v[12:13], v[20:21], s[26:27] op_sel_hi:[1,1,0]
	s_nop 0
	v_pk_mul_f32 v[12:13], v[12:13], v[20:21]
	s_nop 0
	v_pk_fma_f32 v[12:13], v[16:17], v[12:13], 1.0 op_sel_hi:[1,1,0] neg_lo:[1,0,0] neg_hi:[1,0,0]
	s_nop 0
	v_bfi_b32 v11, s17, v13, v11
	v_bfi_b32 v10, s17, v12, v10
	v_pk_add_f32 v[10:11], v[10:11], 1.0 op_sel_hi:[1,0]
	s_nop 0
	v_pk_mul_f32 v[6:7], v[6:7], v[10:11]
	s_nop 0
	v_pk_mul_f32 v[4:5], v[4:5], v[6:7]
	v_pk_mul_f32 v[6:7], v[18:19], v[8:9]
	s_nop 0
	v_pk_mul_f32 v[4:5], v[6:7], v[4:5]
	s_nop 0
	v_cvt_pk_bf16_f32 v3, v4, v5
	v_readlane_b32 s2, v254, 31
	v_readlane_b32 s3, v254, 32
	v_subrev_u32_e32 v141, s2, v14
	v_add_u32_e32 v141, 0x460, v141
	v_and_b32_e32 v142, 0x7c0, v141
	v_and_b32_e32 v143, 0xfffff7ff, v141
	v_add_u32_e32 v143, v143, v142
	v_bfe_u32 v142, v141, 11, 1
	v_lshl_or_b32 v143, v142, 6, v143
	v_bfe_i32 v142, v141, 25, 1
	v_bfi_b32 v143, v142, v141, v143
	global_store_dwordx2 v143, v[2:3], s[2:3]
	s_waitcnt vmcnt(0)
	s_waitcnt lgkmcnt(0)
	s_barrier

; DI int otid() { int t = threadIdx.x; asm volatile("" : "+v"(t)); return t; }
; template <int TRANS, class AP, class BP, class Epi>
; DI void mfma_gemm_tile(const AP& aptr, const BP& bptr, int m0, int n0, int K, const Epi& epi, bf16* lds) {
;   const int tid = otid(), lane = tid & 63, wave = __builtin_amdgcn_readfirstlane(tid >> 6);
;   const int wm = (wave >> 1) * 64, wn = (wave & 1) * 64;
;   const int lr = tid >> 3, lc = ((tid & 7) ^ (lr & 7)) * 8;
;   const int l16 = lane & 15, lq = lane >> 4;
;   const bf16* ap[4]; const bf16* bp[4];
; #pragma unroll
;   for (int i = 0; i < 4; ++i) { ap[i] = aptr(m0 + lr + 32 * i) + lc; bp[i] = bptr(n0 + lr + 32 * i) + lc; }
;   f32x4 acc[4][4];
; #pragma unroll
;   for (int i = 0; i < 4; ++i)
; #pragma unroll
;     for (int j = 0; j < 4; ++j) acc[i][j] = f32x4{0.f, 0.f, 0.f, 0.f};
;   const int nk = K >> 6;
;     ...
;   GEMM_STAGE(0, 0);
;   if (nk > 1) GEMM_STAGE(1, 1);
;   const unsigned lbase = (unsigned)(size_t)lds;
;   const unsigned sw0 = (unsigned)(((lq ^ (l16 & 7)) * 8) * 2), sw1 = (unsigned)((((4 + lq) ^ (l16 & 7)) * 8) * 2);
;   const unsigned a_row = (unsigned)((wm + l16) * 128), b_row = (unsigned)((128 * 64 + (wn + l16) * 64) * 2);
;     ...
;   for (int ks = 0; ks < nk; ++ks) {
;     if (ks + 1 < nk) asm volatile("s_waitcnt vmcnt(8)\n\ts_barrier" ::: "memory");
;     else asm volatile("s_waitcnt vmcnt(0)\n\ts_barrier" ::: "memory");
;     const unsigned sb_ = lbase + (unsigned)((ks & 1) * (2 * 128 * 64) * 2);
;     const unsigned a0 = sb_ + a_row + sw0, a1 = sb_ + a_row + sw1, b0 = sb_ + b_row + sw0, b1 = sb_ + b_row + sw1;
;     bf16x8 af[2][4], bfr[2][4];
;     LDSR(af[0][0], a0, 0); LDSR(af[0][1], a0, 2048); LDSR(af[0][2], a0, 4096); LDSR(af[0][3], a0, 6144);
;     LDSR(bfr[0][0], b0, 0); LDSR(bfr[0][1], b0, 2048); LDSR(bfr[0][2], b0, 4096); LDSR(bfr[0][3], b0, 6144);
;     LDSR(af[1][0], a1, 0); LDSR(af[1][1], a1, 2048); LDSR(af[1][2], a1, 4096); LDSR(af[1][3], a1, 6144);
;     LDSR(bfr[1][0], b1, 0); LDSR(bfr[1][1], b1, 2048); LDSR(bfr[1][2], b1, 4096); LDSR(bfr[1][3], b1, 6144);
; DI void phase_odd_c(const Ctx& c, bf16* lds) {
;   for (int it = vblock(); it < 512; it += gridDim.x) {
;     const int bk = it >> 2, b = bk >> 6, k1 = bk & 63, mt = it & 3;
;     mfma_gemm_tile<1>(RowPtr{c.UT() + (size_t)bk * 512 * 256, 256}, BPStage2{c.WL() + WL_W2F / 2, k1}, mt * 128, 0, 256, EpiStage2{c.P(), c.HY(), b, k1}, lds);
.LBB0_436:
	s_ashr_i32 s0, s6, 2
	s_ashr_i32 s1, s0, 31
	v_mov_b32_e32 v0, v172
	s_and_b32 s7, s0, 63
	s_lshl_b64 s[0:1], s[0:1], 18
	s_add_u32 s8, s66, s0
	v_readfirstlane_b32 s10, v0
	v_ashrrev_i32_e32 v5, 3, v0
	v_and_b32_e32 v20, 15, v0
	v_lshrrev_b32_e32 v3, 4, v0
	v_bfe_u32 v112, v0, 4, 2
	v_and_b32_e32 v4, 7, v0
	v_xor_b32_e32 v0, v5, v0
	v_and_or_b32 v113, s10, 64, v20
	s_addc_u32 s9, s84, s1
	s_and_b32 s0, s4, 0x180
	v_lshl_or_b32 v2, v5, 6, s7
	v_bitop3_b32 v7, v3, v4, 3 bitop3:0x6c
	v_bitop3_b32 v9, v112, v4, 4 bitop3:0x36
	s_ashr_i32 s1, s10, 1
	v_lshlrev_b32_e32 v0, 4, v0
	v_lshlrev_b32_e32 v114, 7, v113
	v_add_u32_e32 v10, s0, v5
	v_ashrrev_i32_e32 v3, 31, v2
	v_add_u32_e32 v6, 0x1000, v2
	s_lshl_b32 s10, s10, 4
	v_lshlrev_b32_e32 v128, 4, v7
	v_lshlrev_b32_e32 v129, 4, v9
	s_andn2_b32 s1, s1, 63
	v_and_b32_e32 v0, 0x70, v0
	v_or_b32_e32 v21, 0x4000, v114
	v_ashrrev_i32_e32 v11, 31, v10
	v_add_u32_e32 v4, 0x800, v2
	v_add_u32_e32 v8, 0x1800, v2
	v_lshlrev_b64 v[2:3], 9, v[2:3]
	v_ashrrev_i32_e32 v7, 31, v6
	s_and_b32 s22, s10, 0xfffffc00
	v_lshl_add_u64 v[12:13], s[8:9], 0, v[0:1]
	v_lshl_add_u64 v[14:15], s[56:57], 0, v[0:1]
	v_or_b32_e32 v0, s1, v20
	v_or_b32_e32 v142, v21, v128
	v_or_b32_e32 v143, v21, v129
	v_lshlrev_b64 v[20:21], 9, v[10:11]
	v_lshlrev_b64 v[16:17], 9, v[6:7]
	s_add_i32 s24, s22, 0x4000
	v_lshl_add_u64 v[6:7], v[14:15], 0, v[2:3]
	v_lshl_add_u64 v[2:3], v[12:13], 0, v[20:21]
	s_mov_b32 m0, s22
	v_ashrrev_i32_e32 v5, 31, v4
	s_add_i32 s25, s22, 0x1000
	global_load_lds_dwordx4 v[2:3], off
	s_mov_b32 m0, s24
	v_ashrrev_i32_e32 v9, 31, v8
	v_lshlrev_b64 v[4:5], 9, v[4:5]
	s_add_i32 s23, s22, 0x5000
	v_lshl_add_u64 v[20:21], v[2:3], 0, s[2:3]
	global_load_lds_dwordx4 v[6:7], off
	s_mov_b32 m0, s25
	v_lshlrev_b64 v[18:19], 9, v[8:9]
	s_add_i32 s21, s22, 0x2000
	v_lshl_add_u64 v[8:9], v[14:15], 0, v[4:5]
	global_load_lds_dwordx4 v[20:21], off
	s_mov_b32 m0, s23
	s_add_i32 s20, s22, 0x6000
	v_lshl_add_u64 v[22:23], v[2:3], 0, s[30:31]
	global_load_lds_dwordx4 v[8:9], off
	s_mov_b32 m0, s21
	s_add_i32 s19, s22, 0x3000
	v_lshl_add_u64 v[10:11], v[14:15], 0, v[16:17]
	global_load_lds_dwordx4 v[22:23], off
	s_mov_b32 m0, s20
	s_add_i32 s18, s22, 0x7000
	v_lshl_add_u64 v[24:25], v[2:3], 0, s[46:47]
	global_load_lds_dwordx4 v[10:11], off
	s_mov_b32 m0, s19
	s_add_i32 s17, s22, 0x8000
	v_lshl_add_u64 v[4:5], v[14:15], 0, v[18:19]
	global_load_lds_dwordx4 v[24:25], off
	s_mov_b32 m0, s18
	s_add_i32 s16, s22, 0xc000
	v_lshl_add_u64 v[26:27], v[2:3], 0, s[26:27]
	global_load_lds_dwordx4 v[4:5], off
	s_mov_b32 m0, s17
	s_add_i32 s13, s22, 0x9000
	v_lshl_add_u64 v[12:13], v[6:7], 0, s[26:27]
	global_load_lds_dwordx4 v[26:27], off
	s_mov_b32 m0, s16
	s_add_i32 s12, s22, 0xd000
	v_lshl_add_u64 v[28:29], v[2:3], 0, s[28:29]
	global_load_lds_dwordx4 v[12:13], off
	s_mov_b32 m0, s13
	s_add_i32 s11, s22, 0xa000
	v_lshl_add_u64 v[14:15], v[8:9], 0, s[26:27]
	global_load_lds_dwordx4 v[28:29], off
	s_mov_b32 m0, s12
	s_add_i32 s10, s22, 0xe000
	v_lshl_add_u64 v[30:31], v[2:3], 0, s[34:35]
	global_load_lds_dwordx4 v[14:15], off
	s_mov_b32 m0, s11
	s_add_i32 s9, s22, 0xb000
	v_lshl_add_u64 v[16:17], v[10:11], 0, s[26:27]
	global_load_lds_dwordx4 v[30:31], off
	s_mov_b32 m0, s10
	s_add_i32 s8, s22, 0xf000
	v_lshl_add_u64 v[32:33], v[2:3], 0, s[36:37]
	global_load_lds_dwordx4 v[16:17], off
	s_mov_b32 m0, s9
	v_lshl_add_u64 v[18:19], v[4:5], 0, s[26:27]
	global_load_lds_dwordx4 v[32:33], off
	s_mov_b32 m0, s8
	v_lshlrev_b32_e32 v0, 7, v0
	global_load_lds_dwordx4 v[18:19], off
	v_or_b32_e32 v144, v0, v128
	v_or_b32_e32 v145, v0, v129
	s_waitcnt vmcnt(8)
	s_barrier
	ds_read_b128 v[12:15], v144 offset:0
	ds_read_b128 v[16:19], v144 offset:0x800
	ds_read_b128 v[20:23], v144 offset:0x1000
	ds_read_b128 v[24:27], v144 offset:0x1800
	ds_read_b128 v[28:31], v142 offset:0
	ds_read_b128 v[32:35], v142 offset:0x800
	ds_read_b128 v[36:39], v142 offset:0x1000
	ds_read_b128 v[40:43], v142 offset:0x1800
	ds_read_b128 v[44:47], v145 offset:0
	ds_read_b128 v[48:51], v145 offset:0x800
	ds_read_b128 v[52:55], v145 offset:0x1000
	ds_read_b128 v[56:59], v145 offset:0x1800
	ds_read_b128 v[60:63], v143 offset:0
	ds_read_b128 v[64:67], v143 offset:0x800
	ds_read_b128 v[68:71], v143 offset:0x1000
	ds_read_b128 v[72:75], v143 offset:0x1800
	s_mov_b32 m0, s22
	s_waitcnt lgkmcnt(0)
	s_barrier
; #define LDSR(dst, addr, off) asm volatile("ds_read_b128 %0, %1 offset:%2" : "=&v"(dst) : "v"(addr), "n"(off))
; #define LDSR(dst, addr, off) asm volatile("ds_read_b128 %0, %1 offset:%2" : "=&v"(dst) : "v"(addr), "n"(off))
; template <int TRANS, class AP, class BP, class Epi>
; DI void mfma_gemm_tile(const AP& aptr, const BP& bptr, int m0, int n0, int K, const Epi& epi, bf16* lds) {
;     ...
;   for (int ks = 0; ks < nk; ++ks) {
;     if (ks + 1 < nk) asm volatile("s_waitcnt vmcnt(8)\n\ts_barrier" ::: "memory");
;     else asm volatile("s_waitcnt vmcnt(0)\n\ts_barrier" ::: "memory");
;     const unsigned sb_ = lbase + (unsigned)((ks & 1) * (2 * 128 * 64) * 2);
;     const unsigned a0 = sb_ + a_row + sw0, a1 = sb_ + a_row + sw1, b0 = sb_ + b_row + sw0, b1 = sb_ + b_row + sw1;
;     bf16x8 af[2][4], bfr[2][4];
;     LDSR(af[0][0], a0, 0); LDSR(af[0][1], a0, 2048); LDSR(af[0][2], a0, 4096); LDSR(af[0][3], a0, 6144);
;     LDSR(bfr[0][0], b0, 0); LDSR(bfr[0][1], b0, 2048); LDSR(bfr[0][2], b0, 4096); LDSR(bfr[0][3], b0, 6144);
;     LDSR(af[1][0], a1, 0); LDSR(af[1][1], a1, 2048); LDSR(af[1][2], a1, 4096); LDSR(af[1][3], a1, 6144);
;     LDSR(bfr[1][0], b1, 0); LDSR(bfr[1][1], b1, 2048); LDSR(bfr[1][2], b1, 4096); LDSR(bfr[1][3], b1, 6144);
;     asm volatile("s_waitcnt lgkmcnt(0)" : "+v"(af[0][0]), "+v"(af[0][1]), "+v"(af[0][2]), "+v"(af[0][3]), "+v"(bfr[0][0]), "+v"(bfr[0][1]), "+v"(bfr[0][2]), "+v"(bfr[0][3]),
;                  "+v"(af[1][0]), "+v"(af[1][1]), "+v"(af[1][2]), "+v"(af[1][3]), "+v"(bfr[1][0]), "+v"(bfr[1][1]), "+v"(bfr[1][2]), "+v"(bfr[1][3]) : : "memory");
;     if (ks + 2 < nk) {
;       asm volatile("s_barrier" ::: "memory");
;       GEMM_STAGE(ks & 1, ks + 2);
;     }
; #pragma unroll
;     for (int kk = 0; kk < 2; ++kk)
; #pragma unroll
;       for (int i = 0; i < 4; ++i)
; #pragma unroll
;         for (int j = 0; j < 4; ++j)
;           acc[i][j] = TRANS ? __builtin_amdgcn_mfma_f32_16x16x32_bf16(af[kk][i], bfr[kk][j], acc[i][j], 0, 0, 0)
;                             : __builtin_amdgcn_mfma_f32_16x16x32_bf16(bfr[kk][j], af[kk][i], acc[i][j], 0, 0, 0);
;   }
	v_lshl_add_u64 v[122:123], v[2:3], 0, s[42:43]
	v_mfma_f32_16x16x32_bf16 v[76:79], v[12:15], v[28:31], 0
	v_lshl_add_u64 v[116:117], v[8:9], 0, s[86:87]
	v_lshl_add_u64 v[124:125], v[2:3], 0, s[90:91]
	v_lshl_add_u64 v[118:119], v[10:11], 0, s[86:87]
	v_mfma_f32_16x16x32_bf16 v[80:83], v[12:15], v[32:35], 0
	v_lshl_add_u64 v[126:127], v[2:3], 0, s[38:39]
	v_lshl_add_u64 v[120:121], v[4:5], 0, s[86:87]
	v_add_u32_e32 v0, 0x8000, v0
	v_mfma_f32_16x16x32_bf16 v[84:87], v[12:15], v[36:39], 0
	v_or_b32_e32 v166, v0, v128
	v_or_b32_e32 v0, v0, v129
	v_lshl_add_u64 v[10:11], v[10:11], 0, s[92:93]
	v_mfma_f32_16x16x32_bf16 v[92:95], v[16:19], v[32:35], 0
	s_add_i32 s1, s1, s0
	s_add_i32 s6, s6, s40
	s_add_i32 s4, s4, s73
	v_mfma_f32_16x16x32_bf16 v[12:15], v[12:15], v[40:43], 0
	v_mfma_f32_16x16x32_bf16 v[88:91], v[16:19], v[28:31], 0
	v_mfma_f32_16x16x32_bf16 v[96:99], v[16:19], v[36:39], 0
	v_mfma_f32_16x16x32_bf16 v[16:19], v[16:19], v[40:43], 0
	v_mfma_f32_16x16x32_bf16 v[100:103], v[20:23], v[28:31], 0
	v_mfma_f32_16x16x32_bf16 v[104:107], v[20:23], v[32:35], 0
	v_mfma_f32_16x16x32_bf16 v[108:111], v[20:23], v[36:39], 0
	v_mfma_f32_16x16x32_bf16 v[20:23], v[20:23], v[40:43], 0
	v_mfma_f32_16x16x32_bf16 v[28:31], v[24:27], v[28:31], 0
	v_mfma_f32_16x16x32_bf16 v[32:35], v[24:27], v[32:35], 0
	v_mfma_f32_16x16x32_bf16 v[36:39], v[24:27], v[36:39], 0
	v_mfma_f32_16x16x32_bf16 v[24:27], v[24:27], v[40:43], 0
	v_mfma_f32_16x16x32_bf16 v[40:43], v[44:47], v[60:63], v[76:79]
	v_mfma_f32_16x16x32_bf16 v[76:79], v[44:47], v[64:67], v[80:83]
	v_mfma_f32_16x16x32_bf16 v[80:83], v[44:47], v[68:71], v[84:87]
	v_mfma_f32_16x16x32_bf16 v[84:87], v[48:51], v[64:67], v[92:95]
	s_nop 2
	v_lshl_add_u64 v[92:93], v[2:3], 0, s[86:87]
	v_mfma_f32_16x16x32_bf16 v[12:15], v[44:47], v[72:75], v[12:15]
	v_or_b32_e32 v44, 0xc000, v114
	v_lshl_add_u64 v[114:115], v[6:7], 0, s[86:87]
	global_load_lds_dwordx4 v[92:93], off
	s_mov_b32 m0, s24
	v_or_b32_e32 v159, v44, v128
	global_load_lds_dwordx4 v[114:115], off
	s_mov_b32 m0, s25
	v_or_b32_e32 v161, v44, v129
	global_load_lds_dwordx4 v[122:123], off
	s_mov_b32 m0, s23
	v_mfma_f32_16x16x32_bf16 v[44:47], v[48:51], v[60:63], v[88:91]
	global_load_lds_dwordx4 v[116:117], off
	s_mov_b32 m0, s21
	v_mfma_f32_16x16x32_bf16 v[88:91], v[48:51], v[68:71], v[96:99]
	global_load_lds_dwordx4 v[124:125], off
	s_mov_b32 m0, s20
	v_mfma_f32_16x16x32_bf16 v[16:19], v[48:51], v[72:75], v[16:19]
	global_load_lds_dwordx4 v[118:119], off
	s_mov_b32 m0, s19
	v_mfma_f32_16x16x32_bf16 v[92:95], v[52:55], v[64:67], v[104:107]
	global_load_lds_dwordx4 v[126:127], off
	s_mov_b32 m0, s18
	v_mfma_f32_16x16x32_bf16 v[32:35], v[56:59], v[64:67], v[32:35]
	global_load_lds_dwordx4 v[120:121], off
	s_waitcnt vmcnt(8)
	s_barrier
	v_mfma_f32_16x16x32_bf16 v[48:51], v[52:55], v[60:63], v[100:103]
	s_mov_b32 m0, s17
	v_mfma_f32_16x16x32_bf16 v[96:99], v[52:55], v[68:71], v[108:111]
	v_mfma_f32_16x16x32_bf16 v[20:23], v[52:55], v[72:75], v[20:23]
	ds_read_b128 v[52:55], v166 offset:0
	v_mfma_f32_16x16x32_bf16 v[28:31], v[56:59], v[60:63], v[28:31]
	v_mfma_f32_16x16x32_bf16 v[36:39], v[56:59], v[68:71], v[36:39]
	v_mfma_f32_16x16x32_bf16 v[24:27], v[56:59], v[72:75], v[24:27]
	ds_read_b128 v[56:59], v166 offset:0x800
	ds_read_b128 v[60:63], v166 offset:0x1000
	ds_read_b128 v[64:67], v166 offset:0x1800
	ds_read_b128 v[68:71], v159 offset:0
	ds_read_b128 v[72:75], v159 offset:0x800
	ds_read_b128 v[100:103], v159 offset:0x1000
	ds_read_b128 v[104:107], v159 offset:0x1800
	ds_read_b128 v[108:111], v0 offset:0
	ds_read_b128 v[114:117], v0 offset:0x800
	ds_read_b128 v[118:121], v0 offset:0x1000
	ds_read_b128 v[122:125], v0 offset:0x1800
	ds_read_b128 v[126:129], v161 offset:0
	ds_read_b128 v[130:133], v161 offset:0x800
	ds_read_b128 v[134:137], v161 offset:0x1000
	ds_read_b128 v[138:141], v161 offset:0x1800
	s_nop 0
	s_waitcnt lgkmcnt(0)
	s_barrier
	s_nop 0
	v_mfma_f32_16x16x32_bf16 v[76:79], v[52:55], v[72:75], v[76:79]
	v_mfma_f32_16x16x32_bf16 v[40:43], v[52:55], v[68:71], v[40:43]
	v_mfma_f32_16x16x32_bf16 v[80:83], v[52:55], v[100:103], v[80:83]
	v_mfma_f32_16x16x32_bf16 v[12:15], v[52:55], v[104:107], v[12:15]
	v_mfma_f32_16x16x32_bf16 v[44:47], v[56:59], v[68:71], v[44:47]
	v_mfma_f32_16x16x32_bf16 v[52:55], v[56:59], v[72:75], v[84:87]
	v_mfma_f32_16x16x32_bf16 v[84:87], v[56:59], v[100:103], v[88:91]
	v_mfma_f32_16x16x32_bf16 v[16:19], v[56:59], v[104:107], v[16:19]
	v_mfma_f32_16x16x32_bf16 v[56:59], v[60:63], v[72:75], v[92:95]
	v_mfma_f32_16x16x32_bf16 v[32:35], v[64:67], v[72:75], v[32:35]
	v_lshl_add_u64 v[74:75], v[2:3], 0, s[92:93]
	global_load_lds_dwordx4 v[74:75], off
	v_mfma_f32_16x16x32_bf16 v[48:51], v[60:63], v[68:71], v[48:51]
	s_mov_b32 m0, s16
	v_lshl_add_u64 v[72:73], v[4:5], 0, s[92:93]
	v_mfma_f32_16x16x32_bf16 v[28:31], v[64:67], v[68:71], v[28:31]
	v_lshl_add_u64 v[68:69], v[6:7], 0, s[92:93]
	global_load_lds_dwordx4 v[68:69], off
	v_mfma_f32_16x16x32_bf16 v[88:91], v[60:63], v[100:103], v[96:99]
	s_mov_b32 m0, s13
	v_lshl_add_u64 v[70:71], v[8:9], 0, s[92:93]
	v_mfma_f32_16x16x32_bf16 v[20:23], v[60:63], v[104:107], v[20:23]
	v_mfma_f32_16x16x32_bf16 v[60:63], v[108:111], v[130:133], v[76:79]
	s_nop 2
	v_lshl_add_u64 v[76:77], v[2:3], 0, s[50:51]
	global_load_lds_dwordx4 v[76:77], off
	s_mov_b32 m0, s12
	v_lshl_add_u64 v[78:79], v[2:3], 0, s[94:95]
	global_load_lds_dwordx4 v[70:71], off
	s_mov_b32 m0, s11
	v_mfma_f32_16x16x32_bf16 v[36:39], v[64:67], v[100:103], v[36:39]
	global_load_lds_dwordx4 v[78:79], off
	s_mov_b32 m0, s10
	v_mfma_f32_16x16x32_bf16 v[24:27], v[64:67], v[104:107], v[24:27]
	global_load_lds_dwordx4 v[10:11], off
	s_mov_b32 m0, s9
	v_mfma_f32_16x16x32_bf16 v[40:43], v[108:111], v[126:129], v[40:43]
	v_mfma_f32_16x16x32_bf16 v[64:67], v[108:111], v[134:137], v[80:83]
	s_nop 2
	v_lshl_add_u64 v[80:81], v[2:3], 0, s[54:55]
	global_load_lds_dwordx4 v[80:81], off
	s_mov_b32 m0, s8
	v_mfma_f32_16x16x32_bf16 v[12:15], v[108:111], v[138:141], v[12:15]
	global_load_lds_dwordx4 v[72:73], off
	s_waitcnt vmcnt(8)
	s_barrier
; #define LDSR(dst, addr, off) asm volatile("ds_read_b128 %0, %1 offset:%2" : "=&v"(dst) : "v"(addr), "n"(off))
; #define LDSR(dst, addr, off) asm volatile("ds_read_b128 %0, %1 offset:%2" : "=&v"(dst) : "v"(addr), "n"(off))
; template <int TRANS, class AP, class BP, class Epi>
; DI void mfma_gemm_tile(const AP& aptr, const BP& bptr, int m0, int n0, int K, const Epi& epi, bf16* lds) {
;     ...
;   for (int ks = 0; ks < nk; ++ks) {
;     if (ks + 1 < nk) asm volatile("s_waitcnt vmcnt(8)\n\ts_barrier" ::: "memory");
;     else asm volatile("s_waitcnt vmcnt(0)\n\ts_barrier" ::: "memory");
;     const unsigned sb_ = lbase + (unsigned)((ks & 1) * (2 * 128 * 64) * 2);
;     const unsigned a0 = sb_ + a_row + sw0, a1 = sb_ + a_row + sw1, b0 = sb_ + b_row + sw0, b1 = sb_ + b_row + sw1;
;     bf16x8 af[2][4], bfr[2][4];
;     LDSR(af[0][0], a0, 0); LDSR(af[0][1], a0, 2048); LDSR(af[0][2], a0, 4096); LDSR(af[0][3], a0, 6144);
;     LDSR(bfr[0][0], b0, 0); LDSR(bfr[0][1], b0, 2048); LDSR(bfr[0][2], b0, 4096); LDSR(bfr[0][3], b0, 6144);
;     LDSR(af[1][0], a1, 0); LDSR(af[1][1], a1, 2048); LDSR(af[1][2], a1, 4096); LDSR(af[1][3], a1, 6144);
;     LDSR(bfr[1][0], b1, 0); LDSR(bfr[1][1], b1, 2048); LDSR(bfr[1][2], b1, 4096); LDSR(bfr[1][3], b1, 6144);
;     asm volatile("s_waitcnt lgkmcnt(0)" : "+v"(af[0][0]), "+v"(af[0][1]), "+v"(af[0][2]), "+v"(af[0][3]), "+v"(bfr[0][0]), "+v"(bfr[0][1]), "+v"(bfr[0][2]), "+v"(bfr[0][3]),
;                  "+v"(af[1][0]), "+v"(af[1][1]), "+v"(af[1][2]), "+v"(af[1][3]), "+v"(bfr[1][0]), "+v"(bfr[1][1]), "+v"(bfr[1][2]), "+v"(bfr[1][3]) : : "memory");
;     if (ks + 2 < nk) {
;       asm volatile("s_barrier" ::: "memory");
;       GEMM_STAGE(ks & 1, ks + 2);
;     }
; #pragma unroll
;     for (int kk = 0; kk < 2; ++kk)
; #pragma unroll
;       for (int i = 0; i < 4; ++i)
; #pragma unroll
;         for (int j = 0; j < 4; ++j)
;           acc[i][j] = TRANS ? __builtin_amdgcn_mfma_f32_16x16x32_bf16(af[kk][i], bfr[kk][j], acc[i][j], 0, 0, 0)
;                             : __builtin_amdgcn_mfma_f32_16x16x32_bf16(bfr[kk][j], af[kk][i], acc[i][j], 0, 0, 0);
;   }
	v_mfma_f32_16x16x32_bf16 v[44:47], v[114:117], v[126:129], v[44:47]
	ds_read_b128 v[68:71], v144 offset:0
	ds_read_b128 v[72:75], v144 offset:0x800
	ds_read_b128 v[76:79], v144 offset:0x1000
	v_mfma_f32_16x16x32_bf16 v[52:55], v[114:117], v[130:133], v[52:55]
	ds_read_b128 v[80:83], v144 offset:0x1800
	s_and_b32 s8, s5, 0xffffe000
	s_add_i32 s5, s5, s72
	v_mfma_f32_16x16x32_bf16 v[6:9], v[114:117], v[134:137], v[84:87]
	ds_read_b128 v[84:87], v142 offset:0
	s_cmpk_lt_i32 s6, 0x200
	v_mfma_f32_16x16x32_bf16 v[16:19], v[114:117], v[138:141], v[16:19]
	v_mfma_f32_16x16x32_bf16 v[2:5], v[118:121], v[126:129], v[48:51]
	v_mfma_f32_16x16x32_bf16 v[48:51], v[118:121], v[130:133], v[56:59]
	v_mfma_f32_16x16x32_bf16 v[56:59], v[118:121], v[134:137], v[88:91]
	ds_read_b128 v[88:91], v142 offset:0x800
	ds_read_b128 v[92:95], v142 offset:0x1000
	ds_read_b128 v[96:99], v142 offset:0x1800
	v_mfma_f32_16x16x32_bf16 v[20:23], v[118:121], v[138:141], v[20:23]
	ds_read_b128 v[100:103], v145 offset:0
	ds_read_b128 v[104:107], v145 offset:0x800
	ds_read_b128 v[108:111], v145 offset:0x1000
	v_mfma_f32_16x16x32_bf16 v[28:31], v[122:125], v[126:129], v[28:31]
	ds_read_b128 v[114:117], v145 offset:0x1800
	ds_read_b128 v[118:121], v143 offset:0
	v_mfma_f32_16x16x32_bf16 v[32:35], v[122:125], v[130:133], v[32:35]
	v_mfma_f32_16x16x32_bf16 v[36:39], v[122:125], v[134:137], v[36:39]
	v_mfma_f32_16x16x32_bf16 v[24:27], v[122:125], v[138:141], v[24:27]
	ds_read_b128 v[122:125], v143 offset:0x800
	ds_read_b128 v[126:129], v143 offset:0x1000
	ds_read_b128 v[130:133], v143 offset:0x1800
	s_nop 0
	s_waitcnt lgkmcnt(0)
	s_waitcnt vmcnt(0)
	s_barrier
	s_nop 0
	v_mfma_f32_16x16x32_bf16 v[40:43], v[68:71], v[84:87], v[40:43]
	v_mfma_f32_16x16x32_bf16 v[60:63], v[68:71], v[88:91], v[60:63]
	v_mfma_f32_16x16x32_bf16 v[64:67], v[68:71], v[92:95], v[64:67]
	v_mfma_f32_16x16x32_bf16 v[10:13], v[68:71], v[96:99], v[12:15]
	v_mfma_f32_16x16x32_bf16 v[44:47], v[72:75], v[84:87], v[44:47]
	v_mfma_f32_16x16x32_bf16 v[52:55], v[72:75], v[88:91], v[52:55]
	v_mfma_f32_16x16x32_bf16 v[6:9], v[72:75], v[92:95], v[6:9]
	v_mfma_f32_16x16x32_bf16 v[14:17], v[72:75], v[96:99], v[16:19]
	v_mfma_f32_16x16x32_bf16 v[2:5], v[76:79], v[84:87], v[2:5]
	v_mfma_f32_16x16x32_bf16 v[48:51], v[76:79], v[88:91], v[48:51]
	v_mfma_f32_16x16x32_bf16 v[56:59], v[76:79], v[92:95], v[56:59]
	v_mfma_f32_16x16x32_bf16 v[18:21], v[76:79], v[96:99], v[20:23]
	v_mfma_f32_16x16x32_bf16 v[28:31], v[80:83], v[84:87], v[28:31]
	ds_read_b128 v[84:87], v166 offset:0
	ds_read_b128 v[154:157], v166 offset:0x800
	ds_read_b128 v[162:165], v166 offset:0x1000
	v_mfma_f32_16x16x32_bf16 v[68:71], v[80:83], v[88:91], v[32:35]
	v_mfma_f32_16x16x32_bf16 v[72:75], v[80:83], v[92:95], v[36:39]
	ds_read_b128 v[34:37], v166 offset:0x1800
	ds_read_b128 v[166:169], v159 offset:0
	ds_read_b128 v[182:185], v159 offset:0x800
	v_mfma_f32_16x16x32_bf16 v[76:79], v[80:83], v[96:99], v[24:27]
	v_mfma_f32_16x16x32_bf16 v[38:41], v[100:103], v[118:121], v[40:43]
	v_mfma_f32_16x16x32_bf16 v[60:63], v[100:103], v[122:125], v[60:63]
	v_mfma_f32_16x16x32_bf16 v[64:67], v[100:103], v[126:129], v[64:67]
	v_mfma_f32_16x16x32_bf16 v[80:83], v[100:103], v[130:133], v[10:13]
	v_mfma_f32_16x16x32_bf16 v[42:45], v[104:107], v[118:121], v[44:47]
	v_mfma_f32_16x16x32_bf16 v[134:137], v[104:107], v[122:125], v[52:55]
	v_mfma_f32_16x16x32_bf16 v[138:141], v[104:107], v[126:129], v[6:9]
	v_mfma_f32_16x16x32_bf16 v[142:145], v[104:107], v[130:133], v[14:17]
	v_mfma_f32_16x16x32_bf16 v[146:149], v[108:111], v[118:121], v[2:5]
	v_mfma_f32_16x16x32_bf16 v[46:49], v[108:111], v[122:125], v[48:51]
	v_mfma_f32_16x16x32_bf16 v[150:153], v[108:111], v[126:129], v[56:59]
	ds_read_b128 v[54:57], v159 offset:0x1000
	ds_read_b128 v[50:53], v159 offset:0x1800
	v_mfma_f32_16x16x32_bf16 v[106:109], v[108:111], v[130:133], v[18:21]
	v_mov_b64_e32 v[110:111], s[62:63]
	v_mfma_f32_16x16x32_bf16 v[118:121], v[114:117], v[118:121], v[28:31]
	ds_read_b128 v[30:33], v0 offset:0
	ds_read_b128 v[26:29], v0 offset:0x800
	ds_read_b128 v[14:17], v0 offset:0x1000
	v_mfma_f32_16x16x32_bf16 v[122:125], v[114:117], v[122:125], v[68:71]
	ds_read_b128 v[2:5], v0 offset:0x1800
	ds_read_b128 v[18:21], v161 offset:0
	ds_read_b128 v[22:25], v161 offset:0x800
	v_mfma_f32_16x16x32_bf16 v[70:73], v[114:117], v[126:129], v[72:75]
	ds_read_b128 v[10:13], v161 offset:0x1000
	ds_read_b128 v[6:9], v161 offset:0x1800
	v_lshl_or_b32 v0, v113, 6, s8
	v_mfma_f32_16x16x32_bf16 v[74:77], v[114:117], v[130:133], v[76:79]
	s_waitcnt lgkmcnt(0)
; template <int TRANS, class AP, class BP, class Epi>
; DI void mfma_gemm_tile(const AP& aptr, const BP& bptr, int m0, int n0, int K, const Epi& epi, bf16* lds) {
;     ...
; #pragma unroll
;     for (int kk = 0; kk < 2; ++kk)
; #pragma unroll
;       for (int i = 0; i < 4; ++i)
; #pragma unroll
;         for (int j = 0; j < 4; ++j)
;           acc[i][j] = TRANS ? __builtin_amdgcn_mfma_f32_16x16x32_bf16(af[kk][i], bfr[kk][j], acc[i][j], 0, 0, 0)
;                             : __builtin_amdgcn_mfma_f32_16x16x32_bf16(bfr[kk][j], af[kk][i], acc[i][j], 0, 0, 0);
;   }
;     ...
; #pragma unroll
;   for (int i = 0; i < 4; ++i)
; #pragma unroll
;     for (int j = 0; j < 4; ++j) {
;       if (TRANS) epi(m0 + wm + 16 * i + 4 * lq, n0 + wn + 16 * j + l16, acc[i][j]);
;       else epi(m0 + wm + 16 * i + l16, n0 + wn + 16 * j + 4 * lq, acc[i][j]);
	s_nop 0
	v_mfma_f32_16x16x32_bf16 v[102:105], v[84:87], v[166:169], v[38:41]
	v_mfma_f32_16x16x32_bf16 v[98:101], v[84:87], v[182:185], v[60:63]
	v_mfma_f32_16x16x32_bf16 v[94:97], v[84:87], v[54:57], v[64:67]
	v_mfma_f32_16x16x32_bf16 v[90:93], v[84:87], v[50:53], v[80:83]
	v_mfma_f32_16x16x32_bf16 v[86:89], v[154:157], v[166:169], v[42:45]
	v_mfma_f32_16x16x32_bf16 v[82:85], v[154:157], v[182:185], v[134:137]
	v_mfma_f32_16x16x32_bf16 v[78:81], v[154:157], v[54:57], v[138:141]
	v_mfma_f32_16x16x32_bf16 v[66:69], v[154:157], v[50:53], v[142:145]
	v_mfma_f32_16x16x32_bf16 v[58:61], v[162:165], v[182:185], v[46:49]
	v_mfma_f32_16x16x32_bf16 v[46:49], v[162:165], v[54:57], v[150:153]
	v_mfma_f32_16x16x32_bf16 v[42:45], v[162:165], v[50:53], v[106:109]
	v_mfma_f32_16x16x32_bf16 v[38:41], v[34:37], v[166:169], v[118:121]
	v_mfma_f32_16x16x32_bf16 v[106:109], v[34:37], v[182:185], v[122:125]
	v_mfma_f32_16x16x32_bf16 v[54:57], v[34:37], v[54:57], v[70:73]
	v_mfma_f32_16x16x32_bf16 v[34:37], v[34:37], v[50:53], v[74:77]
	v_or_b32_e32 v50, s7, v0
	v_lshl_or_b32 v52, v112, 2, s1
	v_ashrrev_i32_e32 v51, 31, v50
	v_mfma_f32_16x16x32_bf16 v[62:65], v[162:165], v[166:169], v[146:149]
	v_ashrrev_i32_e32 v53, 31, v52
	v_lshlrev_b64 v[52:53], 1, v[52:53]
	v_mfma_f32_16x16x32_bf16 v[70:73], v[30:33], v[18:21], v[102:105]
	s_nop 2
	v_or_b32_e32 v104, 0x400, v50
	v_mfma_f32_16x16x32_bf16 v[74:77], v[30:33], v[22:25], v[98:101]
	v_mad_i64_i32 v[102:103], s[0:1], v50, s78, v[110:111]
	v_ashrrev_i32_e32 v105, 31, v104
	s_nop 0
	v_or_b32_e32 v98, 0x800, v50
	v_or_b32_e32 v100, 0xc00, v50
	v_lshlrev_b64 v[50:51], 11, v[50:51]
	v_ashrrev_i32_e32 v99, 31, v98
	v_ashrrev_i32_e32 v101, 31, v100
	v_mfma_f32_16x16x32_bf16 v[94:97], v[30:33], v[10:13], v[94:97]
	v_lshl_add_u64 v[50:51], s[60:61], 0, v[50:51]
	v_lshl_add_u64 v[102:103], v[102:103], 0, v[52:53]
	v_lshl_add_u64 v[112:113], v[50:51], 0, v[52:53]
	v_mfma_f32_16x16x32_bf16 v[90:93], v[30:33], v[6:9], v[90:93]
	v_mad_i64_i32 v[30:31], s[0:1], v104, s78, v[110:111]
	v_mad_i64_i32 v[32:33], s[0:1], v98, s78, v[110:111]
	v_mfma_f32_16x16x32_bf16 v[86:89], v[26:29], v[18:21], v[86:89]
	v_lshlrev_b64 v[104:105], 11, v[104:105]
	v_lshlrev_b64 v[98:99], 11, v[98:99]
	v_mad_i64_i32 v[110:111], s[0:1], v100, s78, v[110:111]
	v_mfma_f32_16x16x32_bf16 v[82:85], v[26:29], v[22:25], v[82:85]
	v_lshl_add_u64 v[114:115], v[30:31], 0, v[52:53]
	v_lshl_add_u64 v[30:31], s[60:61], 0, v[104:105]
	v_lshl_add_u64 v[50:51], v[32:33], 0, v[52:53]
	v_mfma_f32_16x16x32_bf16 v[78:81], v[26:29], v[10:13], v[78:81]
	v_lshl_add_u64 v[32:33], s[60:61], 0, v[98:99]
	v_pk_mul_f32 v[70:71], v[70:71], s[80:81] op_sel_hi:[1,0]
	v_pk_mul_f32 v[72:73], v[72:73], s[80:81] op_sel_hi:[1,0]
	v_mfma_f32_16x16x32_bf16 v[66:69], v[26:29], v[6:9], v[66:69]
	v_lshlrev_b64 v[26:27], 11, v[100:101]
	v_lshl_add_u64 v[26:27], s[60:61], 0, v[26:27]
	v_lshl_add_u64 v[28:29], v[110:111], 0, v[52:53]
	v_mfma_f32_16x16x32_bf16 v[98:101], v[14:17], v[10:13], v[46:49]
	v_lshl_add_u64 v[26:27], v[26:27], 0, v[52:53]
	global_load_dwordx2 v[192:193], v[102:103], off offset:1056
	global_load_dwordx2 v[194:195], v[102:103], off offset:1024
	global_load_dwordx2 v[196:197], v[102:103], off offset:1088
	global_load_dwordx2 v[198:199], v[102:103], off offset:1120
	global_load_dwordx2 v[200:201], v[114:115], off offset:1024
	global_load_dwordx2 v[202:203], v[114:115], off offset:1056
	global_load_dwordx2 v[204:205], v[114:115], off offset:1088
	global_load_dwordx2 v[206:207], v[114:115], off offset:1120
	global_load_dwordx2 v[208:209], v[50:51], off offset:1024
	global_load_dwordx2 v[210:211], v[50:51], off offset:1056
	global_load_dwordx2 v[212:213], v[50:51], off offset:1088
	global_load_dwordx2 v[214:215], v[50:51], off offset:1120
	global_load_dwordx2 v[216:217], v[28:29], off offset:1024
	global_load_dwordx2 v[218:219], v[28:29], off offset:1056
	global_load_dwordx2 v[220:221], v[28:29], off offset:1088
	global_load_dwordx2 v[222:223], v[28:29], off offset:1120
	v_pk_mul_f32 v[86:87], v[86:87], s[80:81] op_sel_hi:[1,0]
	v_mfma_f32_16x16x32_bf16 v[62:65], v[14:17], v[18:21], v[62:65]
	v_lshl_add_u64 v[46:47], v[30:31], 0, v[52:53]
	v_lshl_add_u64 v[30:31], v[32:33], 0, v[52:53]
	s_nop 0
	v_pk_mul_f32 v[32:33], v[98:99], s[80:81] op_sel_hi:[1,0]
	v_mfma_f32_16x16x32_bf16 v[58:61], v[14:17], v[22:25], v[58:61]
	v_mul_f32_e64 v88, v88, s80
	v_mul_f32_e64 v89, v89, s80
	s_nop 0
	v_pk_mul_f32 v[62:63], v[62:63], s[80:81] op_sel_hi:[1,0]
	v_pk_mul_f32 v[64:65], v[64:65], s[80:81] op_sel_hi:[1,0]
	v_mfma_f32_16x16x32_bf16 v[14:17], v[14:17], v[6:9], v[42:45]
	v_mul_f32_e64 v74, v74, s80
	v_mul_f32_e64 v75, v75, s80
	v_pk_mul_f32 v[76:77], v[76:77], s[80:81] op_sel_hi:[1,0]
	v_pk_mul_f32 v[82:83], v[82:83], s[80:81] op_sel_hi:[1,0]
	v_mfma_f32_16x16x32_bf16 v[42:45], v[2:5], v[22:25], v[106:109]
	v_mul_f32_e64 v22, v78, s80
	v_mul_f32_e64 v23, v79, s80
	v_pk_mul_f32 v[24:25], v[80:81], s[80:81] op_sel_hi:[1,0]
	v_pk_mul_f32 v[84:85], v[84:85], s[80:81] op_sel_hi:[1,0]
	v_mfma_f32_16x16x32_bf16 v[52:55], v[2:5], v[10:13], v[54:57]
	v_mul_f32_e64 v10, v14, s80
	v_mul_f32_e64 v11, v15, s80
	v_pk_mul_f32 v[12:13], v[16:17], s[80:81] op_sel_hi:[1,0]
	v_pk_mul_f32 v[58:59], v[58:59], s[80:81] op_sel_hi:[1,0]
	v_mfma_f32_16x16x32_bf16 v[38:41], v[2:5], v[18:21], v[38:41]
	v_mul_f32_e64 v18, v94, s80
	v_mul_f32_e64 v19, v95, s80
	v_pk_mul_f32 v[20:21], v[96:97], s[80:81] op_sel_hi:[1,0]
	v_pk_mul_f32 v[60:61], v[60:61], s[80:81] op_sel_hi:[1,0]
	v_mfma_f32_16x16x32_bf16 v[102:105], v[2:5], v[6:9], v[34:37]
	v_mul_f32_e64 v2, v90, s80
	v_mul_f32_e64 v3, v91, s80
	v_pk_mul_f32 v[4:5], v[92:93], s[80:81] op_sel_hi:[1,0]
	v_pk_mul_f32 v[6:7], v[66:67], s[80:81] op_sel_hi:[1,0]
	v_pk_mul_f32 v[36:37], v[52:53], s[80:81] op_sel_hi:[1,0]
	v_pk_mul_f32 v[8:9], v[68:69], s[80:81] op_sel_hi:[1,0]
	v_pk_mul_f32 v[66:67], v[38:39], s[80:81] op_sel_hi:[1,0]
	v_pk_mul_f32 v[38:39], v[54:55], s[80:81] op_sel_hi:[1,0]
	v_pk_mul_f32 v[34:35], v[100:101], s[80:81] op_sel_hi:[1,0]
	v_pk_mul_f32 v[14:15], v[102:103], s[80:81] op_sel_hi:[1,0]
	v_pk_mul_f32 v[16:17], v[104:105], s[80:81] op_sel_hi:[1,0]
	v_pk_mul_f32 v[40:41], v[40:41], s[80:81] op_sel_hi:[1,0]
	v_pk_mul_f32 v[42:43], v[42:43], s[80:81] op_sel_hi:[1,0]
	v_pk_mul_f32 v[44:45], v[44:45], s[80:81] op_sel_hi:[1,0]
	s_waitcnt vmcnt(12)
	v_lshlrev_b32_e32 v54, 16, v192
	v_and_b32_e32 v55, 0xffff0000, v192
	v_lshlrev_b32_e32 v52, 16, v194
	v_and_b32_e32 v53, 0xffff0000, v194
	v_lshlrev_b32_e32 v48, 16, v195
	v_and_b32_e32 v49, 0xffff0000, v195
	v_lshlrev_b32_e32 v68, 16, v193
	v_and_b32_e32 v69, 0xffff0000, v193
	v_mul_f32_e32 v0, 0xbfb8aa3b, v52
	v_mul_f32_e32 v92, 0xbfb8aa3b, v53
	v_mul_f32_e32 v93, 0xbfb8aa3b, v48
	v_mul_f32_e32 v94, 0xbfb8aa3b, v49
	v_mul_f32_e32 v95, 0xbfb8aa3b, v54
	v_mul_f32_e32 v96, 0xbfb8aa3b, v55
	v_mul_f32_e32 v97, 0xbfb8aa3b, v68
	v_mul_f32_e32 v98, 0xbfb8aa3b, v69
	v_exp_f32_e32 v0, v0
	v_exp_f32_e32 v92, v92
	v_exp_f32_e32 v93, v93
	v_lshlrev_b32_e32 v78, 16, v196
	v_and_b32_e32 v79, 0xffff0000, v196
	v_lshlrev_b32_e32 v80, 16, v197
	v_and_b32_e32 v81, 0xffff0000, v197
	v_mul_f32_e32 v99, 0xbfb8aa3b, v78
	v_lshlrev_b32_e32 v90, 16, v198
	v_and_b32_e32 v91, 0xffff0000, v198
	v_lshlrev_b32_e32 v56, 16, v199
	v_and_b32_e32 v57, 0xffff0000, v199
	v_mul_f32_e32 v100, 0xbfb8aa3b, v79
	v_mul_f32_e32 v101, 0xbfb8aa3b, v80
	v_mul_f32_e32 v102, 0xbfb8aa3b, v81
	v_mul_f32_e32 v103, 0xbfb8aa3b, v90
	v_mul_f32_e32 v104, 0xbfb8aa3b, v91
	v_mul_f32_e32 v105, 0xbfb8aa3b, v56
	v_mul_f32_e32 v106, 0xbfb8aa3b, v57
	v_exp_f32_e32 v94, v94
	v_exp_f32_e32 v95, v95
	v_exp_f32_e32 v96, v96
	v_exp_f32_e32 v97, v97
	v_exp_f32_e32 v98, v98
	v_exp_f32_e32 v99, v99
	v_exp_f32_e32 v100, v100
	v_exp_f32_e32 v101, v101
	v_exp_f32_e32 v102, v102
	v_exp_f32_e32 v103, v103
	v_exp_f32_e32 v104, v104
	v_exp_f32_e32 v105, v105
	v_exp_f32_e32 v106, v106
	v_add_f32_e32 v0, 1.0, v0
	v_add_f32_e32 v107, 1.0, v92
	v_add_f32_e32 v108, 1.0, v93
	v_add_f32_e32 v109, 1.0, v94
	v_add_f32_e32 v110, 1.0, v95
	v_add_f32_e32 v111, 1.0, v96
	v_add_f32_e32 v116, 1.0, v97
	v_add_f32_e32 v117, 1.0, v98
	v_add_f32_e32 v118, 1.0, v99
	v_add_f32_e32 v119, 1.0, v100
	v_add_f32_e32 v120, 1.0, v101
	v_add_f32_e32 v121, 1.0, v102
	v_add_f32_e32 v122, 1.0, v103
	v_add_f32_e32 v123, 1.0, v104
	v_add_f32_e32 v124, 1.0, v105
	v_add_f32_e32 v125, 1.0, v106
	v_rcp_f32_e32 v92, v0
	v_rcp_f32_e32 v93, v107
	v_rcp_f32_e32 v94, v108
	v_rcp_f32_e32 v95, v109
	v_rcp_f32_e32 v96, v110
	v_rcp_f32_e32 v97, v111
	v_rcp_f32_e32 v98, v116
	v_rcp_f32_e32 v99, v117
	v_rcp_f32_e32 v100, v118
	v_rcp_f32_e32 v101, v119
	v_rcp_f32_e32 v102, v120
	v_rcp_f32_e32 v103, v121
	v_rcp_f32_e32 v104, v122
	v_rcp_f32_e32 v105, v123
	v_rcp_f32_e32 v106, v124
	v_rcp_f32_e32 v107, v125
	v_pk_mul_f32 v[52:53], v[92:93], v[52:53]
	v_pk_mul_f32 v[48:49], v[94:95], v[48:49]
	v_pk_mul_f32 v[54:55], v[96:97], v[54:55]
	v_pk_mul_f32 v[68:69], v[98:99], v[68:69]
	v_pk_mul_f32 v[78:79], v[100:101], v[78:79]
	v_pk_mul_f32 v[80:81], v[102:103], v[80:81]
	v_pk_mul_f32 v[90:91], v[104:105], v[90:91]
	v_pk_mul_f32 v[56:57], v[106:107], v[56:57]
	v_pk_mul_f32 v[52:53], v[70:71], v[52:53]
	v_pk_mul_f32 v[48:49], v[72:73], v[48:49]
	v_pk_mul_f32 v[54:55], v[86:87], v[54:55]
	v_pk_mul_f32 v[68:69], v[88:89], v[68:69]
	v_pk_mul_f32 v[62:63], v[62:63], v[78:79]
	v_pk_mul_f32 v[64:65], v[64:65], v[80:81]
	v_pk_mul_f32 v[66:67], v[66:67], v[90:91]
	v_pk_mul_f32 v[40:41], v[40:41], v[56:57]
	v_cvt_pk_bf16_f32 v52, v52, v53
	v_cvt_pk_bf16_f32 v53, v48, v49
	v_cvt_pk_bf16_f32 v48, v54, v55
	v_cvt_pk_bf16_f32 v49, v68, v69
	v_cvt_pk_bf16_f32 v54, v62, v63
	v_cvt_pk_bf16_f32 v55, v64, v65
	v_cvt_pk_bf16_f32 v56, v66, v67
	v_cvt_pk_bf16_f32 v57, v40, v41
	v_readlane_b32 s12, v254, 31
	v_readlane_b32 s13, v254, 32
	v_subrev_u32_e32 v158, s12, v112
	v_and_b32_e32 v160, 0x7c0, v158
	v_and_b32_e32 v170, 0xfffff7ff, v158
	v_add_u32_e32 v170, v170, v160
	v_bfe_u32 v160, v158, 11, 1
	v_lshl_or_b32 v170, v160, 6, v170
	v_bfe_i32 v160, v158, 25, 1
	v_bfi_b32 v170, v160, v158, v170
	global_store_dwordx2 v170, v[52:53], s[12:13]
	v_readlane_b32 s12, v254, 31
	v_readlane_b32 s13, v254, 32
	v_subrev_u32_e32 v158, s12, v112
	v_add_u32_e32 v158, 32, v158
	v_and_b32_e32 v160, 0x7c0, v158
	v_and_b32_e32 v170, 0xfffff7ff, v158
	v_add_u32_e32 v170, v170, v160
	v_bfe_u32 v160, v158, 11, 1
	v_lshl_or_b32 v170, v160, 6, v170
	v_bfe_i32 v160, v158, 25, 1
	v_bfi_b32 v170, v160, v158, v170
	global_store_dwordx2 v170, v[48:49], s[12:13]
	v_readlane_b32 s12, v254, 31
	v_readlane_b32 s13, v254, 32
	v_subrev_u32_e32 v158, s12, v112
	v_add_u32_e32 v158, 64, v158
	v_and_b32_e32 v160, 0x7c0, v158
	v_and_b32_e32 v170, 0xfffff7ff, v158
	v_add_u32_e32 v170, v170, v160
	v_bfe_u32 v160, v158, 11, 1
	v_lshl_or_b32 v170, v160, 6, v170
	v_bfe_i32 v160, v158, 25, 1
	v_bfi_b32 v170, v160, v158, v170
	global_store_dwordx2 v170, v[54:55], s[12:13]
	v_readlane_b32 s12, v254, 31
	v_readlane_b32 s13, v254, 32
	v_subrev_u32_e32 v158, s12, v112
	v_add_u32_e32 v158, 0x60, v158
	v_and_b32_e32 v160, 0x7c0, v158
	v_and_b32_e32 v170, 0xfffff7ff, v158
	v_add_u32_e32 v170, v170, v160
	v_bfe_u32 v160, v158, 11, 1
	v_lshl_or_b32 v170, v160, 6, v170
	v_bfe_i32 v160, v158, 25, 1
	v_bfi_b32 v170, v160, v158, v170
	global_store_dwordx2 v170, v[56:57], s[12:13]
	s_nop 0
	s_waitcnt vmcnt(12)
	v_lshlrev_b32_e32 v56, 16, v200
	v_and_b32_e32 v57, 0xffff0000, v200
	v_lshlrev_b32_e32 v40, 16, v201
	v_and_b32_e32 v41, 0xffff0000, v201
	v_lshlrev_b32_e32 v62, 16, v202
	v_and_b32_e32 v63, 0xffff0000, v202
	v_lshlrev_b32_e32 v48, 16, v203
	v_and_b32_e32 v49, 0xffff0000, v203
	v_lshlrev_b32_e32 v64, 16, v204
	v_and_b32_e32 v65, 0xffff0000, v204
	v_lshlrev_b32_e32 v52, 16, v205
	v_and_b32_e32 v53, 0xffff0000, v205
	v_lshlrev_b32_e32 v66, 16, v206
	v_and_b32_e32 v67, 0xffff0000, v206
	v_lshlrev_b32_e32 v54, 16, v207
	v_and_b32_e32 v55, 0xffff0000, v207
	v_mul_f32_e32 v0, 0xbfb8aa3b, v56
	v_mul_f32_e32 v68, 0xbfb8aa3b, v57
	v_mul_f32_e32 v69, 0xbfb8aa3b, v40
	v_mul_f32_e32 v70, 0xbfb8aa3b, v41
	v_mul_f32_e32 v71, 0xbfb8aa3b, v62
	v_mul_f32_e32 v72, 0xbfb8aa3b, v63
	v_mul_f32_e32 v73, 0xbfb8aa3b, v48
	v_mul_f32_e32 v78, 0xbfb8aa3b, v49
	v_mul_f32_e32 v79, 0xbfb8aa3b, v64
	v_mul_f32_e32 v80, 0xbfb8aa3b, v65
	v_mul_f32_e32 v81, 0xbfb8aa3b, v52
	v_mul_f32_e32 v86, 0xbfb8aa3b, v53
	v_mul_f32_e32 v87, 0xbfb8aa3b, v66
	v_mul_f32_e32 v88, 0xbfb8aa3b, v67
	v_mul_f32_e32 v89, 0xbfb8aa3b, v54
	v_mul_f32_e32 v90, 0xbfb8aa3b, v55
	v_exp_f32_e32 v0, v0
	v_exp_f32_e32 v68, v68
	v_exp_f32_e32 v69, v69
	v_exp_f32_e32 v70, v70
	v_exp_f32_e32 v71, v71
	v_exp_f32_e32 v72, v72
	v_exp_f32_e32 v73, v73
	v_exp_f32_e32 v78, v78
	v_exp_f32_e32 v79, v79
	v_exp_f32_e32 v80, v80
	v_exp_f32_e32 v81, v81
	v_exp_f32_e32 v86, v86
	v_exp_f32_e32 v87, v87
	v_exp_f32_e32 v88, v88
	v_exp_f32_e32 v89, v89
	v_exp_f32_e32 v90, v90
	v_add_f32_e32 v0, 1.0, v0
	v_add_f32_e32 v91, 1.0, v68
	v_add_f32_e32 v92, 1.0, v69
	v_add_f32_e32 v93, 1.0, v70
	v_add_f32_e32 v94, 1.0, v71
	v_add_f32_e32 v95, 1.0, v72
	v_add_f32_e32 v96, 1.0, v73
	v_add_f32_e32 v97, 1.0, v78
	v_add_f32_e32 v98, 1.0, v79
	v_add_f32_e32 v99, 1.0, v80
	v_add_f32_e32 v100, 1.0, v81
	v_add_f32_e32 v101, 1.0, v86
	v_add_f32_e32 v102, 1.0, v87
	v_add_f32_e32 v103, 1.0, v88
	v_add_f32_e32 v104, 1.0, v89
	v_add_f32_e32 v105, 1.0, v90
	v_rcp_f32_e32 v68, v0
	v_rcp_f32_e32 v69, v91
	v_rcp_f32_e32 v70, v92
	v_rcp_f32_e32 v71, v93
	v_rcp_f32_e32 v72, v94
	v_rcp_f32_e32 v73, v95
	v_rcp_f32_e32 v78, v96
	v_rcp_f32_e32 v79, v97
	v_rcp_f32_e32 v80, v98
	v_rcp_f32_e32 v81, v99
	v_rcp_f32_e32 v86, v100
	v_rcp_f32_e32 v87, v101
	v_rcp_f32_e32 v88, v102
	v_rcp_f32_e32 v89, v103
	v_rcp_f32_e32 v90, v104
	v_rcp_f32_e32 v91, v105
	v_pk_mul_f32 v[56:57], v[68:69], v[56:57]
	v_pk_mul_f32 v[40:41], v[70:71], v[40:41]
	v_pk_mul_f32 v[62:63], v[72:73], v[62:63]
	v_pk_mul_f32 v[48:49], v[78:79], v[48:49]
	v_pk_mul_f32 v[64:65], v[80:81], v[64:65]
	v_pk_mul_f32 v[52:53], v[86:87], v[52:53]
	v_pk_mul_f32 v[66:67], v[88:89], v[66:67]
	v_pk_mul_f32 v[54:55], v[90:91], v[54:55]
	v_pk_mul_f32 v[56:57], v[74:75], v[56:57]
	v_pk_mul_f32 v[40:41], v[76:77], v[40:41]
	v_pk_mul_f32 v[62:63], v[82:83], v[62:63]
	v_pk_mul_f32 v[48:49], v[84:85], v[48:49]
	v_pk_mul_f32 v[58:59], v[58:59], v[64:65]
	v_pk_mul_f32 v[52:53], v[60:61], v[52:53]
	v_pk_mul_f32 v[42:43], v[42:43], v[66:67]
	v_pk_mul_f32 v[44:45], v[44:45], v[54:55]
	v_cvt_pk_bf16_f32 v54, v56, v57
	v_cvt_pk_bf16_f32 v55, v40, v41
	v_cvt_pk_bf16_f32 v40, v62, v63
	v_cvt_pk_bf16_f32 v41, v48, v49
	v_cvt_pk_bf16_f32 v48, v58, v59
	v_cvt_pk_bf16_f32 v49, v52, v53
	v_cvt_pk_bf16_f32 v42, v42, v43
	v_cvt_pk_bf16_f32 v43, v44, v45
	v_readlane_b32 s12, v254, 31
	v_readlane_b32 s13, v254, 32
	v_subrev_u32_e32 v158, s12, v46
	v_and_b32_e32 v160, 0x7c0, v158
	v_and_b32_e32 v170, 0xfffff7ff, v158
	v_add_u32_e32 v170, v170, v160
	v_bfe_u32 v160, v158, 11, 1
	v_lshl_or_b32 v170, v160, 6, v170
	v_bfe_i32 v160, v158, 25, 1
	v_bfi_b32 v170, v160, v158, v170
	global_store_dwordx2 v170, v[54:55], s[12:13]
	v_readlane_b32 s12, v254, 31
	v_readlane_b32 s13, v254, 32
	v_subrev_u32_e32 v158, s12, v46
	v_add_u32_e32 v158, 32, v158
	v_and_b32_e32 v160, 0x7c0, v158
	v_and_b32_e32 v170, 0xfffff7ff, v158
	v_add_u32_e32 v170, v170, v160
	v_bfe_u32 v160, v158, 11, 1
	v_lshl_or_b32 v170, v160, 6, v170
	v_bfe_i32 v160, v158, 25, 1
	v_bfi_b32 v170, v160, v158, v170
	global_store_dwordx2 v170, v[40:41], s[12:13]
	v_readlane_b32 s12, v254, 31
	v_readlane_b32 s13, v254, 32
	v_subrev_u32_e32 v158, s12, v46
	v_add_u32_e32 v158, 64, v158
	v_and_b32_e32 v160, 0x7c0, v158
	v_and_b32_e32 v170, 0xfffff7ff, v158
	v_add_u32_e32 v170, v170, v160
	v_bfe_u32 v160, v158, 11, 1
	v_lshl_or_b32 v170, v160, 6, v170
	v_bfe_i32 v160, v158, 25, 1
	v_bfi_b32 v170, v160, v158, v170
	global_store_dwordx2 v170, v[48:49], s[12:13]
	v_readlane_b32 s12, v254, 31
	v_readlane_b32 s13, v254, 32
	v_subrev_u32_e32 v158, s12, v46
	v_add_u32_e32 v158, 0x60, v158
	v_and_b32_e32 v160, 0x7c0, v158
	v_and_b32_e32 v170, 0xfffff7ff, v158
	v_add_u32_e32 v170, v170, v160
	v_bfe_u32 v160, v158, 11, 1
	v_lshl_or_b32 v170, v160, 6, v170
	v_bfe_i32 v160, v158, 25, 1
	v_bfi_b32 v170, v160, v158, v170
	global_store_dwordx2 v170, v[42:43], s[12:13]
	s_nop 0
	s_waitcnt vmcnt(12)
	v_lshlrev_b32_e32 v48, 16, v208
	v_and_b32_e32 v49, 0xffff0000, v208
	v_lshlrev_b32_e32 v40, 16, v209
	v_and_b32_e32 v41, 0xffff0000, v209
	v_lshlrev_b32_e32 v50, 16, v210
	v_and_b32_e32 v51, 0xffff0000, v210
	v_lshlrev_b32_e32 v42, 16, v211
	v_and_b32_e32 v43, 0xffff0000, v211
	v_lshlrev_b32_e32 v52, 16, v212
	v_and_b32_e32 v53, 0xffff0000, v212
	v_lshlrev_b32_e32 v44, 16, v213
	v_and_b32_e32 v45, 0xffff0000, v213
	v_lshlrev_b32_e32 v54, 16, v214
	v_and_b32_e32 v55, 0xffff0000, v214
	v_lshlrev_b32_e32 v46, 16, v215
	v_and_b32_e32 v47, 0xffff0000, v215
	v_mul_f32_e32 v0, 0xbfb8aa3b, v48
	v_mul_f32_e32 v56, 0xbfb8aa3b, v49
	v_mul_f32_e32 v57, 0xbfb8aa3b, v40
	v_mul_f32_e32 v58, 0xbfb8aa3b, v41
	v_mul_f32_e32 v59, 0xbfb8aa3b, v50
	v_mul_f32_e32 v60, 0xbfb8aa3b, v51
	v_mul_f32_e32 v61, 0xbfb8aa3b, v42
	v_mul_f32_e32 v62, 0xbfb8aa3b, v43
	v_mul_f32_e32 v63, 0xbfb8aa3b, v52
	v_mul_f32_e32 v64, 0xbfb8aa3b, v53
	v_mul_f32_e32 v65, 0xbfb8aa3b, v44
	v_mul_f32_e32 v66, 0xbfb8aa3b, v45
	v_mul_f32_e32 v67, 0xbfb8aa3b, v54
	v_mul_f32_e32 v68, 0xbfb8aa3b, v55
	v_mul_f32_e32 v69, 0xbfb8aa3b, v46
	v_mul_f32_e32 v70, 0xbfb8aa3b, v47
	v_exp_f32_e32 v0, v0
	v_exp_f32_e32 v56, v56
	v_exp_f32_e32 v57, v57
	v_exp_f32_e32 v58, v58
	v_exp_f32_e32 v59, v59
	v_exp_f32_e32 v60, v60
	v_exp_f32_e32 v61, v61
	v_exp_f32_e32 v62, v62
	v_exp_f32_e32 v63, v63
	v_exp_f32_e32 v64, v64
	v_exp_f32_e32 v65, v65
	v_exp_f32_e32 v66, v66
	v_exp_f32_e32 v67, v67
	v_exp_f32_e32 v68, v68
	v_exp_f32_e32 v69, v69
	v_exp_f32_e32 v70, v70
	v_add_f32_e32 v0, 1.0, v0
	v_add_f32_e32 v71, 1.0, v56
	v_add_f32_e32 v72, 1.0, v57
	v_add_f32_e32 v73, 1.0, v58
	v_add_f32_e32 v74, 1.0, v59
	v_add_f32_e32 v75, 1.0, v60
	v_add_f32_e32 v76, 1.0, v61
	v_add_f32_e32 v77, 1.0, v62
	v_add_f32_e32 v78, 1.0, v63
	v_add_f32_e32 v79, 1.0, v64
	v_add_f32_e32 v80, 1.0, v65
	v_add_f32_e32 v81, 1.0, v66
	v_add_f32_e32 v82, 1.0, v67
	v_add_f32_e32 v83, 1.0, v68
	v_add_f32_e32 v84, 1.0, v69
	v_add_f32_e32 v85, 1.0, v70
	v_rcp_f32_e32 v56, v0
	v_rcp_f32_e32 v57, v71
	v_rcp_f32_e32 v58, v72
	v_rcp_f32_e32 v59, v73
	v_rcp_f32_e32 v60, v74
	v_rcp_f32_e32 v61, v75
	v_rcp_f32_e32 v62, v76
	v_rcp_f32_e32 v63, v77
	v_rcp_f32_e32 v64, v78
	v_rcp_f32_e32 v65, v79
	v_rcp_f32_e32 v66, v80
	v_rcp_f32_e32 v67, v81
	v_rcp_f32_e32 v68, v82
	v_rcp_f32_e32 v69, v83
	v_rcp_f32_e32 v70, v84
	v_rcp_f32_e32 v71, v85
	v_pk_mul_f32 v[48:49], v[56:57], v[48:49]
	v_pk_mul_f32 v[40:41], v[58:59], v[40:41]
	v_pk_mul_f32 v[50:51], v[60:61], v[50:51]
	v_pk_mul_f32 v[42:43], v[62:63], v[42:43]
	v_pk_mul_f32 v[52:53], v[64:65], v[52:53]
	v_pk_mul_f32 v[44:45], v[66:67], v[44:45]
	v_pk_mul_f32 v[54:55], v[68:69], v[54:55]
	v_pk_mul_f32 v[46:47], v[70:71], v[46:47]
	v_pk_mul_f32 v[18:19], v[18:19], v[48:49]
	v_pk_mul_f32 v[20:21], v[20:21], v[40:41]
	v_pk_mul_f32 v[22:23], v[22:23], v[50:51]
	v_pk_mul_f32 v[24:25], v[24:25], v[42:43]
	v_pk_mul_f32 v[32:33], v[32:33], v[52:53]
	v_pk_mul_f32 v[34:35], v[34:35], v[44:45]
	v_pk_mul_f32 v[36:37], v[36:37], v[54:55]
	v_pk_mul_f32 v[38:39], v[38:39], v[46:47]
	v_cvt_pk_bf16_f32 v18, v18, v19
	v_cvt_pk_bf16_f32 v19, v20, v21
	v_cvt_pk_bf16_f32 v20, v22, v23
	v_cvt_pk_bf16_f32 v21, v24, v25
	v_cvt_pk_bf16_f32 v22, v32, v33
	v_cvt_pk_bf16_f32 v23, v34, v35
	v_cvt_pk_bf16_f32 v24, v36, v37
	v_cvt_pk_bf16_f32 v25, v38, v39
	v_readlane_b32 s12, v254, 31
	v_readlane_b32 s13, v254, 32
	v_subrev_u32_e32 v158, s12, v30
	v_and_b32_e32 v160, 0x7c0, v158
	v_and_b32_e32 v170, 0xfffff7ff, v158
	v_add_u32_e32 v170, v170, v160
	v_bfe_u32 v160, v158, 11, 1
	v_lshl_or_b32 v170, v160, 6, v170
	v_bfe_i32 v160, v158, 25, 1
	v_bfi_b32 v170, v160, v158, v170
	global_store_dwordx2 v170, v[18:19], s[12:13]
	v_readlane_b32 s12, v254, 31
	v_readlane_b32 s13, v254, 32
	v_subrev_u32_e32 v158, s12, v30
	v_add_u32_e32 v158, 32, v158
	v_and_b32_e32 v160, 0x7c0, v158
	v_and_b32_e32 v170, 0xfffff7ff, v158
	v_add_u32_e32 v170, v170, v160
	v_bfe_u32 v160, v158, 11, 1
	v_lshl_or_b32 v170, v160, 6, v170
	v_bfe_i32 v160, v158, 25, 1
	v_bfi_b32 v170, v160, v158, v170
	global_store_dwordx2 v170, v[20:21], s[12:13]
	v_readlane_b32 s12, v254, 31
	v_readlane_b32 s13, v254, 32
	v_subrev_u32_e32 v158, s12, v30
	v_add_u32_e32 v158, 64, v158
	v_and_b32_e32 v160, 0x7c0, v158
	v_and_b32_e32 v170, 0xfffff7ff, v158
	v_add_u32_e32 v170, v170, v160
	v_bfe_u32 v160, v158, 11, 1
	v_lshl_or_b32 v170, v160, 6, v170
	v_bfe_i32 v160, v158, 25, 1
	v_bfi_b32 v170, v160, v158, v170
	global_store_dwordx2 v170, v[22:23], s[12:13]
	v_readlane_b32 s12, v254, 31
	v_readlane_b32 s13, v254, 32
	v_subrev_u32_e32 v158, s12, v30
	v_add_u32_e32 v158, 0x60, v158
	v_and_b32_e32 v160, 0x7c0, v158
	v_and_b32_e32 v170, 0xfffff7ff, v158
	v_add_u32_e32 v170, v170, v160
	v_bfe_u32 v160, v158, 11, 1
	v_lshl_or_b32 v170, v160, 6, v170
	v_bfe_i32 v160, v158, 25, 1
	v_bfi_b32 v170, v160, v158, v170
	global_store_dwordx2 v170, v[24:25], s[12:13]
	s_nop 0
	s_waitcnt vmcnt(12)
	v_lshlrev_b32_e32 v28, 16, v216
	v_and_b32_e32 v29, 0xffff0000, v216
	v_lshlrev_b32_e32 v18, 16, v217
	v_and_b32_e32 v19, 0xffff0000, v217
	v_lshlrev_b32_e32 v30, 16, v218
	v_and_b32_e32 v31, 0xffff0000, v218
	v_lshlrev_b32_e32 v20, 16, v219
	v_and_b32_e32 v21, 0xffff0000, v219
	v_lshlrev_b32_e32 v32, 16, v220
	v_and_b32_e32 v33, 0xffff0000, v220
	v_lshlrev_b32_e32 v22, 16, v221
	v_and_b32_e32 v23, 0xffff0000, v221
	v_lshlrev_b32_e32 v34, 16, v222
	v_and_b32_e32 v35, 0xffff0000, v222
	v_lshlrev_b32_e32 v24, 16, v223
	v_and_b32_e32 v25, 0xffff0000, v223
	v_mul_f32_e32 v0, 0xbfb8aa3b, v28
	v_mul_f32_e32 v36, 0xbfb8aa3b, v29
	v_mul_f32_e32 v37, 0xbfb8aa3b, v18
	v_mul_f32_e32 v38, 0xbfb8aa3b, v19
	v_mul_f32_e32 v39, 0xbfb8aa3b, v30
	v_mul_f32_e32 v40, 0xbfb8aa3b, v31
	v_mul_f32_e32 v41, 0xbfb8aa3b, v20
	v_mul_f32_e32 v42, 0xbfb8aa3b, v21
	v_mul_f32_e32 v43, 0xbfb8aa3b, v32
	v_mul_f32_e32 v44, 0xbfb8aa3b, v33
	v_mul_f32_e32 v45, 0xbfb8aa3b, v22
	v_mul_f32_e32 v46, 0xbfb8aa3b, v23
	v_mul_f32_e32 v47, 0xbfb8aa3b, v34
	v_mul_f32_e32 v48, 0xbfb8aa3b, v35
	v_mul_f32_e32 v49, 0xbfb8aa3b, v24
	v_mul_f32_e32 v50, 0xbfb8aa3b, v25
	v_exp_f32_e32 v0, v0
	v_exp_f32_e32 v36, v36
	v_exp_f32_e32 v37, v37
	v_exp_f32_e32 v38, v38
	v_exp_f32_e32 v39, v39
	v_exp_f32_e32 v40, v40
	v_exp_f32_e32 v41, v41
	v_exp_f32_e32 v42, v42
	v_exp_f32_e32 v43, v43
	v_exp_f32_e32 v44, v44
	v_exp_f32_e32 v45, v45
	v_exp_f32_e32 v46, v46
	v_exp_f32_e32 v47, v47
	v_exp_f32_e32 v48, v48
	v_exp_f32_e32 v49, v49
	v_exp_f32_e32 v50, v50
	v_add_f32_e32 v0, 1.0, v0
	v_add_f32_e32 v51, 1.0, v36
	v_add_f32_e32 v52, 1.0, v37
	v_add_f32_e32 v53, 1.0, v38
	v_add_f32_e32 v54, 1.0, v39
	v_add_f32_e32 v55, 1.0, v40
	v_add_f32_e32 v56, 1.0, v41
	v_add_f32_e32 v57, 1.0, v42
	v_add_f32_e32 v58, 1.0, v43
	v_add_f32_e32 v59, 1.0, v44
	v_add_f32_e32 v60, 1.0, v45
	v_add_f32_e32 v61, 1.0, v46
	v_add_f32_e32 v62, 1.0, v47
	v_add_f32_e32 v63, 1.0, v48
	v_add_f32_e32 v64, 1.0, v49
	v_add_f32_e32 v65, 1.0, v50
	v_rcp_f32_e32 v36, v0
	v_rcp_f32_e32 v37, v51
	v_rcp_f32_e32 v38, v52
	v_rcp_f32_e32 v39, v53
	v_rcp_f32_e32 v40, v54
	v_rcp_f32_e32 v41, v55
	v_rcp_f32_e32 v42, v56
	v_rcp_f32_e32 v43, v57
	v_rcp_f32_e32 v44, v58
	v_rcp_f32_e32 v45, v59
	v_rcp_f32_e32 v46, v60
	v_rcp_f32_e32 v47, v61
	v_rcp_f32_e32 v48, v62
	v_rcp_f32_e32 v49, v63
	v_rcp_f32_e32 v50, v64
	v_rcp_f32_e32 v51, v65
	v_pk_mul_f32 v[28:29], v[36:37], v[28:29]
	v_pk_mul_f32 v[18:19], v[38:39], v[18:19]
	v_pk_mul_f32 v[30:31], v[40:41], v[30:31]
	v_pk_mul_f32 v[20:21], v[42:43], v[20:21]
	v_pk_mul_f32 v[32:33], v[44:45], v[32:33]
	v_pk_mul_f32 v[22:23], v[46:47], v[22:23]
	v_pk_mul_f32 v[34:35], v[48:49], v[34:35]
	v_pk_mul_f32 v[24:25], v[50:51], v[24:25]
	v_pk_mul_f32 v[2:3], v[2:3], v[28:29]
	v_pk_mul_f32 v[4:5], v[4:5], v[18:19]
	v_pk_mul_f32 v[6:7], v[6:7], v[30:31]
	v_pk_mul_f32 v[8:9], v[8:9], v[20:21]
	v_pk_mul_f32 v[10:11], v[10:11], v[32:33]
	v_pk_mul_f32 v[12:13], v[12:13], v[22:23]
	v_pk_mul_f32 v[14:15], v[14:15], v[34:35]
	v_pk_mul_f32 v[16:17], v[16:17], v[24:25]
	v_cvt_pk_bf16_f32 v2, v2, v3
	v_cvt_pk_bf16_f32 v3, v4, v5
	v_cvt_pk_bf16_f32 v4, v6, v7
	v_cvt_pk_bf16_f32 v5, v8, v9
	v_cvt_pk_bf16_f32 v6, v10, v11
	v_cvt_pk_bf16_f32 v7, v12, v13
	v_cvt_pk_bf16_f32 v8, v14, v15
	v_cvt_pk_bf16_f32 v9, v16, v17
	v_readlane_b32 s12, v254, 31
	v_readlane_b32 s13, v254, 32
	v_subrev_u32_e32 v158, s12, v26
	v_and_b32_e32 v160, 0x7c0, v158
	v_and_b32_e32 v170, 0xfffff7ff, v158
	v_add_u32_e32 v170, v170, v160
	v_bfe_u32 v160, v158, 11, 1
	v_lshl_or_b32 v170, v160, 6, v170
	v_bfe_i32 v160, v158, 25, 1
	v_bfi_b32 v170, v160, v158, v170
	global_store_dwordx2 v170, v[2:3], s[12:13]
	v_readlane_b32 s12, v254, 31
	v_readlane_b32 s13, v254, 32
	v_subrev_u32_e32 v158, s12, v26
	v_add_u32_e32 v158, 32, v158
	v_and_b32_e32 v160, 0x7c0, v158
	v_and_b32_e32 v170, 0xfffff7ff, v158
	v_add_u32_e32 v170, v170, v160
	v_bfe_u32 v160, v158, 11, 1
	v_lshl_or_b32 v170, v160, 6, v170
	v_bfe_i32 v160, v158, 25, 1
	v_bfi_b32 v170, v160, v158, v170
	global_store_dwordx2 v170, v[4:5], s[12:13]
	v_readlane_b32 s12, v254, 31
	v_readlane_b32 s13, v254, 32
	v_subrev_u32_e32 v158, s12, v26
	v_add_u32_e32 v158, 64, v158
	v_and_b32_e32 v160, 0x7c0, v158
	v_and_b32_e32 v170, 0xfffff7ff, v158
	v_add_u32_e32 v170, v170, v160
	v_bfe_u32 v160, v158, 11, 1
	v_lshl_or_b32 v170, v160, 6, v170
	v_bfe_i32 v160, v158, 25, 1
	v_bfi_b32 v170, v160, v158, v170
	global_store_dwordx2 v170, v[6:7], s[12:13]
	v_readlane_b32 s12, v254, 31
	v_readlane_b32 s13, v254, 32
	v_subrev_u32_e32 v158, s12, v26
	v_add_u32_e32 v158, 0x60, v158
	v_and_b32_e32 v160, 0x7c0, v158
	v_and_b32_e32 v170, 0xfffff7ff, v158
	v_add_u32_e32 v170, v170, v160
	v_bfe_u32 v160, v158, 11, 1
	v_lshl_or_b32 v170, v160, 6, v170
	v_bfe_i32 v160, v158, 25, 1
	v_bfi_b32 v170, v160, v158, v170
	global_store_dwordx2 v170, v[8:9], s[12:13]
	s_waitcnt vmcnt(0)
	s_waitcnt lgkmcnt(0)
	s_barrier
	s_cbranch_scc1 .LBB0_436

; DI float silu(float x) { return x * __builtin_amdgcn_rcpf(1.f + __expf(-x)); }
;   DI bf16* HY() const { return (bf16*)(p.ws + WS_HY); }
;   DI bf16* P() const { return (bf16*)(p.ws + WS_P); }
; DI u32x2 pk4(f32x4 v) { return u32x2{pk2(v[0], v[1]), pk2(v[2], v[3])}; }
; DI f32x4 unpk4(u32x2 u) { return f32x4{__uint_as_float(u[0] << 16), __uint_as_float(u[0] & 0xffff0000u), __uint_as_float(u[1] << 16), __uint_as_float(u[1] & 0xffff0000u)}; }
; DI void attn_item(const Ctx& c, int item, bf16* lds) {
;     ...
; #pragma unroll
;   for (int qs = 0; qs < 2; ++qs) {
;     const float inv = 1.f / xhalf_sum(lsum[qs]);
;     const int row = rowbase + wave * 64 + qs * 32 + r;
;     const bf16* mg = c.P() + (size_t)row * LDP + C_MG + h * 64;
;     bf16* dst = c.HY() + (size_t)row * D + 512 + h * 64;
; #pragma unroll
;     for (int vt = 0; vt < 2; ++vt)
; #pragma unroll
;       for (int g = 0; g < 4; ++g) {
;         const int vd = 32 * vt + 8 * g + 4 * hh;
;         const f32x4 g4 = unpk4(*(const u32x2*)(mg + vd));
;         f32x4 o = {ot[qs][vt][4 * g] * inv * silu(g4[0]), ot[qs][vt][4 * g + 1] * inv * silu(g4[1]), ot[qs][vt][4 * g + 2] * inv * silu(g4[2]), ot[qs][vt][4 * g + 3] * inv * silu(g4[3])};
;         *(u32x2*)(dst + vd) = pk4(o);
;       }
.LBB0_820:
	v_mov_b32_e32 v2, v0
	s_nop 1
	v_permlane32_swap_b32_e32 v0, v2
	v_add_f32_e32 v0, v0, v2
	v_div_scale_f32 v2, s[4:5], v0, v0, 1.0
	v_rcp_f32_e32 v3, v2
	s_lshl_b32 s1, s7, 5
	s_and_b32 s1, s1, 0xffffe000
	s_or_b32 s1, s1, s8
	v_fma_f32 v4, -v2, v3, 1.0
	v_fmac_f32_e32 v3, v4, v3
	v_div_scale_f32 v4, vcc, 1.0, v0, 1.0
	v_mul_f32_e32 v5, v4, v3
	v_fma_f32 v6, -v2, v5, v4
	v_fmac_f32_e32 v5, v6, v3
	v_fma_f32 v2, -v2, v5, v4
	v_div_fmas_f32 v2, v2, v3, v5
	v_add_u32_e32 v9, s1, v157
	v_div_fixup_f32 v0, v2, v0, 1.0
	v_mov_b64_e32 v[2:3], s[88:89]
	v_mad_i64_i32 v[4:5], s[4:5], v9, s78, v[2:3]
	s_lshl_b32 s0, s0, 7
	s_mov_b32 s5, s85
	s_and_b32 s4, s0, 0x380
	v_lshl_add_u64 v[6:7], v[4:5], 0, s[4:5]
	s_movk_i32 s2, 0xf400
	v_mov_b32_e32 v157, v1
	v_mad_i64_i32 v[4:5], s[0:1], v9, s2, v[4:5]
	v_lshl_add_u64 v[6:7], v[6:7], 0, v[156:157]
	s_mov_b64 s[8:9], 0x3228f80
	v_lshl_add_u64 v[10:11], v[4:5], 0, s[4:5]
	v_lshl_add_u64 v[4:5], v[6:7], 0, s[8:9]
	v_add_co_u32_e32 v6, vcc, s81, v6
	s_nop 1
	v_addc_co_u32_e32 v7, vcc, 0, v7, vcc
	s_barrier
	s_mov_b64 s[10:11], 0x28000
	v_lshl_add_u64 v[112:113], v[6:7], 0, s[10:11]
	v_lshl_add_u64 v[114:115], v[4:5], 0, s[10:11]
	global_load_dwordx2 v[80:81], v[6:7], off offset:3968
	global_load_dwordx2 v[82:83], v[4:5], off offset:16
	global_load_dwordx2 v[84:85], v[4:5], off offset:32
	global_load_dwordx2 v[86:87], v[4:5], off offset:48
	global_load_dwordx2 v[88:89], v[4:5], off offset:64
	global_load_dwordx2 v[90:91], v[4:5], off offset:80
	global_load_dwordx2 v[92:93], v[4:5], off offset:96
	global_load_dwordx2 v[94:95], v[4:5], off offset:112
	global_load_dwordx2 v[96:97], v[112:113], off offset:3968
	global_load_dwordx2 v[98:99], v[114:115], off offset:16
	global_load_dwordx2 v[100:101], v[114:115], off offset:32
	global_load_dwordx2 v[102:103], v[114:115], off offset:48
	global_load_dwordx2 v[104:105], v[114:115], off offset:64
	global_load_dwordx2 v[106:107], v[114:115], off offset:80
	global_load_dwordx2 v[108:109], v[114:115], off offset:96
	global_load_dwordx2 v[110:111], v[114:115], off offset:112
	v_pk_mul_f32 v[64:65], v[64:65], v[0:1] op_sel_hi:[1,0]
	v_lshl_add_u64 v[10:11], v[10:11], 0, v[156:157]
	s_mov_b64 s[10:11], 0x1128400
	s_mov_b32 s3, 0x1128000
	v_pk_mul_f32 v[48:49], v[48:49], v[0:1] op_sel_hi:[1,0]
	s_add_i32 s6, s6, s41
	s_cmp_gt_i32 s6, 63
	s_waitcnt vmcnt(15)
	v_lshlrev_b32_e32 v12, 16, v80
	v_and_b32_e32 v13, 0xffff0000, v80
	v_mul_f32_e32 v6, 0xbfb8aa3b, v12
	v_exp_f32_e32 v6, v6
	s_nop 0
	v_add_f32_e32 v6, 1.0, v6
	v_rcp_f32_e32 v14, v6
	v_mul_f32_e32 v6, 0xbfb8aa3b, v13
	v_exp_f32_e32 v6, v6
	s_nop 0
	v_add_f32_e32 v6, 1.0, v6
	v_rcp_f32_e32 v15, v6
	v_lshlrev_b32_e32 v6, 16, v81
	v_and_b32_e32 v7, 0xffff0000, v81
	v_pk_mul_f32 v[12:13], v[14:15], v[12:13]
	s_nop 0
	v_pk_mul_f32 v[12:13], v[64:65], v[12:13]
	v_pk_mul_f32 v[64:65], v[66:67], v[0:1] op_sel_hi:[1,0]
	v_cvt_pk_bf16_f32 v12, v12, v13
	v_mul_f32_e32 v13, 0xbfb8aa3b, v6
	v_exp_f32_e32 v13, v13
	s_nop 0
	v_add_f32_e32 v13, 1.0, v13
	v_rcp_f32_e32 v14, v13
	v_mul_f32_e32 v13, 0xbfb8aa3b, v7
	v_exp_f32_e32 v13, v13
	s_nop 0
	v_add_f32_e32 v13, 1.0, v13
	v_rcp_f32_e32 v15, v13
	s_nop 0
	v_pk_mul_f32 v[6:7], v[14:15], v[6:7]
	s_nop 0
	v_pk_mul_f32 v[6:7], v[64:65], v[6:7]
	v_pk_mul_f32 v[64:65], v[68:69], v[0:1] op_sel_hi:[1,0]
	v_cvt_pk_bf16_f32 v13, v6, v7
	v_lshl_add_u64 v[6:7], v[10:11], 0, s[10:11]
	v_add_co_u32_e32 v10, vcc, s3, v10
	s_nop 1
	v_addc_co_u32_e32 v11, vcc, 0, v11, vcc
	v_readlane_b32 s12, v254, 31
	v_readlane_b32 s13, v254, 32
	v_subrev_u32_e32 v136, s12, v10
	v_add_u32_e32 v136, 0x400, v136
	v_and_b32_e32 v137, 0x7c0, v136
	v_and_b32_e32 v138, 0xfffff7ff, v136
	v_add_u32_e32 v138, v138, v137
	v_bfe_u32 v137, v136, 11, 1
	v_lshl_or_b32 v138, v137, 6, v138
	v_bfe_i32 v137, v136, 25, 1
	v_bfi_b32 v138, v137, v136, v138
	global_store_dwordx2 v138, v[12:13], s[12:13]
	s_waitcnt vmcnt(15)
	v_lshlrev_b32_e32 v12, 16, v82
	v_and_b32_e32 v13, 0xffff0000, v82
	v_mul_f32_e32 v10, 0xbfb8aa3b, v12
	v_exp_f32_e32 v10, v10
	s_nop 0
	v_add_f32_e32 v10, 1.0, v10
	v_rcp_f32_e32 v14, v10
	v_mul_f32_e32 v10, 0xbfb8aa3b, v13
	v_exp_f32_e32 v10, v10
	s_nop 0
	v_add_f32_e32 v10, 1.0, v10
	v_rcp_f32_e32 v15, v10
	s_nop 0
	v_pk_mul_f32 v[12:13], v[14:15], v[12:13]
	s_nop 0
	v_pk_mul_f32 v[12:13], v[64:65], v[12:13]
	v_pk_mul_f32 v[64:65], v[70:71], v[0:1] op_sel_hi:[1,0]
	v_cvt_pk_bf16_f32 v10, v12, v13
	v_lshlrev_b32_e32 v12, 16, v83
	v_and_b32_e32 v13, 0xffff0000, v83
	v_mul_f32_e32 v11, 0xbfb8aa3b, v12
	v_exp_f32_e32 v11, v11
	s_nop 0
	v_add_f32_e32 v11, 1.0, v11
	v_rcp_f32_e32 v14, v11
	v_mul_f32_e32 v11, 0xbfb8aa3b, v13
	v_exp_f32_e32 v11, v11
	s_nop 0
	v_add_f32_e32 v11, 1.0, v11
	v_rcp_f32_e32 v15, v11
	s_nop 0
	v_pk_mul_f32 v[12:13], v[14:15], v[12:13]
	s_nop 0
	v_pk_mul_f32 v[12:13], v[64:65], v[12:13]
	v_pk_mul_f32 v[64:65], v[72:73], v[0:1] op_sel_hi:[1,0]
	v_cvt_pk_bf16_f32 v11, v12, v13
	v_readlane_b32 s12, v254, 31
	v_readlane_b32 s13, v254, 32
	v_subrev_u32_e32 v136, s12, v6
	v_add_u32_e32 v136, 16, v136
	v_and_b32_e32 v137, 0x7c0, v136
	v_and_b32_e32 v138, 0xfffff7ff, v136
	v_add_u32_e32 v138, v138, v137
	v_bfe_u32 v137, v136, 11, 1
	v_lshl_or_b32 v138, v137, 6, v138
	v_bfe_i32 v137, v136, 25, 1
	v_bfi_b32 v138, v137, v136, v138
	global_store_dwordx2 v138, v[10:11], s[12:13]
	s_waitcnt vmcnt(15)
; DI float silu(float x) { return x * __builtin_amdgcn_rcpf(1.f + __expf(-x)); }
; DI u32x2 pk4(f32x4 v) { return u32x2{pk2(v[0], v[1]), pk2(v[2], v[3])}; }
; DI f32x4 unpk4(u32x2 u) { return f32x4{__uint_as_float(u[0] << 16), __uint_as_float(u[0] & 0xffff0000u), __uint_as_float(u[1] << 16), __uint_as_float(u[1] & 0xffff0000u)}; }
; DI void attn_item(const Ctx& c, int item, bf16* lds) {
;     ...
; #pragma unroll
;     for (int vt = 0; vt < 2; ++vt)
; #pragma unroll
;       for (int g = 0; g < 4; ++g) {
;         const int vd = 32 * vt + 8 * g + 4 * hh;
;         const f32x4 g4 = unpk4(*(const u32x2*)(mg + vd));
;         f32x4 o = {ot[qs][vt][4 * g] * inv * silu(g4[0]), ot[qs][vt][4 * g + 1] * inv * silu(g4[1]), ot[qs][vt][4 * g + 2] * inv * silu(g4[2]), ot[qs][vt][4 * g + 3] * inv * silu(g4[3])};
;         *(u32x2*)(dst + vd) = pk4(o);
;       }
	v_lshlrev_b32_e32 v12, 16, v84
	v_and_b32_e32 v13, 0xffff0000, v84
	v_mul_f32_e32 v10, 0xbfb8aa3b, v12
	v_exp_f32_e32 v10, v10
	s_nop 0
	v_add_f32_e32 v10, 1.0, v10
	v_rcp_f32_e32 v14, v10
	v_mul_f32_e32 v10, 0xbfb8aa3b, v13
	v_exp_f32_e32 v10, v10
	s_nop 0
	v_add_f32_e32 v10, 1.0, v10
	v_rcp_f32_e32 v15, v10
	s_nop 0
	v_pk_mul_f32 v[12:13], v[14:15], v[12:13]
	s_nop 0
	v_pk_mul_f32 v[12:13], v[64:65], v[12:13]
	v_pk_mul_f32 v[64:65], v[74:75], v[0:1] op_sel_hi:[1,0]
	v_cvt_pk_bf16_f32 v10, v12, v13
	v_lshlrev_b32_e32 v12, 16, v85
	v_and_b32_e32 v13, 0xffff0000, v85
	v_mul_f32_e32 v11, 0xbfb8aa3b, v12
	v_exp_f32_e32 v11, v11
	s_nop 0
	v_add_f32_e32 v11, 1.0, v11
	v_rcp_f32_e32 v14, v11
	v_mul_f32_e32 v11, 0xbfb8aa3b, v13
	v_exp_f32_e32 v11, v11
	s_nop 0
	v_add_f32_e32 v11, 1.0, v11
	v_rcp_f32_e32 v15, v11
	s_nop 0
	v_pk_mul_f32 v[12:13], v[14:15], v[12:13]
	s_nop 0
	v_pk_mul_f32 v[12:13], v[64:65], v[12:13]
	v_pk_mul_f32 v[64:65], v[76:77], v[0:1] op_sel_hi:[1,0]
	v_cvt_pk_bf16_f32 v11, v12, v13
	v_readlane_b32 s12, v254, 31
	v_readlane_b32 s13, v254, 32
	v_subrev_u32_e32 v136, s12, v6
	v_add_u32_e32 v136, 32, v136
	v_and_b32_e32 v137, 0x7c0, v136
	v_and_b32_e32 v138, 0xfffff7ff, v136
	v_add_u32_e32 v138, v138, v137
	v_bfe_u32 v137, v136, 11, 1
	v_lshl_or_b32 v138, v137, 6, v138
	v_bfe_i32 v137, v136, 25, 1
	v_bfi_b32 v138, v137, v136, v138
	global_store_dwordx2 v138, v[10:11], s[12:13]
	s_waitcnt vmcnt(15)
	v_lshlrev_b32_e32 v12, 16, v86
	v_and_b32_e32 v13, 0xffff0000, v86
	v_mul_f32_e32 v10, 0xbfb8aa3b, v12
	v_exp_f32_e32 v10, v10
	s_nop 0
	v_add_f32_e32 v10, 1.0, v10
	v_rcp_f32_e32 v14, v10
	v_mul_f32_e32 v10, 0xbfb8aa3b, v13
	v_exp_f32_e32 v10, v10
	s_nop 0
	v_add_f32_e32 v10, 1.0, v10
	v_rcp_f32_e32 v15, v10
	s_nop 0
	v_pk_mul_f32 v[12:13], v[14:15], v[12:13]
	s_nop 0
	v_pk_mul_f32 v[12:13], v[64:65], v[12:13]
	v_pk_mul_f32 v[64:65], v[78:79], v[0:1] op_sel_hi:[1,0]
	v_cvt_pk_bf16_f32 v10, v12, v13
	v_lshlrev_b32_e32 v12, 16, v87
	v_and_b32_e32 v13, 0xffff0000, v87
	v_mul_f32_e32 v11, 0xbfb8aa3b, v12
	v_exp_f32_e32 v11, v11
	s_nop 0
	v_add_f32_e32 v11, 1.0, v11
	v_rcp_f32_e32 v14, v11
	v_mul_f32_e32 v11, 0xbfb8aa3b, v13
	v_exp_f32_e32 v11, v11
	s_nop 0
	v_add_f32_e32 v11, 1.0, v11
	v_rcp_f32_e32 v15, v11
	s_nop 0
	v_pk_mul_f32 v[12:13], v[14:15], v[12:13]
	s_nop 0
	v_pk_mul_f32 v[12:13], v[64:65], v[12:13]
	s_nop 0
	v_cvt_pk_bf16_f32 v11, v12, v13
	v_readlane_b32 s12, v254, 31
	v_readlane_b32 s13, v254, 32
	v_subrev_u32_e32 v136, s12, v6
	v_add_u32_e32 v136, 48, v136
	v_and_b32_e32 v137, 0x7c0, v136
	v_and_b32_e32 v138, 0xfffff7ff, v136
	v_add_u32_e32 v138, v138, v137
	v_bfe_u32 v137, v136, 11, 1
	v_lshl_or_b32 v138, v137, 6, v138
	v_bfe_i32 v137, v136, 25, 1
	v_bfi_b32 v138, v137, v136, v138
	global_store_dwordx2 v138, v[10:11], s[12:13]
	s_waitcnt vmcnt(15)
	v_lshlrev_b32_e32 v12, 16, v88
	v_and_b32_e32 v13, 0xffff0000, v88
	v_mul_f32_e32 v10, 0xbfb8aa3b, v12
	v_exp_f32_e32 v10, v10
	s_nop 0
	v_add_f32_e32 v10, 1.0, v10
	v_rcp_f32_e32 v14, v10
	v_mul_f32_e32 v10, 0xbfb8aa3b, v13
	v_exp_f32_e32 v10, v10
	s_nop 0
	v_add_f32_e32 v10, 1.0, v10
	v_rcp_f32_e32 v15, v10
	s_nop 0
	v_pk_mul_f32 v[12:13], v[14:15], v[12:13]
	s_nop 0
	v_pk_mul_f32 v[12:13], v[48:49], v[12:13]
	v_pk_mul_f32 v[48:49], v[50:51], v[0:1] op_sel_hi:[1,0]
	v_cvt_pk_bf16_f32 v10, v12, v13
	v_lshlrev_b32_e32 v12, 16, v89
	v_and_b32_e32 v13, 0xffff0000, v89
	v_mul_f32_e32 v11, 0xbfb8aa3b, v12
	v_exp_f32_e32 v11, v11
	s_nop 0
	v_add_f32_e32 v11, 1.0, v11
	v_rcp_f32_e32 v14, v11
	v_mul_f32_e32 v11, 0xbfb8aa3b, v13
	v_exp_f32_e32 v11, v11
	s_nop 0
	v_add_f32_e32 v11, 1.0, v11
	v_rcp_f32_e32 v15, v11
	s_nop 0
	v_pk_mul_f32 v[12:13], v[14:15], v[12:13]
	s_nop 0
	v_pk_mul_f32 v[12:13], v[48:49], v[12:13]
	v_pk_mul_f32 v[48:49], v[52:53], v[0:1] op_sel_hi:[1,0]
	v_cvt_pk_bf16_f32 v11, v12, v13
	v_readlane_b32 s12, v254, 31
	v_readlane_b32 s13, v254, 32
	v_subrev_u32_e32 v136, s12, v6
	v_add_u32_e32 v136, 64, v136
	v_and_b32_e32 v137, 0x7c0, v136
	v_and_b32_e32 v138, 0xfffff7ff, v136
	v_add_u32_e32 v138, v138, v137
	v_bfe_u32 v137, v136, 11, 1
	v_lshl_or_b32 v138, v137, 6, v138
	v_bfe_i32 v137, v136, 25, 1
	v_bfi_b32 v138, v137, v136, v138
	global_store_dwordx2 v138, v[10:11], s[12:13]
	s_waitcnt vmcnt(15)
	v_lshlrev_b32_e32 v12, 16, v90
	v_and_b32_e32 v13, 0xffff0000, v90
	v_mul_f32_e32 v10, 0xbfb8aa3b, v12
	v_exp_f32_e32 v10, v10
	s_nop 0
	v_add_f32_e32 v10, 1.0, v10
	v_rcp_f32_e32 v14, v10
	v_mul_f32_e32 v10, 0xbfb8aa3b, v13
	v_exp_f32_e32 v10, v10
	s_nop 0
	v_add_f32_e32 v10, 1.0, v10
	v_rcp_f32_e32 v15, v10
	s_nop 0
	v_pk_mul_f32 v[12:13], v[14:15], v[12:13]
	s_nop 0
	v_pk_mul_f32 v[12:13], v[48:49], v[12:13]
	v_pk_mul_f32 v[48:49], v[54:55], v[0:1] op_sel_hi:[1,0]
	v_cvt_pk_bf16_f32 v10, v12, v13
	v_lshlrev_b32_e32 v12, 16, v91
	v_and_b32_e32 v13, 0xffff0000, v91
	v_mul_f32_e32 v11, 0xbfb8aa3b, v12
	v_exp_f32_e32 v11, v11
	s_nop 0
	v_add_f32_e32 v11, 1.0, v11
	v_rcp_f32_e32 v14, v11
	v_mul_f32_e32 v11, 0xbfb8aa3b, v13
	v_exp_f32_e32 v11, v11
	s_nop 0
	v_add_f32_e32 v11, 1.0, v11
	v_rcp_f32_e32 v15, v11
	s_nop 0
	v_pk_mul_f32 v[12:13], v[14:15], v[12:13]
	s_nop 0
	v_pk_mul_f32 v[12:13], v[48:49], v[12:13]
	v_pk_mul_f32 v[48:49], v[56:57], v[0:1] op_sel_hi:[1,0]
	v_cvt_pk_bf16_f32 v11, v12, v13
	v_readlane_b32 s12, v254, 31
	v_readlane_b32 s13, v254, 32
	v_subrev_u32_e32 v136, s12, v6
	v_add_u32_e32 v136, 0x50, v136
	v_and_b32_e32 v137, 0x7c0, v136
	v_and_b32_e32 v138, 0xfffff7ff, v136
	v_add_u32_e32 v138, v138, v137
	v_bfe_u32 v137, v136, 11, 1
	v_lshl_or_b32 v138, v137, 6, v138
	v_bfe_i32 v137, v136, 25, 1
	v_bfi_b32 v138, v137, v136, v138
	global_store_dwordx2 v138, v[10:11], s[12:13]
	s_waitcnt vmcnt(15)
; DI float silu(float x) { return x * __builtin_amdgcn_rcpf(1.f + __expf(-x)); }
;   DI bf16* HY() const { return (bf16*)(p.ws + WS_HY); }
;   DI bf16* P() const { return (bf16*)(p.ws + WS_P); }
; DI u32x2 pk4(f32x4 v) { return u32x2{pk2(v[0], v[1]), pk2(v[2], v[3])}; }
; DI f32x4 unpk4(u32x2 u) { return f32x4{__uint_as_float(u[0] << 16), __uint_as_float(u[0] & 0xffff0000u), __uint_as_float(u[1] << 16), __uint_as_float(u[1] & 0xffff0000u)}; }
; DI void attn_item(const Ctx& c, int item, bf16* lds) {
;     ...
; #pragma unroll
;   for (int qs = 0; qs < 2; ++qs) {
;     const float inv = 1.f / xhalf_sum(lsum[qs]);
;     const int row = rowbase + wave * 64 + qs * 32 + r;
;     const bf16* mg = c.P() + (size_t)row * LDP + C_MG + h * 64;
;     bf16* dst = c.HY() + (size_t)row * D + 512 + h * 64;
; #pragma unroll
;     for (int vt = 0; vt < 2; ++vt)
; #pragma unroll
;       for (int g = 0; g < 4; ++g) {
;         const int vd = 32 * vt + 8 * g + 4 * hh;
;         const f32x4 g4 = unpk4(*(const u32x2*)(mg + vd));
;         f32x4 o = {ot[qs][vt][4 * g] * inv * silu(g4[0]), ot[qs][vt][4 * g + 1] * inv * silu(g4[1]), ot[qs][vt][4 * g + 2] * inv * silu(g4[2]), ot[qs][vt][4 * g + 3] * inv * silu(g4[3])};
;         *(u32x2*)(dst + vd) = pk4(o);
;       }
	v_lshlrev_b32_e32 v12, 16, v92
	v_and_b32_e32 v13, 0xffff0000, v92
	v_mul_f32_e32 v10, 0xbfb8aa3b, v12
	v_exp_f32_e32 v10, v10
	s_nop 0
	v_add_f32_e32 v10, 1.0, v10
	v_rcp_f32_e32 v14, v10
	v_mul_f32_e32 v10, 0xbfb8aa3b, v13
	v_exp_f32_e32 v10, v10
	s_nop 0
	v_add_f32_e32 v10, 1.0, v10
	v_rcp_f32_e32 v15, v10
	s_nop 0
	v_pk_mul_f32 v[12:13], v[14:15], v[12:13]
	s_nop 0
	v_pk_mul_f32 v[12:13], v[48:49], v[12:13]
	v_pk_mul_f32 v[48:49], v[58:59], v[0:1] op_sel_hi:[1,0]
	v_cvt_pk_bf16_f32 v10, v12, v13
	v_lshlrev_b32_e32 v12, 16, v93
	v_and_b32_e32 v13, 0xffff0000, v93
	v_mul_f32_e32 v11, 0xbfb8aa3b, v12
	v_exp_f32_e32 v11, v11
	s_nop 0
	v_add_f32_e32 v11, 1.0, v11
	v_rcp_f32_e32 v14, v11
	v_mul_f32_e32 v11, 0xbfb8aa3b, v13
	v_exp_f32_e32 v11, v11
	s_nop 0
	v_add_f32_e32 v11, 1.0, v11
	v_rcp_f32_e32 v15, v11
	s_nop 0
	v_pk_mul_f32 v[12:13], v[14:15], v[12:13]
	s_nop 0
	v_pk_mul_f32 v[12:13], v[48:49], v[12:13]
	v_pk_mul_f32 v[14:15], v[60:61], v[0:1] op_sel_hi:[1,0]
	v_cvt_pk_bf16_f32 v11, v12, v13
	v_readlane_b32 s12, v254, 31
	v_readlane_b32 s13, v254, 32
	v_subrev_u32_e32 v136, s12, v6
	v_add_u32_e32 v136, 0x60, v136
	v_and_b32_e32 v137, 0x7c0, v136
	v_and_b32_e32 v138, 0xfffff7ff, v136
	v_add_u32_e32 v138, v138, v137
	v_bfe_u32 v137, v136, 11, 1
	v_lshl_or_b32 v138, v137, 6, v138
	v_bfe_i32 v137, v136, 25, 1
	v_bfi_b32 v138, v137, v136, v138
	global_store_dwordx2 v138, v[10:11], s[12:13]
	s_waitcnt vmcnt(15)
	v_lshlrev_b32_e32 v10, 16, v94
	v_and_b32_e32 v11, 0xffff0000, v94
	v_mul_f32_e32 v4, 0xbfb8aa3b, v10
	v_exp_f32_e32 v4, v4
	s_nop 0
	v_add_f32_e32 v4, 1.0, v4
	v_rcp_f32_e32 v12, v4
	v_mul_f32_e32 v4, 0xbfb8aa3b, v11
	v_exp_f32_e32 v4, v4
	s_nop 0
	v_add_f32_e32 v4, 1.0, v4
	v_rcp_f32_e32 v13, v4
	s_nop 0
	v_pk_mul_f32 v[10:11], v[12:13], v[10:11]
	s_nop 0
	v_pk_mul_f32 v[10:11], v[14:15], v[10:11]
	v_pk_mul_f32 v[14:15], v[62:63], v[0:1] op_sel_hi:[1,0]
	v_cvt_pk_bf16_f32 v4, v10, v11
	v_lshlrev_b32_e32 v10, 16, v95
	v_and_b32_e32 v11, 0xffff0000, v95
	v_mul_f32_e32 v5, 0xbfb8aa3b, v10
	v_mul_f32_e32 v0, 0xbfb8aa3b, v11
	v_exp_f32_e32 v5, v5
	v_exp_f32_e32 v0, v0
	v_add_f32_e32 v5, 1.0, v5
	v_add_f32_e32 v0, 1.0, v0
	v_rcp_f32_e32 v12, v5
	v_rcp_f32_e32 v13, v0
	v_mov_b32_e32 v0, v8
	s_nop 1
	v_permlane32_swap_b32_e32 v8, v0
	v_pk_mul_f32 v[10:11], v[12:13], v[10:11]
	v_add_f32_e32 v0, v8, v0
	v_pk_mul_f32 v[10:11], v[14:15], v[10:11]
	s_nop 0
	v_cvt_pk_bf16_f32 v5, v10, v11
	v_readlane_b32 s12, v254, 31
	v_readlane_b32 s13, v254, 32
	v_subrev_u32_e32 v136, s12, v6
	v_add_u32_e32 v136, 0x70, v136
	v_and_b32_e32 v137, 0x7c0, v136
	v_and_b32_e32 v138, 0xfffff7ff, v136
	v_add_u32_e32 v138, v138, v137
	v_bfe_u32 v137, v136, 11, 1
	v_lshl_or_b32 v138, v137, 6, v138
	v_bfe_i32 v137, v136, 25, 1
	v_bfi_b32 v138, v137, v136, v138
	global_store_dwordx2 v138, v[4:5], s[12:13]
	v_div_scale_f32 v4, s[0:1], v0, v0, 1.0
	v_rcp_f32_e32 v5, v4
	s_nop 0
	v_fma_f32 v6, -v4, v5, 1.0
	v_fmac_f32_e32 v5, v6, v5
	v_div_scale_f32 v6, vcc, 1.0, v0, 1.0
	v_mul_f32_e32 v7, v6, v5
	v_fma_f32 v8, -v4, v7, v6
	v_fmac_f32_e32 v7, v8, v5
	v_fma_f32 v4, -v4, v7, v6
	v_or_b32_e32 v6, 32, v9
	v_div_fmas_f32 v4, v4, v5, v7
	v_mad_i64_i32 v[2:3], s[0:1], v6, s78, v[2:3]
	v_div_fixup_f32 v0, v4, v0, 1.0
	v_lshl_add_u64 v[4:5], v[2:3], 0, s[4:5]
	v_mad_i64_i32 v[2:3], s[0:1], v6, s2, v[2:3]
	v_lshl_add_u64 v[6:7], v[4:5], 0, v[156:157]
	v_lshl_add_u64 v[4:5], v[6:7], 0, s[8:9]
	v_add_co_u32_e32 v6, vcc, s81, v6
	v_pk_mul_f32 v[12:13], v[32:33], v[0:1] op_sel_hi:[1,0]
	s_nop 0
	v_addc_co_u32_e32 v7, vcc, 0, v7, vcc
	v_lshl_add_u64 v[2:3], v[2:3], 0, s[4:5]
	s_waitcnt vmcnt(15)
	v_lshlrev_b32_e32 v8, 16, v96
	v_and_b32_e32 v9, 0xffff0000, v96
	v_mul_f32_e32 v6, 0xbfb8aa3b, v8
	v_exp_f32_e32 v6, v6
	s_nop 0
	v_add_f32_e32 v6, 1.0, v6
	v_rcp_f32_e32 v10, v6
	v_mul_f32_e32 v6, 0xbfb8aa3b, v9
	v_exp_f32_e32 v6, v6
	s_nop 0
	v_add_f32_e32 v6, 1.0, v6
	v_rcp_f32_e32 v11, v6
	s_nop 0
	v_pk_mul_f32 v[8:9], v[10:11], v[8:9]
	s_nop 0
	v_pk_mul_f32 v[8:9], v[12:13], v[8:9]
	v_pk_mul_f32 v[12:13], v[34:35], v[0:1] op_sel_hi:[1,0]
	v_cvt_pk_bf16_f32 v6, v8, v9
	v_lshlrev_b32_e32 v8, 16, v97
	v_and_b32_e32 v9, 0xffff0000, v97
	v_mul_f32_e32 v7, 0xbfb8aa3b, v8
	v_exp_f32_e32 v7, v7
	s_nop 0
	v_add_f32_e32 v7, 1.0, v7
	v_rcp_f32_e32 v10, v7
	v_mul_f32_e32 v7, 0xbfb8aa3b, v9
	v_exp_f32_e32 v7, v7
	s_nop 0
	v_add_f32_e32 v7, 1.0, v7
	v_rcp_f32_e32 v11, v7
	s_nop 0
	v_pk_mul_f32 v[8:9], v[10:11], v[8:9]
	s_nop 0
	v_pk_mul_f32 v[8:9], v[12:13], v[8:9]
	v_pk_mul_f32 v[12:13], v[36:37], v[0:1] op_sel_hi:[1,0]
	v_cvt_pk_bf16_f32 v7, v8, v9
	v_lshl_add_u64 v[8:9], v[2:3], 0, v[156:157]
	v_lshl_add_u64 v[2:3], v[8:9], 0, s[10:11]
	v_add_co_u32_e32 v8, vcc, s3, v8
	s_nop 1
	v_addc_co_u32_e32 v9, vcc, 0, v9, vcc
	v_readlane_b32 s2, v254, 31
	v_readlane_b32 s3, v254, 32
	v_subrev_u32_e32 v136, s2, v8
	v_add_u32_e32 v136, 0x400, v136
	v_and_b32_e32 v137, 0x7c0, v136
	v_and_b32_e32 v138, 0xfffff7ff, v136
	v_add_u32_e32 v138, v138, v137
	v_bfe_u32 v137, v136, 11, 1
	v_lshl_or_b32 v138, v137, 6, v138
	v_bfe_i32 v137, v136, 25, 1
	v_bfi_b32 v138, v137, v136, v138
	global_store_dwordx2 v138, v[6:7], s[2:3]
	s_waitcnt vmcnt(15)
; DI float silu(float x) { return x * __builtin_amdgcn_rcpf(1.f + __expf(-x)); }
; DI u32x2 pk4(f32x4 v) { return u32x2{pk2(v[0], v[1]), pk2(v[2], v[3])}; }
; DI f32x4 unpk4(u32x2 u) { return f32x4{__uint_as_float(u[0] << 16), __uint_as_float(u[0] & 0xffff0000u), __uint_as_float(u[1] << 16), __uint_as_float(u[1] & 0xffff0000u)}; }
; DI void attn_item(const Ctx& c, int item, bf16* lds) {
;     ...
; #pragma unroll
;     for (int vt = 0; vt < 2; ++vt)
; #pragma unroll
;       for (int g = 0; g < 4; ++g) {
;         const int vd = 32 * vt + 8 * g + 4 * hh;
;         const f32x4 g4 = unpk4(*(const u32x2*)(mg + vd));
;         f32x4 o = {ot[qs][vt][4 * g] * inv * silu(g4[0]), ot[qs][vt][4 * g + 1] * inv * silu(g4[1]), ot[qs][vt][4 * g + 2] * inv * silu(g4[2]), ot[qs][vt][4 * g + 3] * inv * silu(g4[3])};
;         *(u32x2*)(dst + vd) = pk4(o);
;       }
	v_lshlrev_b32_e32 v8, 16, v98
	v_and_b32_e32 v9, 0xffff0000, v98
	v_mul_f32_e32 v6, 0xbfb8aa3b, v8
	v_exp_f32_e32 v6, v6
	s_nop 0
	v_add_f32_e32 v6, 1.0, v6
	v_rcp_f32_e32 v10, v6
	v_mul_f32_e32 v6, 0xbfb8aa3b, v9
	v_exp_f32_e32 v6, v6
	s_nop 0
	v_add_f32_e32 v6, 1.0, v6
	v_rcp_f32_e32 v11, v6
	s_nop 0
	v_pk_mul_f32 v[8:9], v[10:11], v[8:9]
	s_nop 0
	v_pk_mul_f32 v[8:9], v[12:13], v[8:9]
	v_pk_mul_f32 v[12:13], v[38:39], v[0:1] op_sel_hi:[1,0]
	v_cvt_pk_bf16_f32 v6, v8, v9
	v_lshlrev_b32_e32 v8, 16, v99
	v_and_b32_e32 v9, 0xffff0000, v99
	v_mul_f32_e32 v7, 0xbfb8aa3b, v8
	v_exp_f32_e32 v7, v7
	s_nop 0
	v_add_f32_e32 v7, 1.0, v7
	v_rcp_f32_e32 v10, v7
	v_mul_f32_e32 v7, 0xbfb8aa3b, v9
	v_exp_f32_e32 v7, v7
	s_nop 0
	v_add_f32_e32 v7, 1.0, v7
	v_rcp_f32_e32 v11, v7
	s_nop 0
	v_pk_mul_f32 v[8:9], v[10:11], v[8:9]
	s_nop 0
	v_pk_mul_f32 v[8:9], v[12:13], v[8:9]
	v_pk_mul_f32 v[12:13], v[40:41], v[0:1] op_sel_hi:[1,0]
	v_cvt_pk_bf16_f32 v7, v8, v9
	v_readlane_b32 s2, v254, 31
	v_readlane_b32 s3, v254, 32
	v_subrev_u32_e32 v136, s2, v2
	v_add_u32_e32 v136, 16, v136
	v_and_b32_e32 v137, 0x7c0, v136
	v_and_b32_e32 v138, 0xfffff7ff, v136
	v_add_u32_e32 v138, v138, v137
	v_bfe_u32 v137, v136, 11, 1
	v_lshl_or_b32 v138, v137, 6, v138
	v_bfe_i32 v137, v136, 25, 1
	v_bfi_b32 v138, v137, v136, v138
	global_store_dwordx2 v138, v[6:7], s[2:3]
	s_waitcnt vmcnt(15)
	v_lshlrev_b32_e32 v8, 16, v100
	v_and_b32_e32 v9, 0xffff0000, v100
	v_mul_f32_e32 v6, 0xbfb8aa3b, v8
	v_exp_f32_e32 v6, v6
	s_nop 0
	v_add_f32_e32 v6, 1.0, v6
	v_rcp_f32_e32 v10, v6
	v_mul_f32_e32 v6, 0xbfb8aa3b, v9
	v_exp_f32_e32 v6, v6
	s_nop 0
	v_add_f32_e32 v6, 1.0, v6
	v_rcp_f32_e32 v11, v6
	s_nop 0
	v_pk_mul_f32 v[8:9], v[10:11], v[8:9]
	s_nop 0
	v_pk_mul_f32 v[8:9], v[12:13], v[8:9]
	v_pk_mul_f32 v[12:13], v[42:43], v[0:1] op_sel_hi:[1,0]
	v_cvt_pk_bf16_f32 v6, v8, v9
	v_lshlrev_b32_e32 v8, 16, v101
	v_and_b32_e32 v9, 0xffff0000, v101
	v_mul_f32_e32 v7, 0xbfb8aa3b, v8
	v_exp_f32_e32 v7, v7
	s_nop 0
	v_add_f32_e32 v7, 1.0, v7
	v_rcp_f32_e32 v10, v7
	v_mul_f32_e32 v7, 0xbfb8aa3b, v9
	v_exp_f32_e32 v7, v7
	s_nop 0
	v_add_f32_e32 v7, 1.0, v7
	v_rcp_f32_e32 v11, v7
	s_nop 0
	v_pk_mul_f32 v[8:9], v[10:11], v[8:9]
	s_nop 0
	v_pk_mul_f32 v[8:9], v[12:13], v[8:9]
	v_pk_mul_f32 v[12:13], v[44:45], v[0:1] op_sel_hi:[1,0]
	v_cvt_pk_bf16_f32 v7, v8, v9
	v_readlane_b32 s2, v254, 31
	v_readlane_b32 s3, v254, 32
	v_subrev_u32_e32 v136, s2, v2
	v_add_u32_e32 v136, 32, v136
	v_and_b32_e32 v137, 0x7c0, v136
	v_and_b32_e32 v138, 0xfffff7ff, v136
	v_add_u32_e32 v138, v138, v137
	v_bfe_u32 v137, v136, 11, 1
	v_lshl_or_b32 v138, v137, 6, v138
	v_bfe_i32 v137, v136, 25, 1
	v_bfi_b32 v138, v137, v136, v138
	global_store_dwordx2 v138, v[6:7], s[2:3]
	s_waitcnt vmcnt(15)
	v_lshlrev_b32_e32 v8, 16, v102
	v_and_b32_e32 v9, 0xffff0000, v102
	v_mul_f32_e32 v6, 0xbfb8aa3b, v8
	v_exp_f32_e32 v6, v6
	s_nop 0
	v_add_f32_e32 v6, 1.0, v6
	v_rcp_f32_e32 v10, v6
	v_mul_f32_e32 v6, 0xbfb8aa3b, v9
	v_exp_f32_e32 v6, v6
	s_nop 0
	v_add_f32_e32 v6, 1.0, v6
	v_rcp_f32_e32 v11, v6
	s_nop 0
	v_pk_mul_f32 v[8:9], v[10:11], v[8:9]
	s_nop 0
	v_pk_mul_f32 v[8:9], v[12:13], v[8:9]
	v_pk_mul_f32 v[12:13], v[46:47], v[0:1] op_sel_hi:[1,0]
	v_cvt_pk_bf16_f32 v6, v8, v9
	v_lshlrev_b32_e32 v8, 16, v103
	v_and_b32_e32 v9, 0xffff0000, v103
	v_mul_f32_e32 v7, 0xbfb8aa3b, v8
	v_exp_f32_e32 v7, v7
	s_nop 0
	v_add_f32_e32 v7, 1.0, v7
	v_rcp_f32_e32 v10, v7
	v_mul_f32_e32 v7, 0xbfb8aa3b, v9
	v_exp_f32_e32 v7, v7
	s_nop 0
	v_add_f32_e32 v7, 1.0, v7
	v_rcp_f32_e32 v11, v7
	s_nop 0
	v_pk_mul_f32 v[8:9], v[10:11], v[8:9]
	s_nop 0
	v_pk_mul_f32 v[8:9], v[12:13], v[8:9]
	v_pk_mul_f32 v[12:13], v[16:17], v[0:1] op_sel_hi:[1,0]
	v_cvt_pk_bf16_f32 v7, v8, v9
	v_readlane_b32 s2, v254, 31
	v_readlane_b32 s3, v254, 32
	v_subrev_u32_e32 v136, s2, v2
	v_add_u32_e32 v136, 48, v136
	v_and_b32_e32 v137, 0x7c0, v136
	v_and_b32_e32 v138, 0xfffff7ff, v136
	v_add_u32_e32 v138, v138, v137
	v_bfe_u32 v137, v136, 11, 1
	v_lshl_or_b32 v138, v137, 6, v138
	v_bfe_i32 v137, v136, 25, 1
	v_bfi_b32 v138, v137, v136, v138
	global_store_dwordx2 v138, v[6:7], s[2:3]
	s_waitcnt vmcnt(15)
; DI float silu(float x) { return x * __builtin_amdgcn_rcpf(1.f + __expf(-x)); }
; DI u32x2 pk4(f32x4 v) { return u32x2{pk2(v[0], v[1]), pk2(v[2], v[3])}; }
; DI f32x4 unpk4(u32x2 u) { return f32x4{__uint_as_float(u[0] << 16), __uint_as_float(u[0] & 0xffff0000u), __uint_as_float(u[1] << 16), __uint_as_float(u[1] & 0xffff0000u)}; }
; DI void attn_item(const Ctx& c, int item, bf16* lds) {
;     ...
; #pragma unroll
;     for (int vt = 0; vt < 2; ++vt)
; #pragma unroll
;       for (int g = 0; g < 4; ++g) {
;         const int vd = 32 * vt + 8 * g + 4 * hh;
;         const f32x4 g4 = unpk4(*(const u32x2*)(mg + vd));
;         f32x4 o = {ot[qs][vt][4 * g] * inv * silu(g4[0]), ot[qs][vt][4 * g + 1] * inv * silu(g4[1]), ot[qs][vt][4 * g + 2] * inv * silu(g4[2]), ot[qs][vt][4 * g + 3] * inv * silu(g4[3])};
;         *(u32x2*)(dst + vd) = pk4(o);
;       }
	v_lshlrev_b32_e32 v8, 16, v104
	v_and_b32_e32 v9, 0xffff0000, v104
	v_mul_f32_e32 v6, 0xbfb8aa3b, v8
	v_exp_f32_e32 v6, v6
	s_nop 0
	v_add_f32_e32 v6, 1.0, v6
	v_rcp_f32_e32 v10, v6
	v_mul_f32_e32 v6, 0xbfb8aa3b, v9
	v_exp_f32_e32 v6, v6
	s_nop 0
	v_add_f32_e32 v6, 1.0, v6
	v_rcp_f32_e32 v11, v6
	s_nop 0
	v_pk_mul_f32 v[8:9], v[10:11], v[8:9]
	s_nop 0
	v_pk_mul_f32 v[8:9], v[12:13], v[8:9]
	v_pk_mul_f32 v[12:13], v[18:19], v[0:1] op_sel_hi:[1,0]
	v_cvt_pk_bf16_f32 v6, v8, v9
	v_lshlrev_b32_e32 v8, 16, v105
	v_and_b32_e32 v9, 0xffff0000, v105
	v_mul_f32_e32 v7, 0xbfb8aa3b, v8
	v_exp_f32_e32 v7, v7
	s_nop 0
	v_add_f32_e32 v7, 1.0, v7
	v_rcp_f32_e32 v10, v7
	v_mul_f32_e32 v7, 0xbfb8aa3b, v9
	v_exp_f32_e32 v7, v7
	s_nop 0
	v_add_f32_e32 v7, 1.0, v7
	v_rcp_f32_e32 v11, v7
	s_nop 0
	v_pk_mul_f32 v[8:9], v[10:11], v[8:9]
	s_nop 0
	v_pk_mul_f32 v[8:9], v[12:13], v[8:9]
	v_pk_mul_f32 v[12:13], v[20:21], v[0:1] op_sel_hi:[1,0]
	v_cvt_pk_bf16_f32 v7, v8, v9
	v_readlane_b32 s2, v254, 31
	v_readlane_b32 s3, v254, 32
	v_subrev_u32_e32 v136, s2, v2
	v_add_u32_e32 v136, 64, v136
	v_and_b32_e32 v137, 0x7c0, v136
	v_and_b32_e32 v138, 0xfffff7ff, v136
	v_add_u32_e32 v138, v138, v137
	v_bfe_u32 v137, v136, 11, 1
	v_lshl_or_b32 v138, v137, 6, v138
	v_bfe_i32 v137, v136, 25, 1
	v_bfi_b32 v138, v137, v136, v138
	global_store_dwordx2 v138, v[6:7], s[2:3]
	s_waitcnt vmcnt(15)
	v_lshlrev_b32_e32 v8, 16, v106
	v_and_b32_e32 v9, 0xffff0000, v106
	v_mul_f32_e32 v6, 0xbfb8aa3b, v8
	v_exp_f32_e32 v6, v6
	s_nop 0
	v_add_f32_e32 v6, 1.0, v6
	v_rcp_f32_e32 v10, v6
	v_mul_f32_e32 v6, 0xbfb8aa3b, v9
	v_exp_f32_e32 v6, v6
	s_nop 0
	v_add_f32_e32 v6, 1.0, v6
	v_rcp_f32_e32 v11, v6
	s_nop 0
	v_pk_mul_f32 v[8:9], v[10:11], v[8:9]
	s_nop 0
	v_pk_mul_f32 v[8:9], v[12:13], v[8:9]
	v_pk_mul_f32 v[12:13], v[22:23], v[0:1] op_sel_hi:[1,0]
	v_cvt_pk_bf16_f32 v6, v8, v9
	v_lshlrev_b32_e32 v8, 16, v107
	v_and_b32_e32 v9, 0xffff0000, v107
	v_mul_f32_e32 v7, 0xbfb8aa3b, v8
	v_exp_f32_e32 v7, v7
	s_nop 0
	v_add_f32_e32 v7, 1.0, v7
	v_rcp_f32_e32 v10, v7
	v_mul_f32_e32 v7, 0xbfb8aa3b, v9
	v_exp_f32_e32 v7, v7
	s_nop 0
	v_add_f32_e32 v7, 1.0, v7
	v_rcp_f32_e32 v11, v7
	s_nop 0
	v_pk_mul_f32 v[8:9], v[10:11], v[8:9]
	s_nop 0
	v_pk_mul_f32 v[8:9], v[12:13], v[8:9]
	v_pk_mul_f32 v[12:13], v[24:25], v[0:1] op_sel_hi:[1,0]
	v_cvt_pk_bf16_f32 v7, v8, v9
	v_readlane_b32 s2, v254, 31
	v_readlane_b32 s3, v254, 32
	v_subrev_u32_e32 v136, s2, v2
	v_add_u32_e32 v136, 0x50, v136
	v_and_b32_e32 v137, 0x7c0, v136
	v_and_b32_e32 v138, 0xfffff7ff, v136
	v_add_u32_e32 v138, v138, v137
	v_bfe_u32 v137, v136, 11, 1
	v_lshl_or_b32 v138, v137, 6, v138
	v_bfe_i32 v137, v136, 25, 1
	v_bfi_b32 v138, v137, v136, v138
	global_store_dwordx2 v138, v[6:7], s[2:3]
	s_waitcnt vmcnt(15)
	v_lshlrev_b32_e32 v8, 16, v108
	v_and_b32_e32 v9, 0xffff0000, v108
	v_mul_f32_e32 v6, 0xbfb8aa3b, v8
	v_exp_f32_e32 v6, v6
	s_nop 0
	v_add_f32_e32 v6, 1.0, v6
	v_rcp_f32_e32 v10, v6
	v_mul_f32_e32 v6, 0xbfb8aa3b, v9
	v_exp_f32_e32 v6, v6
	s_nop 0
	v_add_f32_e32 v6, 1.0, v6
	v_rcp_f32_e32 v11, v6
	s_nop 0
	v_pk_mul_f32 v[8:9], v[10:11], v[8:9]
	s_nop 0
	v_pk_mul_f32 v[8:9], v[12:13], v[8:9]
	v_pk_mul_f32 v[12:13], v[26:27], v[0:1] op_sel_hi:[1,0]
	v_cvt_pk_bf16_f32 v6, v8, v9
	v_lshlrev_b32_e32 v8, 16, v109
	v_and_b32_e32 v9, 0xffff0000, v109
	v_mul_f32_e32 v7, 0xbfb8aa3b, v8
	v_exp_f32_e32 v7, v7
	s_nop 0
	v_add_f32_e32 v7, 1.0, v7
	v_rcp_f32_e32 v10, v7
	v_mul_f32_e32 v7, 0xbfb8aa3b, v9
	v_exp_f32_e32 v7, v7
	s_nop 0
	v_add_f32_e32 v7, 1.0, v7
	v_rcp_f32_e32 v11, v7
	s_nop 0
	v_pk_mul_f32 v[8:9], v[10:11], v[8:9]
	s_nop 0
	v_pk_mul_f32 v[8:9], v[12:13], v[8:9]
	v_pk_mul_f32 v[10:11], v[28:29], v[0:1] op_sel_hi:[1,0]
	v_cvt_pk_bf16_f32 v7, v8, v9
	v_readlane_b32 s2, v254, 31
	v_readlane_b32 s3, v254, 32
	v_subrev_u32_e32 v136, s2, v2
	v_add_u32_e32 v136, 0x60, v136
	v_and_b32_e32 v137, 0x7c0, v136
	v_and_b32_e32 v138, 0xfffff7ff, v136
	v_add_u32_e32 v138, v138, v137
	v_bfe_u32 v137, v136, 11, 1
	v_lshl_or_b32 v138, v137, 6, v138
	v_bfe_i32 v137, v136, 25, 1
	v_bfi_b32 v138, v137, v136, v138
	global_store_dwordx2 v138, v[6:7], s[2:3]
	s_waitcnt vmcnt(15)
	v_lshlrev_b32_e32 v6, 16, v110
	v_and_b32_e32 v7, 0xffff0000, v110
	v_mul_f32_e32 v4, 0xbfb8aa3b, v6
	v_exp_f32_e32 v4, v4
	s_nop 0
	v_add_f32_e32 v4, 1.0, v4
	v_rcp_f32_e32 v8, v4
	v_mul_f32_e32 v4, 0xbfb8aa3b, v7
	v_exp_f32_e32 v4, v4
	s_nop 0
	v_add_f32_e32 v4, 1.0, v4
	v_rcp_f32_e32 v9, v4
	s_nop 0
	v_pk_mul_f32 v[6:7], v[8:9], v[6:7]
	s_nop 0
	v_pk_mul_f32 v[6:7], v[10:11], v[6:7]
	v_pk_mul_f32 v[10:11], v[30:31], v[0:1] op_sel_hi:[1,0]
	v_cvt_pk_bf16_f32 v4, v6, v7
	v_lshlrev_b32_e32 v6, 16, v111
	v_and_b32_e32 v7, 0xffff0000, v111
	v_mul_f32_e32 v5, 0xbfb8aa3b, v6
	v_mul_f32_e32 v0, 0xbfb8aa3b, v7
	v_exp_f32_e32 v5, v5
	v_exp_f32_e32 v0, v0
	v_add_f32_e32 v5, 1.0, v5
	v_add_f32_e32 v0, 1.0, v0
	v_rcp_f32_e32 v8, v5
	v_rcp_f32_e32 v9, v0
	s_nop 0
	v_pk_mul_f32 v[6:7], v[8:9], v[6:7]
	s_nop 0
	v_pk_mul_f32 v[6:7], v[10:11], v[6:7]
	s_nop 0
	v_cvt_pk_bf16_f32 v5, v6, v7
	v_readlane_b32 s2, v254, 31
	v_readlane_b32 s3, v254, 32
	v_subrev_u32_e32 v136, s2, v2
	v_add_u32_e32 v136, 0x70, v136
	v_and_b32_e32 v137, 0x7c0, v136
	v_and_b32_e32 v138, 0xfffff7ff, v136
	v_add_u32_e32 v138, v138, v137
	v_bfe_u32 v137, v136, 11, 1
	v_lshl_or_b32 v138, v137, 6, v138
	v_bfe_i32 v137, v136, 25, 1
	v_bfi_b32 v138, v137, v136, v138
	global_store_dwordx2 v138, v[4:5], s[2:3]
	s_cbranch_scc1 .LBB0_804

; DI float silu(float x) { return x * __builtin_amdgcn_rcpf(1.f + __expf(-x)); }
;   DI bf16* HY() const { return (bf16*)(p.ws + WS_HY); }
;   DI bf16* P() const { return (bf16*)(p.ws + WS_P); }
; DI f32x4 unpk4(u32x2 u) { return f32x4{__uint_as_float(u[0] << 16), __uint_as_float(u[0] & 0xffff0000u), __uint_as_float(u[1] << 16), __uint_as_float(u[1] & 0xffff0000u)}; }
; DI void gla_g3_item(const Ctx& c, int l, int item, bf16* lds) {
;     ...
;   float ss = 0.f;
; #pragma unroll
;   for (int j = 0; j < 8; ++j)
; #pragma unroll
;     for (int r = 0; r < 4; ++r) ss += o[j][r] * o[j][r];
;   ss += __shfl_xor(ss, 16); ss += __shfl_xor(ss, 32);
;   const float rstd = rsqrtf(ss * (1.f / 128.f) + LN_EPS);
;   const int row = row0 + 16 * wave + l16;
;   const bf16* gg = c.P() + (size_t)row * LDP + C_GG + h * 128;
;   bf16* dst = c.HY() + (size_t)row * D + h * 128;
; #pragma unroll
;   for (int j = 0; j < 8; ++j) {
;     const int v = 16 * j + 4 * lq;
;     const float4 gn = *(const float4*)(p.gla_norm_g + li * 128 + v);
;     const f32x4 g4 = unpk4(*(const u32x2*)(gg + v));
;     f32x4 y = {o[j][0] * rstd * gn.x * silu(g4[0]), o[j][1] * rstd * gn.y * silu(g4[1]), o[j][2] * rstd * gn.z * silu(g4[2]), o[j][3] * rstd * gn.w * silu(g4[3])};
.LBB0_997:
	v_mul_f32_e32 v0, v31, v31
	v_fmac_f32_e32 v0, v30, v30
	v_fmac_f32_e32 v0, v32, v32
	v_fmac_f32_e32 v0, v33, v33
	v_fmac_f32_e32 v0, v26, v26
	v_fmac_f32_e32 v0, v27, v27
	v_fmac_f32_e32 v0, v28, v28
	v_fmac_f32_e32 v0, v29, v29
	v_fmac_f32_e32 v0, v22, v22
	v_fmac_f32_e32 v0, v23, v23
	v_fmac_f32_e32 v0, v24, v24
	v_fmac_f32_e32 v0, v25, v25
	v_fmac_f32_e32 v0, v18, v18
	v_fmac_f32_e32 v0, v19, v19
	v_fmac_f32_e32 v0, v20, v20
	v_fmac_f32_e32 v0, v21, v21
	v_fmac_f32_e32 v0, v14, v14
	v_fmac_f32_e32 v0, v15, v15
	v_fmac_f32_e32 v0, v16, v16
	v_fmac_f32_e32 v0, v17, v17
	v_fmac_f32_e32 v0, v10, v10
	v_fmac_f32_e32 v0, v11, v11
	v_fmac_f32_e32 v0, v12, v12
	v_fmac_f32_e32 v0, v13, v13
	v_pk_mul_f32 v[36:37], v[6:7], v[6:7]
	v_pk_mul_f32 v[34:35], v[8:9], v[8:9]
	v_add_f32_e32 v0, v0, v36
	v_add_f32_e32 v0, v37, v0
	v_add_f32_e32 v0, v34, v0
	v_add_f32_e32 v0, v35, v0
	v_pk_mul_f32 v[36:37], v[2:3], v[2:3]
	v_pk_mul_f32 v[34:35], v[4:5], v[4:5]
	v_add_f32_e32 v0, v0, v36
	v_add_f32_e32 v0, v37, v0
	v_add_f32_e32 v0, v34, v0
	v_add_f32_e32 v0, v35, v0
	v_and_b32_e32 v35, 64, v178
	v_xor_b32_e32 v34, 16, v178
	v_add_u32_e32 v35, 64, v35
	v_cmp_lt_i32_e32 vcc, v34, v35
	s_mov_b32 s0, 0x800000
	v_readlane_b32 s88, v254, 47
	v_cndmask_b32_e32 v34, v178, v34, vcc
	v_lshlrev_b32_e32 v34, 2, v34
	ds_bpermute_b32 v34, v34, v0
	v_readlane_b32 s89, v254, 48
	v_add_u32_e32 v36, s80, v136
	s_movk_i32 s78, 0x1400
	v_mov_b64_e32 v[38:39], s[88:89]
	s_waitcnt lgkmcnt(0)
	v_add_f32_e32 v0, v0, v34
	v_xor_b32_e32 v34, 32, v178
	v_cmp_lt_i32_e32 vcc, v34, v35
	v_ashrrev_i32_e32 v37, 31, v36
	v_mad_i64_i32 v[38:39], s[4:5], v36, s78, v[38:39]
	v_cndmask_b32_e32 v34, v178, v34, vcc
	v_lshlrev_b32_e32 v34, 2, v34
	ds_bpermute_b32 v34, v34, v0
	v_readlane_b32 s60, v254, 31
	s_mov_b32 s5, s85
	v_lshlrev_b64 v[36:37], 11, v[36:37]
	v_readlane_b32 s61, v254, 32
	s_waitcnt lgkmcnt(0)
	v_add_f32_e32 v0, v0, v34
	v_fmamk_f32 v0, v0, 0x3c000000, v177
	v_cmp_gt_f32_e32 vcc, s0, v0
	v_mul_f32_e32 v34, 0x4b800000, v0
	v_readlane_b32 s0, v254, 49
	v_cndmask_b32_e32 v0, v0, v34, vcc
	v_rsq_f32_e32 v0, v0
	s_lshl_b32 s4, s0, 1
	v_lshl_add_u64 v[38:39], v[38:39], 0, s[4:5]
	v_lshl_add_u64 v[36:37], s[60:61], 0, v[36:37]
	v_mul_f32_e32 v34, 0x45800000, v0
	v_cndmask_b32_e32 v34, v0, v34, vcc
	v_lshlrev_b32_e32 v0, 1, v135
	v_lshl_add_u64 v[42:43], v[36:37], 0, s[4:5]
	v_lshl_add_u64 v[38:39], v[38:39], 0, v[0:1]
	s_mov_b64 s[4:5], 0x3228840
	s_mov_b32 s81, 0x3228000
	v_lshl_add_u64 v[36:37], v[38:39], 0, s[4:5]
	v_add_co_u32_e32 v38, vcc, s81, v38
	v_readlane_b32 s0, v254, 61
	s_nop 0
	v_addc_co_u32_e32 v39, vcc, 0, v39, vcc
	v_lshlrev_b32_e32 v35, 2, v135
	v_readlane_b32 s1, v254, 62
	v_pk_mul_f32 v[30:31], v[30:31], v[34:35] op_sel_hi:[1,0]
	v_pk_mul_f32 v[32:33], v[32:33], v[34:35] op_sel_hi:[1,0]
	v_pk_mul_f32 v[26:27], v[26:27], v[34:35] op_sel_hi:[1,0]
	v_pk_mul_f32 v[28:29], v[28:29], v[34:35] op_sel_hi:[1,0]
	v_pk_mul_f32 v[22:23], v[22:23], v[34:35] op_sel_hi:[1,0]
	global_load_dwordx2 v[100:101], v[38:39], off offset:2112
	global_load_dwordx4 v[116:119], v35, s[0:1]
	global_load_dwordx2 v[102:103], v[36:37], off offset:32
	global_load_dwordx4 v[120:123], v35, s[0:1] offset:64
	global_load_dwordx2 v[104:105], v[36:37], off offset:64
	global_load_dwordx4 v[124:127], v35, s[0:1] offset:128
	global_load_dwordx2 v[106:107], v[36:37], off offset:96
	global_load_dwordx4 v[128:131], v35, s[0:1] offset:192
	global_load_dwordx2 v[108:109], v[36:37], off offset:128
	global_load_dwordx4 v[132:135], v35, s[0:1] offset:256
	global_load_dwordx2 v[110:111], v[36:37], off offset:160
	global_load_dwordx4 v[136:139], v35, s[0:1] offset:320
	global_load_dwordx2 v[112:113], v[36:37], off offset:192
	global_load_dwordx4 v[140:143], v35, s[0:1] offset:384
	global_load_dwordx2 v[114:115], v[36:37], off offset:224
	global_load_dwordx4 v[144:147], v35, s[0:1] offset:448
	v_pk_mul_f32 v[24:25], v[24:25], v[34:35] op_sel_hi:[1,0]
	v_pk_mul_f32 v[18:19], v[18:19], v[34:35] op_sel_hi:[1,0]
	v_pk_mul_f32 v[20:21], v[20:21], v[34:35] op_sel_hi:[1,0]
	v_pk_mul_f32 v[14:15], v[14:15], v[34:35] op_sel_hi:[1,0]
	v_pk_mul_f32 v[16:17], v[16:17], v[34:35] op_sel_hi:[1,0]
	v_pk_mul_f32 v[10:11], v[10:11], v[34:35] op_sel_hi:[1,0]
	v_pk_mul_f32 v[12:13], v[12:13], v[34:35] op_sel_hi:[1,0]
	v_pk_mul_f32 v[6:7], v[6:7], v[34:35] op_sel_hi:[1,0]
	v_pk_mul_f32 v[8:9], v[8:9], v[34:35] op_sel_hi:[1,0]
	v_pk_mul_f32 v[2:3], v[2:3], v[34:35] op_sel_hi:[1,0]
	v_pk_mul_f32 v[4:5], v[4:5], v[34:35] op_sel_hi:[1,0]
	v_readlane_b32 s62, v254, 33
	v_readlane_b32 s86, v254, 57
	s_mov_b64 s[4:5], 0
	v_readlane_b32 s40, v254, 29
	v_readlane_b32 s63, v254, 34
	v_readlane_b32 s66, v254, 35
	v_readlane_b32 s64, v254, 36
	v_readlane_b32 s65, v254, 37
	v_readlane_b32 s74, v254, 38
	v_readlane_b32 s68, v254, 39
	v_readlane_b32 s69, v254, 40
	v_readlane_b32 s75, v254, 41
	v_readlane_b32 s71, v254, 42
	v_readlane_b32 s72, v254, 43
	v_readlane_b32 s73, v254, 44
	v_readlane_b32 s67, v254, 45
	v_readlane_b32 s70, v254, 46
	s_movk_i32 s76, 0x2000
	s_movk_i32 s77, 0x4000
	s_movk_i32 s79, 0x110
	v_readlane_b32 s87, v254, 58
	v_readlane_b32 s18, v255, 0
	v_readlane_b32 s41, v254, 30
	s_waitcnt vmcnt(15)
	v_lshlrev_b32_e32 v46, 16, v100
	v_and_b32_e32 v47, 0xffff0000, v100
	v_mul_f32_e32 v44, 0xbfb8aa3b, v46
	v_exp_f32_e32 v44, v44
	s_waitcnt vmcnt(14)
; DI float silu(float x) { return x * __builtin_amdgcn_rcpf(1.f + __expf(-x)); }
;   DI bf16* HY() const { return (bf16*)(p.ws + WS_HY); }
;   DI bf16* P() const { return (bf16*)(p.ws + WS_P); }
; DI u32x2 pk4(f32x4 v) { return u32x2{pk2(v[0], v[1]), pk2(v[2], v[3])}; }
; DI f32x4 unpk4(u32x2 u) { return f32x4{__uint_as_float(u[0] << 16), __uint_as_float(u[0] & 0xffff0000u), __uint_as_float(u[1] << 16), __uint_as_float(u[1] & 0xffff0000u)}; }
; DI void gla_g3_item(const Ctx& c, int l, int item, bf16* lds) {
;     ...
;   const int row = row0 + 16 * wave + l16;
;   const bf16* gg = c.P() + (size_t)row * LDP + C_GG + h * 128;
;   bf16* dst = c.HY() + (size_t)row * D + h * 128;
; #pragma unroll
;   for (int j = 0; j < 8; ++j) {
;     const int v = 16 * j + 4 * lq;
;     const float4 gn = *(const float4*)(p.gla_norm_g + li * 128 + v);
;     const f32x4 g4 = unpk4(*(const u32x2*)(gg + v));
;     f32x4 y = {o[j][0] * rstd * gn.x * silu(g4[0]), o[j][1] * rstd * gn.y * silu(g4[1]), o[j][2] * rstd * gn.z * silu(g4[2]), o[j][3] * rstd * gn.w * silu(g4[3])};
;     *(u32x2*)(dst + v) = pk4(y);
;   }
	v_pk_mul_f32 v[30:31], v[116:117], v[30:31]
	v_mul_f32_e32 v38, 0xbfb8aa3b, v47
	v_exp_f32_e32 v38, v38
	v_add_f32_e32 v44, 1.0, v44
	v_rcp_f32_e32 v48, v44
	v_pk_mul_f32 v[32:33], v[118:119], v[32:33]
	v_add_f32_e32 v38, 1.0, v38
	v_rcp_f32_e32 v49, v38
	s_nop 0
	v_pk_mul_f32 v[38:39], v[48:49], v[46:47]
	s_nop 0
	v_pk_mul_f32 v[30:31], v[30:31], v[38:39]
	s_nop 0
	v_cvt_pk_bf16_f32 v38, v30, v31
	v_lshlrev_b32_e32 v30, 16, v101
	v_mul_f32_e32 v39, 0xbfb8aa3b, v30
	v_exp_f32_e32 v39, v39
	v_and_b32_e32 v31, 0xffff0000, v101
	v_add_f32_e32 v39, 1.0, v39
	v_rcp_f32_e32 v44, v39
	v_mul_f32_e32 v39, 0xbfb8aa3b, v31
	v_exp_f32_e32 v39, v39
	s_nop 0
	v_add_f32_e32 v39, 1.0, v39
	v_rcp_f32_e32 v45, v39
	s_nop 0
	v_pk_mul_f32 v[30:31], v[44:45], v[30:31]
	s_nop 0
	v_pk_mul_f32 v[30:31], v[32:33], v[30:31]
	s_nop 0
	v_cvt_pk_bf16_f32 v39, v30, v31
	v_lshl_add_u64 v[30:31], v[42:43], 0, v[0:1]
	v_readlane_b32 s2, v254, 31
	v_readlane_b32 s3, v254, 32
	v_subrev_u32_e32 v62, s2, v30
	v_and_b32_e32 v63, 0x7c0, v62
	v_and_b32_e32 v64, 0xfffff7ff, v62
	v_add_u32_e32 v64, v64, v63
	v_bfe_u32 v63, v62, 11, 1
	v_lshl_or_b32 v64, v63, 6, v64
	v_bfe_i32 v63, v62, 25, 1
	v_bfi_b32 v64, v63, v62, v64
	global_store_dwordx2 v64, v[38:39], s[2:3]
	s_nop 0
	s_waitcnt vmcnt(14)
	v_lshlrev_b32_e32 v42, 16, v102
	v_mul_f32_e32 v0, 0xbfb8aa3b, v42
	v_exp_f32_e32 v0, v0
	v_and_b32_e32 v43, 0xffff0000, v102
	v_lshlrev_b32_e32 v32, 16, v103
	s_waitcnt vmcnt(13)
	v_pk_mul_f32 v[26:27], v[120:121], v[26:27]
	v_add_f32_e32 v0, 1.0, v0
	v_rcp_f32_e32 v44, v0
	v_mul_f32_e32 v0, 0xbfb8aa3b, v43
	v_exp_f32_e32 v0, v0
	v_and_b32_e32 v33, 0xffff0000, v103
	v_pk_mul_f32 v[28:29], v[122:123], v[28:29]
	v_add_f32_e32 v0, 1.0, v0
	v_rcp_f32_e32 v45, v0
	v_mul_f32_e32 v0, 0xbfb8aa3b, v32
	v_exp_f32_e32 v0, v0
	v_pk_mul_f32 v[38:39], v[44:45], v[42:43]
	s_nop 0
	v_pk_mul_f32 v[26:27], v[26:27], v[38:39]
	v_add_f32_e32 v0, 1.0, v0
	v_rcp_f32_e32 v38, v0
	v_mul_f32_e32 v0, 0xbfb8aa3b, v33
	v_exp_f32_e32 v0, v0
	v_cvt_pk_bf16_f32 v26, v26, v27
	v_add_f32_e32 v0, 1.0, v0
	v_rcp_f32_e32 v39, v0
	s_nop 0
	v_pk_mul_f32 v[32:33], v[38:39], v[32:33]
	s_nop 0
	v_pk_mul_f32 v[28:29], v[28:29], v[32:33]
	s_nop 0
	v_cvt_pk_bf16_f32 v27, v28, v29
	v_readlane_b32 s2, v254, 31
	v_readlane_b32 s3, v254, 32
	v_subrev_u32_e32 v62, s2, v30
	v_add_u32_e32 v62, 32, v62
	v_and_b32_e32 v63, 0x7c0, v62
	v_and_b32_e32 v64, 0xfffff7ff, v62
	v_add_u32_e32 v64, v64, v63
	v_bfe_u32 v63, v62, 11, 1
	v_lshl_or_b32 v64, v63, 6, v64
	v_bfe_i32 v63, v62, 25, 1
	v_bfi_b32 v64, v63, v62, v64
	global_store_dwordx2 v64, v[26:27], s[2:3]
	s_nop 0
	s_waitcnt vmcnt(13)
	v_lshlrev_b32_e32 v38, 16, v104
	v_mul_f32_e32 v0, 0xbfb8aa3b, v38
	v_exp_f32_e32 v0, v0
	v_and_b32_e32 v39, 0xffff0000, v104
	s_waitcnt vmcnt(12)
	v_pk_mul_f32 v[22:23], v[22:23], v[124:125]
	v_pk_mul_f32 v[24:25], v[24:25], v[126:127]
	v_add_f32_e32 v0, 1.0, v0
	v_rcp_f32_e32 v40, v0
	v_mul_f32_e32 v0, 0xbfb8aa3b, v39
	v_exp_f32_e32 v0, v0
	s_nop 0
	v_add_f32_e32 v0, 1.0, v0
	v_rcp_f32_e32 v41, v0
	s_nop 0
	v_pk_mul_f32 v[26:27], v[40:41], v[38:39]
	s_nop 0
	v_pk_mul_f32 v[22:23], v[22:23], v[26:27]
	v_lshlrev_b32_e32 v26, 16, v105
	v_mul_f32_e32 v0, 0xbfb8aa3b, v26
	v_exp_f32_e32 v0, v0
	v_and_b32_e32 v27, 0xffff0000, v105
	v_cvt_pk_bf16_f32 v22, v22, v23
	v_add_f32_e32 v0, 1.0, v0
	v_rcp_f32_e32 v32, v0
	v_mul_f32_e32 v0, 0xbfb8aa3b, v27
	v_exp_f32_e32 v0, v0
	s_nop 0
	v_add_f32_e32 v0, 1.0, v0
	v_rcp_f32_e32 v33, v0
	s_nop 0
	v_pk_mul_f32 v[26:27], v[32:33], v[26:27]
	s_nop 0
	v_pk_mul_f32 v[24:25], v[24:25], v[26:27]
	s_nop 0
	v_cvt_pk_bf16_f32 v23, v24, v25
	v_readlane_b32 s2, v254, 31
	v_readlane_b32 s3, v254, 32
	v_subrev_u32_e32 v62, s2, v30
	v_add_u32_e32 v62, 64, v62
	v_and_b32_e32 v63, 0x7c0, v62
	v_and_b32_e32 v64, 0xfffff7ff, v62
	v_add_u32_e32 v64, v64, v63
	v_bfe_u32 v63, v62, 11, 1
	v_lshl_or_b32 v64, v63, 6, v64
	v_bfe_i32 v63, v62, 25, 1
	v_bfi_b32 v64, v63, v62, v64
	global_store_dwordx2 v64, v[22:23], s[2:3]
	s_nop 0
	s_waitcnt vmcnt(12)
	v_lshlrev_b32_e32 v28, 16, v106
	v_mul_f32_e32 v0, 0xbfb8aa3b, v28
	v_exp_f32_e32 v0, v0
	v_and_b32_e32 v29, 0xffff0000, v106
	s_waitcnt vmcnt(11)
	v_pk_mul_f32 v[18:19], v[18:19], v[128:129]
	v_pk_mul_f32 v[20:21], v[20:21], v[130:131]
	v_add_f32_e32 v0, 1.0, v0
	v_rcp_f32_e32 v32, v0
	v_mul_f32_e32 v0, 0xbfb8aa3b, v29
	v_exp_f32_e32 v0, v0
	s_nop 0
	v_add_f32_e32 v0, 1.0, v0
	v_rcp_f32_e32 v33, v0
	s_nop 0
	v_pk_mul_f32 v[22:23], v[32:33], v[28:29]
	s_nop 0
	v_pk_mul_f32 v[18:19], v[18:19], v[22:23]
	v_lshlrev_b32_e32 v22, 16, v107
	v_mul_f32_e32 v0, 0xbfb8aa3b, v22
	v_exp_f32_e32 v0, v0
	v_and_b32_e32 v23, 0xffff0000, v107
	v_cvt_pk_bf16_f32 v18, v18, v19
	v_add_f32_e32 v0, 1.0, v0
	v_rcp_f32_e32 v26, v0
	v_mul_f32_e32 v0, 0xbfb8aa3b, v23
	v_exp_f32_e32 v0, v0
	s_nop 0
	v_add_f32_e32 v0, 1.0, v0
	v_rcp_f32_e32 v27, v0
	s_nop 0
	v_pk_mul_f32 v[22:23], v[26:27], v[22:23]
	s_nop 0
	v_pk_mul_f32 v[20:21], v[20:21], v[22:23]
	s_nop 0
	v_cvt_pk_bf16_f32 v19, v20, v21
	v_readlane_b32 s2, v254, 31
	v_readlane_b32 s3, v254, 32
	v_subrev_u32_e32 v62, s2, v30
	v_add_u32_e32 v62, 0x60, v62
	v_and_b32_e32 v63, 0x7c0, v62
	v_and_b32_e32 v64, 0xfffff7ff, v62
	v_add_u32_e32 v64, v64, v63
	v_bfe_u32 v63, v62, 11, 1
	v_lshl_or_b32 v64, v63, 6, v64
	v_bfe_i32 v63, v62, 25, 1
	v_bfi_b32 v64, v63, v62, v64
	global_store_dwordx2 v64, v[18:19], s[2:3]
	s_nop 0
	s_waitcnt vmcnt(11)
; DI float silu(float x) { return x * __builtin_amdgcn_rcpf(1.f + __expf(-x)); }
;   DI bf16* HY() const { return (bf16*)(p.ws + WS_HY); }
;   DI bf16* P() const { return (bf16*)(p.ws + WS_P); }
; DI u32x2 pk4(f32x4 v) { return u32x2{pk2(v[0], v[1]), pk2(v[2], v[3])}; }
; DI f32x4 unpk4(u32x2 u) { return f32x4{__uint_as_float(u[0] << 16), __uint_as_float(u[0] & 0xffff0000u), __uint_as_float(u[1] << 16), __uint_as_float(u[1] & 0xffff0000u)}; }
; DI void gla_g3_item(const Ctx& c, int l, int item, bf16* lds) {
;     ...
;   const int row = row0 + 16 * wave + l16;
;   const bf16* gg = c.P() + (size_t)row * LDP + C_GG + h * 128;
;   bf16* dst = c.HY() + (size_t)row * D + h * 128;
; #pragma unroll
;   for (int j = 0; j < 8; ++j) {
;     const int v = 16 * j + 4 * lq;
;     const float4 gn = *(const float4*)(p.gla_norm_g + li * 128 + v);
;     const f32x4 g4 = unpk4(*(const u32x2*)(gg + v));
;     f32x4 y = {o[j][0] * rstd * gn.x * silu(g4[0]), o[j][1] * rstd * gn.y * silu(g4[1]), o[j][2] * rstd * gn.z * silu(g4[2]), o[j][3] * rstd * gn.w * silu(g4[3])};
;     *(u32x2*)(dst + v) = pk4(y);
;   }
	v_lshlrev_b32_e32 v24, 16, v108
	v_mul_f32_e32 v0, 0xbfb8aa3b, v24
	v_exp_f32_e32 v0, v0
	v_and_b32_e32 v25, 0xffff0000, v108
	s_waitcnt vmcnt(10)
	v_pk_mul_f32 v[14:15], v[14:15], v[132:133]
	v_pk_mul_f32 v[16:17], v[16:17], v[134:135]
	v_add_f32_e32 v0, 1.0, v0
	v_rcp_f32_e32 v26, v0
	v_mul_f32_e32 v0, 0xbfb8aa3b, v25
	v_exp_f32_e32 v0, v0
	s_nop 0
	v_add_f32_e32 v0, 1.0, v0
	v_rcp_f32_e32 v27, v0
	s_nop 0
	v_pk_mul_f32 v[18:19], v[26:27], v[24:25]
	s_nop 0
	v_pk_mul_f32 v[14:15], v[14:15], v[18:19]
	v_lshlrev_b32_e32 v18, 16, v109
	v_mul_f32_e32 v0, 0xbfb8aa3b, v18
	v_exp_f32_e32 v0, v0
	v_and_b32_e32 v19, 0xffff0000, v109
	v_cvt_pk_bf16_f32 v14, v14, v15
	v_add_f32_e32 v0, 1.0, v0
	v_rcp_f32_e32 v22, v0
	v_mul_f32_e32 v0, 0xbfb8aa3b, v19
	v_exp_f32_e32 v0, v0
	s_nop 0
	v_add_f32_e32 v0, 1.0, v0
	v_rcp_f32_e32 v23, v0
	s_nop 0
	v_pk_mul_f32 v[18:19], v[22:23], v[18:19]
	s_nop 0
	v_pk_mul_f32 v[16:17], v[16:17], v[18:19]
	s_nop 0
	v_cvt_pk_bf16_f32 v15, v16, v17
	v_readlane_b32 s2, v254, 31
	v_readlane_b32 s3, v254, 32
	v_subrev_u32_e32 v62, s2, v30
	v_add_u32_e32 v62, 0x80, v62
	v_and_b32_e32 v63, 0x7c0, v62
	v_and_b32_e32 v64, 0xfffff7ff, v62
	v_add_u32_e32 v64, v64, v63
	v_bfe_u32 v63, v62, 11, 1
	v_lshl_or_b32 v64, v63, 6, v64
	v_bfe_i32 v63, v62, 25, 1
	v_bfi_b32 v64, v63, v62, v64
	global_store_dwordx2 v64, v[14:15], s[2:3]
	s_nop 0
	s_waitcnt vmcnt(10)
	v_lshlrev_b32_e32 v20, 16, v110
	v_mul_f32_e32 v0, 0xbfb8aa3b, v20
	v_exp_f32_e32 v0, v0
	v_and_b32_e32 v21, 0xffff0000, v110
	s_waitcnt vmcnt(9)
	v_pk_mul_f32 v[10:11], v[10:11], v[136:137]
	v_pk_mul_f32 v[12:13], v[12:13], v[138:139]
	v_add_f32_e32 v0, 1.0, v0
	v_rcp_f32_e32 v22, v0
	v_mul_f32_e32 v0, 0xbfb8aa3b, v21
	v_exp_f32_e32 v0, v0
	s_nop 0
	v_add_f32_e32 v0, 1.0, v0
	v_rcp_f32_e32 v23, v0
	s_nop 0
	v_pk_mul_f32 v[14:15], v[22:23], v[20:21]
	s_nop 0
	v_pk_mul_f32 v[10:11], v[10:11], v[14:15]
	v_lshlrev_b32_e32 v14, 16, v111
	v_mul_f32_e32 v0, 0xbfb8aa3b, v14
	v_exp_f32_e32 v0, v0
	v_and_b32_e32 v15, 0xffff0000, v111
	v_cvt_pk_bf16_f32 v10, v10, v11
	v_add_f32_e32 v0, 1.0, v0
	v_rcp_f32_e32 v18, v0
	v_mul_f32_e32 v0, 0xbfb8aa3b, v15
	v_exp_f32_e32 v0, v0
	s_nop 0
	v_add_f32_e32 v0, 1.0, v0
	v_rcp_f32_e32 v19, v0
	s_nop 0
	v_pk_mul_f32 v[14:15], v[18:19], v[14:15]
	s_nop 0
	v_pk_mul_f32 v[12:13], v[12:13], v[14:15]
	s_nop 0
	v_cvt_pk_bf16_f32 v11, v12, v13
	v_readlane_b32 s2, v254, 31
	v_readlane_b32 s3, v254, 32
	v_subrev_u32_e32 v62, s2, v30
	v_add_u32_e32 v62, 0xa0, v62
	v_and_b32_e32 v63, 0x7c0, v62
	v_and_b32_e32 v64, 0xfffff7ff, v62
	v_add_u32_e32 v64, v64, v63
	v_bfe_u32 v63, v62, 11, 1
	v_lshl_or_b32 v64, v63, 6, v64
	v_bfe_i32 v63, v62, 25, 1
	v_bfi_b32 v64, v63, v62, v64
	global_store_dwordx2 v64, v[10:11], s[2:3]
	s_nop 0
	s_waitcnt vmcnt(9)
	v_lshlrev_b32_e32 v16, 16, v112
	v_mul_f32_e32 v0, 0xbfb8aa3b, v16
	v_exp_f32_e32 v0, v0
	v_and_b32_e32 v17, 0xffff0000, v112
	s_waitcnt vmcnt(8)
	v_pk_mul_f32 v[6:7], v[6:7], v[140:141]
	v_pk_mul_f32 v[8:9], v[8:9], v[142:143]
	v_add_f32_e32 v0, 1.0, v0
	v_rcp_f32_e32 v18, v0
	v_mul_f32_e32 v0, 0xbfb8aa3b, v17
	v_exp_f32_e32 v0, v0
	s_nop 0
	v_add_f32_e32 v0, 1.0, v0
	v_rcp_f32_e32 v19, v0
	s_nop 0
	v_pk_mul_f32 v[10:11], v[18:19], v[16:17]
	s_nop 0
	v_pk_mul_f32 v[6:7], v[6:7], v[10:11]
	v_lshlrev_b32_e32 v10, 16, v113
	v_mul_f32_e32 v0, 0xbfb8aa3b, v10
	v_exp_f32_e32 v0, v0
	v_and_b32_e32 v11, 0xffff0000, v113
	v_cvt_pk_bf16_f32 v6, v6, v7
	v_add_f32_e32 v0, 1.0, v0
	v_rcp_f32_e32 v14, v0
	v_mul_f32_e32 v0, 0xbfb8aa3b, v11
	v_exp_f32_e32 v0, v0
	s_nop 0
	v_add_f32_e32 v0, 1.0, v0
	v_rcp_f32_e32 v15, v0
	s_nop 0
	v_pk_mul_f32 v[10:11], v[14:15], v[10:11]
	s_nop 0
	v_pk_mul_f32 v[8:9], v[8:9], v[10:11]
	s_nop 0
	v_cvt_pk_bf16_f32 v7, v8, v9
	v_readlane_b32 s2, v254, 31
	v_readlane_b32 s3, v254, 32
	v_subrev_u32_e32 v62, s2, v30
	v_add_u32_e32 v62, 0xc0, v62
	v_and_b32_e32 v63, 0x7c0, v62
	v_and_b32_e32 v64, 0xfffff7ff, v62
	v_add_u32_e32 v64, v64, v63
	v_bfe_u32 v63, v62, 11, 1
	v_lshl_or_b32 v64, v63, 6, v64
	v_bfe_i32 v63, v62, 25, 1
	v_bfi_b32 v64, v63, v62, v64
	global_store_dwordx2 v64, v[6:7], s[2:3]
	s_nop 0
	s_waitcnt vmcnt(8)
	v_lshlrev_b32_e32 v12, 16, v114
	v_mul_f32_e32 v0, 0xbfb8aa3b, v12
	v_exp_f32_e32 v0, v0
	v_and_b32_e32 v13, 0xffff0000, v114
	v_lshlrev_b32_e32 v6, 16, v115
	s_waitcnt vmcnt(7)
	v_pk_mul_f32 v[2:3], v[2:3], v[144:145]
	v_add_f32_e32 v0, 1.0, v0
	v_rcp_f32_e32 v14, v0
	v_mul_f32_e32 v0, 0xbfb8aa3b, v13
	v_exp_f32_e32 v0, v0
	v_and_b32_e32 v7, 0xffff0000, v115
	v_pk_mul_f32 v[4:5], v[4:5], v[146:147]
	v_add_f32_e32 v0, 1.0, v0
	v_rcp_f32_e32 v15, v0
	v_mul_f32_e32 v0, 0xbfb8aa3b, v6
	v_exp_f32_e32 v0, v0
	v_pk_mul_f32 v[8:9], v[14:15], v[12:13]
	s_nop 0
	v_pk_mul_f32 v[2:3], v[2:3], v[8:9]
	v_add_f32_e32 v0, 1.0, v0
	v_rcp_f32_e32 v8, v0
	v_mul_f32_e32 v0, 0xbfb8aa3b, v7
	v_exp_f32_e32 v0, v0
	v_cvt_pk_bf16_f32 v2, v2, v3
	v_add_f32_e32 v0, 1.0, v0
	v_rcp_f32_e32 v9, v0
	s_nop 0
	v_pk_mul_f32 v[6:7], v[8:9], v[6:7]
	s_nop 0
	v_pk_mul_f32 v[4:5], v[4:5], v[6:7]
	s_nop 0
	v_cvt_pk_bf16_f32 v3, v4, v5
	v_readlane_b32 s2, v254, 31
	v_readlane_b32 s3, v254, 32
	v_subrev_u32_e32 v62, s2, v30
	v_add_u32_e32 v62, 0xe0, v62
	v_and_b32_e32 v63, 0x7c0, v62
	v_and_b32_e32 v64, 0xfffff7ff, v62
	v_add_u32_e32 v64, v64, v63
	v_bfe_u32 v63, v62, 11, 1
	v_lshl_or_b32 v64, v63, 6, v64
	v_bfe_i32 v63, v62, 25, 1
	v_bfi_b32 v64, v63, v62, v64
	global_store_dwordx2 v64, v[2:3], s[2:3]

; DI int otid() { int t = threadIdx.x; asm volatile("" : "+v"(t)); return t; }
;   DI bf16* K() const { return (bf16*)(p.ws + WS_K); }
; template <class AP, class BP, class Epi>
; DI void mfma_gemm_big_tile(const AP& aptr, const BP& bptr, int m0, int n0, int K, const Epi& epi, bf16* lds) {
;   const int tid = otid(), lane = tid & 63, wave = __builtin_amdgcn_readfirstlane(tid >> 6);
;   const int wm = (wave >> 1) * 128, wn = (wave & 1) * 64;
;   const int l16 = lane & 15, lq = lane >> 4;
;   const int lrow = tid >> 2, lcol = ((tid & 3) ^ ((-(tid >> 4)) & 3)) * 8;
;   const bf16* ap[4]; const bf16* bp[2];
; #pragma unroll
;   for (int i = 0; i < 4; ++i) ap[i] = aptr(m0 + lrow + 64 * i) + lcol;
; #pragma unroll
;   for (int i = 0; i < 2; ++i) bp[i] = bptr(n0 + lrow + 64 * i) + lcol;
;   f32x4 acc[8][4];
; #pragma unroll
;   for (int i = 0; i < 8; ++i)
; #pragma unroll
;     for (int j = 0; j < 4; ++j) acc[i][j] = f32x4{0.f, 0.f, 0.f, 0.f};
;   const int nk = K >> 5;
;     ...
;   BG_ISSUE(0, 0);
;   BG_ISSUE(1, 1);
;   asm volatile("s_waitcnt vmcnt(6)\n\ts_barrier" ::: "memory");
;   const unsigned lbase = (unsigned)(size_t)lds;
;   const unsigned a_off = (unsigned)(((wm + l16) * 32 + (lq ^ ((-(l16 >> 2)) & 3)) * 8) * 2);
;   const unsigned b_off = (unsigned)((256 * 32 + (wn + l16) * 32 + (lq ^ ((-(l16 >> 2)) & 3)) * 8) * 2);
.LBB0_1105:
	s_add_i32 s0, s13, s74
	s_ashr_i32 s1, s0, 31
	s_lshr_b32 s1, s1, 29
	v_mov_b32_e32 v26, v172
	s_add_i32 s1, s0, s1
	s_lshl_b32 s8, s1, 5
	v_lshrrev_b32_e32 v142, 4, v26
	s_and_b32 s1, s1, 0x1fffff8
	v_sub_u32_e32 v27, 0, v142
	s_and_b32 s14, s8, 0xffffff00
	s_sub_i32 s0, s0, s1
	v_ashrrev_i32_e32 v18, 2, v26
	v_xor_b32_e32 v0, v26, v27
	s_lshl_b32 s15, s0, 7
	v_readfirstlane_b32 s0, v26
	v_add_u32_e32 v2, s14, v18
	v_lshlrev_b32_e32 v0, 4, v0
	s_and_b32 s16, s0, 64
	v_and_b32_e32 v0, 48, v0
	v_ashrrev_i32_e32 v3, 31, v2
	v_add_u32_e32 v10, 64, v2
	s_and_b32 s19, s0, 0xffffff80
	s_lshl_b32 s0, s0, 4
	v_lshl_add_u64 v[4:5], s[60:61], 0, v[0:1]
	v_bfe_u32 v30, v26, 2, 1
	v_mul_i32_i24_e32 v30, 0xfffff840, v30
	v_ashrrev_i32_e32 v31, 31, v30
	v_lshl_add_u64 v[4:5], v[4:5], 0, v[30:31]
	v_lshlrev_b64 v[6:7], 11, v[2:3]
	v_ashrrev_i32_e32 v11, 31, v10
	v_add_u32_e32 v14, 0x80, v2
	s_and_b32 s20, s0, 0xfffffc00
	v_lshl_add_u64 v[8:9], v[4:5], 0, v[6:7]
	v_lshlrev_b64 v[10:11], 11, v[10:11]
	v_ashrrev_i32_e32 v15, 31, v14
	v_add_u32_e32 v2, 0xc0, v2
	v_add_u32_e32 v18, s15, v18
	s_mov_b32 m0, s20
	v_lshl_add_u64 v[12:13], v[4:5], 0, v[10:11]
	v_lshlrev_b64 v[14:15], 11, v[14:15]
	v_ashrrev_i32_e32 v3, 31, v2
	v_ashrrev_i32_e32 v19, 31, v18
	global_load_lds_dwordx4 v[8:9], off
	s_add_i32 m0, s20, 0x1000
	v_lshl_add_u64 v[16:17], v[4:5], 0, v[14:15]
	v_lshlrev_b64 v[2:3], 11, v[2:3]
	v_lshlrev_b64 v[22:23], 11, v[18:19]
	v_add_u32_e32 v18, 64, v18
	global_load_lds_dwordx4 v[12:13], off
	s_add_i32 m0, s20, 0x2000
	v_lshl_add_u64 v[4:5], v[4:5], 0, v[2:3]
	v_lshl_add_u64 v[20:21], s[44:45], 0, v[0:1]
	v_ashrrev_i32_e32 v19, 31, v18
	global_load_lds_dwordx4 v[16:17], off
	s_add_i32 m0, s20, 0x3000
	v_lshl_add_u64 v[24:25], v[20:21], 0, v[22:23]
	v_lshlrev_b64 v[18:19], 11, v[18:19]
	global_load_lds_dwordx4 v[4:5], off
	s_add_i32 m0, s20, 0x4000
	v_lshl_add_u64 v[20:21], v[20:21], 0, v[18:19]
	global_load_lds_dwordx4 v[24:25], off
	s_add_i32 m0, s20, 0x5000
	v_lshl_add_u64 v[8:9], v[8:9], 0, 64
	v_lshl_add_u64 v[8:9], v[8:9], 0, 64
	global_load_lds_dwordx4 v[20:21], off
	s_add_i32 m0, s20, 0x6000
	v_lshl_add_u64 v[4:5], v[4:5], 0, 64
	v_lshl_add_u64 v[4:5], v[4:5], 0, 64
	global_load_lds_dwordx4 v[8:9], off
	v_lshl_add_u64 v[8:9], v[12:13], 0, 64
	v_lshl_add_u64 v[8:9], v[8:9], 0, 64
	s_add_i32 m0, s20, 0x7000
	v_and_b32_e32 v0, 15, v26
	global_load_lds_dwordx4 v[8:9], off
	v_lshl_add_u64 v[8:9], v[16:17], 0, 64
	v_lshl_add_u64 v[8:9], v[8:9], 0, 64
	s_add_i32 m0, s20, 0x8000
	v_readlane_b32 s0, v254, 0
	global_load_lds_dwordx4 v[8:9], off
	s_add_i32 m0, s20, 0x9000
	v_readlane_b32 s1, v254, 1
	global_load_lds_dwordx4 v[4:5], off
	v_lshl_add_u64 v[4:5], v[24:25], 0, 64
	s_add_i32 m0, s20, 0xa000
	s_mov_b32 s17, 2
	global_load_lds_dwordx4 v[4:5], off
	v_lshl_add_u64 v[4:5], v[20:21], 0, 64
	s_add_i32 m0, s20, 0xb000
	s_mov_b32 s18, 0
	global_load_lds_dwordx4 v[4:5], off
	v_lshrrev_b32_e32 v5, 2, v26
	v_sub_u32_e32 v5, 0, v5
	v_xor_b32_e32 v5, v142, v5
	v_lshlrev_b32_e32 v5, 4, v5
	v_or_b32_e32 v4, s19, v0
	v_and_b32_e32 v5, 48, v5
	v_lshl_or_b32 v143, v4, 6, v5
	v_or_b32_e32 v4, s16, v0
	v_lshlrev_b32_e32 v4, 6, v4
	v_or3_b32 v144, v4, v5, s77
	v_bitop3_b32 v4, v26, 3, v27 bitop3:0x48
	v_lshlrev_b32_e32 v4, 4, v4
	v_or_b32_e32 v18, v18, v4
	v_or_b32_e32 v22, v22, v4
	v_lshl_add_u64 v[130:131], s[0:1], 0, v[18:19]
	v_lshl_add_u64 v[132:133], s[0:1], 0, v[22:23]
	v_readlane_b32 s0, v253, 55
	s_waitcnt vmcnt(6)
	s_barrier
; template <class AP, class BP, class Epi>
; DI void mfma_gemm_big_tile(const AP& aptr, const BP& bptr, int m0, int n0, int K, const Epi& epi, bf16* lds) {
;     ...
;   const bf16* ap[4]; const bf16* bp[2];
; #pragma unroll
;   for (int i = 0; i < 4; ++i) ap[i] = aptr(m0 + lrow + 64 * i) + lcol;
; #pragma unroll
;   for (int i = 0; i < 2; ++i) bp[i] = bptr(n0 + lrow + 64 * i) + lcol;
;   f32x4 acc[8][4];
; #pragma unroll
;   for (int i = 0; i < 8; ++i)
; #pragma unroll
;     for (int j = 0; j < 4; ++j) acc[i][j] = f32x4{0.f, 0.f, 0.f, 0.f};
	v_or_b32_e32 v2, v2, v4
	v_readlane_b32 s1, v253, 56
	v_or_b32_e32 v14, v14, v4
	v_or_b32_e32 v10, v10, v4
	v_lshl_add_u64 v[134:135], s[0:1], 0, v[2:3]
	v_or_b32_e32 v6, v6, v4
	v_mov_b32_e32 v2, 0
	v_lshl_add_u64 v[136:137], s[0:1], 0, v[14:15]
	v_lshl_add_u64 v[138:139], s[0:1], 0, v[10:11]
	v_lshl_add_u64 v[140:141], s[0:1], 0, v[6:7]
	v_lshl_add_u64 v[30:31], v[30:31], 0, 64
	v_lshl_add_u64 v[30:31], v[30:31], 0, 64
	v_lshl_add_u64 v[134:135], v[134:135], 0, v[30:31]
	v_lshl_add_u64 v[136:137], v[136:137], 0, v[30:31]
	v_lshl_add_u64 v[138:139], v[138:139], 0, v[30:31]
	v_lshl_add_u64 v[140:141], v[140:141], 0, v[30:31]
	s_mov_b64 s[0:1], 0
	s_mov_b32 s21, 0
	v_mov_b32_e32 v3, v2
	v_mov_b32_e32 v4, v2
	v_mov_b32_e32 v5, v2
	v_mov_b32_e32 v6, v2
	v_mov_b32_e32 v7, v2
	v_mov_b32_e32 v8, v2
	v_mov_b32_e32 v9, v2
	v_mov_b32_e32 v10, v2
	v_mov_b32_e32 v11, v2
	v_mov_b32_e32 v12, v2
	v_mov_b32_e32 v13, v2
	v_mov_b32_e32 v14, v2
	v_mov_b32_e32 v15, v2
	v_mov_b32_e32 v16, v2
	v_mov_b32_e32 v17, v2
	v_mov_b32_e32 v18, v2
	v_mov_b32_e32 v19, v2
	v_mov_b32_e32 v20, v2
	v_mov_b32_e32 v21, v2
	v_mov_b32_e32 v22, v2
	v_mov_b32_e32 v23, v2
	v_mov_b32_e32 v24, v2
	v_mov_b32_e32 v25, v2
	v_mov_b32_e32 v26, v2
	v_mov_b32_e32 v27, v2
	v_mov_b32_e32 v28, v2
	v_mov_b32_e32 v29, v2
	v_mov_b32_e32 v30, v2
	v_mov_b32_e32 v31, v2
	v_mov_b32_e32 v32, v2
	v_mov_b32_e32 v33, v2
	v_mov_b32_e32 v34, v2
	v_mov_b32_e32 v35, v2
	v_mov_b32_e32 v36, v2
	v_mov_b32_e32 v37, v2
	v_mov_b32_e32 v38, v2
	v_mov_b32_e32 v39, v2
	v_mov_b32_e32 v40, v2
	v_mov_b32_e32 v41, v2
	v_mov_b32_e32 v42, v2
	v_mov_b32_e32 v43, v2
	v_mov_b32_e32 v44, v2
	v_mov_b32_e32 v45, v2
	v_mov_b32_e32 v46, v2
	v_mov_b32_e32 v47, v2
	v_mov_b32_e32 v48, v2
	v_mov_b32_e32 v49, v2
	v_mov_b32_e32 v50, v2
	v_mov_b32_e32 v51, v2
	v_mov_b32_e32 v52, v2
	v_mov_b32_e32 v53, v2
	v_mov_b32_e32 v54, v2
	v_mov_b32_e32 v55, v2
	v_mov_b32_e32 v56, v2
	v_mov_b32_e32 v57, v2
	v_mov_b32_e32 v58, v2
	v_mov_b32_e32 v59, v2
	v_mov_b32_e32 v60, v2
	v_mov_b32_e32 v61, v2
	v_mov_b32_e32 v62, v2
	v_mov_b32_e32 v63, v2
	v_mov_b32_e32 v64, v2
	v_mov_b32_e32 v65, v2
	v_mov_b32_e32 v66, v2
	v_mov_b32_e32 v67, v2
	v_mov_b32_e32 v68, v2
	v_mov_b32_e32 v69, v2
	v_mov_b32_e32 v70, v2
	v_mov_b32_e32 v71, v2
	v_mov_b32_e32 v72, v2
	v_mov_b32_e32 v73, v2
	v_mov_b32_e32 v74, v2
	v_mov_b32_e32 v75, v2
	v_mov_b32_e32 v76, v2
	v_mov_b32_e32 v77, v2
	v_mov_b32_e32 v78, v2
	v_mov_b32_e32 v79, v2
	v_mov_b32_e32 v80, v2
	v_mov_b32_e32 v81, v2
	v_mov_b32_e32 v82, v2
	v_mov_b32_e32 v83, v2
	v_mov_b32_e32 v84, v2
	v_mov_b32_e32 v85, v2
	v_mov_b32_e32 v86, v2
	v_mov_b32_e32 v87, v2
	v_mov_b32_e32 v88, v2
	v_mov_b32_e32 v89, v2
	v_mov_b32_e32 v90, v2
	v_mov_b32_e32 v91, v2
	v_mov_b32_e32 v92, v2
	v_mov_b32_e32 v93, v2
	v_mov_b32_e32 v94, v2
	v_mov_b32_e32 v95, v2
	v_mov_b32_e32 v96, v2
	v_mov_b32_e32 v97, v2
	v_mov_b32_e32 v98, v2
	v_mov_b32_e32 v99, v2
	v_mov_b32_e32 v100, v2
	v_mov_b32_e32 v101, v2
	v_mov_b32_e32 v102, v2
	v_mov_b32_e32 v103, v2
	v_mov_b32_e32 v104, v2
	v_mov_b32_e32 v105, v2
	v_mov_b32_e32 v106, v2
	v_mov_b32_e32 v107, v2
	v_mov_b32_e32 v108, v2
	v_mov_b32_e32 v109, v2
	v_mov_b32_e32 v110, v2
	v_mov_b32_e32 v111, v2
	v_mov_b32_e32 v112, v2
	v_mov_b32_e32 v113, v2
	v_mov_b32_e32 v114, v2
	v_mov_b32_e32 v115, v2
	v_mov_b32_e32 v116, v2
	v_mov_b32_e32 v117, v2
	v_mov_b32_e32 v118, v2
	v_mov_b32_e32 v119, v2
	v_mov_b32_e32 v120, v2
	v_mov_b32_e32 v121, v2
	v_mov_b32_e32 v122, v2
	v_mov_b32_e32 v123, v2
	v_mov_b32_e32 v124, v2
	v_mov_b32_e32 v125, v2
	v_mov_b32_e32 v126, v2
	v_mov_b32_e32 v127, v2
	v_mov_b32_e32 v128, v2
	v_mov_b32_e32 v129, v2
	s_branch .LBB0_1107

; template <class AP, class BP, class Epi>
; DI void mfma_gemm_big_tile(const AP& aptr, const BP& bptr, int m0, int n0, int K, const Epi& epi, bf16* lds) {
;     ...
;   BG_ISSUE(0, 0);
;   BG_ISSUE(1, 1);
;   asm volatile("s_waitcnt vmcnt(6)\n\ts_barrier" ::: "memory");
;   const unsigned lbase = (unsigned)(size_t)lds;
;   const unsigned a_off = (unsigned)(((wm + l16) * 32 + (lq ^ ((-(l16 >> 2)) & 3)) * 8) * 2);
;   const unsigned b_off = (unsigned)((256 * 32 + (wn + l16) * 32 + (lq ^ ((-(l16 >> 2)) & 3)) * 8) * 2);
;     ...
;   int cur = 0, nxt = 2;
;   for (int ks = 0; ks < nk; ++ks) {
;     if (ks + 2 < nk) BG_ISSUE(nxt, ks + 2);
.LBB0_1107:
	s_cmp_gt_u32 s18, 29
	s_cselect_b64 s[8:9], -1, 0
	s_and_b64 vcc, exec, s[8:9]
	s_cbranch_vccnz .LBB0_1109
	s_mul_i32 s10, s17, 0x6000
	s_add_i32 s10, s20, s10
	v_lshl_add_u64 v[146:147], s[0:1], 1, v[140:141]
	s_mov_b32 m0, s10
	s_nop 0
	global_load_lds_dwordx4 v[146:147], off
	v_lshl_add_u64 v[146:147], s[0:1], 1, v[138:139]
	s_add_i32 m0, s10, 0x1000
	s_nop 0
	global_load_lds_dwordx4 v[146:147], off
	v_lshl_add_u64 v[146:147], s[0:1], 1, v[136:137]
	s_add_i32 m0, s10, 0x2000
	s_nop 0
	global_load_lds_dwordx4 v[146:147], off
	v_lshl_add_u64 v[146:147], s[0:1], 1, v[134:135]
	s_add_i32 m0, s10, 0x3000
	s_nop 0
	global_load_lds_dwordx4 v[146:147], off
	v_lshl_add_u64 v[146:147], v[132:133], 0, s[0:1]
	s_add_i32 m0, s10, 0x4000
	s_nop 0
	global_load_lds_dwordx4 v[146:147], off
	v_lshl_add_u64 v[146:147], v[130:131], 0, s[0:1]
	s_add_i32 m0, s10, 0x5000
	s_nop 0
	global_load_lds_dwordx4 v[146:147], off
